# PV blocks in all attention bodies: per-MFMA counted lgkmcnt waits instead of lgkmcnt(0) per 4-MFMA group (on top of GEMM K-loop reschedule)
# speedup vs baseline: 1.0487x; 1.0133x over previous
; __device__ __forceinline__ void finishSM(f32x16& p0, f32x16& p1, float& l_reg, bf16x8& pa0, bf16x8& pa1, bf16x8& pa2, bf16x8& pa3) {
; #pragma unroll
;   for (int r = 0; r < 16; ++r) p1[r] = __builtin_amdgcn_exp2f(p1[r]);
;   float ps = 0;
; #pragma unroll
;   for (int r = 0; r < 16; ++r) ps += p0[r];
; #pragma unroll
;   for (int r = 0; r < 16; ++r) ps += p1[r];
;   { auto rr = __builtin_amdgcn_permlane32_swap(__float_as_uint(ps), __float_as_uint(ps), false, false);
;     ps = __uint_as_float(rr[0]) + __uint_as_float(rr[1]); }
;   l_reg += ps;
;     ...
;   PK4(p0, 0, pa0); PK4(p0, 8, pa1); PK4(p1, 0, pa2); PK4(p1, 8, pa3);
;     ...
; }
; template <int DQK, int QL>
; __device__ __forceinline__ void qkt(f32x16& p0, f32x16& p1, const char* Ks, const bf16x8 (&qr)[DQK / 16 - QL], const char* qlds, const int (&kofs)[4], float negM) {
;   constexpr int QR = DQK / 16 - QL;
; #pragma unroll
;   for (int r = 0; r < 16; ++r) { p0[r] = negM; p1[r] = negM; }
; #pragma unroll
;   for (int d0 = 0; d0 < DQK / 16; ++d0) {
;     const char* kp = Ks + kofs[d0 & 3] + (d0 >> 2) * 128;
;     bf16x8 b0 = *reinterpret_cast<const bf16x8*>(kp);
;     bf16x8 b1 = *reinterpret_cast<const bf16x8*>(kp + 32 * DQK * 2);
;     bf16x8 qf;
;     if constexpr (QL > 0) { if (d0 < QR) qf = qr[d0 < QR ? d0 : 0]; else qf = *reinterpret_cast<const bf16x8*>(qlds + (d0 - QR) * 1024); }
;     else qf = qr[d0];
;     p0 = __builtin_amdgcn_mfma_f32_32x32x16_bf16(b0, qf, p0, 0, 0, 0);
;     p1 = __builtin_amdgcn_mfma_f32_32x32x16_bf16(b1, qf, p1, 0, 0, 0);
;   }
; }
; template <int NCB> __device__ __forceinline__ int v_st(int k, int c) {
;   const int kk = (k & ~0xC) | ((k & 4) << 1) | ((k & 8) >> 1);
;   return ((kk >> 3) * NCB + (c >> 5)) * 512 + ((kk & 7) * 32 + (c & 31)) * 2;
; }
; __device__ __forceinline__ int v_rd_base(int lane) { return ((lane & 3) << 3) | (((lane >> 2) & 3) << 6) | (((lane >> 4) & 1) << 5) | (((lane >> 5) & 1) << 8); }
; template <int OFF> __device__ __forceinline__ s16x4 tr_read(int vb) {
;   s16x4 r; asm volatile("ds_read_b64_tr_b16 %0, %1 offset:%2" : "=&v"(r) : "v"(vb), "i"(OFF) : "memory"); return r;
; }
; template <int NCB, int D0> __device__ __forceinline__ void pv_one(f32x16& od, int vb, bf16x8 pa0, bf16x8 pa1, bf16x8 pa2, bf16x8 pa3) {
;   constexpr int KSTEP = NCB * 1024, HALF = NCB * 512, B0 = D0 * 512;
.LBB0_323:
	ds_read_b128 v[96:99], v174 offset:40960
	ds_read_b128 v[182:185], v174 offset:45056
	v_mov_b64_e32 v[126:127], s[18:19]
	v_mov_b64_e32 v[124:125], s[16:17]
	v_mov_b64_e32 v[122:123], s[14:15]
	v_mov_b64_e32 v[120:121], s[12:13]
	v_mov_b64_e32 v[118:119], s[10:11]
	v_mov_b64_e32 v[116:117], s[8:9]
	v_mov_b64_e32 v[114:115], s[6:7]
	v_mov_b64_e32 v[112:113], s[4:5]
	v_exp_f32_e32 v100, v68
	v_exp_f32_e32 v101, v69
	s_waitcnt lgkmcnt(1)
	v_mfma_f32_32x32x16_bf16 v[80:95], v[96:99], v[142:145], v[112:127]
	ds_read_b128 v[96:99], v175 offset:40960
	ds_read_b128 v[186:189], v175 offset:45056
	v_exp_f32_e32 v102, v70
	v_exp_f32_e32 v103, v71
	v_exp_f32_e32 v104, v72
	v_exp_f32_e32 v105, v73
	v_exp_f32_e32 v106, v74
	v_exp_f32_e32 v107, v75
	s_waitcnt lgkmcnt(1)
	v_mfma_f32_32x32x16_bf16 v[80:95], v[96:99], v[138:141], v[80:95]
	ds_read_b128 v[96:99], v173 offset:40960
	ds_read_b128 v[190:193], v173 offset:45056
	v_exp_f32_e32 v108, v76
	v_exp_f32_e32 v109, v77
	v_exp_f32_e32 v110, v78
	v_exp_f32_e32 v79, v79
	s_waitcnt lgkmcnt(1)
	v_mfma_f32_32x32x16_bf16 v[80:95], v[96:99], v[134:137], v[80:95]
	ds_read_b128 v[96:99], v176 offset:40960
	ds_read_b128 v[194:197], v176 offset:45056
	s_waitcnt lgkmcnt(1)
	v_mfma_f32_32x32x16_bf16 v[80:95], v[96:99], v[130:133], v[80:95]
	v_exp_f32_e32 v96, v64
	v_add_f32_e32 v64, 0, v165
	v_add_f32_e32 v64, v167, v64
	v_add_f32_e32 v64, v157, v64
	v_add_f32_e32 v64, v166, v64
	v_add_f32_e32 v64, v155, v64
	v_add_f32_e32 v64, v164, v64
	v_add_f32_e32 v64, v154, v64
	v_add_f32_e32 v64, v156, v64
	v_add_f32_e32 v64, v151, v64
	v_add_f32_e32 v64, v153, v64
	v_add_f32_e32 v64, v149, v64
	v_add_f32_e32 v64, v152, v64
	v_add_f32_e32 v64, v147, v64
	v_exp_f32_e32 v97, v65
	v_add_f32_e32 v64, v150, v64
	v_exp_f32_e32 v98, v66
	v_add_f32_e32 v64, v146, v64
	v_exp_f32_e32 v99, v67
	v_add_f32_e32 v64, v148, v64
	v_add_f32_e32 v64, v96, v64
	v_add_f32_e32 v64, v97, v64
	v_add_f32_e32 v64, v98, v64
	v_add_f32_e32 v64, v99, v64
	v_add_f32_e32 v64, v100, v64
	v_add_f32_e32 v64, v101, v64
	v_add_f32_e32 v64, v102, v64
	v_add_f32_e32 v64, v103, v64
	v_add_f32_e32 v64, v104, v64
	v_add_f32_e32 v64, v105, v64
	v_add_f32_e32 v64, v106, v64
	v_add_f32_e32 v64, v107, v64
	v_add_f32_e32 v64, v108, v64
	v_add_f32_e32 v64, v109, v64
	v_add_f32_e32 v64, v110, v64
	v_add_f32_e32 v180, v79, v64
	v_mov_b32_e32 v181, v180
	s_nop 1
	v_permlane32_swap_b32_e32 v180, v181
	v_cvt_pk_bf16_f32 v64, v165, v167
	v_cvt_pk_bf16_f32 v65, v157, v166
	v_cvt_pk_bf16_f32 v66, v155, v164
	v_cvt_pk_bf16_f32 v67, v154, v156
	v_cvt_pk_bf16_f32 v68, v151, v153
	v_cvt_pk_bf16_f32 v69, v149, v152
	v_cvt_pk_bf16_f32 v70, v147, v150
	v_cvt_pk_bf16_f32 v71, v146, v148
	v_cvt_pk_bf16_f32 v72, v96, v97
	v_cvt_pk_bf16_f32 v73, v98, v99
	v_cvt_pk_bf16_f32 v74, v100, v101
	v_cvt_pk_bf16_f32 v75, v102, v103
	v_cvt_pk_bf16_f32 v76, v104, v105
	v_cvt_pk_bf16_f32 v77, v106, v107
	v_cvt_pk_bf16_f32 v78, v108, v109
	v_cvt_pk_bf16_f32 v79, v110, v79
	s_nop 0
	v_permlane32_swap_b32_e32 v64, v66
	v_permlane32_swap_b32_e32 v65, v67
	v_permlane32_swap_b32_e32 v68, v70
	v_permlane32_swap_b32_e32 v69, v71
	v_permlane32_swap_b32_e32 v72, v74
	v_permlane32_swap_b32_e32 v73, v75
	v_permlane32_swap_b32_e32 v76, v78
	v_permlane32_swap_b32_e32 v77, v79
	v_lshl_add_u64 v[164:165], s[80:81], 0, v[158:159]
	v_mfma_f32_32x32x16_bf16 v[96:111], v[182:185], v[142:145], v[112:127]
	v_lshl_add_u64 v[168:169], s[80:81], 0, v[160:161]
	v_lshl_add_u64 v[166:167], s[80:81], 0, v[162:163]
	s_nop 4
	v_add_co_u32_e32 v112, vcc, s90, v164
	v_mfma_f32_32x32x16_bf16 v[96:111], v[186:189], v[138:141], v[96:111]
	s_nop 0
	v_addc_co_u32_e32 v113, vcc, 0, v165, vcc
	v_add_co_u32_e32 v114, vcc, s90, v168
	s_nop 1
	v_addc_co_u32_e32 v115, vcc, 0, v169, vcc
	global_load_dwordx4 v[146:149], v[112:113], off offset:1280
	global_load_dwordx4 v[150:153], v[114:115], off offset:2304
	v_add_co_u32_e32 v112, vcc, s90, v166
	v_mfma_f32_32x32x16_bf16 v[96:111], v[190:193], v[134:137], v[96:111]
	s_nop 0
	v_addc_co_u32_e32 v113, vcc, 0, v167, vcc
	global_load_dwordx4 v[154:157], v[112:113], off offset:2304
	s_waitcnt lgkmcnt(0)
	v_mfma_f32_32x32x16_bf16 v[96:111], v[194:197], v[130:133], v[96:111]
	ds_read_b64_tr_b16 v[112:113], v172 offset:0
	ds_read_b64_tr_b16 v[114:115], v172 offset:0x800
	ds_read_b64_tr_b16 v[116:117], v172 offset:0x1000
	ds_read_b64_tr_b16 v[118:119], v172 offset:0x1800
	ds_read_b64_tr_b16 v[120:121], v172 offset:0x2000
	ds_read_b64_tr_b16 v[122:123], v172 offset:0x2800
	ds_read_b64_tr_b16 v[124:125], v172 offset:0x3000
	ds_read_b64_tr_b16 v[126:127], v172 offset:0x3800
	s_nop 0
	s_waitcnt lgkmcnt(6)
	v_mfma_f32_32x32x16_bf16 v[0:15], v[64:67], v[112:115], v[0:15]
	ds_read_b64_tr_b16 v[112:113], v172 offset:0x200
	ds_read_b64_tr_b16 v[114:115], v172 offset:0xa00
	s_waitcnt lgkmcnt(6)
	v_mfma_f32_32x32x16_bf16 v[0:15], v[68:71], v[116:119], v[0:15]
	ds_read_b64_tr_b16 v[116:117], v172 offset:0x1200
	ds_read_b64_tr_b16 v[118:119], v172 offset:0x1a00
	s_waitcnt lgkmcnt(6)
	v_mfma_f32_32x32x16_bf16 v[0:15], v[72:75], v[120:123], v[0:15]
	ds_read_b64_tr_b16 v[120:121], v172 offset:0x2200
	ds_read_b64_tr_b16 v[122:123], v172 offset:0x2a00
	s_waitcnt lgkmcnt(6)
	v_mfma_f32_32x32x16_bf16 v[0:15], v[76:79], v[124:127], v[0:15]
	ds_read_b64_tr_b16 v[124:125], v172 offset:0x3200
	ds_read_b64_tr_b16 v[126:127], v172 offset:0x3a00
	s_waitcnt lgkmcnt(6)
; #define WAIT_L0() asm volatile("s_waitcnt lgkmcnt(0)" ::: "memory")
; #define SBAR() __builtin_amdgcn_sched_barrier(0)
; __device__ __forceinline__ int crow(int r, int hi) { return (r & 3) + 8 * (r >> 2) + 4 * hi; }
; template <bool GM>
; __device__ __forceinline__ void partialSM(f32x16& p0, f32x16& p1, bool mask, int kbase, int L, int qpos, int hi) {
;   if (mask) {
; #pragma unroll
;     for (int r = 0; r < 16; ++r) {
;       int k = kbase + crow(r, hi);
;       asm volatile("" : "+v"(k) : "v"(p0[r]));
;       bool ok = k < L;
;       if (GM) ok = ok && (k < 16 || abs(qpos - k) <= 128);
;       p0[r] = ok ? p0[r] : -1e30f;
;       int k2 = k + 32;
;       asm volatile("" : "+v"(k2) : "v"(p1[r]));
;       bool ok2 = k2 < L;
;       if (GM) ok2 = ok2 && (k2 < 16 || abs(qpos - k2) <= 128);
;       p1[r] = ok2 ? p1[r] : -1e30f;
;     }
;   }
; template <int NCB, int D0> __device__ __forceinline__ void pv_one(f32x16& od, int vb, bf16x8 pa0, bf16x8 pa1, bf16x8 pa2, bf16x8 pa3) {
;   constexpr int KSTEP = NCB * 1024, HALF = NCB * 512, B0 = D0 * 512;
;   const s16x4 l0 = tr_read<B0>(vb), h0 = tr_read<B0 + HALF>(vb), l1 = tr_read<B0 + KSTEP>(vb), h1 = tr_read<B0 + KSTEP + HALF>(vb);
;   const s16x4 l2 = tr_read<B0 + 2 * KSTEP>(vb), h2 = tr_read<B0 + 2 * KSTEP + HALF>(vb), l3 = tr_read<B0 + 3 * KSTEP>(vb), h3 = tr_read<B0 + 3 * KSTEP + HALF>(vb);
;   WAIT_L0(); SBAR();
;     ...
;   od = __builtin_amdgcn_mfma_f32_32x32x16_bf16(pa0, PK(l0, h0), od, 0, 0, 0);
;   od = __builtin_amdgcn_mfma_f32_32x32x16_bf16(pa1, PK(l1, h1), od, 0, 0, 0);
;   od = __builtin_amdgcn_mfma_f32_32x32x16_bf16(pa2, PK(l2, h2), od, 0, 0, 0);
;   od = __builtin_amdgcn_mfma_f32_32x32x16_bf16(pa3, PK(l3, h3), od, 0, 0, 0);
;     ...
; }
	v_mfma_f32_32x32x16_bf16 v[16:31], v[64:67], v[112:115], v[16:31]
	ds_read_b64_tr_b16 v[112:113], v172 offset:0x400
	ds_read_b64_tr_b16 v[114:115], v172 offset:0xc00
	s_waitcnt lgkmcnt(6)
	v_mfma_f32_32x32x16_bf16 v[16:31], v[68:71], v[116:119], v[16:31]
	ds_read_b64_tr_b16 v[116:117], v172 offset:0x1400
	ds_read_b64_tr_b16 v[118:119], v172 offset:0x1c00
	s_waitcnt lgkmcnt(6)
	v_mfma_f32_32x32x16_bf16 v[16:31], v[72:75], v[120:123], v[16:31]
	ds_read_b64_tr_b16 v[120:121], v172 offset:0x2400
	ds_read_b64_tr_b16 v[122:123], v172 offset:0x2c00
	s_waitcnt lgkmcnt(6)
	v_mfma_f32_32x32x16_bf16 v[16:31], v[76:79], v[124:127], v[16:31]
	ds_read_b64_tr_b16 v[124:125], v172 offset:0x3400
	ds_read_b64_tr_b16 v[126:127], v172 offset:0x3c00
	s_waitcnt lgkmcnt(6)
	v_mfma_f32_32x32x16_bf16 v[32:47], v[64:67], v[112:115], v[32:47]
	ds_read_b64_tr_b16 v[112:113], v172 offset:0x600
	ds_read_b64_tr_b16 v[114:115], v172 offset:0xe00
	s_waitcnt lgkmcnt(6)
	v_mfma_f32_32x32x16_bf16 v[32:47], v[68:71], v[116:119], v[32:47]
	ds_read_b64_tr_b16 v[116:117], v172 offset:0x1600
	ds_read_b64_tr_b16 v[118:119], v172 offset:0x1e00
	s_waitcnt lgkmcnt(6)
	v_mfma_f32_32x32x16_bf16 v[32:47], v[72:75], v[120:123], v[32:47]
	ds_read_b64_tr_b16 v[120:121], v172 offset:0x2600
	ds_read_b64_tr_b16 v[122:123], v172 offset:0x2e00
	s_waitcnt lgkmcnt(6)
	v_mfma_f32_32x32x16_bf16 v[32:47], v[76:79], v[124:127], v[32:47]
	ds_read_b64_tr_b16 v[124:125], v172 offset:0x3600
	ds_read_b64_tr_b16 v[126:127], v172 offset:0x3e00
	s_waitcnt lgkmcnt(6)
	v_mfma_f32_32x32x16_bf16 v[48:63], v[64:67], v[112:115], v[48:63]
	s_add_i32 s20, s36, 64
	s_cmp_le_i32 s20, s59
	v_add_u32_e32 v182, s36, v171
	s_waitcnt lgkmcnt(4)
	v_mfma_f32_32x32x16_bf16 v[48:63], v[68:71], v[116:119], v[48:63]
	s_waitcnt lgkmcnt(2)
	v_mfma_f32_32x32x16_bf16 v[48:63], v[72:75], v[120:123], v[48:63]
	s_waitcnt lgkmcnt(0)
	v_mfma_f32_32x32x16_bf16 v[48:63], v[76:79], v[124:127], v[48:63]
	s_cbranch_scc1 .LBB0_325
	v_add_u32_e32 v64, 64, v182
	s_nop 0
	v_cmp_gt_i32_e32 vcc, s94, v64
	v_add_u32_e32 v64, 32, v64
	s_nop 0
	v_cndmask_b32_e32 v80, v233, v80, vcc
	v_cmp_gt_i32_e32 vcc, s94, v64
	v_add_u32_e32 v64, 0x41, v182
	s_nop 0
	v_cndmask_b32_e32 v96, v233, v96, vcc
	v_cmp_gt_i32_e32 vcc, s94, v64
	v_add_u32_e32 v64, 32, v64
	s_nop 0
	v_cndmask_b32_e32 v81, v233, v81, vcc
	v_cmp_gt_i32_e32 vcc, s94, v64
	v_add_u32_e32 v64, 0x42, v182
	s_nop 0
	v_cndmask_b32_e32 v97, v233, v97, vcc
	v_cmp_gt_i32_e32 vcc, s94, v64
	v_add_u32_e32 v64, 32, v64
	s_nop 0
	v_cndmask_b32_e32 v82, v233, v82, vcc
	v_cmp_gt_i32_e32 vcc, s94, v64
	v_add_u32_e32 v64, 0x43, v182
	s_nop 0
	v_cndmask_b32_e32 v98, v233, v98, vcc
	v_cmp_gt_i32_e32 vcc, s94, v64
	v_add_u32_e32 v64, 32, v64
	s_nop 0
	v_cndmask_b32_e32 v83, v233, v83, vcc
	v_cmp_gt_i32_e32 vcc, s94, v64
	v_add_u32_e32 v64, 0x48, v182
	s_nop 0
	v_cndmask_b32_e32 v99, v233, v99, vcc
	v_cmp_gt_i32_e32 vcc, s94, v64
	v_add_u32_e32 v64, 32, v64
	s_nop 0
	v_cndmask_b32_e32 v84, v233, v84, vcc
	v_cmp_gt_i32_e32 vcc, s94, v64
	v_add_u32_e32 v64, 0x49, v182
	s_nop 0
	v_cndmask_b32_e32 v100, v233, v100, vcc
	v_cmp_gt_i32_e32 vcc, s94, v64
	v_add_u32_e32 v64, 32, v64
	s_nop 0
	v_cndmask_b32_e32 v85, v233, v85, vcc
	v_cmp_gt_i32_e32 vcc, s94, v64
	v_add_u32_e32 v64, 0x4a, v182
	s_nop 0
	v_cndmask_b32_e32 v101, v233, v101, vcc
	v_cmp_gt_i32_e32 vcc, s94, v64
	v_add_u32_e32 v64, 32, v64
	s_nop 0
	v_cndmask_b32_e32 v86, v233, v86, vcc
	v_cmp_gt_i32_e32 vcc, s94, v64
	v_add_u32_e32 v64, 0x4b, v182
	s_nop 0
	v_cndmask_b32_e32 v102, v233, v102, vcc
	v_cmp_gt_i32_e32 vcc, s94, v64
	v_add_u32_e32 v64, 32, v64
	s_nop 0
	v_cndmask_b32_e32 v87, v233, v87, vcc
	v_cmp_gt_i32_e32 vcc, s94, v64
	v_add_u32_e32 v64, 0x50, v182
	s_nop 0
	v_cndmask_b32_e32 v103, v233, v103, vcc
	v_cmp_gt_i32_e32 vcc, s94, v64
	v_add_u32_e32 v64, 32, v64
	s_nop 0
	v_cndmask_b32_e32 v88, v233, v88, vcc
	v_cmp_gt_i32_e32 vcc, s94, v64
	v_add_u32_e32 v64, 0x51, v182
	s_nop 0
	v_cndmask_b32_e32 v104, v233, v104, vcc
	v_cmp_gt_i32_e32 vcc, s94, v64
	v_add_u32_e32 v64, 32, v64
	s_nop 0
	v_cndmask_b32_e32 v89, v233, v89, vcc
	v_cmp_gt_i32_e32 vcc, s94, v64
	v_add_u32_e32 v64, 0x52, v182
	s_nop 0
	v_cndmask_b32_e32 v105, v233, v105, vcc
	v_cmp_gt_i32_e32 vcc, s94, v64
	v_add_u32_e32 v64, 32, v64
	s_nop 0
	v_cndmask_b32_e32 v90, v233, v90, vcc
	v_cmp_gt_i32_e32 vcc, s94, v64
	v_add_u32_e32 v64, 0x53, v182
	s_nop 0
	v_cndmask_b32_e32 v106, v233, v106, vcc
	v_cmp_gt_i32_e32 vcc, s94, v64
	v_add_u32_e32 v64, 32, v64
	s_nop 0
	v_cndmask_b32_e32 v91, v233, v91, vcc
	v_cmp_gt_i32_e32 vcc, s94, v64
	v_add_u32_e32 v64, 0x58, v182
	s_nop 0
	v_cndmask_b32_e32 v107, v233, v107, vcc
	v_cmp_gt_i32_e32 vcc, s94, v64
	v_add_u32_e32 v64, 32, v64
	s_nop 0
	v_cndmask_b32_e32 v92, v233, v92, vcc
	v_cmp_gt_i32_e32 vcc, s94, v64
	v_add_u32_e32 v64, 0x59, v182
	s_nop 0
	v_cndmask_b32_e32 v108, v233, v108, vcc
	v_cmp_gt_i32_e32 vcc, s94, v64
	v_add_u32_e32 v64, 32, v64
	s_nop 0
	v_cndmask_b32_e32 v93, v233, v93, vcc
	v_cmp_gt_i32_e32 vcc, s94, v64
	v_add_u32_e32 v64, 0x5a, v182
	s_nop 0
	v_cndmask_b32_e32 v109, v233, v109, vcc
	v_cmp_gt_i32_e32 vcc, s94, v64
	v_add_u32_e32 v64, 32, v64
	s_nop 0
	v_cndmask_b32_e32 v94, v233, v94, vcc
	v_cmp_gt_i32_e32 vcc, s94, v64
	v_add_u32_e32 v64, 0x5b, v182
	s_nop 0
	v_cndmask_b32_e32 v110, v233, v110, vcc
	v_cmp_gt_i32_e32 vcc, s94, v64
	v_add_u32_e32 v64, 32, v64
	s_nop 0
	v_cndmask_b32_e32 v95, v233, v95, vcc
	v_cmp_gt_i32_e32 vcc, s94, v64
	s_nop 1
	v_cndmask_b32_e32 v111, v233, v111, vcc

; #define WAIT_L0() asm volatile("s_waitcnt lgkmcnt(0)" ::: "memory")
; #define SBAR() __builtin_amdgcn_sched_barrier(0)
; __device__ __forceinline__ int crow(int r, int hi) { return (r & 3) + 8 * (r >> 2) + 4 * hi; }
; template <bool GM>
; __device__ __forceinline__ void partialSM(f32x16& p0, f32x16& p1, bool mask, int kbase, int L, int qpos, int hi) {
;   if (mask) {
; #pragma unroll
;     for (int r = 0; r < 16; ++r) {
;       int k = kbase + crow(r, hi);
;       asm volatile("" : "+v"(k) : "v"(p0[r]));
;       bool ok = k < L;
;       if (GM) ok = ok && (k < 16 || abs(qpos - k) <= 128);
;       p0[r] = ok ? p0[r] : -1e30f;
;       int k2 = k + 32;
;       asm volatile("" : "+v"(k2) : "v"(p1[r]));
;       bool ok2 = k2 < L;
;       if (GM) ok2 = ok2 && (k2 < 16 || abs(qpos - k2) <= 128);
;       p1[r] = ok2 ? p1[r] : -1e30f;
;     }
;   }
; template <int NCB, int D0> __device__ __forceinline__ void pv_one(f32x16& od, int vb, bf16x8 pa0, bf16x8 pa1, bf16x8 pa2, bf16x8 pa3) {
;   constexpr int KSTEP = NCB * 1024, HALF = NCB * 512, B0 = D0 * 512;
;   const s16x4 l0 = tr_read<B0>(vb), h0 = tr_read<B0 + HALF>(vb), l1 = tr_read<B0 + KSTEP>(vb), h1 = tr_read<B0 + KSTEP + HALF>(vb);
;   const s16x4 l2 = tr_read<B0 + 2 * KSTEP>(vb), h2 = tr_read<B0 + 2 * KSTEP + HALF>(vb), l3 = tr_read<B0 + 3 * KSTEP>(vb), h3 = tr_read<B0 + 3 * KSTEP + HALF>(vb);
;   WAIT_L0(); SBAR();
;     ...
;   od = __builtin_amdgcn_mfma_f32_32x32x16_bf16(pa0, PK(l0, h0), od, 0, 0, 0);
;   od = __builtin_amdgcn_mfma_f32_32x32x16_bf16(pa1, PK(l1, h1), od, 0, 0, 0);
;   od = __builtin_amdgcn_mfma_f32_32x32x16_bf16(pa2, PK(l2, h2), od, 0, 0, 0);
;   od = __builtin_amdgcn_mfma_f32_32x32x16_bf16(pa3, PK(l3, h3), od, 0, 0, 0);
;     ...
; }
.LBB0_327:
	s_addk_i32 s36, 0x80
	ds_read_b64_tr_b16 v[114:115], v128 offset:0
	ds_read_b64_tr_b16 v[116:117], v128 offset:0x800
	ds_read_b64_tr_b16 v[118:119], v128 offset:0x1000
	ds_read_b64_tr_b16 v[120:121], v128 offset:0x1800
	ds_read_b64_tr_b16 v[122:123], v128 offset:0x2000
	ds_read_b64_tr_b16 v[124:125], v128 offset:0x2800
	ds_read_b64_tr_b16 v[164:165], v128 offset:0x3000
	ds_read_b64_tr_b16 v[166:167], v128 offset:0x3800
	s_nop 0
	s_waitcnt lgkmcnt(6)
	v_mfma_f32_32x32x16_bf16 v[0:15], v[96:99], v[114:117], v[0:15]
	ds_read_b64_tr_b16 v[114:115], v128 offset:0x200
	ds_read_b64_tr_b16 v[116:117], v128 offset:0xa00
	s_waitcnt lgkmcnt(6)
	v_mfma_f32_32x32x16_bf16 v[0:15], v[100:103], v[118:121], v[0:15]
	ds_read_b64_tr_b16 v[118:119], v128 offset:0x1200
	ds_read_b64_tr_b16 v[120:121], v128 offset:0x1a00
	s_waitcnt lgkmcnt(6)
	v_mfma_f32_32x32x16_bf16 v[0:15], v[104:107], v[122:125], v[0:15]
	ds_read_b64_tr_b16 v[122:123], v128 offset:0x2200
	ds_read_b64_tr_b16 v[124:125], v128 offset:0x2a00
	s_waitcnt lgkmcnt(6)
	v_mfma_f32_32x32x16_bf16 v[0:15], v[108:111], v[164:167], v[0:15]
	ds_read_b64_tr_b16 v[164:165], v128 offset:0x3200
	ds_read_b64_tr_b16 v[166:167], v128 offset:0x3a00
	s_waitcnt lgkmcnt(6)
	v_mfma_f32_32x32x16_bf16 v[16:31], v[96:99], v[114:117], v[16:31]
	ds_read_b64_tr_b16 v[114:115], v128 offset:0x400
	ds_read_b64_tr_b16 v[116:117], v128 offset:0xc00
	s_waitcnt lgkmcnt(6)
	v_mfma_f32_32x32x16_bf16 v[16:31], v[100:103], v[118:121], v[16:31]
	ds_read_b64_tr_b16 v[118:119], v128 offset:0x1400
	ds_read_b64_tr_b16 v[120:121], v128 offset:0x1c00
	s_waitcnt lgkmcnt(6)
	v_mfma_f32_32x32x16_bf16 v[16:31], v[104:107], v[122:125], v[16:31]
	ds_read_b64_tr_b16 v[122:123], v128 offset:0x2400
	ds_read_b64_tr_b16 v[124:125], v128 offset:0x2c00
	s_waitcnt lgkmcnt(6)
	v_mfma_f32_32x32x16_bf16 v[16:31], v[108:111], v[164:167], v[16:31]
	ds_read_b64_tr_b16 v[164:165], v128 offset:0x3400
	ds_read_b64_tr_b16 v[166:167], v128 offset:0x3c00
	s_waitcnt lgkmcnt(6)
	v_mfma_f32_32x32x16_bf16 v[32:47], v[96:99], v[114:117], v[32:47]
	ds_read_b64_tr_b16 v[114:115], v128 offset:0x600
	ds_read_b64_tr_b16 v[116:117], v128 offset:0xe00
	s_waitcnt lgkmcnt(6)
	v_mfma_f32_32x32x16_bf16 v[32:47], v[100:103], v[118:121], v[32:47]
	ds_read_b64_tr_b16 v[118:119], v128 offset:0x1600
	ds_read_b64_tr_b16 v[120:121], v128 offset:0x1e00
	s_waitcnt lgkmcnt(6)
	v_mfma_f32_32x32x16_bf16 v[32:47], v[104:107], v[122:125], v[32:47]
	ds_read_b64_tr_b16 v[122:123], v128 offset:0x2600
	ds_read_b64_tr_b16 v[124:125], v128 offset:0x2e00
	s_waitcnt lgkmcnt(6)
	v_mfma_f32_32x32x16_bf16 v[32:47], v[108:111], v[164:167], v[32:47]
	ds_read_b64_tr_b16 v[164:165], v128 offset:0x3600
	ds_read_b64_tr_b16 v[166:167], v128 offset:0x3e00
	s_waitcnt lgkmcnt(6)
	v_mfma_f32_32x32x16_bf16 v[48:63], v[96:99], v[114:117], v[48:63]
	s_cmp_le_i32 s36, s59
	s_waitcnt lgkmcnt(4)
	v_mfma_f32_32x32x16_bf16 v[48:63], v[100:103], v[118:121], v[48:63]
	s_waitcnt lgkmcnt(2)
	v_mfma_f32_32x32x16_bf16 v[48:63], v[104:107], v[122:125], v[48:63]
	s_waitcnt lgkmcnt(0)
	v_mfma_f32_32x32x16_bf16 v[48:63], v[108:111], v[164:167], v[48:63]
	s_cbranch_scc1 .LBB0_329
	v_add_u32_e32 v96, 0x80, v182
	s_nop 0
	v_cmp_gt_i32_e32 vcc, s94, v96
	v_add_u32_e32 v96, 32, v96
	s_nop 0
	v_cndmask_b32_e32 v80, v233, v80, vcc
	v_cmp_gt_i32_e32 vcc, s94, v96
	v_add_u32_e32 v96, 0x81, v182
	s_nop 0
	v_cndmask_b32_e32 v64, v233, v64, vcc
	v_cmp_gt_i32_e32 vcc, s94, v96
	v_add_u32_e32 v96, 32, v96
	s_nop 0
	v_cndmask_b32_e32 v81, v233, v81, vcc
	v_cmp_gt_i32_e32 vcc, s94, v96
	v_add_u32_e32 v96, 0x82, v182
	s_nop 0
	v_cndmask_b32_e32 v65, v233, v65, vcc
	v_cmp_gt_i32_e32 vcc, s94, v96
	v_add_u32_e32 v96, 32, v96
	s_nop 0
	v_cndmask_b32_e32 v82, v233, v82, vcc
	v_cmp_gt_i32_e32 vcc, s94, v96
	v_add_u32_e32 v96, 0x83, v182
	s_nop 0
	v_cndmask_b32_e32 v66, v233, v66, vcc
	v_cmp_gt_i32_e32 vcc, s94, v96
	v_add_u32_e32 v96, 32, v96
	s_nop 0
	v_cndmask_b32_e32 v83, v233, v83, vcc
	v_cmp_gt_i32_e32 vcc, s94, v96
	v_add_u32_e32 v96, 0x88, v182
	s_nop 0
	v_cndmask_b32_e32 v67, v233, v67, vcc
	v_cmp_gt_i32_e32 vcc, s94, v96
	v_add_u32_e32 v96, 32, v96
	s_nop 0
	v_cndmask_b32_e32 v84, v233, v84, vcc
	v_cmp_gt_i32_e32 vcc, s94, v96
	v_add_u32_e32 v96, 0x89, v182
	s_nop 0
	v_cndmask_b32_e32 v68, v233, v68, vcc
	v_cmp_gt_i32_e32 vcc, s94, v96
	v_add_u32_e32 v96, 32, v96
	s_nop 0
	v_cndmask_b32_e32 v85, v233, v85, vcc
	v_cmp_gt_i32_e32 vcc, s94, v96
	v_add_u32_e32 v96, 0x8a, v182
	s_nop 0
	v_cndmask_b32_e32 v69, v233, v69, vcc
	v_cmp_gt_i32_e32 vcc, s94, v96
	v_add_u32_e32 v96, 32, v96
	s_nop 0
	v_cndmask_b32_e32 v86, v233, v86, vcc
	v_cmp_gt_i32_e32 vcc, s94, v96
	v_add_u32_e32 v96, 0x8b, v182
	s_nop 0
	v_cndmask_b32_e32 v70, v233, v70, vcc
	v_cmp_gt_i32_e32 vcc, s94, v96
	v_add_u32_e32 v96, 32, v96
	s_nop 0
	v_cndmask_b32_e32 v87, v233, v87, vcc
	v_cmp_gt_i32_e32 vcc, s94, v96
	v_add_u32_e32 v96, 0x90, v182
	s_nop 0
	v_cndmask_b32_e32 v71, v233, v71, vcc
	v_cmp_gt_i32_e32 vcc, s94, v96
	v_add_u32_e32 v96, 32, v96
	s_nop 0
	v_cndmask_b32_e32 v88, v233, v88, vcc
	v_cmp_gt_i32_e32 vcc, s94, v96
	v_add_u32_e32 v96, 0x91, v182
	s_nop 0
	v_cndmask_b32_e32 v72, v233, v72, vcc
	v_cmp_gt_i32_e32 vcc, s94, v96
	v_add_u32_e32 v96, 32, v96
	s_nop 0
	v_cndmask_b32_e32 v89, v233, v89, vcc
	v_cmp_gt_i32_e32 vcc, s94, v96
	v_add_u32_e32 v96, 0x92, v182
	s_nop 0
	v_cndmask_b32_e32 v73, v233, v73, vcc
	v_cmp_gt_i32_e32 vcc, s94, v96
	v_add_u32_e32 v96, 32, v96
	s_nop 0
	v_cndmask_b32_e32 v90, v233, v90, vcc
	v_cmp_gt_i32_e32 vcc, s94, v96
	v_add_u32_e32 v96, 0x93, v182
	s_nop 0
	v_cndmask_b32_e32 v74, v233, v74, vcc
	v_cmp_gt_i32_e32 vcc, s94, v96
	v_add_u32_e32 v96, 32, v96
	s_nop 0
	v_cndmask_b32_e32 v91, v233, v91, vcc
	v_cmp_gt_i32_e32 vcc, s94, v96
	v_add_u32_e32 v96, 0x98, v182
	s_nop 0
	v_cndmask_b32_e32 v75, v233, v75, vcc
	v_cmp_gt_i32_e32 vcc, s94, v96
	v_add_u32_e32 v96, 32, v96
	s_nop 0
	v_cndmask_b32_e32 v92, v233, v92, vcc
	v_cmp_gt_i32_e32 vcc, s94, v96
	v_add_u32_e32 v96, 0x99, v182
	s_nop 0
	v_cndmask_b32_e32 v76, v233, v76, vcc
	v_cmp_gt_i32_e32 vcc, s94, v96
	v_add_u32_e32 v96, 32, v96
	s_nop 0
	v_cndmask_b32_e32 v93, v233, v93, vcc
	v_cmp_gt_i32_e32 vcc, s94, v96
	v_add_u32_e32 v96, 0x9a, v182
	s_nop 0
	v_cndmask_b32_e32 v77, v233, v77, vcc
	v_cmp_gt_i32_e32 vcc, s94, v96
	v_add_u32_e32 v96, 32, v96
	s_nop 0
	v_cndmask_b32_e32 v94, v233, v94, vcc
	v_cmp_gt_i32_e32 vcc, s94, v96
	v_add_u32_e32 v96, 0x9b, v182
	s_nop 0
	v_cndmask_b32_e32 v78, v233, v78, vcc
	v_cmp_gt_i32_e32 vcc, s94, v96
	v_add_u32_e32 v96, 32, v96
	s_nop 0
	v_cndmask_b32_e32 v95, v233, v95, vcc
	v_cmp_gt_i32_e32 vcc, s94, v96
	s_nop 1
	v_cndmask_b32_e32 v79, v233, v79, vcc

; __device__ __forceinline__ void finishSM(f32x16& p0, f32x16& p1, float& l_reg, bf16x8& pa0, bf16x8& pa1, bf16x8& pa2, bf16x8& pa3) {
; #pragma unroll
;   for (int r = 0; r < 16; ++r) p1[r] = __builtin_amdgcn_exp2f(p1[r]);
;   float ps = 0;
; #pragma unroll
;   for (int r = 0; r < 16; ++r) ps += p0[r];
; #pragma unroll
;   for (int r = 0; r < 16; ++r) ps += p1[r];
;   { auto rr = __builtin_amdgcn_permlane32_swap(__float_as_uint(ps), __float_as_uint(ps), false, false);
;     ps = __uint_as_float(rr[0]) + __uint_as_float(rr[1]); }
;   l_reg += ps;
;     ...
;   PK4(p0, 0, pa0); PK4(p0, 8, pa1); PK4(p1, 0, pa2); PK4(p1, 8, pa3);
;     ...
; }
; template <int DQK, int QL>
; __device__ __forceinline__ void qkt(f32x16& p0, f32x16& p1, const char* Ks, const bf16x8 (&qr)[DQK / 16 - QL], const char* qlds, const int (&kofs)[4], float negM) {
;   constexpr int QR = DQK / 16 - QL;
; #pragma unroll
;   for (int r = 0; r < 16; ++r) { p0[r] = negM; p1[r] = negM; }
; #pragma unroll
;   for (int d0 = 0; d0 < DQK / 16; ++d0) {
;     const char* kp = Ks + kofs[d0 & 3] + (d0 >> 2) * 128;
;     bf16x8 b0 = *reinterpret_cast<const bf16x8*>(kp);
;     bf16x8 b1 = *reinterpret_cast<const bf16x8*>(kp + 32 * DQK * 2);
;     bf16x8 qf;
;     if constexpr (QL > 0) { if (d0 < QR) qf = qr[d0 < QR ? d0 : 0]; else qf = *reinterpret_cast<const bf16x8*>(qlds + (d0 - QR) * 1024); }
;     else qf = qr[d0];
;     p0 = __builtin_amdgcn_mfma_f32_32x32x16_bf16(b0, qf, p0, 0, 0, 0);
;     p1 = __builtin_amdgcn_mfma_f32_32x32x16_bf16(b1, qf, p1, 0, 0, 0);
;   }
; }
; template <int NCB> __device__ __forceinline__ int v_st(int k, int c) {
;   const int kk = (k & ~0xC) | ((k & 4) << 1) | ((k & 8) >> 1);
;   return ((kk >> 3) * NCB + (c >> 5)) * 512 + ((kk & 7) * 32 + (c & 31)) * 2;
; }
; __device__ __forceinline__ int v_rd_base(int lane) { return ((lane & 3) << 3) | (((lane >> 2) & 3) << 6) | (((lane >> 4) & 1) << 5) | (((lane >> 5) & 1) << 8); }
; template <int OFF> __device__ __forceinline__ s16x4 tr_read(int vb) {
;   s16x4 r; asm volatile("ds_read_b64_tr_b16 %0, %1 offset:%2" : "=&v"(r) : "v"(vb), "i"(OFF) : "memory"); return r;
; }
; template <int NCB, int D0> __device__ __forceinline__ void pv_one(f32x16& od, int vb, bf16x8 pa0, bf16x8 pa1, bf16x8 pa2, bf16x8 pa3) {
;   constexpr int KSTEP = NCB * 1024, HALF = NCB * 512, B0 = D0 * 512;
.LBB0_333:
	v_exp_f32_e32 v178, v64
	v_exp_f32_e32 v179, v65
	v_exp_f32_e32 v180, v66
	v_exp_f32_e32 v181, v67
	v_exp_f32_e32 v182, v68
	v_exp_f32_e32 v183, v69
	v_exp_f32_e32 v184, v70
	v_exp_f32_e32 v185, v71
	v_exp_f32_e32 v159, v72
	v_exp_f32_e32 v160, v73
	v_exp_f32_e32 v161, v74
	v_exp_f32_e32 v162, v75
	v_exp_f32_e32 v163, v76
	v_exp_f32_e32 v168, v77
	v_exp_f32_e32 v169, v78
	v_exp_f32_e32 v177, v79
	v_add_f32_e32 v80, 0, v165
	s_mov_b64 s[22:23], -1
	s_and_b64 vcc, exec, s[20:21]
	v_add_f32_e32 v186, v167, v80
	s_cbranch_vccz .LBB0_335
	v_add_f32_e32 v64, v157, v186
	v_add_f32_e32 v64, v166, v64
	v_add_f32_e32 v64, v155, v64
	v_add_f32_e32 v64, v164, v64
	v_add_f32_e32 v64, v154, v64
	v_add_f32_e32 v64, v156, v64
	v_add_f32_e32 v64, v151, v64
	v_add_f32_e32 v64, v153, v64
	v_add_f32_e32 v64, v149, v64
	v_add_f32_e32 v64, v152, v64
	v_add_f32_e32 v64, v147, v64
	v_add_f32_e32 v64, v150, v64
	v_add_f32_e32 v64, v146, v64
	v_add_f32_e32 v64, v148, v64
	v_add_f32_e32 v64, v178, v64
	v_add_f32_e32 v64, v179, v64
	v_add_f32_e32 v64, v180, v64
	v_add_f32_e32 v64, v181, v64
	v_add_f32_e32 v64, v182, v64
	v_add_f32_e32 v64, v183, v64
	v_add_f32_e32 v64, v184, v64
	v_add_f32_e32 v64, v185, v64
	v_add_f32_e32 v64, v159, v64
	v_add_f32_e32 v64, v160, v64
	v_add_f32_e32 v64, v161, v64
	v_add_f32_e32 v64, v162, v64
	v_add_f32_e32 v64, v163, v64
	v_add_f32_e32 v64, v168, v64
	v_add_f32_e32 v64, v169, v64
	v_add_f32_e32 v64, v177, v64
	v_mov_b32_e32 v65, v64
	s_nop 1
	v_permlane32_swap_b32_e32 v64, v65
	v_add_f32_e32 v64, v64, v65
	v_add_f32_e32 v158, v170, v64
	v_cvt_pk_bf16_f32 v188, v165, v167
	v_cvt_pk_bf16_f32 v189, v157, v166
	v_cvt_pk_bf16_f32 v190, v155, v164
	v_cvt_pk_bf16_f32 v191, v154, v156
	v_cvt_pk_bf16_f32 v192, v151, v153
	v_cvt_pk_bf16_f32 v193, v149, v152
	v_cvt_pk_bf16_f32 v194, v147, v150
	v_cvt_pk_bf16_f32 v195, v146, v148
	v_cvt_pk_bf16_f32 v196, v178, v179
	v_cvt_pk_bf16_f32 v197, v180, v181
	v_cvt_pk_bf16_f32 v198, v182, v183
	v_cvt_pk_bf16_f32 v199, v184, v185
	v_cvt_pk_bf16_f32 v200, v159, v160
	v_cvt_pk_bf16_f32 v201, v161, v162
	v_cvt_pk_bf16_f32 v202, v163, v168
	v_cvt_pk_bf16_f32 v203, v169, v177
	s_nop 0
	v_permlane32_swap_b32_e32 v188, v190
	v_permlane32_swap_b32_e32 v189, v191
	v_permlane32_swap_b32_e32 v192, v194
	v_permlane32_swap_b32_e32 v193, v195
	v_permlane32_swap_b32_e32 v196, v198
	v_permlane32_swap_b32_e32 v197, v199
	v_permlane32_swap_b32_e32 v200, v202
	v_permlane32_swap_b32_e32 v201, v203
	ds_read_b64_tr_b16 v[80:81], v172 offset:0
	ds_read_b64_tr_b16 v[82:83], v172 offset:0x800
	ds_read_b64_tr_b16 v[84:85], v172 offset:0x1000
	ds_read_b64_tr_b16 v[86:87], v172 offset:0x1800
	ds_read_b64_tr_b16 v[88:89], v172 offset:0x2000
	ds_read_b64_tr_b16 v[90:91], v172 offset:0x2800
	ds_read_b64_tr_b16 v[92:93], v172 offset:0x3000
	ds_read_b64_tr_b16 v[94:95], v172 offset:0x3800
	s_nop 0
	s_waitcnt lgkmcnt(6)
	v_mfma_f32_32x32x16_bf16 v[64:79], v[188:191], v[80:83], v[0:15]
	ds_read_b64_tr_b16 v[96:97], v172 offset:0x200
	ds_read_b64_tr_b16 v[98:99], v172 offset:0xa00
	ds_read_b64_tr_b16 v[100:101], v172 offset:0x1200
	ds_read_b64_tr_b16 v[102:103], v172 offset:0x1a00
	ds_read_b64_tr_b16 v[104:105], v172 offset:0x2200
	ds_read_b64_tr_b16 v[106:107], v172 offset:0x2a00
	ds_read_b64_tr_b16 v[108:109], v172 offset:0x3200
	s_waitcnt lgkmcnt(11)
	v_mfma_f32_32x32x16_bf16 v[64:79], v[192:195], v[84:87], v[64:79]
	ds_read_b64_tr_b16 v[110:111], v172 offset:0x3a00
	s_waitcnt lgkmcnt(10)
	v_mfma_f32_32x32x16_bf16 v[64:79], v[196:199], v[88:91], v[64:79]
	s_waitcnt lgkmcnt(8)
	v_mfma_f32_32x32x16_bf16 v[64:79], v[200:203], v[92:95], v[64:79]
	s_waitcnt lgkmcnt(6)
	v_mfma_f32_32x32x16_bf16 v[80:95], v[188:191], v[96:99], v[16:31]
	ds_read_b64_tr_b16 v[112:113], v172 offset:0x400
	ds_read_b64_tr_b16 v[114:115], v172 offset:0xc00
	ds_read_b64_tr_b16 v[116:117], v172 offset:0x1400
	ds_read_b64_tr_b16 v[118:119], v172 offset:0x1c00
	ds_read_b64_tr_b16 v[120:121], v172 offset:0x2400
	ds_read_b64_tr_b16 v[122:123], v172 offset:0x2c00
	ds_read_b64_tr_b16 v[124:125], v172 offset:0x3400
	s_waitcnt lgkmcnt(11)
	v_mfma_f32_32x32x16_bf16 v[80:95], v[192:195], v[100:103], v[80:95]
	ds_read_b64_tr_b16 v[126:127], v172 offset:0x3c00
	s_waitcnt lgkmcnt(10)
	v_mfma_f32_32x32x16_bf16 v[80:95], v[196:199], v[104:107], v[80:95]
	s_waitcnt lgkmcnt(8)
	v_mfma_f32_32x32x16_bf16 v[80:95], v[200:203], v[108:111], v[80:95]
	s_waitcnt lgkmcnt(6)
	v_mfma_f32_32x32x16_bf16 v[96:111], v[188:191], v[112:115], v[32:47]
	ds_read_b64_tr_b16 v[204:205], v172 offset:0x600
	ds_read_b64_tr_b16 v[206:207], v172 offset:0xe00
	ds_read_b64_tr_b16 v[208:209], v172 offset:0x1600
	ds_read_b64_tr_b16 v[210:211], v172 offset:0x1e00
	ds_read_b64_tr_b16 v[212:213], v172 offset:0x2600
	ds_read_b64_tr_b16 v[214:215], v172 offset:0x2e00
	ds_read_b64_tr_b16 v[216:217], v172 offset:0x3600
	s_waitcnt lgkmcnt(11)
	v_mfma_f32_32x32x16_bf16 v[96:111], v[192:195], v[116:119], v[96:111]
	ds_read_b64_tr_b16 v[218:219], v172 offset:0x3e00
	s_waitcnt lgkmcnt(10)
	v_mfma_f32_32x32x16_bf16 v[96:111], v[196:199], v[120:123], v[96:111]
	s_waitcnt lgkmcnt(8)
	v_mfma_f32_32x32x16_bf16 v[96:111], v[200:203], v[124:127], v[96:111]
	s_waitcnt lgkmcnt(6)
	v_mfma_f32_32x32x16_bf16 v[112:127], v[188:191], v[204:207], v[48:63]
	s_mov_b64 s[22:23], 0
	s_waitcnt lgkmcnt(4)
	v_mfma_f32_32x32x16_bf16 v[112:127], v[192:195], v[208:211], v[112:127]
	s_waitcnt lgkmcnt(2)
	v_mfma_f32_32x32x16_bf16 v[112:127], v[196:199], v[212:215], v[112:127]
	s_waitcnt lgkmcnt(0)
	v_mfma_f32_32x32x16_bf16 v[112:127], v[200:203], v[216:219], v[112:127]
; __device__ __forceinline__ void finishSM(f32x16& p0, f32x16& p1, float& l_reg, bf16x8& pa0, bf16x8& pa1, bf16x8& pa2, bf16x8& pa3) {
; #pragma unroll
;   for (int r = 0; r < 16; ++r) p1[r] = __builtin_amdgcn_exp2f(p1[r]);
;   float ps = 0;
; #pragma unroll
;   for (int r = 0; r < 16; ++r) ps += p0[r];
; #pragma unroll
;   for (int r = 0; r < 16; ++r) ps += p1[r];
;   { auto rr = __builtin_amdgcn_permlane32_swap(__float_as_uint(ps), __float_as_uint(ps), false, false);
;     ps = __uint_as_float(rr[0]) + __uint_as_float(rr[1]); }
;   l_reg += ps;
;     ...
;   PK4(p0, 0, pa0); PK4(p0, 8, pa1); PK4(p1, 0, pa2); PK4(p1, 8, pa3);
;     ...
; }
; template <int DQK, int QL>
; __device__ __forceinline__ void qkt(f32x16& p0, f32x16& p1, const char* Ks, const bf16x8 (&qr)[DQK / 16 - QL], const char* qlds, const int (&kofs)[4], float negM) {
;   constexpr int QR = DQK / 16 - QL;
; #pragma unroll
;   for (int r = 0; r < 16; ++r) { p0[r] = negM; p1[r] = negM; }
; #pragma unroll
;   for (int d0 = 0; d0 < DQK / 16; ++d0) {
;     const char* kp = Ks + kofs[d0 & 3] + (d0 >> 2) * 128;
;     bf16x8 b0 = *reinterpret_cast<const bf16x8*>(kp);
;     bf16x8 b1 = *reinterpret_cast<const bf16x8*>(kp + 32 * DQK * 2);
;     bf16x8 qf;
;     if constexpr (QL > 0) { if (d0 < QR) qf = qr[d0 < QR ? d0 : 0]; else qf = *reinterpret_cast<const bf16x8*>(qlds + (d0 - QR) * 1024); }
;     else qf = qr[d0];
;     p0 = __builtin_amdgcn_mfma_f32_32x32x16_bf16(b0, qf, p0, 0, 0, 0);
;     p1 = __builtin_amdgcn_mfma_f32_32x32x16_bf16(b1, qf, p1, 0, 0, 0);
;   }
; }
; template <int NCB> __device__ __forceinline__ int v_st(int k, int c) {
;   const int kk = (k & ~0xC) | ((k & 4) << 1) | ((k & 8) >> 1);
;   return ((kk >> 3) * NCB + (c >> 5)) * 512 + ((kk & 7) * 32 + (c & 31)) * 2;
; }
; __device__ __forceinline__ int v_rd_base(int lane) { return ((lane & 3) << 3) | (((lane >> 2) & 3) << 6) | (((lane >> 4) & 1) << 5) | (((lane >> 5) & 1) << 8); }
; template <int OFF> __device__ __forceinline__ s16x4 tr_read(int vb) {
;   s16x4 r; asm volatile("ds_read_b64_tr_b16 %0, %1 offset:%2" : "=&v"(r) : "v"(vb), "i"(OFF) : "memory"); return r;
; }
; template <int NCB, int D0> __device__ __forceinline__ void pv_one(f32x16& od, int vb, bf16x8 pa0, bf16x8 pa1, bf16x8 pa2, bf16x8 pa3) {
;   constexpr int KSTEP = NCB * 1024, HALF = NCB * 512, B0 = D0 * 512;
.LBB0_335:
	s_andn2_b64 vcc, exec, s[22:23]
	s_cbranch_vccnz .LBB0_339
	ds_read_b128 v[64:67], v174 offset:40960
	s_nop 8
	ds_read_b128 v[112:115], v174 offset:45056
	v_mov_b64_e32 v[110:111], s[18:19]
	v_mov_b64_e32 v[108:109], s[16:17]
	v_mov_b64_e32 v[106:107], s[14:15]
	v_mov_b64_e32 v[104:105], s[12:13]
	v_mov_b64_e32 v[102:103], s[10:11]
	v_mov_b64_e32 v[100:101], s[8:9]
	v_mov_b64_e32 v[98:99], s[6:7]
	v_mov_b64_e32 v[96:97], s[4:5]
	s_waitcnt lgkmcnt(1)
	s_nop 0
	v_mfma_f32_32x32x16_bf16 v[80:95], v[64:67], v[142:145], v[96:111]
	s_waitcnt lgkmcnt(0)
	v_mfma_f32_32x32x16_bf16 v[64:79], v[112:115], v[142:145], v[96:111]
	s_nop 6
	ds_read_b128 v[96:99], v175 offset:40960
	ds_read_b128 v[100:103], v175 offset:45056
	s_waitcnt lgkmcnt(1)
	v_mfma_f32_32x32x16_bf16 v[80:95], v[96:99], v[138:141], v[80:95]
	s_waitcnt lgkmcnt(0)
	v_mfma_f32_32x32x16_bf16 v[64:79], v[100:103], v[138:141], v[64:79]
	ds_read_b128 v[96:99], v173 offset:40960
	ds_read_b128 v[100:103], v173 offset:45056
	s_waitcnt lgkmcnt(1)
	v_mfma_f32_32x32x16_bf16 v[80:95], v[96:99], v[134:137], v[80:95]
	s_waitcnt lgkmcnt(0)
	v_mfma_f32_32x32x16_bf16 v[64:79], v[100:103], v[134:137], v[64:79]
	ds_read_b128 v[96:99], v176 offset:40960
	ds_read_b128 v[100:103], v176 offset:45056
	s_waitcnt lgkmcnt(1)
	v_mfma_f32_32x32x16_bf16 v[80:95], v[96:99], v[130:133], v[80:95]
	v_add_f32_e32 v96, v157, v186
	v_add_f32_e32 v96, v166, v96
	v_add_f32_e32 v96, v155, v96
	v_add_f32_e32 v96, v164, v96
	v_add_f32_e32 v96, v154, v96
	v_add_f32_e32 v96, v156, v96
	v_add_f32_e32 v96, v151, v96
	v_add_f32_e32 v96, v153, v96
	v_add_f32_e32 v96, v149, v96
	v_add_f32_e32 v96, v152, v96
	v_add_f32_e32 v96, v147, v96
	v_add_f32_e32 v96, v150, v96
	v_add_f32_e32 v96, v146, v96
	v_add_f32_e32 v96, v148, v96
	v_add_f32_e32 v96, v178, v96
	v_add_f32_e32 v96, v179, v96
	v_add_f32_e32 v96, v180, v96
	v_add_f32_e32 v96, v181, v96
	v_add_f32_e32 v96, v182, v96
	v_add_f32_e32 v96, v183, v96
	v_add_f32_e32 v96, v184, v96
	v_add_f32_e32 v96, v185, v96
	v_add_f32_e32 v96, v159, v96
	v_add_f32_e32 v96, v160, v96
	s_waitcnt lgkmcnt(0)
	v_mfma_f32_32x32x16_bf16 v[64:79], v[100:103], v[130:133], v[64:79]
	v_add_f32_e32 v96, v161, v96
	v_add_f32_e32 v96, v162, v96
	v_add_f32_e32 v96, v163, v96
	v_add_f32_e32 v96, v168, v96
	v_add_f32_e32 v96, v169, v96
	v_add_f32_e32 v96, v177, v96
	v_mov_b32_e32 v97, v96
	s_nop 1
	v_permlane32_swap_b32_e32 v96, v97
	v_cvt_pk_bf16_f32 v98, v165, v167
	v_cvt_pk_bf16_f32 v99, v157, v166
	v_cvt_pk_bf16_f32 v100, v155, v164
	v_cvt_pk_bf16_f32 v101, v154, v156
	v_cvt_pk_bf16_f32 v102, v151, v153
	v_cvt_pk_bf16_f32 v103, v149, v152
	v_cvt_pk_bf16_f32 v104, v147, v150
	v_cvt_pk_bf16_f32 v105, v146, v148
	v_cvt_pk_bf16_f32 v106, v178, v179
	v_cvt_pk_bf16_f32 v107, v180, v181
	v_cvt_pk_bf16_f32 v108, v182, v183
	v_cvt_pk_bf16_f32 v109, v184, v185
	v_cvt_pk_bf16_f32 v110, v159, v160
	v_cvt_pk_bf16_f32 v111, v161, v162
	v_cvt_pk_bf16_f32 v112, v163, v168
	v_cvt_pk_bf16_f32 v113, v169, v177
	s_nop 0
	v_permlane32_swap_b32_e32 v98, v100
	v_permlane32_swap_b32_e32 v99, v101
	v_permlane32_swap_b32_e32 v102, v104
	v_permlane32_swap_b32_e32 v103, v105
	v_permlane32_swap_b32_e32 v106, v108
	v_permlane32_swap_b32_e32 v107, v109
	v_permlane32_swap_b32_e32 v110, v112
	v_permlane32_swap_b32_e32 v111, v113
	ds_read_b64_tr_b16 v[114:115], v172 offset:0
	ds_read_b64_tr_b16 v[116:117], v172 offset:0x800
	ds_read_b64_tr_b16 v[118:119], v172 offset:0x1000
	ds_read_b64_tr_b16 v[120:121], v172 offset:0x1800
	ds_read_b64_tr_b16 v[122:123], v172 offset:0x2000
	ds_read_b64_tr_b16 v[124:125], v172 offset:0x2800
	ds_read_b64_tr_b16 v[130:131], v172 offset:0x3000
	ds_read_b64_tr_b16 v[132:133], v172 offset:0x3800
	s_nop 0
	s_waitcnt lgkmcnt(6)
	v_mfma_f32_32x32x16_bf16 v[0:15], v[98:101], v[114:117], v[0:15]
	ds_read_b64_tr_b16 v[114:115], v172 offset:0x200
	ds_read_b64_tr_b16 v[116:117], v172 offset:0xa00
	s_waitcnt lgkmcnt(6)
	v_mfma_f32_32x32x16_bf16 v[0:15], v[102:105], v[118:121], v[0:15]
	ds_read_b64_tr_b16 v[118:119], v172 offset:0x1200
	ds_read_b64_tr_b16 v[120:121], v172 offset:0x1a00
	s_waitcnt lgkmcnt(6)
	v_mfma_f32_32x32x16_bf16 v[0:15], v[106:109], v[122:125], v[0:15]
	ds_read_b64_tr_b16 v[122:123], v172 offset:0x2200
	ds_read_b64_tr_b16 v[124:125], v172 offset:0x2a00
	s_waitcnt lgkmcnt(6)
	v_mfma_f32_32x32x16_bf16 v[0:15], v[110:113], v[130:133], v[0:15]
	ds_read_b64_tr_b16 v[130:131], v172 offset:0x3200
	ds_read_b64_tr_b16 v[132:133], v172 offset:0x3a00
	s_waitcnt lgkmcnt(6)
	v_mfma_f32_32x32x16_bf16 v[16:31], v[98:101], v[114:117], v[16:31]
	ds_read_b64_tr_b16 v[114:115], v172 offset:0x400
	ds_read_b64_tr_b16 v[116:117], v172 offset:0xc00
	s_waitcnt lgkmcnt(6)
	v_mfma_f32_32x32x16_bf16 v[16:31], v[102:105], v[118:121], v[16:31]
	ds_read_b64_tr_b16 v[118:119], v172 offset:0x1400
	ds_read_b64_tr_b16 v[120:121], v172 offset:0x1c00
	s_waitcnt lgkmcnt(6)
	v_mfma_f32_32x32x16_bf16 v[16:31], v[106:109], v[122:125], v[16:31]
	ds_read_b64_tr_b16 v[122:123], v172 offset:0x2400
	ds_read_b64_tr_b16 v[124:125], v172 offset:0x2c00
	s_waitcnt lgkmcnt(6)
	v_mfma_f32_32x32x16_bf16 v[16:31], v[110:113], v[130:133], v[16:31]
	ds_read_b64_tr_b16 v[130:131], v172 offset:0x3400
	ds_read_b64_tr_b16 v[132:133], v172 offset:0x3c00
	s_waitcnt lgkmcnt(6)
	v_mfma_f32_32x32x16_bf16 v[32:47], v[98:101], v[114:117], v[32:47]
	ds_read_b64_tr_b16 v[114:115], v172 offset:0x600
	ds_read_b64_tr_b16 v[116:117], v172 offset:0xe00
	s_waitcnt lgkmcnt(6)
	v_mfma_f32_32x32x16_bf16 v[32:47], v[102:105], v[118:121], v[32:47]
	ds_read_b64_tr_b16 v[118:119], v172 offset:0x1600
	ds_read_b64_tr_b16 v[120:121], v172 offset:0x1e00
	s_waitcnt lgkmcnt(6)
	v_mfma_f32_32x32x16_bf16 v[32:47], v[106:109], v[122:125], v[32:47]
	ds_read_b64_tr_b16 v[122:123], v172 offset:0x2600
	ds_read_b64_tr_b16 v[124:125], v172 offset:0x2e00
	s_waitcnt lgkmcnt(6)
	v_mfma_f32_32x32x16_bf16 v[32:47], v[110:113], v[130:133], v[32:47]
	ds_read_b64_tr_b16 v[130:131], v172 offset:0x3600
	ds_read_b64_tr_b16 v[132:133], v172 offset:0x3e00
	s_waitcnt lgkmcnt(6)
	v_mfma_f32_32x32x16_bf16 v[48:63], v[98:101], v[114:117], v[48:63]
	s_lshl_b32 s20, s26, 6
	s_cmp_le_i32 s20, s59
	s_waitcnt lgkmcnt(4)
	v_mfma_f32_32x32x16_bf16 v[48:63], v[102:105], v[118:121], v[48:63]
	s_waitcnt lgkmcnt(2)
	v_mfma_f32_32x32x16_bf16 v[48:63], v[106:109], v[122:125], v[48:63]
	s_waitcnt lgkmcnt(0)
	v_mfma_f32_32x32x16_bf16 v[48:63], v[110:113], v[130:133], v[48:63]
	s_cbranch_scc1 .LBB0_338
; __device__ __forceinline__ int crow(int r, int hi) { return (r & 3) + 8 * (r >> 2) + 4 * hi; }
; template <bool GM>
; __device__ __forceinline__ void partialSM(f32x16& p0, f32x16& p1, bool mask, int kbase, int L, int qpos, int hi) {
;   if (mask) {
; #pragma unroll
;     for (int r = 0; r < 16; ++r) {
;       int k = kbase + crow(r, hi);
;       asm volatile("" : "+v"(k) : "v"(p0[r]));
;       bool ok = k < L;
;       if (GM) ok = ok && (k < 16 || abs(qpos - k) <= 128);
;       p0[r] = ok ? p0[r] : -1e30f;
;       int k2 = k + 32;
;       asm volatile("" : "+v"(k2) : "v"(p1[r]));
;       bool ok2 = k2 < L;
;       if (GM) ok2 = ok2 && (k2 < 16 || abs(qpos - k2) <= 128);
;       p1[r] = ok2 ? p1[r] : -1e30f;
;     }
;   }
	v_or_b32_e32 v98, s20, v171
	v_mov_b32_e32 v99, v98
	s_nop 0
	v_cmp_gt_i32_e32 vcc, s94, v99
	v_add_u32_e32 v99, 32, v99
	s_nop 0
	v_cndmask_b32_e32 v80, v233, v80, vcc
	v_cmp_gt_i32_e32 vcc, s94, v99
	v_or_b32_e32 v99, 1, v98
	s_nop 0
	v_cndmask_b32_e32 v64, v233, v64, vcc
	v_cmp_gt_i32_e32 vcc, s94, v99
	v_add_u32_e32 v99, 32, v99
	s_nop 0
	v_cndmask_b32_e32 v81, v233, v81, vcc
	v_cmp_gt_i32_e32 vcc, s94, v99
	v_or_b32_e32 v99, 2, v98
	s_nop 0
	v_cndmask_b32_e32 v65, v233, v65, vcc
	v_cmp_gt_i32_e32 vcc, s94, v99
	v_add_u32_e32 v99, 32, v99
	s_nop 0
	v_cndmask_b32_e32 v82, v233, v82, vcc
	v_cmp_gt_i32_e32 vcc, s94, v99
	v_or_b32_e32 v99, 3, v98
	s_nop 0
	v_cndmask_b32_e32 v66, v233, v66, vcc
	v_cmp_gt_i32_e32 vcc, s94, v99
	v_add_u32_e32 v99, 32, v99
	s_nop 0
	v_cndmask_b32_e32 v83, v233, v83, vcc
	v_cmp_gt_i32_e32 vcc, s94, v99
	v_or_b32_e32 v99, 8, v98
	s_nop 0
	v_cndmask_b32_e32 v67, v233, v67, vcc
	v_cmp_gt_i32_e32 vcc, s94, v99
	v_add_u32_e32 v99, 32, v99
	s_nop 0
	v_cndmask_b32_e32 v84, v233, v84, vcc
	v_cmp_gt_i32_e32 vcc, s94, v99
	v_or_b32_e32 v99, 9, v98
	s_nop 0
	v_cndmask_b32_e32 v68, v233, v68, vcc
	v_cmp_gt_i32_e32 vcc, s94, v99
	v_add_u32_e32 v99, 32, v99
	s_nop 0
	v_cndmask_b32_e32 v85, v233, v85, vcc
	v_cmp_gt_i32_e32 vcc, s94, v99
	v_or_b32_e32 v99, 10, v98
	s_nop 0
	v_cndmask_b32_e32 v69, v233, v69, vcc
	v_cmp_gt_i32_e32 vcc, s94, v99
	v_add_u32_e32 v99, 32, v99
	s_nop 0
	v_cndmask_b32_e32 v86, v233, v86, vcc
	v_cmp_gt_i32_e32 vcc, s94, v99
	v_or_b32_e32 v99, 11, v98
	s_nop 0
	v_cndmask_b32_e32 v70, v233, v70, vcc
	v_cmp_gt_i32_e32 vcc, s94, v99
	v_add_u32_e32 v99, 32, v99
	s_nop 0
	v_cndmask_b32_e32 v87, v233, v87, vcc
	v_cmp_gt_i32_e32 vcc, s94, v99
	v_or_b32_e32 v99, 16, v98
	s_nop 0
	v_cndmask_b32_e32 v71, v233, v71, vcc
	v_cmp_gt_i32_e32 vcc, s94, v99
	v_add_u32_e32 v99, 32, v99
	s_nop 0
	v_cndmask_b32_e32 v88, v233, v88, vcc
	v_cmp_gt_i32_e32 vcc, s94, v99
	v_or_b32_e32 v99, 17, v98
	s_nop 0
	v_cndmask_b32_e32 v72, v233, v72, vcc
	v_cmp_gt_i32_e32 vcc, s94, v99
	v_add_u32_e32 v99, 32, v99
	s_nop 0
	v_cndmask_b32_e32 v89, v233, v89, vcc
	v_cmp_gt_i32_e32 vcc, s94, v99
	v_or_b32_e32 v99, 18, v98
	s_nop 0
	v_cndmask_b32_e32 v73, v233, v73, vcc
	v_cmp_gt_i32_e32 vcc, s94, v99
	v_add_u32_e32 v99, 32, v99
	s_nop 0
	v_cndmask_b32_e32 v90, v233, v90, vcc
	v_cmp_gt_i32_e32 vcc, s94, v99
	v_or_b32_e32 v99, 19, v98
	s_nop 0
	v_cndmask_b32_e32 v74, v233, v74, vcc
	v_cmp_gt_i32_e32 vcc, s94, v99
	v_add_u32_e32 v99, 32, v99
	s_nop 0
	v_cndmask_b32_e32 v91, v233, v91, vcc
	v_cmp_gt_i32_e32 vcc, s94, v99
	v_or_b32_e32 v99, 24, v98
	s_nop 0
	v_cndmask_b32_e32 v75, v233, v75, vcc
	v_cmp_gt_i32_e32 vcc, s94, v99
	v_add_u32_e32 v99, 32, v99
	s_nop 0
	v_cndmask_b32_e32 v92, v233, v92, vcc
	v_cmp_gt_i32_e32 vcc, s94, v99
	v_or_b32_e32 v99, 25, v98
	s_nop 0
	v_cndmask_b32_e32 v76, v233, v76, vcc
	v_cmp_gt_i32_e32 vcc, s94, v99
	v_add_u32_e32 v99, 32, v99
	s_nop 0
	v_cndmask_b32_e32 v93, v233, v93, vcc
	v_cmp_gt_i32_e32 vcc, s94, v99
	v_or_b32_e32 v99, 26, v98
	v_or_b32_e32 v98, 27, v98
	v_cndmask_b32_e32 v77, v233, v77, vcc
	v_cmp_gt_i32_e32 vcc, s94, v99
	v_add_u32_e32 v99, 32, v99
	s_nop 0
	v_cndmask_b32_e32 v94, v233, v94, vcc
	v_cmp_gt_i32_e32 vcc, s94, v99
	s_nop 1
	v_cndmask_b32_e32 v78, v233, v78, vcc
	v_cmp_gt_i32_e32 vcc, s94, v98
	v_add_u32_e32 v98, 32, v98
	s_nop 0
	v_cndmask_b32_e32 v95, v233, v95, vcc
	v_cmp_gt_i32_e32 vcc, s94, v98
	s_nop 1
	v_cndmask_b32_e32 v79, v233, v79, vcc
; __device__ __forceinline__ void finishSM(f32x16& p0, f32x16& p1, float& l_reg, bf16x8& pa0, bf16x8& pa1, bf16x8& pa2, bf16x8& pa3) {
; #pragma unroll
;   for (int r = 0; r < 16; ++r) p1[r] = __builtin_amdgcn_exp2f(p1[r]);
;   float ps = 0;
; #pragma unroll
;   for (int r = 0; r < 16; ++r) ps += p0[r];
; #pragma unroll
;   for (int r = 0; r < 16; ++r) ps += p1[r];
;   { auto rr = __builtin_amdgcn_permlane32_swap(__float_as_uint(ps), __float_as_uint(ps), false, false);
;     ps = __uint_as_float(rr[0]) + __uint_as_float(rr[1]); }
;   l_reg += ps;
;     ...
;   PK4(p0, 0, pa0); PK4(p0, 8, pa1); PK4(p1, 0, pa2); PK4(p1, 8, pa3);
;     ...
; }
; template <int DQK, int QL>
; __device__ __forceinline__ void qkt(f32x16& p0, f32x16& p1, const char* Ks, const bf16x8 (&qr)[DQK / 16 - QL], const char* qlds, const int (&kofs)[4], float negM) {
;   constexpr int QR = DQK / 16 - QL;
; #pragma unroll
;   for (int r = 0; r < 16; ++r) { p0[r] = negM; p1[r] = negM; }
; #pragma unroll
;   for (int d0 = 0; d0 < DQK / 16; ++d0) {
;     const char* kp = Ks + kofs[d0 & 3] + (d0 >> 2) * 128;
;     bf16x8 b0 = *reinterpret_cast<const bf16x8*>(kp);
;     bf16x8 b1 = *reinterpret_cast<const bf16x8*>(kp + 32 * DQK * 2);
;     bf16x8 qf;
;     if constexpr (QL > 0) { if (d0 < QR) qf = qr[d0 < QR ? d0 : 0]; else qf = *reinterpret_cast<const bf16x8*>(qlds + (d0 - QR) * 1024); }
;     else qf = qr[d0];
;     p0 = __builtin_amdgcn_mfma_f32_32x32x16_bf16(b0, qf, p0, 0, 0, 0);
;     p1 = __builtin_amdgcn_mfma_f32_32x32x16_bf16(b1, qf, p1, 0, 0, 0);
;   }
; }
; template <int NCB> __device__ __forceinline__ int v_st(int k, int c) {
;   const int kk = (k & ~0xC) | ((k & 4) << 1) | ((k & 8) >> 1);
;   return ((kk >> 3) * NCB + (c >> 5)) * 512 + ((kk & 7) * 32 + (c & 31)) * 2;
; }
; __device__ __forceinline__ int v_rd_base(int lane) { return ((lane & 3) << 3) | (((lane >> 2) & 3) << 6) | (((lane >> 4) & 1) << 5) | (((lane >> 5) & 1) << 8); }
; template <int OFF> __device__ __forceinline__ s16x4 tr_read(int vb) {
;   s16x4 r; asm volatile("ds_read_b64_tr_b16 %0, %1 offset:%2" : "=&v"(r) : "v"(vb), "i"(OFF) : "memory"); return r;
; }
; template <int NCB, int D0> __device__ __forceinline__ void pv_one(f32x16& od, int vb, bf16x8 pa0, bf16x8 pa1, bf16x8 pa2, bf16x8 pa3) {
;   constexpr int KSTEP = NCB * 1024, HALF = NCB * 512, B0 = D0 * 512;
.LBB0_338:
	v_exp_f32_e32 v80, v80
	v_exp_f32_e32 v81, v81
	v_exp_f32_e32 v82, v82
	v_exp_f32_e32 v83, v83
	v_add_f32_e32 v96, v96, v97
	v_exp_f32_e32 v84, v84
	v_exp_f32_e32 v97, v64
	v_add_f32_e32 v64, 0, v80
	v_exp_f32_e32 v85, v85
	v_add_f32_e32 v64, v81, v64
	v_exp_f32_e32 v86, v86
	v_add_f32_e32 v64, v82, v64
	v_exp_f32_e32 v87, v87
	v_add_f32_e32 v64, v83, v64
	v_exp_f32_e32 v88, v88
	v_add_f32_e32 v64, v84, v64
	v_exp_f32_e32 v89, v89
	v_add_f32_e32 v64, v85, v64
	v_exp_f32_e32 v90, v90
	v_add_f32_e32 v64, v86, v64
	v_exp_f32_e32 v91, v91
	v_add_f32_e32 v64, v87, v64
	v_exp_f32_e32 v92, v92
	v_add_f32_e32 v64, v88, v64
	v_exp_f32_e32 v93, v93
	v_add_f32_e32 v64, v89, v64
	v_exp_f32_e32 v94, v94
	v_add_f32_e32 v64, v90, v64
	v_exp_f32_e32 v95, v95
	v_add_f32_e32 v64, v91, v64
	v_add_f32_e32 v64, v92, v64
	v_exp_f32_e32 v98, v65
	v_add_f32_e32 v64, v93, v64
	v_exp_f32_e32 v99, v66
	v_add_f32_e32 v64, v94, v64
	v_exp_f32_e32 v100, v67
	v_add_f32_e32 v64, v95, v64
	v_exp_f32_e32 v101, v68
	v_add_f32_e32 v64, v97, v64
	v_exp_f32_e32 v102, v69
	v_add_f32_e32 v64, v98, v64
	v_exp_f32_e32 v103, v70
	v_add_f32_e32 v64, v99, v64
	v_exp_f32_e32 v104, v71
	v_add_f32_e32 v64, v100, v64
	v_exp_f32_e32 v105, v72
	v_add_f32_e32 v64, v101, v64
	v_exp_f32_e32 v106, v73
	v_add_f32_e32 v64, v102, v64
	v_exp_f32_e32 v107, v74
	v_add_f32_e32 v64, v103, v64
	v_exp_f32_e32 v108, v75
	v_add_f32_e32 v64, v104, v64
	v_exp_f32_e32 v109, v76
	v_add_f32_e32 v64, v105, v64
	v_exp_f32_e32 v110, v77
	v_add_f32_e32 v64, v106, v64
	v_exp_f32_e32 v111, v78
	v_add_f32_e32 v64, v107, v64
	v_exp_f32_e32 v79, v79
	v_add_f32_e32 v64, v108, v64
	v_add_f32_e32 v64, v109, v64
	v_add_f32_e32 v64, v110, v64
	v_add_f32_e32 v64, v111, v64
	v_add_f32_e32 v64, v79, v64
	v_mov_b32_e32 v65, v64
	s_nop 1
	v_permlane32_swap_b32_e32 v64, v65
	v_add_f32_e32 v96, v170, v96
	v_add_f32_e32 v64, v64, v65
	v_add_f32_e32 v158, v96, v64
	v_cvt_pk_bf16_f32 v64, v80, v81
	v_cvt_pk_bf16_f32 v65, v82, v83
	v_cvt_pk_bf16_f32 v66, v84, v85
	v_cvt_pk_bf16_f32 v67, v86, v87
	v_cvt_pk_bf16_f32 v68, v88, v89
	v_cvt_pk_bf16_f32 v69, v90, v91
	v_cvt_pk_bf16_f32 v70, v92, v93
	v_cvt_pk_bf16_f32 v71, v94, v95
	v_cvt_pk_bf16_f32 v72, v97, v98
	v_cvt_pk_bf16_f32 v73, v99, v100
	v_cvt_pk_bf16_f32 v74, v101, v102
	v_cvt_pk_bf16_f32 v75, v103, v104
	v_cvt_pk_bf16_f32 v76, v105, v106
	v_cvt_pk_bf16_f32 v77, v107, v108
	v_cvt_pk_bf16_f32 v78, v109, v110
	v_cvt_pk_bf16_f32 v79, v111, v79
	s_nop 0
	v_permlane32_swap_b32_e32 v64, v66
	v_permlane32_swap_b32_e32 v65, v67
	v_permlane32_swap_b32_e32 v68, v70
	v_permlane32_swap_b32_e32 v69, v71
	v_permlane32_swap_b32_e32 v72, v74
	v_permlane32_swap_b32_e32 v73, v75
	v_permlane32_swap_b32_e32 v76, v78
	v_permlane32_swap_b32_e32 v77, v79
	ds_read_b64_tr_b16 v[80:81], v128 offset:0
	ds_read_b64_tr_b16 v[82:83], v128 offset:0x800
	ds_read_b64_tr_b16 v[84:85], v128 offset:0x1000
	ds_read_b64_tr_b16 v[86:87], v128 offset:0x1800
	ds_read_b64_tr_b16 v[88:89], v128 offset:0x2000
	ds_read_b64_tr_b16 v[90:91], v128 offset:0x2800
	ds_read_b64_tr_b16 v[92:93], v128 offset:0x3000
	ds_read_b64_tr_b16 v[94:95], v128 offset:0x3800
	s_nop 0
	s_waitcnt lgkmcnt(6)
	v_mfma_f32_32x32x16_bf16 v[0:15], v[64:67], v[80:83], v[0:15]
	ds_read_b64_tr_b16 v[80:81], v128 offset:0x200
	ds_read_b64_tr_b16 v[82:83], v128 offset:0xa00
	s_waitcnt lgkmcnt(6)
	v_mfma_f32_32x32x16_bf16 v[0:15], v[68:71], v[84:87], v[0:15]
	ds_read_b64_tr_b16 v[84:85], v128 offset:0x1200
	ds_read_b64_tr_b16 v[86:87], v128 offset:0x1a00
	s_waitcnt lgkmcnt(6)
	v_mfma_f32_32x32x16_bf16 v[0:15], v[72:75], v[88:91], v[0:15]
	ds_read_b64_tr_b16 v[88:89], v128 offset:0x2200
	ds_read_b64_tr_b16 v[90:91], v128 offset:0x2a00
	s_waitcnt lgkmcnt(6)
	v_mfma_f32_32x32x16_bf16 v[0:15], v[76:79], v[92:95], v[0:15]
	ds_read_b64_tr_b16 v[92:93], v128 offset:0x3200
	ds_read_b64_tr_b16 v[94:95], v128 offset:0x3a00
	s_waitcnt lgkmcnt(6)
	v_mfma_f32_32x32x16_bf16 v[16:31], v[64:67], v[80:83], v[16:31]
	ds_read_b64_tr_b16 v[80:81], v128 offset:0x400
	ds_read_b64_tr_b16 v[82:83], v128 offset:0xc00
	s_waitcnt lgkmcnt(6)
	v_mfma_f32_32x32x16_bf16 v[16:31], v[68:71], v[84:87], v[16:31]
	ds_read_b64_tr_b16 v[84:85], v128 offset:0x1400
	ds_read_b64_tr_b16 v[86:87], v128 offset:0x1c00
	s_waitcnt lgkmcnt(6)
	v_mfma_f32_32x32x16_bf16 v[16:31], v[72:75], v[88:91], v[16:31]
	ds_read_b64_tr_b16 v[88:89], v128 offset:0x2400
	ds_read_b64_tr_b16 v[90:91], v128 offset:0x2c00
	s_waitcnt lgkmcnt(6)
	v_mfma_f32_32x32x16_bf16 v[16:31], v[76:79], v[92:95], v[16:31]
	ds_read_b64_tr_b16 v[92:93], v128 offset:0x3400
	ds_read_b64_tr_b16 v[94:95], v128 offset:0x3c00
	s_waitcnt lgkmcnt(6)
	v_mfma_f32_32x32x16_bf16 v[32:47], v[64:67], v[80:83], v[32:47]
	ds_read_b64_tr_b16 v[80:81], v128 offset:0x600
	ds_read_b64_tr_b16 v[82:83], v128 offset:0xe00
	s_waitcnt lgkmcnt(6)
	v_mfma_f32_32x32x16_bf16 v[32:47], v[68:71], v[84:87], v[32:47]
	ds_read_b64_tr_b16 v[84:85], v128 offset:0x1600
	ds_read_b64_tr_b16 v[86:87], v128 offset:0x1e00
	s_waitcnt lgkmcnt(6)
	v_mfma_f32_32x32x16_bf16 v[32:47], v[72:75], v[88:91], v[32:47]
	ds_read_b64_tr_b16 v[88:89], v128 offset:0x2600
	ds_read_b64_tr_b16 v[90:91], v128 offset:0x2e00
	s_waitcnt lgkmcnt(6)
	v_mfma_f32_32x32x16_bf16 v[32:47], v[76:79], v[92:95], v[32:47]
	ds_read_b64_tr_b16 v[92:93], v128 offset:0x3600
	ds_read_b64_tr_b16 v[94:95], v128 offset:0x3e00
	s_waitcnt lgkmcnt(6)
	v_mfma_f32_32x32x16_bf16 v[48:63], v[64:67], v[80:83], v[48:63]
	s_nop 10
	v_mov_b64_e32 v[110:111], v[46:47]
	v_mov_b64_e32 v[108:109], v[44:45]
	v_mov_b64_e32 v[106:107], v[42:43]
	v_mov_b64_e32 v[104:105], v[40:41]
	v_mov_b64_e32 v[102:103], v[38:39]
	v_mov_b64_e32 v[100:101], v[36:37]
	v_mov_b64_e32 v[98:99], v[34:35]
	s_waitcnt lgkmcnt(4)
	v_mfma_f32_32x32x16_bf16 v[48:63], v[68:71], v[84:87], v[48:63]
	v_mov_b64_e32 v[96:97], v[32:33]
	s_waitcnt lgkmcnt(2)
	v_mfma_f32_32x32x16_bf16 v[48:63], v[72:75], v[88:91], v[48:63]
	s_waitcnt lgkmcnt(0)
	v_mfma_f32_32x32x16_bf16 v[48:63], v[76:79], v[92:95], v[48:63]
	v_mov_b64_e32 v[94:95], v[30:31]
	v_mov_b64_e32 v[78:79], v[14:15]
	v_mov_b64_e32 v[92:93], v[28:29]
	v_mov_b64_e32 v[90:91], v[26:27]
	v_mov_b64_e32 v[88:89], v[24:25]
	v_mov_b64_e32 v[86:87], v[22:23]
	v_mov_b64_e32 v[84:85], v[20:21]
	s_nop 4
	v_mov_b64_e32 v[126:127], v[62:63]
	v_mov_b64_e32 v[82:83], v[18:19]
	v_mov_b64_e32 v[80:81], v[16:17]
	v_mov_b64_e32 v[124:125], v[60:61]
	v_mov_b64_e32 v[122:123], v[58:59]
	v_mov_b64_e32 v[120:121], v[56:57]
	v_mov_b64_e32 v[118:119], v[54:55]
	v_mov_b64_e32 v[116:117], v[52:53]
	v_mov_b64_e32 v[114:115], v[50:51]
	v_mov_b64_e32 v[112:113], v[48:49]
	v_mov_b64_e32 v[76:77], v[12:13]
	v_mov_b64_e32 v[74:75], v[10:11]
	v_mov_b64_e32 v[72:73], v[8:9]
	v_mov_b64_e32 v[70:71], v[6:7]
	v_mov_b64_e32 v[68:69], v[4:5]
	v_mov_b64_e32 v[66:67], v[2:3]
	v_mov_b64_e32 v[64:65], v[0:1]

; __device__ __forceinline__ void finishSM(f32x16& p0, f32x16& p1, float& l_reg, bf16x8& pa0, bf16x8& pa1, bf16x8& pa2, bf16x8& pa3) {
; #pragma unroll
;   for (int r = 0; r < 16; ++r) p1[r] = __builtin_amdgcn_exp2f(p1[r]);
;   float ps = 0;
; #pragma unroll
;   for (int r = 0; r < 16; ++r) ps += p0[r];
; #pragma unroll
;   for (int r = 0; r < 16; ++r) ps += p1[r];
;   { auto rr = __builtin_amdgcn_permlane32_swap(__float_as_uint(ps), __float_as_uint(ps), false, false);
;     ps = __uint_as_float(rr[0]) + __uint_as_float(rr[1]); }
;   l_reg += ps;
;     ...
;   PK4(p0, 0, pa0); PK4(p0, 8, pa1); PK4(p1, 0, pa2); PK4(p1, 8, pa3);
;     ...
; }
; template <int DQK, int QL>
; __device__ __forceinline__ void qkt(f32x16& p0, f32x16& p1, const char* Ks, const bf16x8 (&qr)[DQK / 16 - QL], const char* qlds, const int (&kofs)[4], float negM) {
;   constexpr int QR = DQK / 16 - QL;
; #pragma unroll
;   for (int r = 0; r < 16; ++r) { p0[r] = negM; p1[r] = negM; }
; #pragma unroll
;   for (int d0 = 0; d0 < DQK / 16; ++d0) {
;     const char* kp = Ks + kofs[d0 & 3] + (d0 >> 2) * 128;
;     bf16x8 b0 = *reinterpret_cast<const bf16x8*>(kp);
;     bf16x8 b1 = *reinterpret_cast<const bf16x8*>(kp + 32 * DQK * 2);
;     bf16x8 qf;
;     if constexpr (QL > 0) { if (d0 < QR) qf = qr[d0 < QR ? d0 : 0]; else qf = *reinterpret_cast<const bf16x8*>(qlds + (d0 - QR) * 1024); }
;     else qf = qr[d0];
;     p0 = __builtin_amdgcn_mfma_f32_32x32x16_bf16(b0, qf, p0, 0, 0, 0);
;     p1 = __builtin_amdgcn_mfma_f32_32x32x16_bf16(b1, qf, p1, 0, 0, 0);
;   }
; }
; template <int NCB> __device__ __forceinline__ int v_st(int k, int c) {
;   const int kk = (k & ~0xC) | ((k & 4) << 1) | ((k & 8) >> 1);
;   return ((kk >> 3) * NCB + (c >> 5)) * 512 + ((kk & 7) * 32 + (c & 31)) * 2;
; }
; __device__ __forceinline__ int v_rd_base(int lane) { return ((lane & 3) << 3) | (((lane >> 2) & 3) << 6) | (((lane >> 4) & 1) << 5) | (((lane >> 5) & 1) << 8); }
; template <int OFF> __device__ __forceinline__ s16x4 tr_read(int vb) {
;   s16x4 r; asm volatile("ds_read_b64_tr_b16 %0, %1 offset:%2" : "=&v"(r) : "v"(vb), "i"(OFF) : "memory"); return r;
; }
; template <int NCB, int D0> __device__ __forceinline__ void pv_one(f32x16& od, int vb, bf16x8 pa0, bf16x8 pa1, bf16x8 pa2, bf16x8 pa3) {
;   constexpr int KSTEP = NCB * 1024, HALF = NCB * 512, B0 = D0 * 512;
.LBB0_342:
	ds_read_b128 v[96:99], v174 offset:40960
	ds_read_b128 v[182:185], v174 offset:45056
	v_mov_b64_e32 v[126:127], s[18:19]
	v_mov_b64_e32 v[124:125], s[16:17]
	v_mov_b64_e32 v[122:123], s[14:15]
	v_mov_b64_e32 v[120:121], s[12:13]
	v_mov_b64_e32 v[118:119], s[10:11]
	v_mov_b64_e32 v[116:117], s[8:9]
	v_mov_b64_e32 v[114:115], s[6:7]
	v_mov_b64_e32 v[112:113], s[4:5]
	v_exp_f32_e32 v100, v68
	v_exp_f32_e32 v101, v69
	s_waitcnt lgkmcnt(1)
	v_mfma_f32_32x32x16_bf16 v[80:95], v[96:99], v[142:145], v[112:127]
	ds_read_b128 v[96:99], v175 offset:40960
	ds_read_b128 v[186:189], v175 offset:45056
	v_exp_f32_e32 v102, v70
	v_exp_f32_e32 v103, v71
	v_exp_f32_e32 v104, v72
	v_exp_f32_e32 v105, v73
	v_exp_f32_e32 v106, v74
	v_exp_f32_e32 v107, v75
	s_waitcnt lgkmcnt(1)
	v_mfma_f32_32x32x16_bf16 v[80:95], v[96:99], v[138:141], v[80:95]
	ds_read_b128 v[96:99], v173 offset:40960
	ds_read_b128 v[190:193], v173 offset:45056
	v_exp_f32_e32 v108, v76
	v_exp_f32_e32 v109, v77
	v_exp_f32_e32 v110, v78
	v_exp_f32_e32 v79, v79
	s_waitcnt lgkmcnt(1)
	v_mfma_f32_32x32x16_bf16 v[80:95], v[96:99], v[134:137], v[80:95]
	ds_read_b128 v[96:99], v176 offset:40960
	ds_read_b128 v[194:197], v176 offset:45056
	s_waitcnt lgkmcnt(1)
	v_mfma_f32_32x32x16_bf16 v[80:95], v[96:99], v[130:133], v[80:95]
	v_exp_f32_e32 v96, v64
	v_add_f32_e32 v64, 0, v165
	v_add_f32_e32 v64, v167, v64
	v_add_f32_e32 v64, v157, v64
	v_add_f32_e32 v64, v166, v64
	v_add_f32_e32 v64, v155, v64
	v_add_f32_e32 v64, v164, v64
	v_add_f32_e32 v64, v154, v64
	v_add_f32_e32 v64, v156, v64
	v_add_f32_e32 v64, v151, v64
	v_add_f32_e32 v64, v153, v64
	v_add_f32_e32 v64, v149, v64
	v_add_f32_e32 v64, v152, v64
	v_add_f32_e32 v64, v147, v64
	v_exp_f32_e32 v97, v65
	v_add_f32_e32 v64, v150, v64
	v_exp_f32_e32 v98, v66
	v_add_f32_e32 v64, v146, v64
	v_exp_f32_e32 v99, v67
	v_add_f32_e32 v64, v148, v64
	v_add_f32_e32 v64, v96, v64
	v_add_f32_e32 v64, v97, v64
	v_add_f32_e32 v64, v98, v64
	v_add_f32_e32 v64, v99, v64
	v_add_f32_e32 v64, v100, v64
	v_add_f32_e32 v64, v101, v64
	v_add_f32_e32 v64, v102, v64
	v_add_f32_e32 v64, v103, v64
	v_add_f32_e32 v64, v104, v64
	v_add_f32_e32 v64, v105, v64
	v_add_f32_e32 v64, v106, v64
	v_add_f32_e32 v64, v107, v64
	v_add_f32_e32 v64, v108, v64
	v_add_f32_e32 v64, v109, v64
	v_add_f32_e32 v64, v110, v64
	v_add_f32_e32 v180, v79, v64
	v_mov_b32_e32 v181, v180
	s_nop 1
	v_permlane32_swap_b32_e32 v180, v181
	v_cvt_pk_bf16_f32 v64, v165, v167
	v_cvt_pk_bf16_f32 v65, v157, v166
	v_cvt_pk_bf16_f32 v66, v155, v164
	v_cvt_pk_bf16_f32 v67, v154, v156
	v_cvt_pk_bf16_f32 v68, v151, v153
	v_cvt_pk_bf16_f32 v69, v149, v152
	v_cvt_pk_bf16_f32 v70, v147, v150
	v_cvt_pk_bf16_f32 v71, v146, v148
	v_cvt_pk_bf16_f32 v72, v96, v97
	v_cvt_pk_bf16_f32 v73, v98, v99
	v_cvt_pk_bf16_f32 v74, v100, v101
	v_cvt_pk_bf16_f32 v75, v102, v103
	v_cvt_pk_bf16_f32 v76, v104, v105
	v_cvt_pk_bf16_f32 v77, v106, v107
	v_cvt_pk_bf16_f32 v78, v108, v109
	v_cvt_pk_bf16_f32 v79, v110, v79
	s_nop 0
	v_permlane32_swap_b32_e32 v64, v66
	v_permlane32_swap_b32_e32 v65, v67
	v_permlane32_swap_b32_e32 v68, v70
	v_permlane32_swap_b32_e32 v69, v71
	v_permlane32_swap_b32_e32 v72, v74
	v_permlane32_swap_b32_e32 v73, v75
	v_permlane32_swap_b32_e32 v76, v78
	v_permlane32_swap_b32_e32 v77, v79
	v_lshl_add_u64 v[164:165], s[0:1], 0, v[158:159]
	v_mfma_f32_32x32x16_bf16 v[96:111], v[182:185], v[142:145], v[112:127]
	v_lshl_add_u64 v[168:169], s[0:1], 0, v[160:161]
	v_lshl_add_u64 v[166:167], s[0:1], 0, v[162:163]
	s_nop 4
	v_add_co_u32_e32 v112, vcc, s90, v164
	v_mfma_f32_32x32x16_bf16 v[96:111], v[186:189], v[138:141], v[96:111]
	s_nop 0
	v_addc_co_u32_e32 v113, vcc, 0, v165, vcc
	v_add_co_u32_e32 v114, vcc, s90, v168
	s_nop 1
	v_addc_co_u32_e32 v115, vcc, 0, v169, vcc
	global_load_dwordx4 v[146:149], v[112:113], off offset:1408
	global_load_dwordx4 v[150:153], v[114:115], off offset:2304
	v_add_co_u32_e32 v112, vcc, s90, v166
	v_mfma_f32_32x32x16_bf16 v[96:111], v[190:193], v[134:137], v[96:111]
	s_nop 0
	v_addc_co_u32_e32 v113, vcc, 0, v167, vcc
	global_load_dwordx4 v[154:157], v[112:113], off offset:2304
	s_waitcnt lgkmcnt(0)
	v_mfma_f32_32x32x16_bf16 v[96:111], v[194:197], v[130:133], v[96:111]
	ds_read_b64_tr_b16 v[112:113], v172 offset:0
	ds_read_b64_tr_b16 v[114:115], v172 offset:0x800
	ds_read_b64_tr_b16 v[116:117], v172 offset:0x1000
	ds_read_b64_tr_b16 v[118:119], v172 offset:0x1800
	ds_read_b64_tr_b16 v[120:121], v172 offset:0x2000
	ds_read_b64_tr_b16 v[122:123], v172 offset:0x2800
	ds_read_b64_tr_b16 v[124:125], v172 offset:0x3000
	ds_read_b64_tr_b16 v[126:127], v172 offset:0x3800
	s_nop 0
	s_waitcnt lgkmcnt(6)
	v_mfma_f32_32x32x16_bf16 v[0:15], v[64:67], v[112:115], v[0:15]
	ds_read_b64_tr_b16 v[112:113], v172 offset:0x200
	ds_read_b64_tr_b16 v[114:115], v172 offset:0xa00
	s_waitcnt lgkmcnt(6)
	v_mfma_f32_32x32x16_bf16 v[0:15], v[68:71], v[116:119], v[0:15]
	ds_read_b64_tr_b16 v[116:117], v172 offset:0x1200
	ds_read_b64_tr_b16 v[118:119], v172 offset:0x1a00
	s_waitcnt lgkmcnt(6)
	v_mfma_f32_32x32x16_bf16 v[0:15], v[72:75], v[120:123], v[0:15]
	ds_read_b64_tr_b16 v[120:121], v172 offset:0x2200
	ds_read_b64_tr_b16 v[122:123], v172 offset:0x2a00
	s_waitcnt lgkmcnt(6)
	v_mfma_f32_32x32x16_bf16 v[0:15], v[76:79], v[124:127], v[0:15]
	ds_read_b64_tr_b16 v[124:125], v172 offset:0x3200
	ds_read_b64_tr_b16 v[126:127], v172 offset:0x3a00
	s_waitcnt lgkmcnt(6)
; #define WAIT_L0() asm volatile("s_waitcnt lgkmcnt(0)" ::: "memory")
; #define SBAR() __builtin_amdgcn_sched_barrier(0)
; __device__ __forceinline__ int crow(int r, int hi) { return (r & 3) + 8 * (r >> 2) + 4 * hi; }
; template <bool GM>
; __device__ __forceinline__ void partialSM(f32x16& p0, f32x16& p1, bool mask, int kbase, int L, int qpos, int hi) {
;   if (mask) {
; #pragma unroll
;     for (int r = 0; r < 16; ++r) {
;       int k = kbase + crow(r, hi);
;       asm volatile("" : "+v"(k) : "v"(p0[r]));
;       bool ok = k < L;
;       if (GM) ok = ok && (k < 16 || abs(qpos - k) <= 128);
;       p0[r] = ok ? p0[r] : -1e30f;
;       int k2 = k + 32;
;       asm volatile("" : "+v"(k2) : "v"(p1[r]));
;       bool ok2 = k2 < L;
;       if (GM) ok2 = ok2 && (k2 < 16 || abs(qpos - k2) <= 128);
;       p1[r] = ok2 ? p1[r] : -1e30f;
;     }
;   }
; template <int NCB, int D0> __device__ __forceinline__ void pv_one(f32x16& od, int vb, bf16x8 pa0, bf16x8 pa1, bf16x8 pa2, bf16x8 pa3) {
;   constexpr int KSTEP = NCB * 1024, HALF = NCB * 512, B0 = D0 * 512;
;   const s16x4 l0 = tr_read<B0>(vb), h0 = tr_read<B0 + HALF>(vb), l1 = tr_read<B0 + KSTEP>(vb), h1 = tr_read<B0 + KSTEP + HALF>(vb);
;   const s16x4 l2 = tr_read<B0 + 2 * KSTEP>(vb), h2 = tr_read<B0 + 2 * KSTEP + HALF>(vb), l3 = tr_read<B0 + 3 * KSTEP>(vb), h3 = tr_read<B0 + 3 * KSTEP + HALF>(vb);
;   WAIT_L0(); SBAR();
;     ...
;   od = __builtin_amdgcn_mfma_f32_32x32x16_bf16(pa0, PK(l0, h0), od, 0, 0, 0);
;   od = __builtin_amdgcn_mfma_f32_32x32x16_bf16(pa1, PK(l1, h1), od, 0, 0, 0);
;   od = __builtin_amdgcn_mfma_f32_32x32x16_bf16(pa2, PK(l2, h2), od, 0, 0, 0);
;   od = __builtin_amdgcn_mfma_f32_32x32x16_bf16(pa3, PK(l3, h3), od, 0, 0, 0);
;     ...
; }
	v_mfma_f32_32x32x16_bf16 v[16:31], v[64:67], v[112:115], v[16:31]
	ds_read_b64_tr_b16 v[112:113], v172 offset:0x400
	ds_read_b64_tr_b16 v[114:115], v172 offset:0xc00
	s_waitcnt lgkmcnt(6)
	v_mfma_f32_32x32x16_bf16 v[16:31], v[68:71], v[116:119], v[16:31]
	ds_read_b64_tr_b16 v[116:117], v172 offset:0x1400
	ds_read_b64_tr_b16 v[118:119], v172 offset:0x1c00
	s_waitcnt lgkmcnt(6)
	v_mfma_f32_32x32x16_bf16 v[16:31], v[72:75], v[120:123], v[16:31]
	ds_read_b64_tr_b16 v[120:121], v172 offset:0x2400
	ds_read_b64_tr_b16 v[122:123], v172 offset:0x2c00
	s_waitcnt lgkmcnt(6)
	v_mfma_f32_32x32x16_bf16 v[16:31], v[76:79], v[124:127], v[16:31]
	ds_read_b64_tr_b16 v[124:125], v172 offset:0x3400
	ds_read_b64_tr_b16 v[126:127], v172 offset:0x3c00
	s_waitcnt lgkmcnt(6)
	v_mfma_f32_32x32x16_bf16 v[32:47], v[64:67], v[112:115], v[32:47]
	ds_read_b64_tr_b16 v[112:113], v172 offset:0x600
	ds_read_b64_tr_b16 v[114:115], v172 offset:0xe00
	s_waitcnt lgkmcnt(6)
	v_mfma_f32_32x32x16_bf16 v[32:47], v[68:71], v[116:119], v[32:47]
	ds_read_b64_tr_b16 v[116:117], v172 offset:0x1600
	ds_read_b64_tr_b16 v[118:119], v172 offset:0x1e00
	s_waitcnt lgkmcnt(6)
	v_mfma_f32_32x32x16_bf16 v[32:47], v[72:75], v[120:123], v[32:47]
	ds_read_b64_tr_b16 v[120:121], v172 offset:0x2600
	ds_read_b64_tr_b16 v[122:123], v172 offset:0x2e00
	s_waitcnt lgkmcnt(6)
	v_mfma_f32_32x32x16_bf16 v[32:47], v[76:79], v[124:127], v[32:47]
	ds_read_b64_tr_b16 v[124:125], v172 offset:0x3600
	ds_read_b64_tr_b16 v[126:127], v172 offset:0x3e00
	s_waitcnt lgkmcnt(6)
	v_mfma_f32_32x32x16_bf16 v[48:63], v[64:67], v[112:115], v[48:63]
	s_add_i32 s20, s36, 64
	s_cmp_le_i32 s20, s59
	v_add_u32_e32 v182, s36, v171
	s_waitcnt lgkmcnt(4)
	v_mfma_f32_32x32x16_bf16 v[48:63], v[68:71], v[116:119], v[48:63]
	s_waitcnt lgkmcnt(2)
	v_mfma_f32_32x32x16_bf16 v[48:63], v[72:75], v[120:123], v[48:63]
	s_waitcnt lgkmcnt(0)
	v_mfma_f32_32x32x16_bf16 v[48:63], v[76:79], v[124:127], v[48:63]
	s_cbranch_scc1 .LBB0_344
	v_add_u32_e32 v64, 64, v182
	s_nop 0
	v_cmp_gt_i32_e32 vcc, s94, v64
	v_add_u32_e32 v64, 32, v64
	s_nop 0
	v_cndmask_b32_e32 v80, v233, v80, vcc
	v_cmp_gt_i32_e32 vcc, s94, v64
	v_add_u32_e32 v64, 0x41, v182
	s_nop 0
	v_cndmask_b32_e32 v96, v233, v96, vcc
	v_cmp_gt_i32_e32 vcc, s94, v64
	v_add_u32_e32 v64, 32, v64
	s_nop 0
	v_cndmask_b32_e32 v81, v233, v81, vcc
	v_cmp_gt_i32_e32 vcc, s94, v64
	v_add_u32_e32 v64, 0x42, v182
	s_nop 0
	v_cndmask_b32_e32 v97, v233, v97, vcc
	v_cmp_gt_i32_e32 vcc, s94, v64
	v_add_u32_e32 v64, 32, v64
	s_nop 0
	v_cndmask_b32_e32 v82, v233, v82, vcc
	v_cmp_gt_i32_e32 vcc, s94, v64
	v_add_u32_e32 v64, 0x43, v182
	s_nop 0
	v_cndmask_b32_e32 v98, v233, v98, vcc
	v_cmp_gt_i32_e32 vcc, s94, v64
	v_add_u32_e32 v64, 32, v64
	s_nop 0
	v_cndmask_b32_e32 v83, v233, v83, vcc
	v_cmp_gt_i32_e32 vcc, s94, v64
	v_add_u32_e32 v64, 0x48, v182
	s_nop 0
	v_cndmask_b32_e32 v99, v233, v99, vcc
	v_cmp_gt_i32_e32 vcc, s94, v64
	v_add_u32_e32 v64, 32, v64
	s_nop 0
	v_cndmask_b32_e32 v84, v233, v84, vcc
	v_cmp_gt_i32_e32 vcc, s94, v64
	v_add_u32_e32 v64, 0x49, v182
	s_nop 0
	v_cndmask_b32_e32 v100, v233, v100, vcc
	v_cmp_gt_i32_e32 vcc, s94, v64
	v_add_u32_e32 v64, 32, v64
	s_nop 0
	v_cndmask_b32_e32 v85, v233, v85, vcc
	v_cmp_gt_i32_e32 vcc, s94, v64
	v_add_u32_e32 v64, 0x4a, v182
	s_nop 0
	v_cndmask_b32_e32 v101, v233, v101, vcc
	v_cmp_gt_i32_e32 vcc, s94, v64
	v_add_u32_e32 v64, 32, v64
	s_nop 0
	v_cndmask_b32_e32 v86, v233, v86, vcc
	v_cmp_gt_i32_e32 vcc, s94, v64
	v_add_u32_e32 v64, 0x4b, v182
	s_nop 0
	v_cndmask_b32_e32 v102, v233, v102, vcc
	v_cmp_gt_i32_e32 vcc, s94, v64
	v_add_u32_e32 v64, 32, v64
	s_nop 0
	v_cndmask_b32_e32 v87, v233, v87, vcc
	v_cmp_gt_i32_e32 vcc, s94, v64
	v_add_u32_e32 v64, 0x50, v182
	s_nop 0
	v_cndmask_b32_e32 v103, v233, v103, vcc
	v_cmp_gt_i32_e32 vcc, s94, v64
	v_add_u32_e32 v64, 32, v64
	s_nop 0
	v_cndmask_b32_e32 v88, v233, v88, vcc
	v_cmp_gt_i32_e32 vcc, s94, v64
	v_add_u32_e32 v64, 0x51, v182
	s_nop 0
	v_cndmask_b32_e32 v104, v233, v104, vcc
	v_cmp_gt_i32_e32 vcc, s94, v64
	v_add_u32_e32 v64, 32, v64
	s_nop 0
	v_cndmask_b32_e32 v89, v233, v89, vcc
	v_cmp_gt_i32_e32 vcc, s94, v64
	v_add_u32_e32 v64, 0x52, v182
	s_nop 0
	v_cndmask_b32_e32 v105, v233, v105, vcc
	v_cmp_gt_i32_e32 vcc, s94, v64
	v_add_u32_e32 v64, 32, v64
	s_nop 0
	v_cndmask_b32_e32 v90, v233, v90, vcc
	v_cmp_gt_i32_e32 vcc, s94, v64
	v_add_u32_e32 v64, 0x53, v182
	s_nop 0
	v_cndmask_b32_e32 v106, v233, v106, vcc
	v_cmp_gt_i32_e32 vcc, s94, v64
	v_add_u32_e32 v64, 32, v64
	s_nop 0
	v_cndmask_b32_e32 v91, v233, v91, vcc
	v_cmp_gt_i32_e32 vcc, s94, v64
	v_add_u32_e32 v64, 0x58, v182
	s_nop 0
	v_cndmask_b32_e32 v107, v233, v107, vcc
	v_cmp_gt_i32_e32 vcc, s94, v64
	v_add_u32_e32 v64, 32, v64
	s_nop 0
	v_cndmask_b32_e32 v92, v233, v92, vcc
	v_cmp_gt_i32_e32 vcc, s94, v64
	v_add_u32_e32 v64, 0x59, v182
	s_nop 0
	v_cndmask_b32_e32 v108, v233, v108, vcc
	v_cmp_gt_i32_e32 vcc, s94, v64
	v_add_u32_e32 v64, 32, v64
	s_nop 0
	v_cndmask_b32_e32 v93, v233, v93, vcc
	v_cmp_gt_i32_e32 vcc, s94, v64
	v_add_u32_e32 v64, 0x5a, v182
	s_nop 0
	v_cndmask_b32_e32 v109, v233, v109, vcc
	v_cmp_gt_i32_e32 vcc, s94, v64
	v_add_u32_e32 v64, 32, v64
	s_nop 0
	v_cndmask_b32_e32 v94, v233, v94, vcc
	v_cmp_gt_i32_e32 vcc, s94, v64
	v_add_u32_e32 v64, 0x5b, v182
	s_nop 0
	v_cndmask_b32_e32 v110, v233, v110, vcc
	v_cmp_gt_i32_e32 vcc, s94, v64
	v_add_u32_e32 v64, 32, v64
	s_nop 0
	v_cndmask_b32_e32 v95, v233, v95, vcc
	v_cmp_gt_i32_e32 vcc, s94, v64
	s_nop 1
	v_cndmask_b32_e32 v111, v233, v111, vcc

; #define WAIT_L0() asm volatile("s_waitcnt lgkmcnt(0)" ::: "memory")
; #define SBAR() __builtin_amdgcn_sched_barrier(0)
; __device__ __forceinline__ void finishSM(f32x16& p0, f32x16& p1, float& l_reg, bf16x8& pa0, bf16x8& pa1, bf16x8& pa2, bf16x8& pa3) {
; #pragma unroll
;   for (int r = 0; r < 16; ++r) p1[r] = __builtin_amdgcn_exp2f(p1[r]);
;   float ps = 0;
; #pragma unroll
;   for (int r = 0; r < 16; ++r) ps += p0[r];
; #pragma unroll
;   for (int r = 0; r < 16; ++r) ps += p1[r];
;   { auto rr = __builtin_amdgcn_permlane32_swap(__float_as_uint(ps), __float_as_uint(ps), false, false);
;     ps = __uint_as_float(rr[0]) + __uint_as_float(rr[1]); }
;   l_reg += ps;
;     ...
;   PK4(p0, 0, pa0); PK4(p0, 8, pa1); PK4(p1, 0, pa2); PK4(p1, 8, pa3);
;     ...
; }
; template <int NCB, int D0> __device__ __forceinline__ void pv_one(f32x16& od, int vb, bf16x8 pa0, bf16x8 pa1, bf16x8 pa2, bf16x8 pa3) {
;   constexpr int KSTEP = NCB * 1024, HALF = NCB * 512, B0 = D0 * 512;
;   const s16x4 l0 = tr_read<B0>(vb), h0 = tr_read<B0 + HALF>(vb), l1 = tr_read<B0 + KSTEP>(vb), h1 = tr_read<B0 + KSTEP + HALF>(vb);
;   const s16x4 l2 = tr_read<B0 + 2 * KSTEP>(vb), h2 = tr_read<B0 + 2 * KSTEP + HALF>(vb), l3 = tr_read<B0 + 3 * KSTEP>(vb), h3 = tr_read<B0 + 3 * KSTEP + HALF>(vb);
;   WAIT_L0(); SBAR();
;     ...
;   od = __builtin_amdgcn_mfma_f32_32x32x16_bf16(pa0, PK(l0, h0), od, 0, 0, 0);
;   od = __builtin_amdgcn_mfma_f32_32x32x16_bf16(pa1, PK(l1, h1), od, 0, 0, 0);
;   od = __builtin_amdgcn_mfma_f32_32x32x16_bf16(pa2, PK(l2, h2), od, 0, 0, 0);
;   od = __builtin_amdgcn_mfma_f32_32x32x16_bf16(pa3, PK(l3, h3), od, 0, 0, 0);
;     ...
; }
; template <int NCB> __device__ __forceinline__ void pv_all(f32x16 (&o)[NCB], int vb, bf16x8 pa0, bf16x8 pa1, bf16x8 pa2, bf16x8 pa3) {
;   pv_one<NCB, 0>(o[0], vb, pa0, pa1, pa2, pa3); pv_one<NCB, 1>(o[1], vb, pa0, pa1, pa2, pa3);
;   if constexpr (NCB == 4) { pv_one<NCB, 2>(o[2], vb, pa0, pa1, pa2, pa3); pv_one<NCB, 3>(o[3], vb, pa0, pa1, pa2, pa3); }
; }
.LBB0_352:
	v_exp_f32_e32 v178, v64
	v_exp_f32_e32 v179, v65
	v_exp_f32_e32 v180, v66
	v_exp_f32_e32 v181, v67
	v_exp_f32_e32 v182, v68
	v_exp_f32_e32 v183, v69
	v_exp_f32_e32 v184, v70
	v_exp_f32_e32 v185, v71
	v_exp_f32_e32 v159, v72
	v_exp_f32_e32 v160, v73
	v_exp_f32_e32 v161, v74
	v_exp_f32_e32 v162, v75
	v_exp_f32_e32 v163, v76
	v_exp_f32_e32 v168, v77
	v_exp_f32_e32 v169, v78
	v_exp_f32_e32 v177, v79
	v_add_f32_e32 v80, 0, v165
	s_mov_b64 s[0:1], -1
	s_and_b64 vcc, exec, s[20:21]
	v_add_f32_e32 v186, v167, v80
	s_cbranch_vccz .LBB0_354
	v_add_f32_e32 v64, v157, v186
	v_add_f32_e32 v64, v166, v64
	v_add_f32_e32 v64, v155, v64
	v_add_f32_e32 v64, v164, v64
	v_add_f32_e32 v64, v154, v64
	v_add_f32_e32 v64, v156, v64
	v_add_f32_e32 v64, v151, v64
	v_add_f32_e32 v64, v153, v64
	v_add_f32_e32 v64, v149, v64
	v_add_f32_e32 v64, v152, v64
	v_add_f32_e32 v64, v147, v64
	v_add_f32_e32 v64, v150, v64
	v_add_f32_e32 v64, v146, v64
	v_add_f32_e32 v64, v148, v64
	v_add_f32_e32 v64, v178, v64
	v_add_f32_e32 v64, v179, v64
	v_add_f32_e32 v64, v180, v64
	v_add_f32_e32 v64, v181, v64
	v_add_f32_e32 v64, v182, v64
	v_add_f32_e32 v64, v183, v64
	v_add_f32_e32 v64, v184, v64
	v_add_f32_e32 v64, v185, v64
	v_add_f32_e32 v64, v159, v64
	v_add_f32_e32 v64, v160, v64
	v_add_f32_e32 v64, v161, v64
	v_add_f32_e32 v64, v162, v64
	v_add_f32_e32 v64, v163, v64
	v_add_f32_e32 v64, v168, v64
	v_add_f32_e32 v64, v169, v64
	v_add_f32_e32 v64, v177, v64
	v_mov_b32_e32 v65, v64
	s_nop 1
	v_permlane32_swap_b32_e32 v64, v65
	v_add_f32_e32 v64, v64, v65
	v_add_f32_e32 v158, v170, v64
	v_cvt_pk_bf16_f32 v188, v165, v167
	v_cvt_pk_bf16_f32 v189, v157, v166
	v_cvt_pk_bf16_f32 v190, v155, v164
	v_cvt_pk_bf16_f32 v191, v154, v156
	v_cvt_pk_bf16_f32 v192, v151, v153
	v_cvt_pk_bf16_f32 v193, v149, v152
	v_cvt_pk_bf16_f32 v194, v147, v150
	v_cvt_pk_bf16_f32 v195, v146, v148
	v_cvt_pk_bf16_f32 v196, v178, v179
	v_cvt_pk_bf16_f32 v197, v180, v181
	v_cvt_pk_bf16_f32 v198, v182, v183
	v_cvt_pk_bf16_f32 v199, v184, v185
	v_cvt_pk_bf16_f32 v200, v159, v160
	v_cvt_pk_bf16_f32 v201, v161, v162
	v_cvt_pk_bf16_f32 v202, v163, v168
	v_cvt_pk_bf16_f32 v203, v169, v177
	s_nop 0
	v_permlane32_swap_b32_e32 v188, v190
	v_permlane32_swap_b32_e32 v189, v191
	v_permlane32_swap_b32_e32 v192, v194
	v_permlane32_swap_b32_e32 v193, v195
	v_permlane32_swap_b32_e32 v196, v198
	v_permlane32_swap_b32_e32 v197, v199
	v_permlane32_swap_b32_e32 v200, v202
	v_permlane32_swap_b32_e32 v201, v203
	ds_read_b64_tr_b16 v[80:81], v172 offset:0
	ds_read_b64_tr_b16 v[82:83], v172 offset:0x800
	ds_read_b64_tr_b16 v[84:85], v172 offset:0x1000
	ds_read_b64_tr_b16 v[86:87], v172 offset:0x1800
	ds_read_b64_tr_b16 v[88:89], v172 offset:0x2000
	ds_read_b64_tr_b16 v[90:91], v172 offset:0x2800
	ds_read_b64_tr_b16 v[92:93], v172 offset:0x3000
	ds_read_b64_tr_b16 v[94:95], v172 offset:0x3800
	s_nop 0
	s_waitcnt lgkmcnt(6)
	v_mfma_f32_32x32x16_bf16 v[64:79], v[188:191], v[80:83], v[0:15]
	ds_read_b64_tr_b16 v[96:97], v172 offset:0x200
	ds_read_b64_tr_b16 v[98:99], v172 offset:0xa00
	ds_read_b64_tr_b16 v[100:101], v172 offset:0x1200
	ds_read_b64_tr_b16 v[102:103], v172 offset:0x1a00
	ds_read_b64_tr_b16 v[104:105], v172 offset:0x2200
	ds_read_b64_tr_b16 v[106:107], v172 offset:0x2a00
	ds_read_b64_tr_b16 v[108:109], v172 offset:0x3200
	s_waitcnt lgkmcnt(11)
	v_mfma_f32_32x32x16_bf16 v[64:79], v[192:195], v[84:87], v[64:79]
	ds_read_b64_tr_b16 v[110:111], v172 offset:0x3a00
	s_waitcnt lgkmcnt(10)
	v_mfma_f32_32x32x16_bf16 v[64:79], v[196:199], v[88:91], v[64:79]
	s_waitcnt lgkmcnt(8)
	v_mfma_f32_32x32x16_bf16 v[64:79], v[200:203], v[92:95], v[64:79]
	s_waitcnt lgkmcnt(6)
	v_mfma_f32_32x32x16_bf16 v[80:95], v[188:191], v[96:99], v[16:31]
	ds_read_b64_tr_b16 v[112:113], v172 offset:0x400
	ds_read_b64_tr_b16 v[114:115], v172 offset:0xc00
	ds_read_b64_tr_b16 v[116:117], v172 offset:0x1400
	ds_read_b64_tr_b16 v[118:119], v172 offset:0x1c00
	ds_read_b64_tr_b16 v[120:121], v172 offset:0x2400
	ds_read_b64_tr_b16 v[122:123], v172 offset:0x2c00
	ds_read_b64_tr_b16 v[124:125], v172 offset:0x3400
	s_waitcnt lgkmcnt(11)
	v_mfma_f32_32x32x16_bf16 v[80:95], v[192:195], v[100:103], v[80:95]
	ds_read_b64_tr_b16 v[126:127], v172 offset:0x3c00
	s_waitcnt lgkmcnt(10)
	v_mfma_f32_32x32x16_bf16 v[80:95], v[196:199], v[104:107], v[80:95]
	s_waitcnt lgkmcnt(8)
	v_mfma_f32_32x32x16_bf16 v[80:95], v[200:203], v[108:111], v[80:95]
	s_waitcnt lgkmcnt(6)
	v_mfma_f32_32x32x16_bf16 v[96:111], v[188:191], v[112:115], v[32:47]
	ds_read_b64_tr_b16 v[204:205], v172 offset:0x600
	ds_read_b64_tr_b16 v[206:207], v172 offset:0xe00
	ds_read_b64_tr_b16 v[208:209], v172 offset:0x1600
	ds_read_b64_tr_b16 v[210:211], v172 offset:0x1e00
	ds_read_b64_tr_b16 v[212:213], v172 offset:0x2600
	ds_read_b64_tr_b16 v[214:215], v172 offset:0x2e00
	ds_read_b64_tr_b16 v[216:217], v172 offset:0x3600
	s_waitcnt lgkmcnt(11)
	v_mfma_f32_32x32x16_bf16 v[96:111], v[192:195], v[116:119], v[96:111]
	ds_read_b64_tr_b16 v[218:219], v172 offset:0x3e00
	s_waitcnt lgkmcnt(10)
	v_mfma_f32_32x32x16_bf16 v[96:111], v[196:199], v[120:123], v[96:111]
	s_waitcnt lgkmcnt(8)
	v_mfma_f32_32x32x16_bf16 v[96:111], v[200:203], v[124:127], v[96:111]
	s_waitcnt lgkmcnt(6)
	v_mfma_f32_32x32x16_bf16 v[112:127], v[188:191], v[204:207], v[48:63]
	s_mov_b64 s[0:1], 0
	s_waitcnt lgkmcnt(4)
	v_mfma_f32_32x32x16_bf16 v[112:127], v[192:195], v[208:211], v[112:127]
	s_waitcnt lgkmcnt(2)
	v_mfma_f32_32x32x16_bf16 v[112:127], v[196:199], v[212:215], v[112:127]
	s_waitcnt lgkmcnt(0)
	v_mfma_f32_32x32x16_bf16 v[112:127], v[200:203], v[216:219], v[112:127]
; __device__ __forceinline__ void finishSM(f32x16& p0, f32x16& p1, float& l_reg, bf16x8& pa0, bf16x8& pa1, bf16x8& pa2, bf16x8& pa3) {
; #pragma unroll
;   for (int r = 0; r < 16; ++r) p1[r] = __builtin_amdgcn_exp2f(p1[r]);
;   float ps = 0;
; #pragma unroll
;   for (int r = 0; r < 16; ++r) ps += p0[r];
; #pragma unroll
;   for (int r = 0; r < 16; ++r) ps += p1[r];
;   { auto rr = __builtin_amdgcn_permlane32_swap(__float_as_uint(ps), __float_as_uint(ps), false, false);
;     ps = __uint_as_float(rr[0]) + __uint_as_float(rr[1]); }
;   l_reg += ps;
;     ...
;   PK4(p0, 0, pa0); PK4(p0, 8, pa1); PK4(p1, 0, pa2); PK4(p1, 8, pa3);
;     ...
; }
; template <int DQK, int QL>
; __device__ __forceinline__ void qkt(f32x16& p0, f32x16& p1, const char* Ks, const bf16x8 (&qr)[DQK / 16 - QL], const char* qlds, const int (&kofs)[4], float negM) {
;   constexpr int QR = DQK / 16 - QL;
; #pragma unroll
;   for (int r = 0; r < 16; ++r) { p0[r] = negM; p1[r] = negM; }
; #pragma unroll
;   for (int d0 = 0; d0 < DQK / 16; ++d0) {
;     const char* kp = Ks + kofs[d0 & 3] + (d0 >> 2) * 128;
;     bf16x8 b0 = *reinterpret_cast<const bf16x8*>(kp);
;     bf16x8 b1 = *reinterpret_cast<const bf16x8*>(kp + 32 * DQK * 2);
;     bf16x8 qf;
;     if constexpr (QL > 0) { if (d0 < QR) qf = qr[d0 < QR ? d0 : 0]; else qf = *reinterpret_cast<const bf16x8*>(qlds + (d0 - QR) * 1024); }
;     else qf = qr[d0];
;     p0 = __builtin_amdgcn_mfma_f32_32x32x16_bf16(b0, qf, p0, 0, 0, 0);
;     p1 = __builtin_amdgcn_mfma_f32_32x32x16_bf16(b1, qf, p1, 0, 0, 0);
;   }
; }
; template <int NCB> __device__ __forceinline__ int v_st(int k, int c) {
;   const int kk = (k & ~0xC) | ((k & 4) << 1) | ((k & 8) >> 1);
;   return ((kk >> 3) * NCB + (c >> 5)) * 512 + ((kk & 7) * 32 + (c & 31)) * 2;
; }
; __device__ __forceinline__ int v_rd_base(int lane) { return ((lane & 3) << 3) | (((lane >> 2) & 3) << 6) | (((lane >> 4) & 1) << 5) | (((lane >> 5) & 1) << 8); }
; template <int OFF> __device__ __forceinline__ s16x4 tr_read(int vb) {
;   s16x4 r; asm volatile("ds_read_b64_tr_b16 %0, %1 offset:%2" : "=&v"(r) : "v"(vb), "i"(OFF) : "memory"); return r;
; }
; template <int NCB, int D0> __device__ __forceinline__ void pv_one(f32x16& od, int vb, bf16x8 pa0, bf16x8 pa1, bf16x8 pa2, bf16x8 pa3) {
;   constexpr int KSTEP = NCB * 1024, HALF = NCB * 512, B0 = D0 * 512;
.LBB0_354:
	s_andn2_b64 vcc, exec, s[0:1]
	s_cbranch_vccnz .LBB0_358
	ds_read_b128 v[64:67], v174 offset:40960
	s_nop 8
	ds_read_b128 v[112:115], v174 offset:45056
	v_mov_b64_e32 v[110:111], s[18:19]
	v_mov_b64_e32 v[108:109], s[16:17]
	v_mov_b64_e32 v[106:107], s[14:15]
	v_mov_b64_e32 v[104:105], s[12:13]
	v_mov_b64_e32 v[102:103], s[10:11]
	v_mov_b64_e32 v[100:101], s[8:9]
	v_mov_b64_e32 v[98:99], s[6:7]
	v_mov_b64_e32 v[96:97], s[4:5]
	s_waitcnt lgkmcnt(1)
	s_nop 0
	v_mfma_f32_32x32x16_bf16 v[80:95], v[64:67], v[142:145], v[96:111]
	s_waitcnt lgkmcnt(0)
	v_mfma_f32_32x32x16_bf16 v[64:79], v[112:115], v[142:145], v[96:111]
	s_nop 6
	ds_read_b128 v[96:99], v175 offset:40960
	ds_read_b128 v[100:103], v175 offset:45056
	s_waitcnt lgkmcnt(1)
	v_mfma_f32_32x32x16_bf16 v[80:95], v[96:99], v[138:141], v[80:95]
	s_waitcnt lgkmcnt(0)
	v_mfma_f32_32x32x16_bf16 v[64:79], v[100:103], v[138:141], v[64:79]
	ds_read_b128 v[96:99], v173 offset:40960
	ds_read_b128 v[100:103], v173 offset:45056
	s_waitcnt lgkmcnt(1)
	v_mfma_f32_32x32x16_bf16 v[80:95], v[96:99], v[134:137], v[80:95]
	s_waitcnt lgkmcnt(0)
	v_mfma_f32_32x32x16_bf16 v[64:79], v[100:103], v[134:137], v[64:79]
	ds_read_b128 v[96:99], v176 offset:40960
	ds_read_b128 v[100:103], v176 offset:45056
	s_waitcnt lgkmcnt(1)
	v_mfma_f32_32x32x16_bf16 v[80:95], v[96:99], v[130:133], v[80:95]
	v_add_f32_e32 v96, v157, v186
	v_add_f32_e32 v96, v166, v96
	v_add_f32_e32 v96, v155, v96
	v_add_f32_e32 v96, v164, v96
	v_add_f32_e32 v96, v154, v96
	v_add_f32_e32 v96, v156, v96
	v_add_f32_e32 v96, v151, v96
	v_add_f32_e32 v96, v153, v96
	v_add_f32_e32 v96, v149, v96
	v_add_f32_e32 v96, v152, v96
	v_add_f32_e32 v96, v147, v96
	v_add_f32_e32 v96, v150, v96
	v_add_f32_e32 v96, v146, v96
	v_add_f32_e32 v96, v148, v96
	v_add_f32_e32 v96, v178, v96
	v_add_f32_e32 v96, v179, v96
	v_add_f32_e32 v96, v180, v96
	v_add_f32_e32 v96, v181, v96
	v_add_f32_e32 v96, v182, v96
	v_add_f32_e32 v96, v183, v96
	v_add_f32_e32 v96, v184, v96
	v_add_f32_e32 v96, v185, v96
	v_add_f32_e32 v96, v159, v96
	v_add_f32_e32 v96, v160, v96
	s_waitcnt lgkmcnt(0)
	v_mfma_f32_32x32x16_bf16 v[64:79], v[100:103], v[130:133], v[64:79]
	v_add_f32_e32 v96, v161, v96
	v_add_f32_e32 v96, v162, v96
	v_add_f32_e32 v96, v163, v96
	v_add_f32_e32 v96, v168, v96
	v_add_f32_e32 v96, v169, v96
	v_add_f32_e32 v96, v177, v96
	v_mov_b32_e32 v97, v96
	s_nop 1
	v_permlane32_swap_b32_e32 v96, v97
	v_cvt_pk_bf16_f32 v98, v165, v167
	v_cvt_pk_bf16_f32 v99, v157, v166
	v_cvt_pk_bf16_f32 v100, v155, v164
	v_cvt_pk_bf16_f32 v101, v154, v156
	v_cvt_pk_bf16_f32 v102, v151, v153
	v_cvt_pk_bf16_f32 v103, v149, v152
	v_cvt_pk_bf16_f32 v104, v147, v150
	v_cvt_pk_bf16_f32 v105, v146, v148
	v_cvt_pk_bf16_f32 v106, v178, v179
	v_cvt_pk_bf16_f32 v107, v180, v181
	v_cvt_pk_bf16_f32 v108, v182, v183
	v_cvt_pk_bf16_f32 v109, v184, v185
	v_cvt_pk_bf16_f32 v110, v159, v160
	v_cvt_pk_bf16_f32 v111, v161, v162
	v_cvt_pk_bf16_f32 v112, v163, v168
	v_cvt_pk_bf16_f32 v113, v169, v177
	s_nop 0
	v_permlane32_swap_b32_e32 v98, v100
	v_permlane32_swap_b32_e32 v99, v101
	v_permlane32_swap_b32_e32 v102, v104
	v_permlane32_swap_b32_e32 v103, v105
	v_permlane32_swap_b32_e32 v106, v108
	v_permlane32_swap_b32_e32 v107, v109
	v_permlane32_swap_b32_e32 v110, v112
	v_permlane32_swap_b32_e32 v111, v113
	ds_read_b64_tr_b16 v[114:115], v172 offset:0
	ds_read_b64_tr_b16 v[116:117], v172 offset:0x800
	ds_read_b64_tr_b16 v[118:119], v172 offset:0x1000
	ds_read_b64_tr_b16 v[120:121], v172 offset:0x1800
	ds_read_b64_tr_b16 v[122:123], v172 offset:0x2000
	ds_read_b64_tr_b16 v[124:125], v172 offset:0x2800
	ds_read_b64_tr_b16 v[130:131], v172 offset:0x3000
	ds_read_b64_tr_b16 v[132:133], v172 offset:0x3800
	s_nop 0
	s_waitcnt lgkmcnt(6)
	v_mfma_f32_32x32x16_bf16 v[0:15], v[98:101], v[114:117], v[0:15]
	ds_read_b64_tr_b16 v[114:115], v172 offset:0x200
	ds_read_b64_tr_b16 v[116:117], v172 offset:0xa00
	s_waitcnt lgkmcnt(6)
	v_mfma_f32_32x32x16_bf16 v[0:15], v[102:105], v[118:121], v[0:15]
	ds_read_b64_tr_b16 v[118:119], v172 offset:0x1200
	ds_read_b64_tr_b16 v[120:121], v172 offset:0x1a00
	s_waitcnt lgkmcnt(6)
	v_mfma_f32_32x32x16_bf16 v[0:15], v[106:109], v[122:125], v[0:15]
	ds_read_b64_tr_b16 v[122:123], v172 offset:0x2200
	ds_read_b64_tr_b16 v[124:125], v172 offset:0x2a00
	s_waitcnt lgkmcnt(6)
	v_mfma_f32_32x32x16_bf16 v[0:15], v[110:113], v[130:133], v[0:15]
	ds_read_b64_tr_b16 v[130:131], v172 offset:0x3200
	ds_read_b64_tr_b16 v[132:133], v172 offset:0x3a00
	s_waitcnt lgkmcnt(6)
	v_mfma_f32_32x32x16_bf16 v[16:31], v[98:101], v[114:117], v[16:31]
	ds_read_b64_tr_b16 v[114:115], v172 offset:0x400
	ds_read_b64_tr_b16 v[116:117], v172 offset:0xc00
	s_waitcnt lgkmcnt(6)
	v_mfma_f32_32x32x16_bf16 v[16:31], v[102:105], v[118:121], v[16:31]
	ds_read_b64_tr_b16 v[118:119], v172 offset:0x1400
	ds_read_b64_tr_b16 v[120:121], v172 offset:0x1c00
	s_waitcnt lgkmcnt(6)
	v_mfma_f32_32x32x16_bf16 v[16:31], v[106:109], v[122:125], v[16:31]
	ds_read_b64_tr_b16 v[122:123], v172 offset:0x2400
	ds_read_b64_tr_b16 v[124:125], v172 offset:0x2c00
	s_waitcnt lgkmcnt(6)
	v_mfma_f32_32x32x16_bf16 v[16:31], v[110:113], v[130:133], v[16:31]
	ds_read_b64_tr_b16 v[130:131], v172 offset:0x3400
	ds_read_b64_tr_b16 v[132:133], v172 offset:0x3c00
	s_waitcnt lgkmcnt(6)
	v_mfma_f32_32x32x16_bf16 v[32:47], v[98:101], v[114:117], v[32:47]
	ds_read_b64_tr_b16 v[114:115], v172 offset:0x600
	ds_read_b64_tr_b16 v[116:117], v172 offset:0xe00
	s_waitcnt lgkmcnt(6)
	v_mfma_f32_32x32x16_bf16 v[32:47], v[102:105], v[118:121], v[32:47]
	ds_read_b64_tr_b16 v[118:119], v172 offset:0x1600
	ds_read_b64_tr_b16 v[120:121], v172 offset:0x1e00
	s_waitcnt lgkmcnt(6)
	v_mfma_f32_32x32x16_bf16 v[32:47], v[106:109], v[122:125], v[32:47]
	ds_read_b64_tr_b16 v[122:123], v172 offset:0x2600
	ds_read_b64_tr_b16 v[124:125], v172 offset:0x2e00
	s_waitcnt lgkmcnt(6)
	v_mfma_f32_32x32x16_bf16 v[32:47], v[110:113], v[130:133], v[32:47]
	ds_read_b64_tr_b16 v[130:131], v172 offset:0x3600
	ds_read_b64_tr_b16 v[132:133], v172 offset:0x3e00
	s_waitcnt lgkmcnt(6)
	v_mfma_f32_32x32x16_bf16 v[48:63], v[98:101], v[114:117], v[48:63]
	s_lshl_b32 s0, s3, 6
	s_cmp_le_i32 s0, s59
	s_waitcnt lgkmcnt(4)
	v_mfma_f32_32x32x16_bf16 v[48:63], v[102:105], v[118:121], v[48:63]
	s_waitcnt lgkmcnt(2)
	v_mfma_f32_32x32x16_bf16 v[48:63], v[106:109], v[122:125], v[48:63]
	s_waitcnt lgkmcnt(0)
	v_mfma_f32_32x32x16_bf16 v[48:63], v[110:113], v[130:133], v[48:63]
	s_cbranch_scc1 .LBB0_357
; __device__ __forceinline__ int crow(int r, int hi) { return (r & 3) + 8 * (r >> 2) + 4 * hi; }
; template <bool GM>
; __device__ __forceinline__ void partialSM(f32x16& p0, f32x16& p1, bool mask, int kbase, int L, int qpos, int hi) {
;   if (mask) {
; #pragma unroll
;     for (int r = 0; r < 16; ++r) {
;       int k = kbase + crow(r, hi);
;       asm volatile("" : "+v"(k) : "v"(p0[r]));
;       bool ok = k < L;
;       if (GM) ok = ok && (k < 16 || abs(qpos - k) <= 128);
;       p0[r] = ok ? p0[r] : -1e30f;
;       int k2 = k + 32;
;       asm volatile("" : "+v"(k2) : "v"(p1[r]));
;       bool ok2 = k2 < L;
;       if (GM) ok2 = ok2 && (k2 < 16 || abs(qpos - k2) <= 128);
;       p1[r] = ok2 ? p1[r] : -1e30f;
;     }
;   }
	v_or_b32_e32 v98, s0, v171
	v_mov_b32_e32 v99, v98
	s_nop 0
	v_cmp_gt_i32_e32 vcc, s94, v99
	v_add_u32_e32 v99, 32, v99
	s_nop 0
	v_cndmask_b32_e32 v80, v233, v80, vcc
	v_cmp_gt_i32_e32 vcc, s94, v99
	v_or_b32_e32 v99, 1, v98
	s_nop 0
	v_cndmask_b32_e32 v64, v233, v64, vcc
	v_cmp_gt_i32_e32 vcc, s94, v99
	v_add_u32_e32 v99, 32, v99
	s_nop 0
	v_cndmask_b32_e32 v81, v233, v81, vcc
	v_cmp_gt_i32_e32 vcc, s94, v99
	v_or_b32_e32 v99, 2, v98
	s_nop 0
	v_cndmask_b32_e32 v65, v233, v65, vcc
	v_cmp_gt_i32_e32 vcc, s94, v99
	v_add_u32_e32 v99, 32, v99
	s_nop 0
	v_cndmask_b32_e32 v82, v233, v82, vcc
	v_cmp_gt_i32_e32 vcc, s94, v99
	v_or_b32_e32 v99, 3, v98
	s_nop 0
	v_cndmask_b32_e32 v66, v233, v66, vcc
	v_cmp_gt_i32_e32 vcc, s94, v99
	v_add_u32_e32 v99, 32, v99
	s_nop 0
	v_cndmask_b32_e32 v83, v233, v83, vcc
	v_cmp_gt_i32_e32 vcc, s94, v99
	v_or_b32_e32 v99, 8, v98
	s_nop 0
	v_cndmask_b32_e32 v67, v233, v67, vcc
	v_cmp_gt_i32_e32 vcc, s94, v99
	v_add_u32_e32 v99, 32, v99
	s_nop 0
	v_cndmask_b32_e32 v84, v233, v84, vcc
	v_cmp_gt_i32_e32 vcc, s94, v99
	v_or_b32_e32 v99, 9, v98
	s_nop 0
	v_cndmask_b32_e32 v68, v233, v68, vcc
	v_cmp_gt_i32_e32 vcc, s94, v99
	v_add_u32_e32 v99, 32, v99
	s_nop 0
	v_cndmask_b32_e32 v85, v233, v85, vcc
	v_cmp_gt_i32_e32 vcc, s94, v99
	v_or_b32_e32 v99, 10, v98
	s_nop 0
	v_cndmask_b32_e32 v69, v233, v69, vcc
	v_cmp_gt_i32_e32 vcc, s94, v99
	v_add_u32_e32 v99, 32, v99
	s_nop 0
	v_cndmask_b32_e32 v86, v233, v86, vcc
	v_cmp_gt_i32_e32 vcc, s94, v99
	v_or_b32_e32 v99, 11, v98
	s_nop 0
	v_cndmask_b32_e32 v70, v233, v70, vcc
	v_cmp_gt_i32_e32 vcc, s94, v99
	v_add_u32_e32 v99, 32, v99
	s_nop 0
	v_cndmask_b32_e32 v87, v233, v87, vcc
	v_cmp_gt_i32_e32 vcc, s94, v99
	v_or_b32_e32 v99, 16, v98
	s_nop 0
	v_cndmask_b32_e32 v71, v233, v71, vcc
	v_cmp_gt_i32_e32 vcc, s94, v99
	v_add_u32_e32 v99, 32, v99
	s_nop 0
	v_cndmask_b32_e32 v88, v233, v88, vcc
	v_cmp_gt_i32_e32 vcc, s94, v99
	v_or_b32_e32 v99, 17, v98
	s_nop 0
	v_cndmask_b32_e32 v72, v233, v72, vcc
	v_cmp_gt_i32_e32 vcc, s94, v99
	v_add_u32_e32 v99, 32, v99
	s_nop 0
	v_cndmask_b32_e32 v89, v233, v89, vcc
	v_cmp_gt_i32_e32 vcc, s94, v99
	v_or_b32_e32 v99, 18, v98
	s_nop 0
	v_cndmask_b32_e32 v73, v233, v73, vcc
	v_cmp_gt_i32_e32 vcc, s94, v99
	v_add_u32_e32 v99, 32, v99
	s_nop 0
	v_cndmask_b32_e32 v90, v233, v90, vcc
	v_cmp_gt_i32_e32 vcc, s94, v99
	v_or_b32_e32 v99, 19, v98
	s_nop 0
	v_cndmask_b32_e32 v74, v233, v74, vcc
	v_cmp_gt_i32_e32 vcc, s94, v99
	v_add_u32_e32 v99, 32, v99
	s_nop 0
	v_cndmask_b32_e32 v91, v233, v91, vcc
	v_cmp_gt_i32_e32 vcc, s94, v99
	v_or_b32_e32 v99, 24, v98
	s_nop 0
	v_cndmask_b32_e32 v75, v233, v75, vcc
	v_cmp_gt_i32_e32 vcc, s94, v99
	v_add_u32_e32 v99, 32, v99
	s_nop 0
	v_cndmask_b32_e32 v92, v233, v92, vcc
	v_cmp_gt_i32_e32 vcc, s94, v99
	v_or_b32_e32 v99, 25, v98
	s_nop 0
	v_cndmask_b32_e32 v76, v233, v76, vcc
	v_cmp_gt_i32_e32 vcc, s94, v99
	v_add_u32_e32 v99, 32, v99
	s_nop 0
	v_cndmask_b32_e32 v93, v233, v93, vcc
	v_cmp_gt_i32_e32 vcc, s94, v99
	v_or_b32_e32 v99, 26, v98
	v_or_b32_e32 v98, 27, v98
	v_cndmask_b32_e32 v77, v233, v77, vcc
	v_cmp_gt_i32_e32 vcc, s94, v99
	v_add_u32_e32 v99, 32, v99
	s_nop 0
	v_cndmask_b32_e32 v94, v233, v94, vcc
	v_cmp_gt_i32_e32 vcc, s94, v99
	s_nop 1
	v_cndmask_b32_e32 v78, v233, v78, vcc
	v_cmp_gt_i32_e32 vcc, s94, v98
	v_add_u32_e32 v98, 32, v98
	s_nop 0
	v_cndmask_b32_e32 v95, v233, v95, vcc
	v_cmp_gt_i32_e32 vcc, s94, v98
	s_nop 1
	v_cndmask_b32_e32 v79, v233, v79, vcc

; __device__ __forceinline__ void finishSM(f32x16& p0, f32x16& p1, float& l_reg, bf16x8& pa0, bf16x8& pa1, bf16x8& pa2, bf16x8& pa3) {
; #pragma unroll
;   for (int r = 0; r < 16; ++r) p1[r] = __builtin_amdgcn_exp2f(p1[r]);
;   float ps = 0;
; #pragma unroll
;   for (int r = 0; r < 16; ++r) ps += p0[r];
; #pragma unroll
;   for (int r = 0; r < 16; ++r) ps += p1[r];
;   { auto rr = __builtin_amdgcn_permlane32_swap(__float_as_uint(ps), __float_as_uint(ps), false, false);
;     ps = __uint_as_float(rr[0]) + __uint_as_float(rr[1]); }
;   l_reg += ps;
;     ...
;   PK4(p0, 0, pa0); PK4(p0, 8, pa1); PK4(p1, 0, pa2); PK4(p1, 8, pa3);
;     ...
; }
; template <int DQK, int QL>
; __device__ __forceinline__ void qkt(f32x16& p0, f32x16& p1, const char* Ks, const bf16x8 (&qr)[DQK / 16 - QL], const char* qlds, const int (&kofs)[4], float negM) {
;   constexpr int QR = DQK / 16 - QL;
; #pragma unroll
;   for (int r = 0; r < 16; ++r) { p0[r] = negM; p1[r] = negM; }
; #pragma unroll
;   for (int d0 = 0; d0 < DQK / 16; ++d0) {
;     const char* kp = Ks + kofs[d0 & 3] + (d0 >> 2) * 128;
;     bf16x8 b0 = *reinterpret_cast<const bf16x8*>(kp);
;     bf16x8 b1 = *reinterpret_cast<const bf16x8*>(kp + 32 * DQK * 2);
;     bf16x8 qf;
;     if constexpr (QL > 0) { if (d0 < QR) qf = qr[d0 < QR ? d0 : 0]; else qf = *reinterpret_cast<const bf16x8*>(qlds + (d0 - QR) * 1024); }
;     else qf = qr[d0];
;     p0 = __builtin_amdgcn_mfma_f32_32x32x16_bf16(b0, qf, p0, 0, 0, 0);
;     p1 = __builtin_amdgcn_mfma_f32_32x32x16_bf16(b1, qf, p1, 0, 0, 0);
;   }
; }
.LBB0_369:
	v_add_f32_e32 v80, 0, v176
	v_add_f32_e32 v80, v178, v80
	v_add_f32_e32 v80, v174, v80
	v_add_f32_e32 v80, v177, v80
	v_add_f32_e32 v80, v172, v80
	v_add_f32_e32 v80, v175, v80
	v_add_f32_e32 v80, v171, v80
	v_add_f32_e32 v80, v173, v80
	v_add_f32_e32 v80, v147, v80
	v_add_f32_e32 v80, v149, v80
	v_add_f32_e32 v80, v145, v80
	v_add_f32_e32 v80, v148, v80
	v_exp_f32_e32 v64, v64
	v_add_f32_e32 v80, v143, v80
	v_exp_f32_e32 v65, v65
	v_add_f32_e32 v80, v146, v80
	v_exp_f32_e32 v66, v66
	v_add_f32_e32 v80, v142, v80
	v_exp_f32_e32 v67, v67
	v_add_f32_e32 v80, v144, v80
	v_exp_f32_e32 v68, v68
	v_add_f32_e32 v80, v64, v80
	v_exp_f32_e32 v69, v69
	v_add_f32_e32 v80, v65, v80
	v_exp_f32_e32 v70, v70
	v_add_f32_e32 v80, v66, v80
	v_exp_f32_e32 v71, v71
	v_add_f32_e32 v80, v67, v80
	v_exp_f32_e32 v72, v72
	v_add_f32_e32 v80, v68, v80
	v_exp_f32_e32 v73, v73
	v_add_f32_e32 v80, v69, v80
	v_exp_f32_e32 v74, v74
	v_add_f32_e32 v80, v70, v80
	v_exp_f32_e32 v75, v75
	v_add_f32_e32 v80, v71, v80
	v_exp_f32_e32 v76, v76
	v_add_f32_e32 v80, v72, v80
	v_exp_f32_e32 v77, v77
	v_add_f32_e32 v80, v73, v80
	v_exp_f32_e32 v78, v78
	v_add_f32_e32 v80, v74, v80
	v_exp_f32_e32 v79, v79
	v_add_f32_e32 v80, v75, v80
	v_add_f32_e32 v80, v76, v80
	v_add_f32_e32 v80, v77, v80
	v_add_f32_e32 v80, v78, v80
	v_add_f32_e32 v169, v79, v80
	v_mov_b32_e32 v170, v169
	s_nop 1
	v_permlane32_swap_b32_e32 v169, v170
	v_cvt_pk_bf16_f32 v120, v176, v178
	v_cvt_pk_bf16_f32 v121, v174, v177
	v_cvt_pk_bf16_f32 v122, v172, v175
	v_cvt_pk_bf16_f32 v123, v171, v173
	v_cvt_pk_bf16_f32 v124, v147, v149
	v_cvt_pk_bf16_f32 v125, v145, v148
	v_cvt_pk_bf16_f32 v126, v143, v146
	v_cvt_pk_bf16_f32 v127, v142, v144
	v_cvt_pk_bf16_f32 v142, v64, v65
	v_cvt_pk_bf16_f32 v143, v66, v67
	v_cvt_pk_bf16_f32 v144, v68, v69
	v_cvt_pk_bf16_f32 v145, v70, v71
	v_cvt_pk_bf16_f32 v146, v72, v73
	v_cvt_pk_bf16_f32 v147, v74, v75
	v_cvt_pk_bf16_f32 v148, v76, v77
	v_cvt_pk_bf16_f32 v149, v78, v79
	s_nop 0
	v_permlane32_swap_b32_e32 v120, v122
	v_permlane32_swap_b32_e32 v121, v123
	v_permlane32_swap_b32_e32 v124, v126
	v_permlane32_swap_b32_e32 v125, v127
	v_permlane32_swap_b32_e32 v142, v144
	v_permlane32_swap_b32_e32 v143, v145
	v_permlane32_swap_b32_e32 v146, v148
	v_permlane32_swap_b32_e32 v147, v149
	ds_read_b128 v[80:83], v152 offset:57344
	ds_read_b128 v[84:87], v152 offset:57472
	v_mov_b64_e32 v[110:111], s[18:19]
	v_mov_b64_e32 v[108:109], s[16:17]
	v_mov_b64_e32 v[106:107], s[14:15]
	v_mov_b64_e32 v[104:105], s[12:13]
	v_mov_b64_e32 v[102:103], s[10:11]
	v_mov_b64_e32 v[100:101], s[8:9]
	v_mov_b64_e32 v[98:99], s[6:7]
	v_mov_b64_e32 v[96:97], s[4:5]
	v_add_u32_e32 v167, v163, v162
	s_waitcnt lgkmcnt(1)
	v_mfma_f32_32x32x16_bf16 v[64:79], v[80:83], v[138:141], v[96:111]
	ds_read_b128 v[80:83], v156 offset:57344
	ds_read_b128 v[88:91], v152 offset:57600
	s_waitcnt lgkmcnt(1)
	v_mfma_f32_32x32x16_bf16 v[64:79], v[80:83], v[134:137], v[64:79]
	ds_read_b128 v[80:83], v155 offset:57344
	ds_read_b128 v[92:95], v155 offset:57472
	s_waitcnt lgkmcnt(1)
	v_mfma_f32_32x32x16_bf16 v[64:79], v[80:83], v[130:133], v[64:79]
	ds_read_b128 v[80:83], v153 offset:57344
	ds_read_b128 v[112:115], v167
	ds_read_b128 v[116:119], v155 offset:57600
	ds_read_b128 v[172:175], v167 offset:1024
	s_waitcnt lgkmcnt(2)
	v_mfma_f32_32x32x16_bf16 v[64:79], v[80:83], v[112:115], v[64:79]
	s_waitcnt lgkmcnt(0)
	v_mfma_f32_32x32x16_bf16 v[64:79], v[84:87], v[172:175], v[64:79]
	ds_read_b128 v[80:83], v156 offset:57472
	ds_read_b128 v[176:179], v167 offset:2048
	ds_read_b128 v[84:87], v156 offset:57600
	ds_read_b128 v[180:183], v167 offset:3072
	s_waitcnt lgkmcnt(2)
	v_mfma_f32_32x32x16_bf16 v[64:79], v[80:83], v[176:179], v[64:79]
	s_waitcnt lgkmcnt(0)
	v_mfma_f32_32x32x16_bf16 v[64:79], v[92:95], v[180:183], v[64:79]
	ds_read_b128 v[80:83], v153 offset:57472
	ds_read_b128 v[184:187], v167 offset:4096
	ds_read_b128 v[188:191], v167 offset:5120
	ds_read_b128 v[92:95], v153 offset:57600
	ds_read_b128 v[192:195], v167 offset:6144
	ds_read_b128 v[196:199], v167 offset:7168
	ds_read_b128 v[200:203], v160 offset:12288
	ds_read_b128 v[204:207], v160 offset:12416
	ds_read_b128 v[208:211], v158 offset:12288
	ds_read_b128 v[212:215], v158 offset:12416
	ds_read_b128 v[216:219], v159 offset:12288
	ds_read_b128 v[220:223], v160 offset:12544
	s_waitcnt lgkmcnt(10)
	v_mfma_f32_32x32x16_bf16 v[64:79], v[80:83], v[184:187], v[64:79]
	s_waitcnt lgkmcnt(9)
	v_mfma_f32_32x32x16_bf16 v[64:79], v[88:91], v[188:191], v[64:79]
	s_waitcnt lgkmcnt(7)
	v_mfma_f32_32x32x16_bf16 v[64:79], v[84:87], v[192:195], v[64:79]
	s_waitcnt lgkmcnt(6)
	v_mfma_f32_32x32x16_bf16 v[64:79], v[116:119], v[196:199], v[64:79]
	ds_read_b128 v[116:119], v159 offset:12416
	ds_read_b128 v[238:241], v159 offset:12544
	ds_read_b128 v[242:245], v167 offset:8192
	ds_read_b128 v[246:249], v157 offset:12288
	ds_read_b128 v[250:253], v158 offset:12544
	ds_read_b128 v[228:231], v157 offset:12416
	ds_read_b128 v[224:227], v157 offset:12544
	s_waitcnt lgkmcnt(4)
	v_mfma_f32_32x32x16_bf16 v[64:79], v[92:95], v[242:245], v[64:79]
	v_mfma_f32_32x32x16_bf16 v[80:95], v[200:203], v[138:141], v[96:111]
	v_mov_b32_e32 v171, v161
	s_add_u32 s72, s55, s0
	v_lshlrev_b32_e32 v234, 3, v171
	s_addc_u32 s73, s83, s1
	s_nop 2
	v_and_b32_e32 v96, 0x78, v234
	v_lshlrev_b32_e32 v97, 5, v171
	v_mfma_f32_32x32x16_bf16 v[80:95], v[216:219], v[134:137], v[80:95]
	v_and_or_b32 v96, v97, s24, v96
	v_mul_hi_i32 v97, v171, s82
	v_lshrrev_b32_e32 v99, 31, v97
	v_ashrrev_i32_e32 v97, 2, v97
	v_add_u32_e32 v97, v97, v99
	v_mul_lo_u32 v99, v97, 24
	v_lshrrev_b32_e32 v100, 3, v97
	v_sub_u32_e32 v99, v171, v99
	v_bitop3_b32 v97, v100, v97, 1 bitop3:0x6c
	v_mfma_f32_32x32x16_bf16 v[80:95], v[208:211], v[130:133], v[80:95]
	v_bitop3_b32 v99, v97, v99, 7 bitop3:0x6c
	v_mul_lo_u32 v97, v97, s85
	v_lshl_add_u32 v100, v99, 3, v97
	v_add_u32_e32 v97, 0x200, v171
	v_mul_hi_i32 v99, v97, s82
	v_lshrrev_b32_e32 v101, 31, v99
	v_ashrrev_i32_e32 v99, 2, v99
	v_add_u32_e32 v99, v99, v101
	v_mul_lo_u32 v101, v99, 24
	v_sub_u32_e32 v97, v97, v101
	v_lshrrev_b32_e32 v101, 3, v99
	s_waitcnt lgkmcnt(3)
; #define WAIT_L0() asm volatile("s_waitcnt lgkmcnt(0)" ::: "memory")
; #define SBAR() __builtin_amdgcn_sched_barrier(0)
; __device__ __forceinline__ int v_rd_base(int lane) { return ((lane & 3) << 3) | (((lane >> 2) & 3) << 6) | (((lane >> 4) & 1) << 5) | (((lane >> 5) & 1) << 8); }
; #define V_COORDS(T) do { if constexpr (VC == 2) { const int sr = (T) >> 4, sc = ((T) & 15) * 8; vgo[0] = sr * LDV + sc; vgo[VC - 1] = (32 + sr) * LDV + sc; vlo[0] = v_st<NCB>(sr, sc); vlo[VC - 1] = v_st<NCB>(32 + sr, sc); } \
;     else { const int sr = (T) >> 3, sc = ((T) & 7) * 8; vgo[0] = sr * LDV + sc; vlo[0] = v_st<NCB>(sr, sc); } } while (0)
; template <int NCB, int D0> __device__ __forceinline__ void pv_one(f32x16& od, int vb, bf16x8 pa0, bf16x8 pa1, bf16x8 pa2, bf16x8 pa3) {
;   constexpr int KSTEP = NCB * 1024, HALF = NCB * 512, B0 = D0 * 512;
;   const s16x4 l0 = tr_read<B0>(vb), h0 = tr_read<B0 + HALF>(vb), l1 = tr_read<B0 + KSTEP>(vb), h1 = tr_read<B0 + KSTEP + HALF>(vb);
;   const s16x4 l2 = tr_read<B0 + 2 * KSTEP>(vb), h2 = tr_read<B0 + 2 * KSTEP + HALF>(vb), l3 = tr_read<B0 + 3 * KSTEP>(vb), h3 = tr_read<B0 + 3 * KSTEP + HALF>(vb);
;   WAIT_L0(); SBAR();
;     ...
;   od = __builtin_amdgcn_mfma_f32_32x32x16_bf16(pa0, PK(l0, h0), od, 0, 0, 0);
;   od = __builtin_amdgcn_mfma_f32_32x32x16_bf16(pa1, PK(l1, h1), od, 0, 0, 0);
;   od = __builtin_amdgcn_mfma_f32_32x32x16_bf16(pa2, PK(l2, h2), od, 0, 0, 0);
;   od = __builtin_amdgcn_mfma_f32_32x32x16_bf16(pa3, PK(l3, h3), od, 0, 0, 0);
;     ...
; }
;     ...
;   if constexpr (KDMA) {
;   } else {
; #pragma unroll
;     for (int i = 0; i < KC; ++i) { const int c = tid + i * 512, row = c / CPR, cc = c % CPR; kgo[i] = row * LDK + cc * 8; klo[i] = K_OFF + KSWZ(KRS, row, cc * 16); }
;     V_COORDS(tid);
;   }
;   const int vb0 = (int)(uintptr_t)shm + v_rd_base(lane);
;   int kofs[4];
; #pragma unroll
;   for (int b = 0; b < 4; ++b) kofs[b] = (r32 ^ ((r32 >> 3) & 1)) * KRS + ((b * 32 + hi * 16) ^ ((r32 & 7) << 4));
;   bf16x8 ks[KC], vs[VC];
	v_mfma_f32_32x32x16_bf16 v[80:95], v[246:249], v[112:115], v[80:95]
	v_bitop3_b32 v99, v101, v99, 1 bitop3:0x6c
	v_bitop3_b32 v97, v99, v97, 7 bitop3:0x6c
	v_mul_lo_u32 v99, v99, s85
	v_lshl_add_u32 v102, v97, 3, v99
	v_add_u32_e32 v97, 0x400, v171
	v_mul_hi_i32 v99, v97, s82
	v_lshrrev_b32_e32 v101, 31, v99
	v_ashrrev_i32_e32 v99, 2, v99
	v_add_u32_e32 v99, v99, v101
	v_mul_lo_u32 v101, v99, 24
	v_sub_u32_e32 v97, v97, v101
	v_lshrrev_b32_e32 v101, 3, v99
	v_mfma_f32_32x32x16_bf16 v[80:95], v[204:207], v[172:175], v[80:95]
	v_bitop3_b32 v99, v101, v99, 1 bitop3:0x6c
	v_ashrrev_i32_e32 v101, 31, v100
	v_lshl_add_u64 v[100:101], v[100:101], 1, s[72:73]
	v_readfirstlane_b32 s20, v164
	v_bitop3_b32 v97, v99, v97, 7 bitop3:0x6c
	v_mul_lo_u32 v99, v99, s85
	v_lshl_add_u64 v[100:101], v[100:101], 0, s[46:47]
	s_mov_b32 m0, s20
	v_ashrrev_i32_e32 v103, 31, v102
	s_add_u32 s74, s36, s0
	v_lshl_add_u32 v104, v97, 3, v99
	global_load_lds_dwordx4 v[100:101], off
	v_lshl_add_u64 v[100:101], v[102:103], 1, s[72:73]
	v_readfirstlane_b32 s20, v165
	v_ashrrev_i32_e32 v97, 31, v96
	s_addc_u32 s75, s54, s1
	v_add_u32_e32 v98, 0x4000, v96
	v_lshl_add_u64 v[100:101], v[100:101], 0, s[46:47]
	s_mov_b32 m0, s20
	v_ashrrev_i32_e32 v105, 31, v104
	v_lshl_add_u64 v[96:97], v[96:97], 1, s[74:75]
	global_load_lds_dwordx4 v[100:101], off
	v_lshl_add_u64 v[100:101], v[104:105], 1, s[72:73]
	v_readfirstlane_b32 s20, v166
	v_add_co_u32_e32 v96, vcc, s25, v96
	v_ashrrev_i32_e32 v99, 31, v98
	v_lshl_add_u64 v[100:101], v[100:101], 0, s[46:47]
	s_mov_b32 m0, s20
	v_addc_co_u32_e32 v97, vcc, 0, v97, vcc
	v_lshl_add_u64 v[98:99], v[98:99], 1, s[74:75]
	global_load_lds_dwordx4 v[100:101], off
	v_add_co_u32_e32 v98, vcc, s25, v98
	v_mfma_f32_32x32x16_bf16 v[80:95], v[116:119], v[176:179], v[80:95]
	s_nop 0
	v_addc_co_u32_e32 v99, vcc, 0, v99, vcc
	global_load_dwordx4 v[112:115], v[96:97], off offset:256
	global_load_dwordx4 v[116:119], v[98:99], off offset:256
	v_mfma_f32_32x32x16_bf16 v[80:95], v[212:215], v[180:183], v[80:95]
	s_waitcnt lgkmcnt(0)
	v_mfma_f32_32x32x16_bf16 v[80:95], v[228:231], v[184:187], v[80:95]
	v_mfma_f32_32x32x16_bf16 v[80:95], v[220:223], v[188:191], v[80:95]
	v_mfma_f32_32x32x16_bf16 v[80:95], v[238:241], v[192:195], v[80:95]
	v_mfma_f32_32x32x16_bf16 v[80:95], v[250:253], v[196:199], v[80:95]
	v_mfma_f32_32x32x16_bf16 v[80:95], v[224:227], v[242:245], v[80:95]
	ds_read_b64_tr_b16 v[96:97], v151 offset:0
	ds_read_b64_tr_b16 v[98:99], v151 offset:0x800
	ds_read_b64_tr_b16 v[100:101], v151 offset:0x1000
	ds_read_b64_tr_b16 v[102:103], v151 offset:0x1800
	ds_read_b64_tr_b16 v[104:105], v151 offset:0x2000
	ds_read_b64_tr_b16 v[106:107], v151 offset:0x2800
	ds_read_b64_tr_b16 v[108:109], v151 offset:0x3000
	ds_read_b64_tr_b16 v[110:111], v151 offset:0x3800
	s_nop 0
	s_waitcnt lgkmcnt(6)
	v_mfma_f32_32x32x16_bf16 v[0:15], v[120:123], v[96:99], v[0:15]
	ds_read_b64_tr_b16 v[96:97], v151 offset:0x200
	ds_read_b64_tr_b16 v[98:99], v151 offset:0xa00
	s_waitcnt lgkmcnt(6)
	v_mfma_f32_32x32x16_bf16 v[0:15], v[124:127], v[100:103], v[0:15]
	ds_read_b64_tr_b16 v[100:101], v151 offset:0x1200
	ds_read_b64_tr_b16 v[102:103], v151 offset:0x1a00
	s_waitcnt lgkmcnt(6)
	v_mfma_f32_32x32x16_bf16 v[0:15], v[142:145], v[104:107], v[0:15]
	ds_read_b64_tr_b16 v[104:105], v151 offset:0x2200
	ds_read_b64_tr_b16 v[106:107], v151 offset:0x2a00
	s_waitcnt lgkmcnt(6)
	v_mfma_f32_32x32x16_bf16 v[0:15], v[146:149], v[108:111], v[0:15]
	ds_read_b64_tr_b16 v[108:109], v151 offset:0x3200
	ds_read_b64_tr_b16 v[110:111], v151 offset:0x3a00
	s_waitcnt lgkmcnt(6)
	v_mfma_f32_32x32x16_bf16 v[16:31], v[120:123], v[96:99], v[16:31]
	ds_read_b64_tr_b16 v[96:97], v151 offset:0x400
	ds_read_b64_tr_b16 v[98:99], v151 offset:0xc00
	s_waitcnt lgkmcnt(6)
	v_mfma_f32_32x32x16_bf16 v[16:31], v[124:127], v[100:103], v[16:31]
	ds_read_b64_tr_b16 v[100:101], v151 offset:0x1400
	ds_read_b64_tr_b16 v[102:103], v151 offset:0x1c00
	s_waitcnt lgkmcnt(6)
	v_mfma_f32_32x32x16_bf16 v[16:31], v[142:145], v[104:107], v[16:31]
	ds_read_b64_tr_b16 v[104:105], v151 offset:0x2400
	ds_read_b64_tr_b16 v[106:107], v151 offset:0x2c00
	s_waitcnt lgkmcnt(6)
	v_mfma_f32_32x32x16_bf16 v[16:31], v[146:149], v[108:111], v[16:31]
	ds_read_b64_tr_b16 v[108:109], v151 offset:0x3400
	ds_read_b64_tr_b16 v[110:111], v151 offset:0x3c00
	s_waitcnt lgkmcnt(6)
	v_mfma_f32_32x32x16_bf16 v[32:47], v[120:123], v[96:99], v[32:47]
	ds_read_b64_tr_b16 v[96:97], v151 offset:0x600
	ds_read_b64_tr_b16 v[98:99], v151 offset:0xe00
	s_waitcnt lgkmcnt(6)
	v_mfma_f32_32x32x16_bf16 v[32:47], v[124:127], v[100:103], v[32:47]
	ds_read_b64_tr_b16 v[100:101], v151 offset:0x1600
	ds_read_b64_tr_b16 v[102:103], v151 offset:0x1e00
	s_waitcnt lgkmcnt(6)
	v_mfma_f32_32x32x16_bf16 v[32:47], v[142:145], v[104:107], v[32:47]
	ds_read_b64_tr_b16 v[104:105], v151 offset:0x2600
	ds_read_b64_tr_b16 v[106:107], v151 offset:0x2e00
	s_waitcnt lgkmcnt(6)
	v_mfma_f32_32x32x16_bf16 v[32:47], v[146:149], v[108:111], v[32:47]
	ds_read_b64_tr_b16 v[108:109], v151 offset:0x3600
	ds_read_b64_tr_b16 v[110:111], v151 offset:0x3e00
	s_waitcnt lgkmcnt(6)
	v_mfma_f32_32x32x16_bf16 v[48:63], v[120:123], v[96:99], v[48:63]
	s_add_i32 s20, s87, 64
	s_cmp_le_i32 s20, s59
	v_add_u32_e32 v171, s87, v154
	s_waitcnt lgkmcnt(4)
	v_mfma_f32_32x32x16_bf16 v[48:63], v[124:127], v[100:103], v[48:63]
	s_waitcnt lgkmcnt(2)
	v_mfma_f32_32x32x16_bf16 v[48:63], v[142:145], v[104:107], v[48:63]
	s_waitcnt lgkmcnt(0)
	v_mfma_f32_32x32x16_bf16 v[48:63], v[146:149], v[108:111], v[48:63]
	s_cbranch_scc1 .LBB0_371
; __device__ __forceinline__ int crow(int r, int hi) { return (r & 3) + 8 * (r >> 2) + 4 * hi; }
; template <bool GM>
; __device__ __forceinline__ void partialSM(f32x16& p0, f32x16& p1, bool mask, int kbase, int L, int qpos, int hi) {
;   if (mask) {
; #pragma unroll
;     for (int r = 0; r < 16; ++r) {
;       int k = kbase + crow(r, hi);
;       asm volatile("" : "+v"(k) : "v"(p0[r]));
;       bool ok = k < L;
;       if (GM) ok = ok && (k < 16 || abs(qpos - k) <= 128);
;       p0[r] = ok ? p0[r] : -1e30f;
;       int k2 = k + 32;
;       asm volatile("" : "+v"(k2) : "v"(p1[r]));
;       bool ok2 = k2 < L;
;       if (GM) ok2 = ok2 && (k2 < 16 || abs(qpos - k2) <= 128);
;       p1[r] = ok2 ? p1[r] : -1e30f;
;     }
;   }
	v_add_u32_e32 v96, 64, v171
	s_nop 0
	v_cmp_gt_i32_e32 vcc, s94, v96
	v_add_u32_e32 v96, 32, v96
	s_nop 0
	v_cndmask_b32_e32 v64, v233, v64, vcc
	v_cmp_gt_i32_e32 vcc, s94, v96
	v_add_u32_e32 v96, 0x41, v171
	s_nop 0
	v_cndmask_b32_e32 v80, v233, v80, vcc
	v_cmp_gt_i32_e32 vcc, s94, v96
	v_add_u32_e32 v96, 32, v96
	s_nop 0
	v_cndmask_b32_e32 v65, v233, v65, vcc
	v_cmp_gt_i32_e32 vcc, s94, v96
	v_add_u32_e32 v96, 0x42, v171
	s_nop 0
	v_cndmask_b32_e32 v81, v233, v81, vcc
	v_cmp_gt_i32_e32 vcc, s94, v96
	v_add_u32_e32 v96, 32, v96
	s_nop 0
	v_cndmask_b32_e32 v66, v233, v66, vcc
	v_cmp_gt_i32_e32 vcc, s94, v96
	v_add_u32_e32 v96, 0x43, v171
	s_nop 0
	v_cndmask_b32_e32 v82, v233, v82, vcc
	v_cmp_gt_i32_e32 vcc, s94, v96
	v_add_u32_e32 v96, 32, v96
	s_nop 0
	v_cndmask_b32_e32 v67, v233, v67, vcc
	v_cmp_gt_i32_e32 vcc, s94, v96
	v_add_u32_e32 v96, 0x48, v171
	s_nop 0
	v_cndmask_b32_e32 v83, v233, v83, vcc
	v_cmp_gt_i32_e32 vcc, s94, v96
	v_add_u32_e32 v96, 32, v96
	s_nop 0
	v_cndmask_b32_e32 v68, v233, v68, vcc
	v_cmp_gt_i32_e32 vcc, s94, v96
	v_add_u32_e32 v96, 0x49, v171
	s_nop 0
	v_cndmask_b32_e32 v84, v233, v84, vcc
	v_cmp_gt_i32_e32 vcc, s94, v96
	v_add_u32_e32 v96, 32, v96
	s_nop 0
	v_cndmask_b32_e32 v69, v233, v69, vcc
	v_cmp_gt_i32_e32 vcc, s94, v96
	v_add_u32_e32 v96, 0x4a, v171
	s_nop 0
	v_cndmask_b32_e32 v85, v233, v85, vcc
	v_cmp_gt_i32_e32 vcc, s94, v96
	v_add_u32_e32 v96, 32, v96
	s_nop 0
	v_cndmask_b32_e32 v70, v233, v70, vcc
	v_cmp_gt_i32_e32 vcc, s94, v96
	v_add_u32_e32 v96, 0x4b, v171
	s_nop 0
	v_cndmask_b32_e32 v86, v233, v86, vcc
	v_cmp_gt_i32_e32 vcc, s94, v96
	v_add_u32_e32 v96, 32, v96
	s_nop 0
	v_cndmask_b32_e32 v71, v233, v71, vcc
	v_cmp_gt_i32_e32 vcc, s94, v96
	v_add_u32_e32 v96, 0x50, v171
	s_nop 0
	v_cndmask_b32_e32 v87, v233, v87, vcc
	v_cmp_gt_i32_e32 vcc, s94, v96
	v_add_u32_e32 v96, 32, v96
	s_nop 0
	v_cndmask_b32_e32 v72, v233, v72, vcc
	v_cmp_gt_i32_e32 vcc, s94, v96
	v_add_u32_e32 v96, 0x51, v171
	s_nop 0
	v_cndmask_b32_e32 v88, v233, v88, vcc
	v_cmp_gt_i32_e32 vcc, s94, v96
	v_add_u32_e32 v96, 32, v96
	s_nop 0
	v_cndmask_b32_e32 v73, v233, v73, vcc
	v_cmp_gt_i32_e32 vcc, s94, v96
	v_add_u32_e32 v96, 0x52, v171
	s_nop 0
	v_cndmask_b32_e32 v89, v233, v89, vcc
	v_cmp_gt_i32_e32 vcc, s94, v96
	v_add_u32_e32 v96, 32, v96
	s_nop 0
	v_cndmask_b32_e32 v74, v233, v74, vcc
	v_cmp_gt_i32_e32 vcc, s94, v96
	v_add_u32_e32 v96, 0x53, v171
	s_nop 0
	v_cndmask_b32_e32 v90, v233, v90, vcc
	v_cmp_gt_i32_e32 vcc, s94, v96
	v_add_u32_e32 v96, 32, v96
	s_nop 0
	v_cndmask_b32_e32 v75, v233, v75, vcc
	v_cmp_gt_i32_e32 vcc, s94, v96
	v_add_u32_e32 v96, 0x58, v171
	s_nop 0
	v_cndmask_b32_e32 v91, v233, v91, vcc
	v_cmp_gt_i32_e32 vcc, s94, v96
	v_add_u32_e32 v96, 32, v96
	s_nop 0
	v_cndmask_b32_e32 v76, v233, v76, vcc
	v_cmp_gt_i32_e32 vcc, s94, v96
	v_add_u32_e32 v96, 0x59, v171
	s_nop 0
	v_cndmask_b32_e32 v92, v233, v92, vcc
	v_cmp_gt_i32_e32 vcc, s94, v96
	v_add_u32_e32 v96, 32, v96
	s_nop 0
	v_cndmask_b32_e32 v77, v233, v77, vcc
	v_cmp_gt_i32_e32 vcc, s94, v96
	v_add_u32_e32 v96, 0x5a, v171
	s_nop 0
	v_cndmask_b32_e32 v93, v233, v93, vcc
	v_cmp_gt_i32_e32 vcc, s94, v96
	v_add_u32_e32 v96, 32, v96
	s_nop 0
	v_cndmask_b32_e32 v78, v233, v78, vcc
	v_cmp_gt_i32_e32 vcc, s94, v96
	v_add_u32_e32 v96, 0x5b, v171
	s_nop 0
	v_cndmask_b32_e32 v94, v233, v94, vcc
	v_cmp_gt_i32_e32 vcc, s94, v96
	v_add_u32_e32 v96, 32, v96
	s_nop 0
	v_cndmask_b32_e32 v79, v233, v79, vcc
	v_cmp_gt_i32_e32 vcc, s94, v96
	s_nop 1
	v_cndmask_b32_e32 v95, v233, v95, vcc

; #define WAIT_L0() asm volatile("s_waitcnt lgkmcnt(0)" ::: "memory")
; #define SBAR() __builtin_amdgcn_sched_barrier(0)
; __device__ __forceinline__ int crow(int r, int hi) { return (r & 3) + 8 * (r >> 2) + 4 * hi; }
; template <bool GM>
; __device__ __forceinline__ void partialSM(f32x16& p0, f32x16& p1, bool mask, int kbase, int L, int qpos, int hi) {
;   if (mask) {
; #pragma unroll
;     for (int r = 0; r < 16; ++r) {
;       int k = kbase + crow(r, hi);
;       asm volatile("" : "+v"(k) : "v"(p0[r]));
;       bool ok = k < L;
;       if (GM) ok = ok && (k < 16 || abs(qpos - k) <= 128);
;       p0[r] = ok ? p0[r] : -1e30f;
;       int k2 = k + 32;
;       asm volatile("" : "+v"(k2) : "v"(p1[r]));
;       bool ok2 = k2 < L;
;       if (GM) ok2 = ok2 && (k2 < 16 || abs(qpos - k2) <= 128);
;       p1[r] = ok2 ? p1[r] : -1e30f;
;     }
;   }
; template <int NCB, int D0> __device__ __forceinline__ void pv_one(f32x16& od, int vb, bf16x8 pa0, bf16x8 pa1, bf16x8 pa2, bf16x8 pa3) {
;   constexpr int KSTEP = NCB * 1024, HALF = NCB * 512, B0 = D0 * 512;
;   const s16x4 l0 = tr_read<B0>(vb), h0 = tr_read<B0 + HALF>(vb), l1 = tr_read<B0 + KSTEP>(vb), h1 = tr_read<B0 + KSTEP + HALF>(vb);
;   const s16x4 l2 = tr_read<B0 + 2 * KSTEP>(vb), h2 = tr_read<B0 + 2 * KSTEP + HALF>(vb), l3 = tr_read<B0 + 3 * KSTEP>(vb), h3 = tr_read<B0 + 3 * KSTEP + HALF>(vb);
;   WAIT_L0(); SBAR();
;     ...
;   od = __builtin_amdgcn_mfma_f32_32x32x16_bf16(pa0, PK(l0, h0), od, 0, 0, 0);
;   od = __builtin_amdgcn_mfma_f32_32x32x16_bf16(pa1, PK(l1, h1), od, 0, 0, 0);
;   od = __builtin_amdgcn_mfma_f32_32x32x16_bf16(pa2, PK(l2, h2), od, 0, 0, 0);
;   od = __builtin_amdgcn_mfma_f32_32x32x16_bf16(pa3, PK(l3, h3), od, 0, 0, 0);
;     ...
; }
.LBB0_373:
	s_addk_i32 s87, 0x80
	ds_read_b64_tr_b16 v[96:97], v128 offset:0
	ds_read_b64_tr_b16 v[98:99], v128 offset:0x800
	ds_read_b64_tr_b16 v[100:101], v128 offset:0x1000
	ds_read_b64_tr_b16 v[102:103], v128 offset:0x1800
	ds_read_b64_tr_b16 v[104:105], v128 offset:0x2000
	ds_read_b64_tr_b16 v[106:107], v128 offset:0x2800
	ds_read_b64_tr_b16 v[108:109], v128 offset:0x3000
	ds_read_b64_tr_b16 v[110:111], v128 offset:0x3800
	s_nop 0
	s_waitcnt lgkmcnt(6)
	v_mfma_f32_32x32x16_bf16 v[0:15], v[120:123], v[96:99], v[0:15]
	ds_read_b64_tr_b16 v[96:97], v128 offset:0x200
	ds_read_b64_tr_b16 v[98:99], v128 offset:0xa00
	s_waitcnt lgkmcnt(6)
	v_mfma_f32_32x32x16_bf16 v[0:15], v[124:127], v[100:103], v[0:15]
	ds_read_b64_tr_b16 v[100:101], v128 offset:0x1200
	ds_read_b64_tr_b16 v[102:103], v128 offset:0x1a00
	s_waitcnt lgkmcnt(6)
	v_mfma_f32_32x32x16_bf16 v[0:15], v[142:145], v[104:107], v[0:15]
	ds_read_b64_tr_b16 v[104:105], v128 offset:0x2200
	ds_read_b64_tr_b16 v[106:107], v128 offset:0x2a00
	s_waitcnt lgkmcnt(6)
	v_mfma_f32_32x32x16_bf16 v[0:15], v[146:149], v[108:111], v[0:15]
	ds_read_b64_tr_b16 v[108:109], v128 offset:0x3200
	ds_read_b64_tr_b16 v[110:111], v128 offset:0x3a00
	s_waitcnt lgkmcnt(6)
	v_mfma_f32_32x32x16_bf16 v[16:31], v[120:123], v[96:99], v[16:31]
	ds_read_b64_tr_b16 v[96:97], v128 offset:0x400
	ds_read_b64_tr_b16 v[98:99], v128 offset:0xc00
	s_waitcnt lgkmcnt(6)
	v_mfma_f32_32x32x16_bf16 v[16:31], v[124:127], v[100:103], v[16:31]
	ds_read_b64_tr_b16 v[100:101], v128 offset:0x1400
	ds_read_b64_tr_b16 v[102:103], v128 offset:0x1c00
	s_waitcnt lgkmcnt(6)
	v_mfma_f32_32x32x16_bf16 v[16:31], v[142:145], v[104:107], v[16:31]
	ds_read_b64_tr_b16 v[104:105], v128 offset:0x2400
	ds_read_b64_tr_b16 v[106:107], v128 offset:0x2c00
	s_waitcnt lgkmcnt(6)
	v_mfma_f32_32x32x16_bf16 v[16:31], v[146:149], v[108:111], v[16:31]
	ds_read_b64_tr_b16 v[108:109], v128 offset:0x3400
	ds_read_b64_tr_b16 v[110:111], v128 offset:0x3c00
	s_waitcnt lgkmcnt(6)
	v_mfma_f32_32x32x16_bf16 v[32:47], v[120:123], v[96:99], v[32:47]
	ds_read_b64_tr_b16 v[96:97], v128 offset:0x600
	ds_read_b64_tr_b16 v[98:99], v128 offset:0xe00
	s_waitcnt lgkmcnt(6)
	v_mfma_f32_32x32x16_bf16 v[32:47], v[124:127], v[100:103], v[32:47]
	ds_read_b64_tr_b16 v[100:101], v128 offset:0x1600
	ds_read_b64_tr_b16 v[102:103], v128 offset:0x1e00
	s_waitcnt lgkmcnt(6)
	v_mfma_f32_32x32x16_bf16 v[32:47], v[142:145], v[104:107], v[32:47]
	ds_read_b64_tr_b16 v[104:105], v128 offset:0x2600
	ds_read_b64_tr_b16 v[106:107], v128 offset:0x2e00
	s_waitcnt lgkmcnt(6)
	v_mfma_f32_32x32x16_bf16 v[32:47], v[146:149], v[108:111], v[32:47]
	ds_read_b64_tr_b16 v[108:109], v128 offset:0x3600
	ds_read_b64_tr_b16 v[110:111], v128 offset:0x3e00
	s_waitcnt lgkmcnt(6)
	v_mfma_f32_32x32x16_bf16 v[48:63], v[120:123], v[96:99], v[48:63]
	s_cmp_le_i32 s87, s59
	s_waitcnt lgkmcnt(4)
	v_mfma_f32_32x32x16_bf16 v[48:63], v[124:127], v[100:103], v[48:63]
	s_waitcnt lgkmcnt(2)
	v_mfma_f32_32x32x16_bf16 v[48:63], v[142:145], v[104:107], v[48:63]
	s_waitcnt lgkmcnt(0)
	v_mfma_f32_32x32x16_bf16 v[48:63], v[146:149], v[108:111], v[48:63]
	s_cbranch_scc1 .LBB0_375
	v_add_u32_e32 v96, 0x80, v171
	s_nop 0
	v_cmp_gt_i32_e32 vcc, s94, v96
	v_add_u32_e32 v96, 32, v96
	s_nop 0
	v_cndmask_b32_e32 v80, v233, v80, vcc
	v_cmp_gt_i32_e32 vcc, s94, v96
	v_add_u32_e32 v96, 0x81, v171
	s_nop 0
	v_cndmask_b32_e32 v64, v233, v64, vcc
	v_cmp_gt_i32_e32 vcc, s94, v96
	v_add_u32_e32 v96, 32, v96
	s_nop 0
	v_cndmask_b32_e32 v81, v233, v81, vcc
	v_cmp_gt_i32_e32 vcc, s94, v96
	v_add_u32_e32 v96, 0x82, v171
	s_nop 0
	v_cndmask_b32_e32 v65, v233, v65, vcc
	v_cmp_gt_i32_e32 vcc, s94, v96
	v_add_u32_e32 v96, 32, v96
	s_nop 0
	v_cndmask_b32_e32 v82, v233, v82, vcc
	v_cmp_gt_i32_e32 vcc, s94, v96
	v_add_u32_e32 v96, 0x83, v171
	s_nop 0
	v_cndmask_b32_e32 v66, v233, v66, vcc
	v_cmp_gt_i32_e32 vcc, s94, v96
	v_add_u32_e32 v96, 32, v96
	s_nop 0
	v_cndmask_b32_e32 v83, v233, v83, vcc
	v_cmp_gt_i32_e32 vcc, s94, v96
	v_add_u32_e32 v96, 0x88, v171
	s_nop 0
	v_cndmask_b32_e32 v67, v233, v67, vcc
	v_cmp_gt_i32_e32 vcc, s94, v96
	v_add_u32_e32 v96, 32, v96
	s_nop 0
	v_cndmask_b32_e32 v84, v233, v84, vcc
	v_cmp_gt_i32_e32 vcc, s94, v96
	v_add_u32_e32 v96, 0x89, v171
	s_nop 0
	v_cndmask_b32_e32 v68, v233, v68, vcc
	v_cmp_gt_i32_e32 vcc, s94, v96
	v_add_u32_e32 v96, 32, v96
	s_nop 0
	v_cndmask_b32_e32 v85, v233, v85, vcc
	v_cmp_gt_i32_e32 vcc, s94, v96
	v_add_u32_e32 v96, 0x8a, v171
	s_nop 0
	v_cndmask_b32_e32 v69, v233, v69, vcc
	v_cmp_gt_i32_e32 vcc, s94, v96
	v_add_u32_e32 v96, 32, v96
	s_nop 0
	v_cndmask_b32_e32 v86, v233, v86, vcc
	v_cmp_gt_i32_e32 vcc, s94, v96
	v_add_u32_e32 v96, 0x8b, v171
	s_nop 0
	v_cndmask_b32_e32 v70, v233, v70, vcc
	v_cmp_gt_i32_e32 vcc, s94, v96
	v_add_u32_e32 v96, 32, v96
	s_nop 0
	v_cndmask_b32_e32 v87, v233, v87, vcc
	v_cmp_gt_i32_e32 vcc, s94, v96
	v_add_u32_e32 v96, 0x90, v171
	s_nop 0
	v_cndmask_b32_e32 v71, v233, v71, vcc
	v_cmp_gt_i32_e32 vcc, s94, v96
	v_add_u32_e32 v96, 32, v96
	s_nop 0
	v_cndmask_b32_e32 v88, v233, v88, vcc
	v_cmp_gt_i32_e32 vcc, s94, v96
	v_add_u32_e32 v96, 0x91, v171
	s_nop 0
	v_cndmask_b32_e32 v72, v233, v72, vcc
	v_cmp_gt_i32_e32 vcc, s94, v96
	v_add_u32_e32 v96, 32, v96
	s_nop 0
	v_cndmask_b32_e32 v89, v233, v89, vcc
	v_cmp_gt_i32_e32 vcc, s94, v96
	v_add_u32_e32 v96, 0x92, v171
	s_nop 0
	v_cndmask_b32_e32 v73, v233, v73, vcc
	v_cmp_gt_i32_e32 vcc, s94, v96
	v_add_u32_e32 v96, 32, v96
	s_nop 0
	v_cndmask_b32_e32 v90, v233, v90, vcc
	v_cmp_gt_i32_e32 vcc, s94, v96
	v_add_u32_e32 v96, 0x93, v171
	s_nop 0
	v_cndmask_b32_e32 v74, v233, v74, vcc
	v_cmp_gt_i32_e32 vcc, s94, v96
	v_add_u32_e32 v96, 32, v96
	s_nop 0
	v_cndmask_b32_e32 v91, v233, v91, vcc
	v_cmp_gt_i32_e32 vcc, s94, v96
	v_add_u32_e32 v96, 0x98, v171
	s_nop 0
	v_cndmask_b32_e32 v75, v233, v75, vcc
	v_cmp_gt_i32_e32 vcc, s94, v96
	v_add_u32_e32 v96, 32, v96
	s_nop 0
	v_cndmask_b32_e32 v92, v233, v92, vcc
	v_cmp_gt_i32_e32 vcc, s94, v96
	v_add_u32_e32 v96, 0x99, v171
	s_nop 0
	v_cndmask_b32_e32 v76, v233, v76, vcc
	v_cmp_gt_i32_e32 vcc, s94, v96
	v_add_u32_e32 v96, 32, v96
	s_nop 0
	v_cndmask_b32_e32 v93, v233, v93, vcc
	v_cmp_gt_i32_e32 vcc, s94, v96
	v_add_u32_e32 v96, 0x9a, v171
	s_nop 0
	v_cndmask_b32_e32 v77, v233, v77, vcc
	v_cmp_gt_i32_e32 vcc, s94, v96
	v_add_u32_e32 v96, 32, v96
	s_nop 0
	v_cndmask_b32_e32 v94, v233, v94, vcc
	v_cmp_gt_i32_e32 vcc, s94, v96
	v_add_u32_e32 v96, 0x9b, v171
	s_nop 0
	v_cndmask_b32_e32 v78, v233, v78, vcc
	v_cmp_gt_i32_e32 vcc, s94, v96
	v_add_u32_e32 v96, 32, v96
	s_nop 0
	v_cndmask_b32_e32 v95, v233, v95, vcc
	v_cmp_gt_i32_e32 vcc, s94, v96
	s_nop 1
	v_cndmask_b32_e32 v79, v233, v79, vcc

; #define WAIT_L0() asm volatile("s_waitcnt lgkmcnt(0)" ::: "memory")
; #define SBAR() __builtin_amdgcn_sched_barrier(0)
; __device__ __forceinline__ void finishSM(f32x16& p0, f32x16& p1, float& l_reg, bf16x8& pa0, bf16x8& pa1, bf16x8& pa2, bf16x8& pa3) {
; #pragma unroll
;   for (int r = 0; r < 16; ++r) p1[r] = __builtin_amdgcn_exp2f(p1[r]);
;   float ps = 0;
; #pragma unroll
;   for (int r = 0; r < 16; ++r) ps += p0[r];
; #pragma unroll
;   for (int r = 0; r < 16; ++r) ps += p1[r];
;   { auto rr = __builtin_amdgcn_permlane32_swap(__float_as_uint(ps), __float_as_uint(ps), false, false);
;     ps = __uint_as_float(rr[0]) + __uint_as_float(rr[1]); }
;   l_reg += ps;
;     ...
;   PK4(p0, 0, pa0); PK4(p0, 8, pa1); PK4(p1, 0, pa2); PK4(p1, 8, pa3);
;     ...
; }
; template <int NCB, int D0> __device__ __forceinline__ void pv_one(f32x16& od, int vb, bf16x8 pa0, bf16x8 pa1, bf16x8 pa2, bf16x8 pa3) {
;   constexpr int KSTEP = NCB * 1024, HALF = NCB * 512, B0 = D0 * 512;
;   const s16x4 l0 = tr_read<B0>(vb), h0 = tr_read<B0 + HALF>(vb), l1 = tr_read<B0 + KSTEP>(vb), h1 = tr_read<B0 + KSTEP + HALF>(vb);
;   const s16x4 l2 = tr_read<B0 + 2 * KSTEP>(vb), h2 = tr_read<B0 + 2 * KSTEP + HALF>(vb), l3 = tr_read<B0 + 3 * KSTEP>(vb), h3 = tr_read<B0 + 3 * KSTEP + HALF>(vb);
;   WAIT_L0(); SBAR();
;     ...
;   od = __builtin_amdgcn_mfma_f32_32x32x16_bf16(pa0, PK(l0, h0), od, 0, 0, 0);
;   od = __builtin_amdgcn_mfma_f32_32x32x16_bf16(pa1, PK(l1, h1), od, 0, 0, 0);
;   od = __builtin_amdgcn_mfma_f32_32x32x16_bf16(pa2, PK(l2, h2), od, 0, 0, 0);
;   od = __builtin_amdgcn_mfma_f32_32x32x16_bf16(pa3, PK(l3, h3), od, 0, 0, 0);
;     ...
; }
.LBB0_379:
	v_exp_f32_e32 v179, v64
	v_exp_f32_e32 v180, v65
	v_exp_f32_e32 v181, v66
	v_exp_f32_e32 v182, v67
	v_exp_f32_e32 v183, v68
	v_exp_f32_e32 v184, v69
	v_exp_f32_e32 v185, v70
	v_exp_f32_e32 v186, v71
	v_exp_f32_e32 v162, v72
	v_exp_f32_e32 v163, v73
	v_exp_f32_e32 v164, v74
	v_exp_f32_e32 v165, v75
	v_exp_f32_e32 v166, v76
	v_exp_f32_e32 v168, v77
	v_exp_f32_e32 v169, v78
	v_exp_f32_e32 v170, v79
	v_add_f32_e32 v80, 0, v176
	s_mov_b64 s[22:23], -1
	s_and_b64 vcc, exec, s[20:21]
	v_add_f32_e32 v187, v178, v80
	s_cbranch_vccz .LBB0_381
	v_add_f32_e32 v64, v174, v187
	v_add_f32_e32 v64, v177, v64
	v_add_f32_e32 v64, v172, v64
	v_add_f32_e32 v64, v175, v64
	v_add_f32_e32 v64, v171, v64
	v_add_f32_e32 v64, v173, v64
	v_add_f32_e32 v64, v147, v64
	v_add_f32_e32 v64, v149, v64
	v_add_f32_e32 v64, v145, v64
	v_add_f32_e32 v64, v148, v64
	v_add_f32_e32 v64, v143, v64
	v_add_f32_e32 v64, v146, v64
	v_add_f32_e32 v64, v142, v64
	v_add_f32_e32 v64, v144, v64
	v_add_f32_e32 v64, v179, v64
	v_add_f32_e32 v64, v180, v64
	v_add_f32_e32 v64, v181, v64
	v_add_f32_e32 v64, v182, v64
	v_add_f32_e32 v64, v183, v64
	v_add_f32_e32 v64, v184, v64
	v_add_f32_e32 v64, v185, v64
	v_add_f32_e32 v64, v186, v64
	v_add_f32_e32 v64, v162, v64
	v_add_f32_e32 v64, v163, v64
	v_add_f32_e32 v64, v164, v64
	v_add_f32_e32 v64, v165, v64
	v_add_f32_e32 v64, v166, v64
	v_add_f32_e32 v64, v168, v64
	v_add_f32_e32 v64, v169, v64
	v_add_f32_e32 v64, v170, v64
	v_mov_b32_e32 v65, v64
	s_nop 1
	v_permlane32_swap_b32_e32 v64, v65
	v_add_f32_e32 v64, v64, v65
	v_add_f32_e32 v161, v150, v64
	v_cvt_pk_bf16_f32 v188, v176, v178
	v_cvt_pk_bf16_f32 v189, v174, v177
	v_cvt_pk_bf16_f32 v190, v172, v175
	v_cvt_pk_bf16_f32 v191, v171, v173
	v_cvt_pk_bf16_f32 v192, v147, v149
	v_cvt_pk_bf16_f32 v193, v145, v148
	v_cvt_pk_bf16_f32 v194, v143, v146
	v_cvt_pk_bf16_f32 v195, v142, v144
	v_cvt_pk_bf16_f32 v196, v179, v180
	v_cvt_pk_bf16_f32 v197, v181, v182
	v_cvt_pk_bf16_f32 v198, v183, v184
	v_cvt_pk_bf16_f32 v199, v185, v186
	v_cvt_pk_bf16_f32 v200, v162, v163
	v_cvt_pk_bf16_f32 v201, v164, v165
	v_cvt_pk_bf16_f32 v202, v166, v168
	v_cvt_pk_bf16_f32 v203, v169, v170
	s_nop 0
	v_permlane32_swap_b32_e32 v188, v190
	v_permlane32_swap_b32_e32 v189, v191
	v_permlane32_swap_b32_e32 v192, v194
	v_permlane32_swap_b32_e32 v193, v195
	v_permlane32_swap_b32_e32 v196, v198
	v_permlane32_swap_b32_e32 v197, v199
	v_permlane32_swap_b32_e32 v200, v202
	v_permlane32_swap_b32_e32 v201, v203
	ds_read_b64_tr_b16 v[80:81], v151 offset:0
	ds_read_b64_tr_b16 v[82:83], v151 offset:0x800
	ds_read_b64_tr_b16 v[84:85], v151 offset:0x1000
	ds_read_b64_tr_b16 v[86:87], v151 offset:0x1800
	ds_read_b64_tr_b16 v[88:89], v151 offset:0x2000
	ds_read_b64_tr_b16 v[90:91], v151 offset:0x2800
	ds_read_b64_tr_b16 v[92:93], v151 offset:0x3000
	ds_read_b64_tr_b16 v[94:95], v151 offset:0x3800
	s_nop 0
	s_waitcnt lgkmcnt(6)
	v_mfma_f32_32x32x16_bf16 v[64:79], v[188:191], v[80:83], v[0:15]
	ds_read_b64_tr_b16 v[96:97], v151 offset:0x200
	ds_read_b64_tr_b16 v[98:99], v151 offset:0xa00
	ds_read_b64_tr_b16 v[100:101], v151 offset:0x1200
	ds_read_b64_tr_b16 v[102:103], v151 offset:0x1a00
	ds_read_b64_tr_b16 v[104:105], v151 offset:0x2200
	ds_read_b64_tr_b16 v[106:107], v151 offset:0x2a00
	ds_read_b64_tr_b16 v[108:109], v151 offset:0x3200
	s_waitcnt lgkmcnt(11)
	v_mfma_f32_32x32x16_bf16 v[64:79], v[192:195], v[84:87], v[64:79]
	ds_read_b64_tr_b16 v[110:111], v151 offset:0x3a00
	s_waitcnt lgkmcnt(10)
	v_mfma_f32_32x32x16_bf16 v[64:79], v[196:199], v[88:91], v[64:79]
	s_waitcnt lgkmcnt(8)
	v_mfma_f32_32x32x16_bf16 v[64:79], v[200:203], v[92:95], v[64:79]
	s_waitcnt lgkmcnt(6)
	v_mfma_f32_32x32x16_bf16 v[80:95], v[188:191], v[96:99], v[16:31]
	ds_read_b64_tr_b16 v[112:113], v151 offset:0x400
	ds_read_b64_tr_b16 v[114:115], v151 offset:0xc00
	ds_read_b64_tr_b16 v[116:117], v151 offset:0x1400
	ds_read_b64_tr_b16 v[118:119], v151 offset:0x1c00
	ds_read_b64_tr_b16 v[120:121], v151 offset:0x2400
	ds_read_b64_tr_b16 v[122:123], v151 offset:0x2c00
	ds_read_b64_tr_b16 v[124:125], v151 offset:0x3400
	s_waitcnt lgkmcnt(11)
	v_mfma_f32_32x32x16_bf16 v[80:95], v[192:195], v[100:103], v[80:95]
	ds_read_b64_tr_b16 v[126:127], v151 offset:0x3c00
	s_waitcnt lgkmcnt(10)
	v_mfma_f32_32x32x16_bf16 v[80:95], v[196:199], v[104:107], v[80:95]
	s_waitcnt lgkmcnt(8)
	v_mfma_f32_32x32x16_bf16 v[80:95], v[200:203], v[108:111], v[80:95]
	s_waitcnt lgkmcnt(6)
	v_mfma_f32_32x32x16_bf16 v[96:111], v[188:191], v[112:115], v[32:47]
	ds_read_b64_tr_b16 v[204:205], v151 offset:0x600
	ds_read_b64_tr_b16 v[206:207], v151 offset:0xe00
	ds_read_b64_tr_b16 v[208:209], v151 offset:0x1600
	ds_read_b64_tr_b16 v[210:211], v151 offset:0x1e00
	ds_read_b64_tr_b16 v[212:213], v151 offset:0x2600
	ds_read_b64_tr_b16 v[214:215], v151 offset:0x2e00
	ds_read_b64_tr_b16 v[216:217], v151 offset:0x3600
	s_waitcnt lgkmcnt(11)
	v_mfma_f32_32x32x16_bf16 v[96:111], v[192:195], v[116:119], v[96:111]
	ds_read_b64_tr_b16 v[218:219], v151 offset:0x3e00
	s_waitcnt lgkmcnt(10)
	v_mfma_f32_32x32x16_bf16 v[96:111], v[196:199], v[120:123], v[96:111]
	s_waitcnt lgkmcnt(8)
	v_mfma_f32_32x32x16_bf16 v[96:111], v[200:203], v[124:127], v[96:111]
	s_waitcnt lgkmcnt(6)
	v_mfma_f32_32x32x16_bf16 v[112:127], v[188:191], v[204:207], v[48:63]
	s_mov_b64 s[22:23], 0
	s_waitcnt lgkmcnt(4)
	v_mfma_f32_32x32x16_bf16 v[112:127], v[192:195], v[208:211], v[112:127]
	s_waitcnt lgkmcnt(2)
	v_mfma_f32_32x32x16_bf16 v[112:127], v[196:199], v[212:215], v[112:127]
	s_waitcnt lgkmcnt(0)
	v_mfma_f32_32x32x16_bf16 v[112:127], v[200:203], v[216:219], v[112:127]
; __device__ __forceinline__ void finishSM(f32x16& p0, f32x16& p1, float& l_reg, bf16x8& pa0, bf16x8& pa1, bf16x8& pa2, bf16x8& pa3) {
; #pragma unroll
;   for (int r = 0; r < 16; ++r) p1[r] = __builtin_amdgcn_exp2f(p1[r]);
;   float ps = 0;
; #pragma unroll
;   for (int r = 0; r < 16; ++r) ps += p0[r];
; #pragma unroll
;   for (int r = 0; r < 16; ++r) ps += p1[r];
;   { auto rr = __builtin_amdgcn_permlane32_swap(__float_as_uint(ps), __float_as_uint(ps), false, false);
;     ps = __uint_as_float(rr[0]) + __uint_as_float(rr[1]); }
;   l_reg += ps;
;     ...
;   PK4(p0, 0, pa0); PK4(p0, 8, pa1); PK4(p1, 0, pa2); PK4(p1, 8, pa3);
;     ...
; }
; template <int DQK, int QL>
; __device__ __forceinline__ void qkt(f32x16& p0, f32x16& p1, const char* Ks, const bf16x8 (&qr)[DQK / 16 - QL], const char* qlds, const int (&kofs)[4], float negM) {
;   constexpr int QR = DQK / 16 - QL;
; #pragma unroll
;   for (int r = 0; r < 16; ++r) { p0[r] = negM; p1[r] = negM; }
; #pragma unroll
;   for (int d0 = 0; d0 < DQK / 16; ++d0) {
;     const char* kp = Ks + kofs[d0 & 3] + (d0 >> 2) * 128;
;     bf16x8 b0 = *reinterpret_cast<const bf16x8*>(kp);
;     bf16x8 b1 = *reinterpret_cast<const bf16x8*>(kp + 32 * DQK * 2);
;     bf16x8 qf;
;     if constexpr (QL > 0) { if (d0 < QR) qf = qr[d0 < QR ? d0 : 0]; else qf = *reinterpret_cast<const bf16x8*>(qlds + (d0 - QR) * 1024); }
;     else qf = qr[d0];
;     p0 = __builtin_amdgcn_mfma_f32_32x32x16_bf16(b0, qf, p0, 0, 0, 0);
;     p1 = __builtin_amdgcn_mfma_f32_32x32x16_bf16(b1, qf, p1, 0, 0, 0);
;   }
; }
.LBB0_381:
	s_andn2_b64 vcc, exec, s[22:23]
	s_cbranch_vccnz .LBB0_385
	v_add_f32_e32 v64, v174, v187
	v_add_f32_e32 v64, v177, v64
	v_add_f32_e32 v64, v172, v64
	v_add_f32_e32 v64, v175, v64
	v_add_f32_e32 v64, v171, v64
	v_add_f32_e32 v64, v173, v64
	v_add_f32_e32 v64, v147, v64
	v_add_f32_e32 v64, v149, v64
	v_add_f32_e32 v64, v145, v64
	v_add_f32_e32 v64, v148, v64
	v_add_f32_e32 v64, v143, v64
	v_add_f32_e32 v64, v146, v64
	v_add_f32_e32 v64, v142, v64
	v_add_f32_e32 v64, v144, v64
	v_add_f32_e32 v64, v179, v64
	v_add_f32_e32 v64, v180, v64
	v_add_f32_e32 v64, v181, v64
	v_add_f32_e32 v64, v182, v64
	v_add_f32_e32 v64, v183, v64
	v_add_f32_e32 v64, v184, v64
	v_add_f32_e32 v64, v185, v64
	v_add_f32_e32 v64, v186, v64
	v_add_f32_e32 v64, v162, v64
	v_add_f32_e32 v64, v163, v64
	v_add_f32_e32 v64, v164, v64
	v_add_f32_e32 v64, v165, v64
	v_add_f32_e32 v64, v166, v64
	v_add_f32_e32 v64, v168, v64
	v_add_f32_e32 v64, v169, v64
	v_add_f32_e32 v112, v170, v64
	v_mov_b32_e32 v113, v112
	s_nop 1
	v_permlane32_swap_b32_e32 v112, v113
	v_cvt_pk_bf16_f32 v96, v176, v178
	v_cvt_pk_bf16_f32 v97, v174, v177
	v_cvt_pk_bf16_f32 v98, v172, v175
	v_cvt_pk_bf16_f32 v99, v171, v173
	v_cvt_pk_bf16_f32 v100, v147, v149
	v_cvt_pk_bf16_f32 v101, v145, v148
	v_cvt_pk_bf16_f32 v102, v143, v146
	v_cvt_pk_bf16_f32 v103, v142, v144
	v_cvt_pk_bf16_f32 v104, v179, v180
	v_cvt_pk_bf16_f32 v105, v181, v182
	v_cvt_pk_bf16_f32 v106, v183, v184
	v_cvt_pk_bf16_f32 v107, v185, v186
	v_cvt_pk_bf16_f32 v108, v162, v163
	v_cvt_pk_bf16_f32 v109, v164, v165
	v_cvt_pk_bf16_f32 v110, v166, v168
	v_cvt_pk_bf16_f32 v111, v169, v170
	s_nop 0
	v_permlane32_swap_b32_e32 v96, v98
	v_permlane32_swap_b32_e32 v97, v99
	v_permlane32_swap_b32_e32 v100, v102
	v_permlane32_swap_b32_e32 v101, v103
	v_permlane32_swap_b32_e32 v104, v106
	v_permlane32_swap_b32_e32 v105, v107
	v_permlane32_swap_b32_e32 v108, v110
	v_permlane32_swap_b32_e32 v109, v111
	ds_read_b128 v[114:117], v152 offset:57344
	v_mov_b64_e32 v[78:79], s[18:19]
	v_mov_b64_e32 v[76:77], s[16:17]
	v_mov_b64_e32 v[74:75], s[14:15]
	v_mov_b64_e32 v[72:73], s[12:13]
	v_mov_b64_e32 v[70:71], s[10:11]
	v_mov_b64_e32 v[68:69], s[8:9]
	v_mov_b64_e32 v[66:67], s[6:7]
	v_mov_b64_e32 v[64:65], s[4:5]
	s_waitcnt lgkmcnt(0)
	s_nop 0
	v_mfma_f32_32x32x16_bf16 v[80:95], v[114:117], v[138:141], v[64:79]
	ds_read_b128 v[114:117], v160 offset:12288
	s_waitcnt lgkmcnt(0)
	v_mfma_f32_32x32x16_bf16 v[64:79], v[114:117], v[138:141], v[64:79]
	ds_read_b128 v[114:117], v156 offset:57344
	s_waitcnt lgkmcnt(0)
	v_mfma_f32_32x32x16_bf16 v[80:95], v[114:117], v[134:137], v[80:95]
	ds_read_b128 v[114:117], v159 offset:12288
	s_waitcnt lgkmcnt(0)
	v_mfma_f32_32x32x16_bf16 v[64:79], v[114:117], v[134:137], v[64:79]
	ds_read_b128 v[114:117], v155 offset:57344
	s_waitcnt lgkmcnt(0)
	v_mfma_f32_32x32x16_bf16 v[80:95], v[114:117], v[130:133], v[80:95]
	ds_read_b128 v[114:117], v158 offset:12288
	s_waitcnt lgkmcnt(0)
	v_mfma_f32_32x32x16_bf16 v[64:79], v[114:117], v[130:133], v[64:79]
	ds_read_b128 v[114:117], v153 offset:57344
	ds_read_b128 v[118:121], v167
	s_waitcnt lgkmcnt(0)
	v_mfma_f32_32x32x16_bf16 v[80:95], v[114:117], v[118:121], v[80:95]
	ds_read_b128 v[114:117], v157 offset:12288
	s_waitcnt lgkmcnt(0)
	v_mfma_f32_32x32x16_bf16 v[64:79], v[114:117], v[118:121], v[64:79]
	ds_read_b128 v[114:117], v152 offset:57472
	ds_read_b128 v[118:121], v167 offset:1024
	s_waitcnt lgkmcnt(0)
	v_mfma_f32_32x32x16_bf16 v[80:95], v[114:117], v[118:121], v[80:95]
	ds_read_b128 v[114:117], v160 offset:12416
	s_waitcnt lgkmcnt(0)
	v_mfma_f32_32x32x16_bf16 v[64:79], v[114:117], v[118:121], v[64:79]
	ds_read_b128 v[114:117], v156 offset:57472
	ds_read_b128 v[118:121], v167 offset:2048
	s_waitcnt lgkmcnt(0)
	v_mfma_f32_32x32x16_bf16 v[80:95], v[114:117], v[118:121], v[80:95]
	ds_read_b128 v[114:117], v159 offset:12416
	s_waitcnt lgkmcnt(0)
	v_mfma_f32_32x32x16_bf16 v[64:79], v[114:117], v[118:121], v[64:79]
	ds_read_b128 v[114:117], v155 offset:57472
	ds_read_b128 v[118:121], v167 offset:3072
	s_waitcnt lgkmcnt(0)
	v_mfma_f32_32x32x16_bf16 v[80:95], v[114:117], v[118:121], v[80:95]
	ds_read_b128 v[114:117], v158 offset:12416
	s_waitcnt lgkmcnt(0)
	v_mfma_f32_32x32x16_bf16 v[64:79], v[114:117], v[118:121], v[64:79]
	ds_read_b128 v[114:117], v153 offset:57472
	ds_read_b128 v[118:121], v167 offset:4096
	s_waitcnt lgkmcnt(0)
	v_mfma_f32_32x32x16_bf16 v[80:95], v[114:117], v[118:121], v[80:95]
	ds_read_b128 v[114:117], v157 offset:12416
	s_waitcnt lgkmcnt(0)
	v_mfma_f32_32x32x16_bf16 v[64:79], v[114:117], v[118:121], v[64:79]
	ds_read_b128 v[114:117], v152 offset:57600
	ds_read_b128 v[118:121], v167 offset:5120
	s_waitcnt lgkmcnt(0)
	v_mfma_f32_32x32x16_bf16 v[80:95], v[114:117], v[118:121], v[80:95]
	ds_read_b128 v[114:117], v160 offset:12544
	s_waitcnt lgkmcnt(0)
	v_mfma_f32_32x32x16_bf16 v[64:79], v[114:117], v[118:121], v[64:79]
	ds_read_b128 v[114:117], v156 offset:57600
	ds_read_b128 v[118:121], v167 offset:6144
	s_waitcnt lgkmcnt(0)
	v_mfma_f32_32x32x16_bf16 v[80:95], v[114:117], v[118:121], v[80:95]
	ds_read_b128 v[114:117], v159 offset:12544
	s_waitcnt lgkmcnt(0)
	v_mfma_f32_32x32x16_bf16 v[64:79], v[114:117], v[118:121], v[64:79]
	ds_read_b128 v[114:117], v155 offset:57600
	ds_read_b128 v[118:121], v167 offset:7168
	s_waitcnt lgkmcnt(0)
	v_mfma_f32_32x32x16_bf16 v[80:95], v[114:117], v[118:121], v[80:95]
	ds_read_b128 v[114:117], v158 offset:12544
	s_waitcnt lgkmcnt(0)
	v_mfma_f32_32x32x16_bf16 v[64:79], v[114:117], v[118:121], v[64:79]
	ds_read_b128 v[114:117], v153 offset:57600
	ds_read_b128 v[118:121], v167 offset:8192
	s_waitcnt lgkmcnt(0)
; #define WAIT_L0() asm volatile("s_waitcnt lgkmcnt(0)" ::: "memory")
; #define SBAR() __builtin_amdgcn_sched_barrier(0)
; __device__ __forceinline__ int crow(int r, int hi) { return (r & 3) + 8 * (r >> 2) + 4 * hi; }
; template <bool GM>
; __device__ __forceinline__ void partialSM(f32x16& p0, f32x16& p1, bool mask, int kbase, int L, int qpos, int hi) {
;   if (mask) {
; #pragma unroll
;     for (int r = 0; r < 16; ++r) {
;       int k = kbase + crow(r, hi);
;       asm volatile("" : "+v"(k) : "v"(p0[r]));
;       bool ok = k < L;
;       if (GM) ok = ok && (k < 16 || abs(qpos - k) <= 128);
;       p0[r] = ok ? p0[r] : -1e30f;
;       int k2 = k + 32;
;       asm volatile("" : "+v"(k2) : "v"(p1[r]));
;       bool ok2 = k2 < L;
;       if (GM) ok2 = ok2 && (k2 < 16 || abs(qpos - k2) <= 128);
;       p1[r] = ok2 ? p1[r] : -1e30f;
;     }
;   }
; template <int NCB, int D0> __device__ __forceinline__ void pv_one(f32x16& od, int vb, bf16x8 pa0, bf16x8 pa1, bf16x8 pa2, bf16x8 pa3) {
;   constexpr int KSTEP = NCB * 1024, HALF = NCB * 512, B0 = D0 * 512;
;   const s16x4 l0 = tr_read<B0>(vb), h0 = tr_read<B0 + HALF>(vb), l1 = tr_read<B0 + KSTEP>(vb), h1 = tr_read<B0 + KSTEP + HALF>(vb);
;   const s16x4 l2 = tr_read<B0 + 2 * KSTEP>(vb), h2 = tr_read<B0 + 2 * KSTEP + HALF>(vb), l3 = tr_read<B0 + 3 * KSTEP>(vb), h3 = tr_read<B0 + 3 * KSTEP + HALF>(vb);
;   WAIT_L0(); SBAR();
;     ...
;   od = __builtin_amdgcn_mfma_f32_32x32x16_bf16(pa0, PK(l0, h0), od, 0, 0, 0);
;   od = __builtin_amdgcn_mfma_f32_32x32x16_bf16(pa1, PK(l1, h1), od, 0, 0, 0);
;   od = __builtin_amdgcn_mfma_f32_32x32x16_bf16(pa2, PK(l2, h2), od, 0, 0, 0);
;   od = __builtin_amdgcn_mfma_f32_32x32x16_bf16(pa3, PK(l3, h3), od, 0, 0, 0);
;     ...
; }
	v_mfma_f32_32x32x16_bf16 v[80:95], v[114:117], v[118:121], v[80:95]
	ds_read_b128 v[114:117], v157 offset:12544
	s_waitcnt lgkmcnt(0)
	v_mfma_f32_32x32x16_bf16 v[64:79], v[114:117], v[118:121], v[64:79]
	ds_read_b64_tr_b16 v[114:115], v151 offset:0
	ds_read_b64_tr_b16 v[116:117], v151 offset:0x800
	ds_read_b64_tr_b16 v[118:119], v151 offset:0x1000
	ds_read_b64_tr_b16 v[120:121], v151 offset:0x1800
	ds_read_b64_tr_b16 v[122:123], v151 offset:0x2000
	ds_read_b64_tr_b16 v[124:125], v151 offset:0x2800
	ds_read_b64_tr_b16 v[130:131], v151 offset:0x3000
	ds_read_b64_tr_b16 v[132:133], v151 offset:0x3800
	s_nop 0
	s_waitcnt lgkmcnt(6)
	v_mfma_f32_32x32x16_bf16 v[0:15], v[96:99], v[114:117], v[0:15]
	ds_read_b64_tr_b16 v[114:115], v151 offset:0x200
	ds_read_b64_tr_b16 v[116:117], v151 offset:0xa00
	s_waitcnt lgkmcnt(6)
	v_mfma_f32_32x32x16_bf16 v[0:15], v[100:103], v[118:121], v[0:15]
	ds_read_b64_tr_b16 v[118:119], v151 offset:0x1200
	ds_read_b64_tr_b16 v[120:121], v151 offset:0x1a00
	s_waitcnt lgkmcnt(6)
	v_mfma_f32_32x32x16_bf16 v[0:15], v[104:107], v[122:125], v[0:15]
	ds_read_b64_tr_b16 v[122:123], v151 offset:0x2200
	ds_read_b64_tr_b16 v[124:125], v151 offset:0x2a00
	s_waitcnt lgkmcnt(6)
	v_mfma_f32_32x32x16_bf16 v[0:15], v[108:111], v[130:133], v[0:15]
	ds_read_b64_tr_b16 v[130:131], v151 offset:0x3200
	ds_read_b64_tr_b16 v[132:133], v151 offset:0x3a00
	s_waitcnt lgkmcnt(6)
	v_mfma_f32_32x32x16_bf16 v[16:31], v[96:99], v[114:117], v[16:31]
	ds_read_b64_tr_b16 v[114:115], v151 offset:0x400
	ds_read_b64_tr_b16 v[116:117], v151 offset:0xc00
	s_waitcnt lgkmcnt(6)
	v_mfma_f32_32x32x16_bf16 v[16:31], v[100:103], v[118:121], v[16:31]
	ds_read_b64_tr_b16 v[118:119], v151 offset:0x1400
	ds_read_b64_tr_b16 v[120:121], v151 offset:0x1c00
	s_waitcnt lgkmcnt(6)
	v_mfma_f32_32x32x16_bf16 v[16:31], v[104:107], v[122:125], v[16:31]
	ds_read_b64_tr_b16 v[122:123], v151 offset:0x2400
	ds_read_b64_tr_b16 v[124:125], v151 offset:0x2c00
	s_waitcnt lgkmcnt(6)
	v_mfma_f32_32x32x16_bf16 v[16:31], v[108:111], v[130:133], v[16:31]
	ds_read_b64_tr_b16 v[130:131], v151 offset:0x3400
	ds_read_b64_tr_b16 v[132:133], v151 offset:0x3c00
	s_waitcnt lgkmcnt(6)
	v_mfma_f32_32x32x16_bf16 v[32:47], v[96:99], v[114:117], v[32:47]
	ds_read_b64_tr_b16 v[114:115], v151 offset:0x600
	ds_read_b64_tr_b16 v[116:117], v151 offset:0xe00
	s_waitcnt lgkmcnt(6)
	v_mfma_f32_32x32x16_bf16 v[32:47], v[100:103], v[118:121], v[32:47]
	ds_read_b64_tr_b16 v[118:119], v151 offset:0x1600
	ds_read_b64_tr_b16 v[120:121], v151 offset:0x1e00
	s_waitcnt lgkmcnt(6)
	v_mfma_f32_32x32x16_bf16 v[32:47], v[104:107], v[122:125], v[32:47]
	ds_read_b64_tr_b16 v[122:123], v151 offset:0x2600
	ds_read_b64_tr_b16 v[124:125], v151 offset:0x2e00
	s_waitcnt lgkmcnt(6)
	v_mfma_f32_32x32x16_bf16 v[32:47], v[108:111], v[130:133], v[32:47]
	ds_read_b64_tr_b16 v[130:131], v151 offset:0x3600
	ds_read_b64_tr_b16 v[132:133], v151 offset:0x3e00
	s_waitcnt lgkmcnt(6)
	v_mfma_f32_32x32x16_bf16 v[48:63], v[96:99], v[114:117], v[48:63]
	s_lshl_b32 s3, s3, 6
	s_cmp_le_i32 s3, s59
	s_waitcnt lgkmcnt(4)
	v_mfma_f32_32x32x16_bf16 v[48:63], v[100:103], v[118:121], v[48:63]
	s_waitcnt lgkmcnt(2)
	v_mfma_f32_32x32x16_bf16 v[48:63], v[104:107], v[122:125], v[48:63]
	s_waitcnt lgkmcnt(0)
	v_mfma_f32_32x32x16_bf16 v[48:63], v[108:111], v[130:133], v[48:63]
	s_cbranch_scc1 .LBB0_384
	v_or_b32_e32 v96, s3, v154
	v_mov_b32_e32 v97, v96
	s_nop 0
	v_cmp_gt_i32_e32 vcc, s94, v97
	v_add_u32_e32 v97, 32, v97
	s_nop 0
	v_cndmask_b32_e32 v80, v233, v80, vcc
	v_cmp_gt_i32_e32 vcc, s94, v97
	v_or_b32_e32 v97, 1, v96
	s_nop 0
	v_cndmask_b32_e32 v64, v233, v64, vcc
	v_cmp_gt_i32_e32 vcc, s94, v97
	v_add_u32_e32 v97, 32, v97
	s_nop 0
	v_cndmask_b32_e32 v81, v233, v81, vcc
	v_cmp_gt_i32_e32 vcc, s94, v97
	v_or_b32_e32 v97, 2, v96
	s_nop 0
	v_cndmask_b32_e32 v65, v233, v65, vcc
	v_cmp_gt_i32_e32 vcc, s94, v97
	v_add_u32_e32 v97, 32, v97
	s_nop 0
	v_cndmask_b32_e32 v82, v233, v82, vcc
	v_cmp_gt_i32_e32 vcc, s94, v97
	v_or_b32_e32 v97, 3, v96
	s_nop 0
	v_cndmask_b32_e32 v66, v233, v66, vcc
	v_cmp_gt_i32_e32 vcc, s94, v97
	v_add_u32_e32 v97, 32, v97
	s_nop 0
	v_cndmask_b32_e32 v83, v233, v83, vcc
	v_cmp_gt_i32_e32 vcc, s94, v97
	v_or_b32_e32 v97, 8, v96
	s_nop 0
	v_cndmask_b32_e32 v67, v233, v67, vcc
	v_cmp_gt_i32_e32 vcc, s94, v97
	v_add_u32_e32 v97, 32, v97
	s_nop 0
	v_cndmask_b32_e32 v84, v233, v84, vcc
	v_cmp_gt_i32_e32 vcc, s94, v97
	v_or_b32_e32 v97, 9, v96
	s_nop 0
	v_cndmask_b32_e32 v68, v233, v68, vcc
	v_cmp_gt_i32_e32 vcc, s94, v97
	v_add_u32_e32 v97, 32, v97
	s_nop 0
	v_cndmask_b32_e32 v85, v233, v85, vcc
	v_cmp_gt_i32_e32 vcc, s94, v97
	v_or_b32_e32 v97, 10, v96
	s_nop 0
	v_cndmask_b32_e32 v69, v233, v69, vcc
	v_cmp_gt_i32_e32 vcc, s94, v97
	v_add_u32_e32 v97, 32, v97
	s_nop 0
	v_cndmask_b32_e32 v86, v233, v86, vcc
	v_cmp_gt_i32_e32 vcc, s94, v97
	v_or_b32_e32 v97, 11, v96
	s_nop 0
	v_cndmask_b32_e32 v70, v233, v70, vcc
	v_cmp_gt_i32_e32 vcc, s94, v97
	v_add_u32_e32 v97, 32, v97
	s_nop 0
	v_cndmask_b32_e32 v87, v233, v87, vcc
	v_cmp_gt_i32_e32 vcc, s94, v97
	v_or_b32_e32 v97, 16, v96
	s_nop 0
	v_cndmask_b32_e32 v71, v233, v71, vcc
	v_cmp_gt_i32_e32 vcc, s94, v97
	v_add_u32_e32 v97, 32, v97
	s_nop 0
	v_cndmask_b32_e32 v88, v233, v88, vcc
	v_cmp_gt_i32_e32 vcc, s94, v97
	v_or_b32_e32 v97, 17, v96
	s_nop 0
	v_cndmask_b32_e32 v72, v233, v72, vcc
	v_cmp_gt_i32_e32 vcc, s94, v97
	v_add_u32_e32 v97, 32, v97
	s_nop 0
	v_cndmask_b32_e32 v89, v233, v89, vcc
	v_cmp_gt_i32_e32 vcc, s94, v97
	v_or_b32_e32 v97, 18, v96
	s_nop 0
	v_cndmask_b32_e32 v73, v233, v73, vcc
	v_cmp_gt_i32_e32 vcc, s94, v97
	v_add_u32_e32 v97, 32, v97
	s_nop 0
	v_cndmask_b32_e32 v90, v233, v90, vcc
	v_cmp_gt_i32_e32 vcc, s94, v97
	v_or_b32_e32 v97, 19, v96
	s_nop 0
	v_cndmask_b32_e32 v74, v233, v74, vcc
	v_cmp_gt_i32_e32 vcc, s94, v97
	v_add_u32_e32 v97, 32, v97
	s_nop 0
	v_cndmask_b32_e32 v91, v233, v91, vcc
	v_cmp_gt_i32_e32 vcc, s94, v97
	v_or_b32_e32 v97, 24, v96
	s_nop 0
	v_cndmask_b32_e32 v75, v233, v75, vcc
	v_cmp_gt_i32_e32 vcc, s94, v97
	v_add_u32_e32 v97, 32, v97
	s_nop 0
	v_cndmask_b32_e32 v92, v233, v92, vcc
	v_cmp_gt_i32_e32 vcc, s94, v97
	v_or_b32_e32 v97, 25, v96
	s_nop 0
	v_cndmask_b32_e32 v76, v233, v76, vcc
	v_cmp_gt_i32_e32 vcc, s94, v97
	v_add_u32_e32 v97, 32, v97
	s_nop 0
	v_cndmask_b32_e32 v93, v233, v93, vcc
	v_cmp_gt_i32_e32 vcc, s94, v97
	v_or_b32_e32 v97, 26, v96
	v_or_b32_e32 v96, 27, v96
	v_cndmask_b32_e32 v77, v233, v77, vcc
	v_cmp_gt_i32_e32 vcc, s94, v97
	v_add_u32_e32 v97, 32, v97
	s_nop 0
	v_cndmask_b32_e32 v94, v233, v94, vcc
	v_cmp_gt_i32_e32 vcc, s94, v97
	s_nop 1
	v_cndmask_b32_e32 v78, v233, v78, vcc
	v_cmp_gt_i32_e32 vcc, s94, v96
	v_add_u32_e32 v96, 32, v96
	s_nop 0
	v_cndmask_b32_e32 v95, v233, v95, vcc
	v_cmp_gt_i32_e32 vcc, s94, v96
	s_nop 1
	v_cndmask_b32_e32 v79, v233, v79, vcc
; #define WAIT_L0() asm volatile("s_waitcnt lgkmcnt(0)" ::: "memory")
; #define SBAR() __builtin_amdgcn_sched_barrier(0)
; __device__ __forceinline__ void finishSM(f32x16& p0, f32x16& p1, float& l_reg, bf16x8& pa0, bf16x8& pa1, bf16x8& pa2, bf16x8& pa3) {
; #pragma unroll
;   for (int r = 0; r < 16; ++r) p1[r] = __builtin_amdgcn_exp2f(p1[r]);
;   float ps = 0;
; #pragma unroll
;   for (int r = 0; r < 16; ++r) ps += p0[r];
; #pragma unroll
;   for (int r = 0; r < 16; ++r) ps += p1[r];
;   { auto rr = __builtin_amdgcn_permlane32_swap(__float_as_uint(ps), __float_as_uint(ps), false, false);
;     ps = __uint_as_float(rr[0]) + __uint_as_float(rr[1]); }
;   l_reg += ps;
;     ...
;   PK4(p0, 0, pa0); PK4(p0, 8, pa1); PK4(p1, 0, pa2); PK4(p1, 8, pa3);
;     ...
; }
; template <int NCB, int D0> __device__ __forceinline__ void pv_one(f32x16& od, int vb, bf16x8 pa0, bf16x8 pa1, bf16x8 pa2, bf16x8 pa3) {
;   constexpr int KSTEP = NCB * 1024, HALF = NCB * 512, B0 = D0 * 512;
;   const s16x4 l0 = tr_read<B0>(vb), h0 = tr_read<B0 + HALF>(vb), l1 = tr_read<B0 + KSTEP>(vb), h1 = tr_read<B0 + KSTEP + HALF>(vb);
;   const s16x4 l2 = tr_read<B0 + 2 * KSTEP>(vb), h2 = tr_read<B0 + 2 * KSTEP + HALF>(vb), l3 = tr_read<B0 + 3 * KSTEP>(vb), h3 = tr_read<B0 + 3 * KSTEP + HALF>(vb);
;   WAIT_L0(); SBAR();
;     ...
;   od = __builtin_amdgcn_mfma_f32_32x32x16_bf16(pa0, PK(l0, h0), od, 0, 0, 0);
;   od = __builtin_amdgcn_mfma_f32_32x32x16_bf16(pa1, PK(l1, h1), od, 0, 0, 0);
;   od = __builtin_amdgcn_mfma_f32_32x32x16_bf16(pa2, PK(l2, h2), od, 0, 0, 0);
;   od = __builtin_amdgcn_mfma_f32_32x32x16_bf16(pa3, PK(l3, h3), od, 0, 0, 0);
;     ...
; }
.LBB0_384:
	v_exp_f32_e32 v80, v80
	v_exp_f32_e32 v81, v81
	v_exp_f32_e32 v82, v82
	v_exp_f32_e32 v83, v83
	v_exp_f32_e32 v84, v84
	v_exp_f32_e32 v97, v64
	v_add_f32_e32 v64, 0, v80
	v_exp_f32_e32 v85, v85
	v_add_f32_e32 v64, v81, v64
	v_exp_f32_e32 v86, v86
	v_add_f32_e32 v64, v82, v64
	v_exp_f32_e32 v87, v87
	v_add_f32_e32 v64, v83, v64
	v_exp_f32_e32 v88, v88
	v_add_f32_e32 v64, v84, v64
	v_exp_f32_e32 v89, v89
	v_add_f32_e32 v64, v85, v64
	v_exp_f32_e32 v90, v90
	v_add_f32_e32 v64, v86, v64
	v_exp_f32_e32 v91, v91
	v_add_f32_e32 v64, v87, v64
	v_exp_f32_e32 v92, v92
	v_add_f32_e32 v64, v88, v64
	v_exp_f32_e32 v93, v93
	v_add_f32_e32 v64, v89, v64
	v_exp_f32_e32 v94, v94
	v_add_f32_e32 v64, v90, v64
	v_exp_f32_e32 v95, v95
	v_add_f32_e32 v64, v91, v64
	v_add_f32_e32 v64, v92, v64
	v_exp_f32_e32 v98, v65
	v_add_f32_e32 v64, v93, v64
	v_exp_f32_e32 v99, v66
	v_add_f32_e32 v64, v94, v64
	v_exp_f32_e32 v100, v67
	v_add_f32_e32 v64, v95, v64
	v_exp_f32_e32 v101, v68
	v_add_f32_e32 v64, v97, v64
	v_exp_f32_e32 v102, v69
	v_add_f32_e32 v64, v98, v64
	v_exp_f32_e32 v103, v70
	v_add_f32_e32 v64, v99, v64
	v_exp_f32_e32 v104, v71
	v_add_f32_e32 v64, v100, v64
	v_exp_f32_e32 v105, v72
	v_add_f32_e32 v64, v101, v64
	v_exp_f32_e32 v106, v73
	v_add_f32_e32 v64, v102, v64
	v_exp_f32_e32 v107, v74
	v_add_f32_e32 v64, v103, v64
	v_exp_f32_e32 v108, v75
	v_add_f32_e32 v64, v104, v64
	v_exp_f32_e32 v109, v76
	v_add_f32_e32 v64, v105, v64
	v_exp_f32_e32 v110, v77
	v_add_f32_e32 v64, v106, v64
	v_exp_f32_e32 v111, v78
	v_add_f32_e32 v64, v107, v64
	v_exp_f32_e32 v79, v79
	v_add_f32_e32 v64, v108, v64
	v_add_f32_e32 v64, v109, v64
	v_add_f32_e32 v64, v110, v64
	v_add_f32_e32 v64, v111, v64
	v_add_f32_e32 v64, v79, v64
	v_mov_b32_e32 v65, v64
	v_add_f32_e32 v96, v112, v113
	s_nop 0
	v_permlane32_swap_b32_e32 v64, v65
	v_add_f32_e32 v96, v150, v96
	v_add_f32_e32 v64, v64, v65
	v_add_f32_e32 v161, v96, v64
	v_cvt_pk_bf16_f32 v64, v80, v81
	v_cvt_pk_bf16_f32 v65, v82, v83
	v_cvt_pk_bf16_f32 v66, v84, v85
	v_cvt_pk_bf16_f32 v67, v86, v87
	v_cvt_pk_bf16_f32 v68, v88, v89
	v_cvt_pk_bf16_f32 v69, v90, v91
	v_cvt_pk_bf16_f32 v70, v92, v93
	v_cvt_pk_bf16_f32 v71, v94, v95
	v_cvt_pk_bf16_f32 v72, v97, v98
	v_cvt_pk_bf16_f32 v73, v99, v100
	v_cvt_pk_bf16_f32 v74, v101, v102
	v_cvt_pk_bf16_f32 v75, v103, v104
	v_cvt_pk_bf16_f32 v76, v105, v106
	v_cvt_pk_bf16_f32 v77, v107, v108
	v_cvt_pk_bf16_f32 v78, v109, v110
	v_cvt_pk_bf16_f32 v79, v111, v79
	s_nop 0
	v_permlane32_swap_b32_e32 v64, v66
	v_permlane32_swap_b32_e32 v65, v67
	v_permlane32_swap_b32_e32 v68, v70
	v_permlane32_swap_b32_e32 v69, v71
	v_permlane32_swap_b32_e32 v72, v74
	v_permlane32_swap_b32_e32 v73, v75
	v_permlane32_swap_b32_e32 v76, v78
	v_permlane32_swap_b32_e32 v77, v79
	ds_read_b64_tr_b16 v[80:81], v128 offset:0
	ds_read_b64_tr_b16 v[82:83], v128 offset:0x800
	ds_read_b64_tr_b16 v[84:85], v128 offset:0x1000
	ds_read_b64_tr_b16 v[86:87], v128 offset:0x1800
	ds_read_b64_tr_b16 v[88:89], v128 offset:0x2000
	ds_read_b64_tr_b16 v[90:91], v128 offset:0x2800
	ds_read_b64_tr_b16 v[92:93], v128 offset:0x3000
	ds_read_b64_tr_b16 v[94:95], v128 offset:0x3800
	s_nop 0
	s_waitcnt lgkmcnt(6)
	v_mfma_f32_32x32x16_bf16 v[0:15], v[64:67], v[80:83], v[0:15]
	ds_read_b64_tr_b16 v[80:81], v128 offset:0x200
	ds_read_b64_tr_b16 v[82:83], v128 offset:0xa00
	s_waitcnt lgkmcnt(6)
	v_mfma_f32_32x32x16_bf16 v[0:15], v[68:71], v[84:87], v[0:15]
	ds_read_b64_tr_b16 v[84:85], v128 offset:0x1200
	ds_read_b64_tr_b16 v[86:87], v128 offset:0x1a00
	s_waitcnt lgkmcnt(6)
	v_mfma_f32_32x32x16_bf16 v[0:15], v[72:75], v[88:91], v[0:15]
	ds_read_b64_tr_b16 v[88:89], v128 offset:0x2200
	ds_read_b64_tr_b16 v[90:91], v128 offset:0x2a00
	s_waitcnt lgkmcnt(6)
	v_mfma_f32_32x32x16_bf16 v[0:15], v[76:79], v[92:95], v[0:15]
	ds_read_b64_tr_b16 v[92:93], v128 offset:0x3200
	ds_read_b64_tr_b16 v[94:95], v128 offset:0x3a00
	s_waitcnt lgkmcnt(6)
	v_mfma_f32_32x32x16_bf16 v[16:31], v[64:67], v[80:83], v[16:31]
	ds_read_b64_tr_b16 v[80:81], v128 offset:0x400
	ds_read_b64_tr_b16 v[82:83], v128 offset:0xc00
	s_waitcnt lgkmcnt(6)
	v_mfma_f32_32x32x16_bf16 v[16:31], v[68:71], v[84:87], v[16:31]
	ds_read_b64_tr_b16 v[84:85], v128 offset:0x1400
	ds_read_b64_tr_b16 v[86:87], v128 offset:0x1c00
	s_waitcnt lgkmcnt(6)
	v_mfma_f32_32x32x16_bf16 v[16:31], v[72:75], v[88:91], v[16:31]
	ds_read_b64_tr_b16 v[88:89], v128 offset:0x2400
	ds_read_b64_tr_b16 v[90:91], v128 offset:0x2c00
	s_waitcnt lgkmcnt(6)
	v_mfma_f32_32x32x16_bf16 v[16:31], v[76:79], v[92:95], v[16:31]
	ds_read_b64_tr_b16 v[92:93], v128 offset:0x3400
	ds_read_b64_tr_b16 v[94:95], v128 offset:0x3c00
	s_waitcnt lgkmcnt(6)
	v_mfma_f32_32x32x16_bf16 v[32:47], v[64:67], v[80:83], v[32:47]
	ds_read_b64_tr_b16 v[80:81], v128 offset:0x600
	ds_read_b64_tr_b16 v[82:83], v128 offset:0xe00
	s_waitcnt lgkmcnt(6)
	v_mfma_f32_32x32x16_bf16 v[32:47], v[68:71], v[84:87], v[32:47]
	ds_read_b64_tr_b16 v[84:85], v128 offset:0x1600
	ds_read_b64_tr_b16 v[86:87], v128 offset:0x1e00
	s_waitcnt lgkmcnt(6)
	v_mfma_f32_32x32x16_bf16 v[32:47], v[72:75], v[88:91], v[32:47]
	ds_read_b64_tr_b16 v[88:89], v128 offset:0x2600
	ds_read_b64_tr_b16 v[90:91], v128 offset:0x2e00
	s_waitcnt lgkmcnt(6)
	v_mfma_f32_32x32x16_bf16 v[32:47], v[76:79], v[92:95], v[32:47]
	ds_read_b64_tr_b16 v[92:93], v128 offset:0x3600
	ds_read_b64_tr_b16 v[94:95], v128 offset:0x3e00
	s_waitcnt lgkmcnt(6)
	v_mfma_f32_32x32x16_bf16 v[48:63], v[64:67], v[80:83], v[48:63]
	s_nop 10
	v_mov_b64_e32 v[110:111], v[46:47]
	v_mov_b64_e32 v[108:109], v[44:45]
	v_mov_b64_e32 v[106:107], v[42:43]
	v_mov_b64_e32 v[104:105], v[40:41]
	v_mov_b64_e32 v[102:103], v[38:39]
	v_mov_b64_e32 v[100:101], v[36:37]
	v_mov_b64_e32 v[98:99], v[34:35]
	s_waitcnt lgkmcnt(4)
	v_mfma_f32_32x32x16_bf16 v[48:63], v[68:71], v[84:87], v[48:63]
	v_mov_b64_e32 v[96:97], v[32:33]
	s_waitcnt lgkmcnt(2)
	v_mfma_f32_32x32x16_bf16 v[48:63], v[72:75], v[88:91], v[48:63]
	s_waitcnt lgkmcnt(0)
	v_mfma_f32_32x32x16_bf16 v[48:63], v[76:79], v[92:95], v[48:63]
	v_mov_b64_e32 v[94:95], v[30:31]
	v_mov_b64_e32 v[78:79], v[14:15]
	v_mov_b64_e32 v[92:93], v[28:29]
	v_mov_b64_e32 v[90:91], v[26:27]
	v_mov_b64_e32 v[88:89], v[24:25]
	v_mov_b64_e32 v[86:87], v[22:23]
	v_mov_b64_e32 v[84:85], v[20:21]
	s_nop 4
	v_mov_b64_e32 v[126:127], v[62:63]
	v_mov_b64_e32 v[82:83], v[18:19]
	v_mov_b64_e32 v[80:81], v[16:17]
	v_mov_b64_e32 v[124:125], v[60:61]
	v_mov_b64_e32 v[122:123], v[58:59]
	v_mov_b64_e32 v[120:121], v[56:57]
	v_mov_b64_e32 v[118:119], v[54:55]
	v_mov_b64_e32 v[116:117], v[52:53]
	v_mov_b64_e32 v[114:115], v[50:51]
	v_mov_b64_e32 v[112:113], v[48:49]
	v_mov_b64_e32 v[76:77], v[12:13]
	v_mov_b64_e32 v[74:75], v[10:11]
	v_mov_b64_e32 v[72:73], v[8:9]
	v_mov_b64_e32 v[70:71], v[6:7]
	v_mov_b64_e32 v[68:69], v[4:5]
	v_mov_b64_e32 v[66:67], v[2:3]
	v_mov_b64_e32 v[64:65], v[0:1]

; __device__ __forceinline__ void finishSM(f32x16& p0, f32x16& p1, float& l_reg, bf16x8& pa0, bf16x8& pa1, bf16x8& pa2, bf16x8& pa3) {
; #pragma unroll
;   for (int r = 0; r < 16; ++r) p1[r] = __builtin_amdgcn_exp2f(p1[r]);
;   float ps = 0;
; #pragma unroll
;   for (int r = 0; r < 16; ++r) ps += p0[r];
; #pragma unroll
;   for (int r = 0; r < 16; ++r) ps += p1[r];
;   { auto rr = __builtin_amdgcn_permlane32_swap(__float_as_uint(ps), __float_as_uint(ps), false, false);
;     ps = __uint_as_float(rr[0]) + __uint_as_float(rr[1]); }
;   l_reg += ps;
;     ...
;   PK4(p0, 0, pa0); PK4(p0, 8, pa1); PK4(p1, 0, pa2); PK4(p1, 8, pa3);
;     ...
; }
; template <int DQK, int QL>
; __device__ __forceinline__ void qkt(f32x16& p0, f32x16& p1, const char* Ks, const bf16x8 (&qr)[DQK / 16 - QL], const char* qlds, const int (&kofs)[4], float negM) {
;   constexpr int QR = DQK / 16 - QL;
; #pragma unroll
;   for (int r = 0; r < 16; ++r) { p0[r] = negM; p1[r] = negM; }
; #pragma unroll
;   for (int d0 = 0; d0 < DQK / 16; ++d0) {
;     const char* kp = Ks + kofs[d0 & 3] + (d0 >> 2) * 128;
;     bf16x8 b0 = *reinterpret_cast<const bf16x8*>(kp);
;     bf16x8 b1 = *reinterpret_cast<const bf16x8*>(kp + 32 * DQK * 2);
;     bf16x8 qf;
;     if constexpr (QL > 0) { if (d0 < QR) qf = qr[d0 < QR ? d0 : 0]; else qf = *reinterpret_cast<const bf16x8*>(qlds + (d0 - QR) * 1024); }
;     else qf = qr[d0];
;     p0 = __builtin_amdgcn_mfma_f32_32x32x16_bf16(b0, qf, p0, 0, 0, 0);
;     p1 = __builtin_amdgcn_mfma_f32_32x32x16_bf16(b1, qf, p1, 0, 0, 0);
;   }
; }
; template <int NCB> __device__ __forceinline__ int v_st(int k, int c) {
;   const int kk = (k & ~0xC) | ((k & 4) << 1) | ((k & 8) >> 1);
;   return ((kk >> 3) * NCB + (c >> 5)) * 512 + ((kk & 7) * 32 + (c & 31)) * 2;
; }
; __device__ __forceinline__ int v_rd_base(int lane) { return ((lane & 3) << 3) | (((lane >> 2) & 3) << 6) | (((lane >> 4) & 1) << 5) | (((lane >> 5) & 1) << 8); }
; template <int OFF> __device__ __forceinline__ s16x4 tr_read(int vb) {
;   s16x4 r; asm volatile("ds_read_b64_tr_b16 %0, %1 offset:%2" : "=&v"(r) : "v"(vb), "i"(OFF) : "memory"); return r;
; }
; template <int NCB, int D0> __device__ __forceinline__ void pv_one(f32x16& od, int vb, bf16x8 pa0, bf16x8 pa1, bf16x8 pa2, bf16x8 pa3) {
;   constexpr int KSTEP = NCB * 1024, HALF = NCB * 512, B0 = D0 * 512;
.LBB0_398:
	ds_read_b128 v[96:99], v169 offset:40960
	s_waitcnt vmcnt(0)
	ds_read_b128 v[154:157], v169 offset:45056
	v_mov_b64_e32 v[126:127], s[18:19]
	v_mov_b64_e32 v[124:125], s[16:17]
	v_mov_b64_e32 v[122:123], s[14:15]
	v_mov_b64_e32 v[120:121], s[12:13]
	v_mov_b64_e32 v[118:119], s[10:11]
	v_mov_b64_e32 v[116:117], s[8:9]
	v_mov_b64_e32 v[114:115], s[6:7]
	v_mov_b64_e32 v[112:113], s[4:5]
	v_exp_f32_e32 v100, v68
	v_exp_f32_e32 v101, v69
	s_waitcnt lgkmcnt(1)
	v_mfma_f32_32x32x16_bf16 v[80:95], v[96:99], v[142:145], v[112:127]
	ds_read_b128 v[96:99], v168 offset:40960
	ds_read_b128 v[178:181], v168 offset:45056
	v_exp_f32_e32 v102, v70
	v_exp_f32_e32 v103, v71
	v_exp_f32_e32 v190, v72
	v_exp_f32_e32 v191, v73
	v_exp_f32_e32 v192, v74
	v_exp_f32_e32 v193, v75
	s_waitcnt lgkmcnt(1)
	v_mfma_f32_32x32x16_bf16 v[80:95], v[96:99], v[138:141], v[80:95]
	ds_read_b128 v[96:99], v167 offset:40960
	ds_read_b128 v[182:185], v167 offset:45056
	v_exp_f32_e32 v194, v76
	v_exp_f32_e32 v195, v77
	v_exp_f32_e32 v196, v78
	v_exp_f32_e32 v79, v79
	s_waitcnt lgkmcnt(1)
	v_mfma_f32_32x32x16_bf16 v[80:95], v[96:99], v[134:137], v[80:95]
	ds_read_b128 v[96:99], v166 offset:40960
	ds_read_b128 v[186:189], v166 offset:45056
	s_waitcnt lgkmcnt(1)
	v_mfma_f32_32x32x16_bf16 v[80:95], v[96:99], v[130:133], v[80:95]
	v_exp_f32_e32 v96, v64
	v_add_f32_e32 v64, 0, v152
	v_add_f32_e32 v64, v153, v64
	v_add_f32_e32 v64, v150, v64
	v_add_f32_e32 v64, v151, v64
	v_add_f32_e32 v64, v148, v64
	v_add_f32_e32 v64, v149, v64
	v_add_f32_e32 v64, v146, v64
	v_add_f32_e32 v64, v147, v64
	v_add_f32_e32 v64, v110, v64
	v_add_f32_e32 v64, v111, v64
	v_add_f32_e32 v64, v108, v64
	v_add_f32_e32 v64, v109, v64
	v_add_f32_e32 v64, v106, v64
	v_exp_f32_e32 v97, v65
	v_add_f32_e32 v64, v107, v64
	v_exp_f32_e32 v98, v66
	v_add_f32_e32 v64, v104, v64
	v_exp_f32_e32 v99, v67
	v_add_f32_e32 v64, v105, v64
	v_add_f32_e32 v64, v96, v64
	v_add_f32_e32 v64, v97, v64
	v_add_f32_e32 v64, v98, v64
	v_add_f32_e32 v64, v99, v64
	v_add_f32_e32 v64, v100, v64
	v_add_f32_e32 v64, v101, v64
	v_add_f32_e32 v64, v102, v64
	v_add_f32_e32 v64, v103, v64
	v_add_f32_e32 v64, v190, v64
	v_add_f32_e32 v64, v191, v64
	v_add_f32_e32 v64, v192, v64
	v_add_f32_e32 v64, v193, v64
	v_add_f32_e32 v64, v194, v64
	v_add_f32_e32 v64, v195, v64
	v_add_f32_e32 v64, v196, v64
	v_add_f32_e32 v176, v79, v64
	v_mov_b32_e32 v177, v176
	s_nop 1
	v_permlane32_swap_b32_e32 v176, v177
	v_cvt_pk_bf16_f32 v64, v152, v153
	v_cvt_pk_bf16_f32 v65, v150, v151
	v_cvt_pk_bf16_f32 v66, v148, v149
	v_cvt_pk_bf16_f32 v67, v146, v147
	v_cvt_pk_bf16_f32 v68, v110, v111
	v_cvt_pk_bf16_f32 v69, v108, v109
	v_cvt_pk_bf16_f32 v70, v106, v107
	v_cvt_pk_bf16_f32 v71, v104, v105
	v_cvt_pk_bf16_f32 v72, v96, v97
	v_cvt_pk_bf16_f32 v73, v98, v99
	v_cvt_pk_bf16_f32 v74, v100, v101
	v_cvt_pk_bf16_f32 v75, v102, v103
	v_cvt_pk_bf16_f32 v76, v190, v191
	v_cvt_pk_bf16_f32 v77, v192, v193
	v_cvt_pk_bf16_f32 v78, v194, v195
	v_cvt_pk_bf16_f32 v79, v196, v79
	s_nop 0
	v_permlane32_swap_b32_e32 v64, v66
	v_permlane32_swap_b32_e32 v65, v67
	v_permlane32_swap_b32_e32 v68, v70
	v_permlane32_swap_b32_e32 v69, v71
	v_permlane32_swap_b32_e32 v72, v74
	v_permlane32_swap_b32_e32 v73, v75
	v_permlane32_swap_b32_e32 v76, v78
	v_permlane32_swap_b32_e32 v77, v79
	s_add_i32 s68, s69, 0x80
	v_mfma_f32_32x32x16_bf16 v[96:111], v[154:157], v[142:145], v[112:127]
	s_mul_i32 s39, s68, 0xc00
	s_mul_hi_i32 s38, s68, 0xc00
	s_nop 4
	v_mad_i64_i32 v[112:113], s[20:21], s68, v236, v[162:163]
	s_add_u32 s20, s3, s39
	s_addc_u32 s21, s36, s38
	v_lshl_add_u64 v[116:117], v[160:161], 1, s[20:21]
	v_lshl_add_u64 v[114:115], v[158:159], 1, s[20:21]
	global_load_dwordx4 v[146:149], v[112:113], off offset:1024
	global_load_dwordx4 v[150:153], v[114:115], off offset:2048
	global_load_dwordx4 v[154:157], v[116:117], off offset:2048
	v_mfma_f32_32x32x16_bf16 v[96:111], v[178:181], v[138:141], v[96:111]
	v_mfma_f32_32x32x16_bf16 v[96:111], v[182:185], v[134:137], v[96:111]
	s_waitcnt lgkmcnt(0)
	v_mfma_f32_32x32x16_bf16 v[96:111], v[186:189], v[130:133], v[96:111]
	ds_read_b64_tr_b16 v[112:113], v171 offset:0
	ds_read_b64_tr_b16 v[114:115], v171 offset:0x800
	ds_read_b64_tr_b16 v[116:117], v171 offset:0x1000
	ds_read_b64_tr_b16 v[118:119], v171 offset:0x1800
	ds_read_b64_tr_b16 v[120:121], v171 offset:0x2000
	ds_read_b64_tr_b16 v[122:123], v171 offset:0x2800
	ds_read_b64_tr_b16 v[124:125], v171 offset:0x3000
	ds_read_b64_tr_b16 v[126:127], v171 offset:0x3800
	s_nop 0
	s_waitcnt lgkmcnt(6)
	v_mfma_f32_32x32x16_bf16 v[0:15], v[64:67], v[112:115], v[0:15]
	ds_read_b64_tr_b16 v[112:113], v171 offset:0x200
	ds_read_b64_tr_b16 v[114:115], v171 offset:0xa00
	s_waitcnt lgkmcnt(6)
	v_mfma_f32_32x32x16_bf16 v[0:15], v[68:71], v[116:119], v[0:15]
	ds_read_b64_tr_b16 v[116:117], v171 offset:0x1200
	ds_read_b64_tr_b16 v[118:119], v171 offset:0x1a00
	s_waitcnt lgkmcnt(6)
	v_mfma_f32_32x32x16_bf16 v[0:15], v[72:75], v[120:123], v[0:15]
	ds_read_b64_tr_b16 v[120:121], v171 offset:0x2200
	ds_read_b64_tr_b16 v[122:123], v171 offset:0x2a00
	s_waitcnt lgkmcnt(6)
	v_mfma_f32_32x32x16_bf16 v[0:15], v[76:79], v[124:127], v[0:15]
	ds_read_b64_tr_b16 v[124:125], v171 offset:0x3200
	ds_read_b64_tr_b16 v[126:127], v171 offset:0x3a00
	s_waitcnt lgkmcnt(6)
	v_mfma_f32_32x32x16_bf16 v[48:63], v[64:67], v[112:115], v[48:63]
	ds_read_b64_tr_b16 v[112:113], v171 offset:0x400
	ds_read_b64_tr_b16 v[114:115], v171 offset:0xc00
	s_waitcnt lgkmcnt(6)
; #define WAIT_L0() asm volatile("s_waitcnt lgkmcnt(0)" ::: "memory")
; #define SBAR() __builtin_amdgcn_sched_barrier(0)
; __device__ __forceinline__ int crow(int r, int hi) { return (r & 3) + 8 * (r >> 2) + 4 * hi; }
; template <bool GM>
; __device__ __forceinline__ void partialSM(f32x16& p0, f32x16& p1, bool mask, int kbase, int L, int qpos, int hi) {
;   if (mask) {
; #pragma unroll
;     for (int r = 0; r < 16; ++r) {
;       int k = kbase + crow(r, hi);
;       asm volatile("" : "+v"(k) : "v"(p0[r]));
;       bool ok = k < L;
;       if (GM) ok = ok && (k < 16 || abs(qpos - k) <= 128);
;       p0[r] = ok ? p0[r] : -1e30f;
;       int k2 = k + 32;
;       asm volatile("" : "+v"(k2) : "v"(p1[r]));
;       bool ok2 = k2 < L;
;       if (GM) ok2 = ok2 && (k2 < 16 || abs(qpos - k2) <= 128);
;       p1[r] = ok2 ? p1[r] : -1e30f;
;     }
;   }
; template <int NCB, int D0> __device__ __forceinline__ void pv_one(f32x16& od, int vb, bf16x8 pa0, bf16x8 pa1, bf16x8 pa2, bf16x8 pa3) {
;   constexpr int KSTEP = NCB * 1024, HALF = NCB * 512, B0 = D0 * 512;
;   const s16x4 l0 = tr_read<B0>(vb), h0 = tr_read<B0 + HALF>(vb), l1 = tr_read<B0 + KSTEP>(vb), h1 = tr_read<B0 + KSTEP + HALF>(vb);
;   const s16x4 l2 = tr_read<B0 + 2 * KSTEP>(vb), h2 = tr_read<B0 + 2 * KSTEP + HALF>(vb), l3 = tr_read<B0 + 3 * KSTEP>(vb), h3 = tr_read<B0 + 3 * KSTEP + HALF>(vb);
;   WAIT_L0(); SBAR();
;     ...
;   od = __builtin_amdgcn_mfma_f32_32x32x16_bf16(pa0, PK(l0, h0), od, 0, 0, 0);
;   od = __builtin_amdgcn_mfma_f32_32x32x16_bf16(pa1, PK(l1, h1), od, 0, 0, 0);
;   od = __builtin_amdgcn_mfma_f32_32x32x16_bf16(pa2, PK(l2, h2), od, 0, 0, 0);
;   od = __builtin_amdgcn_mfma_f32_32x32x16_bf16(pa3, PK(l3, h3), od, 0, 0, 0);
;     ...
; }
	v_mfma_f32_32x32x16_bf16 v[48:63], v[68:71], v[116:119], v[48:63]
	ds_read_b64_tr_b16 v[116:117], v171 offset:0x1400
	ds_read_b64_tr_b16 v[118:119], v171 offset:0x1c00
	s_waitcnt lgkmcnt(6)
	v_mfma_f32_32x32x16_bf16 v[48:63], v[72:75], v[120:123], v[48:63]
	ds_read_b64_tr_b16 v[120:121], v171 offset:0x2400
	ds_read_b64_tr_b16 v[122:123], v171 offset:0x2c00
	s_waitcnt lgkmcnt(6)
	v_mfma_f32_32x32x16_bf16 v[48:63], v[76:79], v[124:127], v[48:63]
	ds_read_b64_tr_b16 v[124:125], v171 offset:0x3400
	ds_read_b64_tr_b16 v[126:127], v171 offset:0x3c00
	s_waitcnt lgkmcnt(6)
	v_mfma_f32_32x32x16_bf16 v[32:47], v[64:67], v[112:115], v[32:47]
	ds_read_b64_tr_b16 v[112:113], v171 offset:0x600
	ds_read_b64_tr_b16 v[114:115], v171 offset:0xe00
	s_waitcnt lgkmcnt(6)
	v_mfma_f32_32x32x16_bf16 v[32:47], v[68:71], v[116:119], v[32:47]
	ds_read_b64_tr_b16 v[116:117], v171 offset:0x1600
	ds_read_b64_tr_b16 v[118:119], v171 offset:0x1e00
	s_waitcnt lgkmcnt(6)
	v_mfma_f32_32x32x16_bf16 v[32:47], v[72:75], v[120:123], v[32:47]
	ds_read_b64_tr_b16 v[120:121], v171 offset:0x2600
	ds_read_b64_tr_b16 v[122:123], v171 offset:0x2e00
	s_waitcnt lgkmcnt(6)
	v_mfma_f32_32x32x16_bf16 v[32:47], v[76:79], v[124:127], v[32:47]
	ds_read_b64_tr_b16 v[124:125], v171 offset:0x3600
	ds_read_b64_tr_b16 v[126:127], v171 offset:0x3e00
	s_waitcnt lgkmcnt(6)
	v_mfma_f32_32x32x16_bf16 v[16:31], v[64:67], v[112:115], v[16:31]
	s_add_i32 s20, s69, 64
	s_cmp_le_i32 s20, s59
	v_add_u32_e32 v178, s69, v175
	s_waitcnt lgkmcnt(4)
	v_mfma_f32_32x32x16_bf16 v[16:31], v[68:71], v[116:119], v[16:31]
	s_waitcnt lgkmcnt(2)
	v_mfma_f32_32x32x16_bf16 v[16:31], v[72:75], v[120:123], v[16:31]
	s_waitcnt lgkmcnt(0)
	v_mfma_f32_32x32x16_bf16 v[16:31], v[76:79], v[124:127], v[16:31]
	s_cbranch_scc1 .LBB0_400
	v_add_u32_e32 v64, 64, v178
	s_nop 0
	v_cmp_gt_i32_e32 vcc, s94, v64
	v_add_u32_e32 v64, 32, v64
	s_nop 0
	v_cndmask_b32_e32 v80, v233, v80, vcc
	v_cmp_gt_i32_e32 vcc, s94, v64
	v_add_u32_e32 v64, 0x41, v178
	s_nop 0
	v_cndmask_b32_e32 v96, v233, v96, vcc
	v_cmp_gt_i32_e32 vcc, s94, v64
	v_add_u32_e32 v64, 32, v64
	s_nop 0
	v_cndmask_b32_e32 v81, v233, v81, vcc
	v_cmp_gt_i32_e32 vcc, s94, v64
	v_add_u32_e32 v64, 0x42, v178
	s_nop 0
	v_cndmask_b32_e32 v97, v233, v97, vcc
	v_cmp_gt_i32_e32 vcc, s94, v64
	v_add_u32_e32 v64, 32, v64
	s_nop 0
	v_cndmask_b32_e32 v82, v233, v82, vcc
	v_cmp_gt_i32_e32 vcc, s94, v64
	v_add_u32_e32 v64, 0x43, v178
	s_nop 0
	v_cndmask_b32_e32 v98, v233, v98, vcc
	v_cmp_gt_i32_e32 vcc, s94, v64
	v_add_u32_e32 v64, 32, v64
	s_nop 0
	v_cndmask_b32_e32 v83, v233, v83, vcc
	v_cmp_gt_i32_e32 vcc, s94, v64
	v_add_u32_e32 v64, 0x48, v178
	s_nop 0
	v_cndmask_b32_e32 v99, v233, v99, vcc
	v_cmp_gt_i32_e32 vcc, s94, v64
	v_add_u32_e32 v64, 32, v64
	s_nop 0
	v_cndmask_b32_e32 v84, v233, v84, vcc
	v_cmp_gt_i32_e32 vcc, s94, v64
	v_add_u32_e32 v64, 0x49, v178
	s_nop 0
	v_cndmask_b32_e32 v100, v233, v100, vcc
	v_cmp_gt_i32_e32 vcc, s94, v64
	v_add_u32_e32 v64, 32, v64
	s_nop 0
	v_cndmask_b32_e32 v85, v233, v85, vcc
	v_cmp_gt_i32_e32 vcc, s94, v64
	v_add_u32_e32 v64, 0x4a, v178
	s_nop 0
	v_cndmask_b32_e32 v101, v233, v101, vcc
	v_cmp_gt_i32_e32 vcc, s94, v64
	v_add_u32_e32 v64, 32, v64
	s_nop 0
	v_cndmask_b32_e32 v86, v233, v86, vcc
	v_cmp_gt_i32_e32 vcc, s94, v64
	v_add_u32_e32 v64, 0x4b, v178
	s_nop 0
	v_cndmask_b32_e32 v102, v233, v102, vcc
	v_cmp_gt_i32_e32 vcc, s94, v64
	v_add_u32_e32 v64, 32, v64
	s_nop 0
	v_cndmask_b32_e32 v87, v233, v87, vcc
	v_cmp_gt_i32_e32 vcc, s94, v64
	v_add_u32_e32 v64, 0x50, v178
	s_nop 0
	v_cndmask_b32_e32 v103, v233, v103, vcc
	v_cmp_gt_i32_e32 vcc, s94, v64
	v_add_u32_e32 v64, 32, v64
	s_nop 0
	v_cndmask_b32_e32 v88, v233, v88, vcc
	v_cmp_gt_i32_e32 vcc, s94, v64
	v_add_u32_e32 v64, 0x51, v178
	s_nop 0
	v_cndmask_b32_e32 v104, v233, v104, vcc
	v_cmp_gt_i32_e32 vcc, s94, v64
	v_add_u32_e32 v64, 32, v64
	s_nop 0
	v_cndmask_b32_e32 v89, v233, v89, vcc
	v_cmp_gt_i32_e32 vcc, s94, v64
	v_add_u32_e32 v64, 0x52, v178
	s_nop 0
	v_cndmask_b32_e32 v105, v233, v105, vcc
	v_cmp_gt_i32_e32 vcc, s94, v64
	v_add_u32_e32 v64, 32, v64
	s_nop 0
	v_cndmask_b32_e32 v90, v233, v90, vcc
	v_cmp_gt_i32_e32 vcc, s94, v64
	v_add_u32_e32 v64, 0x53, v178
	s_nop 0
	v_cndmask_b32_e32 v106, v233, v106, vcc
	v_cmp_gt_i32_e32 vcc, s94, v64
	v_add_u32_e32 v64, 32, v64
	s_nop 0
	v_cndmask_b32_e32 v91, v233, v91, vcc
	v_cmp_gt_i32_e32 vcc, s94, v64
	v_add_u32_e32 v64, 0x58, v178
	s_nop 0
	v_cndmask_b32_e32 v107, v233, v107, vcc
	v_cmp_gt_i32_e32 vcc, s94, v64
	v_add_u32_e32 v64, 32, v64
	s_nop 0
	v_cndmask_b32_e32 v92, v233, v92, vcc
	v_cmp_gt_i32_e32 vcc, s94, v64
	v_add_u32_e32 v64, 0x59, v178
	s_nop 0
	v_cndmask_b32_e32 v108, v233, v108, vcc
	v_cmp_gt_i32_e32 vcc, s94, v64
	v_add_u32_e32 v64, 32, v64
	s_nop 0
	v_cndmask_b32_e32 v93, v233, v93, vcc
	v_cmp_gt_i32_e32 vcc, s94, v64
	v_add_u32_e32 v64, 0x5a, v178
	s_nop 0
	v_cndmask_b32_e32 v109, v233, v109, vcc
	v_cmp_gt_i32_e32 vcc, s94, v64
	v_add_u32_e32 v64, 32, v64
	s_nop 0
	v_cndmask_b32_e32 v94, v233, v94, vcc
	v_cmp_gt_i32_e32 vcc, s94, v64
	v_add_u32_e32 v64, 0x5b, v178
	s_nop 0
	v_cndmask_b32_e32 v110, v233, v110, vcc
	v_cmp_gt_i32_e32 vcc, s94, v64
	v_add_u32_e32 v64, 32, v64
	s_nop 0
	v_cndmask_b32_e32 v95, v233, v95, vcc
	v_cmp_gt_i32_e32 vcc, s94, v64
	s_nop 1
	v_cndmask_b32_e32 v111, v233, v111, vcc

; #define WAIT_L0() asm volatile("s_waitcnt lgkmcnt(0)" ::: "memory")
; #define SBAR() __builtin_amdgcn_sched_barrier(0)
; __device__ __forceinline__ int crow(int r, int hi) { return (r & 3) + 8 * (r >> 2) + 4 * hi; }
; template <bool GM>
; __device__ __forceinline__ void partialSM(f32x16& p0, f32x16& p1, bool mask, int kbase, int L, int qpos, int hi) {
;   if (mask) {
; #pragma unroll
;     for (int r = 0; r < 16; ++r) {
;       int k = kbase + crow(r, hi);
;       asm volatile("" : "+v"(k) : "v"(p0[r]));
;       bool ok = k < L;
;       if (GM) ok = ok && (k < 16 || abs(qpos - k) <= 128);
;       p0[r] = ok ? p0[r] : -1e30f;
;       int k2 = k + 32;
;       asm volatile("" : "+v"(k2) : "v"(p1[r]));
;       bool ok2 = k2 < L;
;       if (GM) ok2 = ok2 && (k2 < 16 || abs(qpos - k2) <= 128);
;       p1[r] = ok2 ? p1[r] : -1e30f;
;     }
;   }
; template <int NCB, int D0> __device__ __forceinline__ void pv_one(f32x16& od, int vb, bf16x8 pa0, bf16x8 pa1, bf16x8 pa2, bf16x8 pa3) {
;   constexpr int KSTEP = NCB * 1024, HALF = NCB * 512, B0 = D0 * 512;
;   const s16x4 l0 = tr_read<B0>(vb), h0 = tr_read<B0 + HALF>(vb), l1 = tr_read<B0 + KSTEP>(vb), h1 = tr_read<B0 + KSTEP + HALF>(vb);
;   const s16x4 l2 = tr_read<B0 + 2 * KSTEP>(vb), h2 = tr_read<B0 + 2 * KSTEP + HALF>(vb), l3 = tr_read<B0 + 3 * KSTEP>(vb), h3 = tr_read<B0 + 3 * KSTEP + HALF>(vb);
;   WAIT_L0(); SBAR();
;     ...
;   od = __builtin_amdgcn_mfma_f32_32x32x16_bf16(pa0, PK(l0, h0), od, 0, 0, 0);
;   od = __builtin_amdgcn_mfma_f32_32x32x16_bf16(pa1, PK(l1, h1), od, 0, 0, 0);
;   od = __builtin_amdgcn_mfma_f32_32x32x16_bf16(pa2, PK(l2, h2), od, 0, 0, 0);
;   od = __builtin_amdgcn_mfma_f32_32x32x16_bf16(pa3, PK(l3, h3), od, 0, 0, 0);
;     ...
; }
.LBB0_402:
	ds_read_b64_tr_b16 v[114:115], v165 offset:0
	ds_read_b64_tr_b16 v[116:117], v165 offset:0x800
	ds_read_b64_tr_b16 v[118:119], v165 offset:0x1000
	ds_read_b64_tr_b16 v[120:121], v165 offset:0x1800
	ds_read_b64_tr_b16 v[122:123], v165 offset:0x2000
	ds_read_b64_tr_b16 v[124:125], v165 offset:0x2800
	ds_read_b64_tr_b16 v[180:181], v165 offset:0x3000
	ds_read_b64_tr_b16 v[182:183], v165 offset:0x3800
	s_nop 0
	s_waitcnt lgkmcnt(6)
	v_mfma_f32_32x32x16_bf16 v[0:15], v[96:99], v[114:117], v[0:15]
	ds_read_b64_tr_b16 v[114:115], v165 offset:0x200
	ds_read_b64_tr_b16 v[116:117], v165 offset:0xa00
	s_waitcnt lgkmcnt(6)
	v_mfma_f32_32x32x16_bf16 v[0:15], v[100:103], v[118:121], v[0:15]
	ds_read_b64_tr_b16 v[118:119], v165 offset:0x1200
	ds_read_b64_tr_b16 v[120:121], v165 offset:0x1a00
	s_waitcnt lgkmcnt(6)
	v_mfma_f32_32x32x16_bf16 v[0:15], v[104:107], v[122:125], v[0:15]
	ds_read_b64_tr_b16 v[122:123], v165 offset:0x2200
	ds_read_b64_tr_b16 v[124:125], v165 offset:0x2a00
	s_waitcnt lgkmcnt(6)
	v_mfma_f32_32x32x16_bf16 v[0:15], v[108:111], v[180:183], v[0:15]
	ds_read_b64_tr_b16 v[180:181], v165 offset:0x3200
	ds_read_b64_tr_b16 v[182:183], v165 offset:0x3a00
	s_waitcnt lgkmcnt(6)
	v_mfma_f32_32x32x16_bf16 v[48:63], v[96:99], v[114:117], v[48:63]
	ds_read_b64_tr_b16 v[114:115], v165 offset:0x400
	ds_read_b64_tr_b16 v[116:117], v165 offset:0xc00
	s_waitcnt lgkmcnt(6)
	v_mfma_f32_32x32x16_bf16 v[48:63], v[100:103], v[118:121], v[48:63]
	ds_read_b64_tr_b16 v[118:119], v165 offset:0x1400
	ds_read_b64_tr_b16 v[120:121], v165 offset:0x1c00
	s_waitcnt lgkmcnt(6)
	v_mfma_f32_32x32x16_bf16 v[48:63], v[104:107], v[122:125], v[48:63]
	ds_read_b64_tr_b16 v[122:123], v165 offset:0x2400
	ds_read_b64_tr_b16 v[124:125], v165 offset:0x2c00
	s_waitcnt lgkmcnt(6)
	v_mfma_f32_32x32x16_bf16 v[48:63], v[108:111], v[180:183], v[48:63]
	ds_read_b64_tr_b16 v[180:181], v165 offset:0x3400
	ds_read_b64_tr_b16 v[182:183], v165 offset:0x3c00
	s_waitcnt lgkmcnt(6)
	v_mfma_f32_32x32x16_bf16 v[32:47], v[96:99], v[114:117], v[32:47]
	ds_read_b64_tr_b16 v[114:115], v165 offset:0x600
	ds_read_b64_tr_b16 v[116:117], v165 offset:0xe00
	s_waitcnt lgkmcnt(6)
	v_mfma_f32_32x32x16_bf16 v[32:47], v[100:103], v[118:121], v[32:47]
	ds_read_b64_tr_b16 v[118:119], v165 offset:0x1600
	ds_read_b64_tr_b16 v[120:121], v165 offset:0x1e00
	s_waitcnt lgkmcnt(6)
	v_mfma_f32_32x32x16_bf16 v[32:47], v[104:107], v[122:125], v[32:47]
	ds_read_b64_tr_b16 v[122:123], v165 offset:0x2600
	ds_read_b64_tr_b16 v[124:125], v165 offset:0x2e00
	s_waitcnt lgkmcnt(6)
	v_mfma_f32_32x32x16_bf16 v[32:47], v[108:111], v[180:183], v[32:47]
	ds_read_b64_tr_b16 v[180:181], v165 offset:0x3600
	ds_read_b64_tr_b16 v[182:183], v165 offset:0x3e00
	s_waitcnt lgkmcnt(6)
	v_mfma_f32_32x32x16_bf16 v[16:31], v[96:99], v[114:117], v[16:31]
	s_cmp_le_i32 s68, s59
	s_waitcnt lgkmcnt(4)
	v_mfma_f32_32x32x16_bf16 v[16:31], v[100:103], v[118:121], v[16:31]
	s_waitcnt lgkmcnt(2)
	v_mfma_f32_32x32x16_bf16 v[16:31], v[104:107], v[122:125], v[16:31]
	s_waitcnt lgkmcnt(0)
	v_mfma_f32_32x32x16_bf16 v[16:31], v[108:111], v[180:183], v[16:31]
	s_cbranch_scc1 .LBB0_404
	v_add_u32_e32 v96, 0x80, v178
	s_nop 0
	v_cmp_gt_i32_e32 vcc, s94, v96
	v_add_u32_e32 v96, 32, v96
	s_nop 0
	v_cndmask_b32_e32 v80, v233, v80, vcc
	v_cmp_gt_i32_e32 vcc, s94, v96
	v_add_u32_e32 v96, 0x81, v178
	s_nop 0
	v_cndmask_b32_e32 v64, v233, v64, vcc
	v_cmp_gt_i32_e32 vcc, s94, v96
	v_add_u32_e32 v96, 32, v96
	s_nop 0
	v_cndmask_b32_e32 v81, v233, v81, vcc
	v_cmp_gt_i32_e32 vcc, s94, v96
	v_add_u32_e32 v96, 0x82, v178
	s_nop 0
	v_cndmask_b32_e32 v65, v233, v65, vcc
	v_cmp_gt_i32_e32 vcc, s94, v96
	v_add_u32_e32 v96, 32, v96
	s_nop 0
	v_cndmask_b32_e32 v82, v233, v82, vcc
	v_cmp_gt_i32_e32 vcc, s94, v96
	v_add_u32_e32 v96, 0x83, v178
	s_nop 0
	v_cndmask_b32_e32 v66, v233, v66, vcc
	v_cmp_gt_i32_e32 vcc, s94, v96
	v_add_u32_e32 v96, 32, v96
	s_nop 0
	v_cndmask_b32_e32 v83, v233, v83, vcc
	v_cmp_gt_i32_e32 vcc, s94, v96
	v_add_u32_e32 v96, 0x88, v178
	s_nop 0
	v_cndmask_b32_e32 v67, v233, v67, vcc
	v_cmp_gt_i32_e32 vcc, s94, v96
	v_add_u32_e32 v96, 32, v96
	s_nop 0
	v_cndmask_b32_e32 v84, v233, v84, vcc
	v_cmp_gt_i32_e32 vcc, s94, v96
	v_add_u32_e32 v96, 0x89, v178
	s_nop 0
	v_cndmask_b32_e32 v68, v233, v68, vcc
	v_cmp_gt_i32_e32 vcc, s94, v96
	v_add_u32_e32 v96, 32, v96
	s_nop 0
	v_cndmask_b32_e32 v85, v233, v85, vcc
	v_cmp_gt_i32_e32 vcc, s94, v96
	v_add_u32_e32 v96, 0x8a, v178
	s_nop 0
	v_cndmask_b32_e32 v69, v233, v69, vcc
	v_cmp_gt_i32_e32 vcc, s94, v96
	v_add_u32_e32 v96, 32, v96
	s_nop 0
	v_cndmask_b32_e32 v86, v233, v86, vcc
	v_cmp_gt_i32_e32 vcc, s94, v96
	v_add_u32_e32 v96, 0x8b, v178
	s_nop 0
	v_cndmask_b32_e32 v70, v233, v70, vcc
	v_cmp_gt_i32_e32 vcc, s94, v96
	v_add_u32_e32 v96, 32, v96
	s_nop 0
	v_cndmask_b32_e32 v87, v233, v87, vcc
	v_cmp_gt_i32_e32 vcc, s94, v96
	v_add_u32_e32 v96, 0x90, v178
	s_nop 0
	v_cndmask_b32_e32 v71, v233, v71, vcc
	v_cmp_gt_i32_e32 vcc, s94, v96
	v_add_u32_e32 v96, 32, v96
	s_nop 0
	v_cndmask_b32_e32 v88, v233, v88, vcc
	v_cmp_gt_i32_e32 vcc, s94, v96
	v_add_u32_e32 v96, 0x91, v178
	s_nop 0
	v_cndmask_b32_e32 v72, v233, v72, vcc
	v_cmp_gt_i32_e32 vcc, s94, v96
	v_add_u32_e32 v96, 32, v96
	s_nop 0
	v_cndmask_b32_e32 v89, v233, v89, vcc
	v_cmp_gt_i32_e32 vcc, s94, v96
	v_add_u32_e32 v96, 0x92, v178
	s_nop 0
	v_cndmask_b32_e32 v73, v233, v73, vcc
	v_cmp_gt_i32_e32 vcc, s94, v96
	v_add_u32_e32 v96, 32, v96
	s_nop 0
	v_cndmask_b32_e32 v90, v233, v90, vcc
	v_cmp_gt_i32_e32 vcc, s94, v96
	v_add_u32_e32 v96, 0x93, v178
	s_nop 0
	v_cndmask_b32_e32 v74, v233, v74, vcc
	v_cmp_gt_i32_e32 vcc, s94, v96
	v_add_u32_e32 v96, 32, v96
	s_nop 0
	v_cndmask_b32_e32 v91, v233, v91, vcc
	v_cmp_gt_i32_e32 vcc, s94, v96
	v_add_u32_e32 v96, 0x98, v178
	s_nop 0
	v_cndmask_b32_e32 v75, v233, v75, vcc
	v_cmp_gt_i32_e32 vcc, s94, v96
	v_add_u32_e32 v96, 32, v96
	s_nop 0
	v_cndmask_b32_e32 v92, v233, v92, vcc
	v_cmp_gt_i32_e32 vcc, s94, v96
	v_add_u32_e32 v96, 0x99, v178
	s_nop 0
	v_cndmask_b32_e32 v76, v233, v76, vcc
	v_cmp_gt_i32_e32 vcc, s94, v96
	v_add_u32_e32 v96, 32, v96
	s_nop 0
	v_cndmask_b32_e32 v93, v233, v93, vcc
	v_cmp_gt_i32_e32 vcc, s94, v96
	v_add_u32_e32 v96, 0x9a, v178
	s_nop 0
	v_cndmask_b32_e32 v77, v233, v77, vcc
	v_cmp_gt_i32_e32 vcc, s94, v96
	v_add_u32_e32 v96, 32, v96
	s_nop 0
	v_cndmask_b32_e32 v94, v233, v94, vcc
	v_cmp_gt_i32_e32 vcc, s94, v96
	v_add_u32_e32 v96, 0x9b, v178
	s_nop 0
	v_cndmask_b32_e32 v78, v233, v78, vcc
	v_cmp_gt_i32_e32 vcc, s94, v96
	v_add_u32_e32 v96, 32, v96
	s_nop 0
	v_cndmask_b32_e32 v95, v233, v95, vcc
	v_cmp_gt_i32_e32 vcc, s94, v96
	s_nop 1
	v_cndmask_b32_e32 v79, v233, v79, vcc

; #define WAIT_L0() asm volatile("s_waitcnt lgkmcnt(0)" ::: "memory")
; #define SBAR() __builtin_amdgcn_sched_barrier(0)
; __device__ __forceinline__ void finishSM(f32x16& p0, f32x16& p1, float& l_reg, bf16x8& pa0, bf16x8& pa1, bf16x8& pa2, bf16x8& pa3) {
; #pragma unroll
;   for (int r = 0; r < 16; ++r) p1[r] = __builtin_amdgcn_exp2f(p1[r]);
;   float ps = 0;
; #pragma unroll
;   for (int r = 0; r < 16; ++r) ps += p0[r];
; #pragma unroll
;   for (int r = 0; r < 16; ++r) ps += p1[r];
;   { auto rr = __builtin_amdgcn_permlane32_swap(__float_as_uint(ps), __float_as_uint(ps), false, false);
;     ps = __uint_as_float(rr[0]) + __uint_as_float(rr[1]); }
;   l_reg += ps;
;     ...
;   PK4(p0, 0, pa0); PK4(p0, 8, pa1); PK4(p1, 0, pa2); PK4(p1, 8, pa3);
;     ...
; }
; template <int NCB, int D0> __device__ __forceinline__ void pv_one(f32x16& od, int vb, bf16x8 pa0, bf16x8 pa1, bf16x8 pa2, bf16x8 pa3) {
;   constexpr int KSTEP = NCB * 1024, HALF = NCB * 512, B0 = D0 * 512;
;   const s16x4 l0 = tr_read<B0>(vb), h0 = tr_read<B0 + HALF>(vb), l1 = tr_read<B0 + KSTEP>(vb), h1 = tr_read<B0 + KSTEP + HALF>(vb);
;   const s16x4 l2 = tr_read<B0 + 2 * KSTEP>(vb), h2 = tr_read<B0 + 2 * KSTEP + HALF>(vb), l3 = tr_read<B0 + 3 * KSTEP>(vb), h3 = tr_read<B0 + 3 * KSTEP + HALF>(vb);
;   WAIT_L0(); SBAR();
;     ...
;   od = __builtin_amdgcn_mfma_f32_32x32x16_bf16(pa0, PK(l0, h0), od, 0, 0, 0);
;   od = __builtin_amdgcn_mfma_f32_32x32x16_bf16(pa1, PK(l1, h1), od, 0, 0, 0);
;   od = __builtin_amdgcn_mfma_f32_32x32x16_bf16(pa2, PK(l2, h2), od, 0, 0, 0);
;   od = __builtin_amdgcn_mfma_f32_32x32x16_bf16(pa3, PK(l3, h3), od, 0, 0, 0);
;     ...
; }
.LBB0_409:
	v_exp_f32_e32 v121, v64
	v_exp_f32_e32 v122, v65
	v_exp_f32_e32 v123, v66
	v_exp_f32_e32 v124, v67
	v_exp_f32_e32 v125, v68
	v_exp_f32_e32 v126, v69
	v_exp_f32_e32 v127, v70
	s_waitcnt vmcnt(0)
	v_exp_f32_e32 v154, v71
	v_exp_f32_e32 v113, v72
	v_exp_f32_e32 v114, v73
	v_exp_f32_e32 v115, v74
	v_exp_f32_e32 v116, v75
	v_exp_f32_e32 v117, v76
	v_exp_f32_e32 v118, v77
	v_exp_f32_e32 v119, v78
	v_exp_f32_e32 v120, v79
	v_add_f32_e32 v64, 0, v152
	v_add_f32_e32 v155, v153, v64
	s_mov_b64 s[20:21], -1
	s_cmp_ge_i32 s54, s55
	s_cbranch_scc0 .LBB0_411
	v_add_f32_e32 v64, v150, v155
	v_add_f32_e32 v64, v151, v64
	v_add_f32_e32 v64, v148, v64
	v_add_f32_e32 v64, v149, v64
	v_add_f32_e32 v64, v146, v64
	v_add_f32_e32 v64, v147, v64
	v_add_f32_e32 v64, v110, v64
	v_add_f32_e32 v64, v111, v64
	v_add_f32_e32 v64, v108, v64
	v_add_f32_e32 v64, v109, v64
	v_add_f32_e32 v64, v106, v64
	v_add_f32_e32 v64, v107, v64
	v_add_f32_e32 v64, v104, v64
	v_add_f32_e32 v64, v105, v64
	v_add_f32_e32 v64, v121, v64
	v_add_f32_e32 v64, v122, v64
	v_add_f32_e32 v64, v123, v64
	v_add_f32_e32 v64, v124, v64
	v_add_f32_e32 v64, v125, v64
	v_add_f32_e32 v64, v126, v64
	v_add_f32_e32 v64, v127, v64
	v_add_f32_e32 v64, v154, v64
	v_add_f32_e32 v64, v113, v64
	v_add_f32_e32 v64, v114, v64
	v_add_f32_e32 v64, v115, v64
	v_add_f32_e32 v64, v116, v64
	v_add_f32_e32 v64, v117, v64
	v_add_f32_e32 v64, v118, v64
	v_add_f32_e32 v64, v119, v64
	v_add_f32_e32 v64, v120, v64
	v_mov_b32_e32 v65, v64
	s_nop 1
	v_permlane32_swap_b32_e32 v64, v65
	v_add_f32_e32 v64, v64, v65
	v_add_f32_e32 v112, v170, v64
	v_cvt_pk_bf16_f32 v156, v152, v153
	v_cvt_pk_bf16_f32 v157, v150, v151
	v_cvt_pk_bf16_f32 v158, v148, v149
	v_cvt_pk_bf16_f32 v159, v146, v147
	v_cvt_pk_bf16_f32 v160, v110, v111
	v_cvt_pk_bf16_f32 v161, v108, v109
	v_cvt_pk_bf16_f32 v162, v106, v107
	v_cvt_pk_bf16_f32 v163, v104, v105
	v_cvt_pk_bf16_f32 v172, v121, v122
	v_cvt_pk_bf16_f32 v173, v123, v124
	v_cvt_pk_bf16_f32 v174, v125, v126
	v_cvt_pk_bf16_f32 v175, v127, v154
	v_cvt_pk_bf16_f32 v176, v113, v114
	v_cvt_pk_bf16_f32 v177, v115, v116
	v_cvt_pk_bf16_f32 v178, v117, v118
	v_cvt_pk_bf16_f32 v179, v119, v120
	s_nop 0
	v_permlane32_swap_b32_e32 v156, v158
	v_permlane32_swap_b32_e32 v157, v159
	v_permlane32_swap_b32_e32 v160, v162
	v_permlane32_swap_b32_e32 v161, v163
	v_permlane32_swap_b32_e32 v172, v174
	v_permlane32_swap_b32_e32 v173, v175
	v_permlane32_swap_b32_e32 v176, v178
	v_permlane32_swap_b32_e32 v177, v179
	ds_read_b64_tr_b16 v[80:81], v171 offset:0
	ds_read_b64_tr_b16 v[82:83], v171 offset:0x800
	ds_read_b64_tr_b16 v[84:85], v171 offset:0x1000
	ds_read_b64_tr_b16 v[86:87], v171 offset:0x1800
	ds_read_b64_tr_b16 v[88:89], v171 offset:0x2000
	ds_read_b64_tr_b16 v[90:91], v171 offset:0x2800
	ds_read_b64_tr_b16 v[92:93], v171 offset:0x3000
	ds_read_b64_tr_b16 v[94:95], v171 offset:0x3800
	s_nop 0
	s_waitcnt lgkmcnt(6)
	v_mfma_f32_32x32x16_bf16 v[64:79], v[156:159], v[80:83], v[0:15]
	s_waitcnt lgkmcnt(4)
	v_mfma_f32_32x32x16_bf16 v[64:79], v[160:163], v[84:87], v[64:79]
	s_waitcnt lgkmcnt(2)
	v_mfma_f32_32x32x16_bf16 v[64:79], v[172:175], v[88:91], v[64:79]
	ds_read_b64_tr_b16 v[88:89], v171 offset:0x200
	ds_read_b64_tr_b16 v[90:91], v171 offset:0xa00
	s_waitcnt lgkmcnt(2)
	v_mfma_f32_32x32x16_bf16 v[64:79], v[176:179], v[92:95], v[64:79]
	ds_read_b64_tr_b16 v[92:93], v171 offset:0x1200
	ds_read_b64_tr_b16 v[94:95], v171 offset:0x1a00
	ds_read_b64_tr_b16 v[96:97], v171 offset:0x2200
	ds_read_b64_tr_b16 v[98:99], v171 offset:0x2a00
	ds_read_b64_tr_b16 v[100:101], v171 offset:0x3200
	ds_read_b64_tr_b16 v[102:103], v171 offset:0x3a00
	s_waitcnt lgkmcnt(6)
	v_mfma_f32_32x32x16_bf16 v[72:87], v[156:159], v[88:91], v[48:63]
	s_waitcnt lgkmcnt(4)
	v_mfma_f32_32x32x16_bf16 v[72:87], v[160:163], v[92:95], v[72:87]
	s_waitcnt lgkmcnt(2)
	v_mfma_f32_32x32x16_bf16 v[72:87], v[172:175], v[96:99], v[72:87]
	ds_read_b64_tr_b16 v[96:97], v171 offset:0x400
	ds_read_b64_tr_b16 v[98:99], v171 offset:0xc00
	s_waitcnt lgkmcnt(2)
	v_mfma_f32_32x32x16_bf16 v[72:87], v[176:179], v[100:103], v[72:87]
	ds_read_b64_tr_b16 v[100:101], v171 offset:0x1400
	ds_read_b64_tr_b16 v[102:103], v171 offset:0x1c00
	ds_read_b64_tr_b16 v[180:181], v171 offset:0x2400
	ds_read_b64_tr_b16 v[182:183], v171 offset:0x2c00
	ds_read_b64_tr_b16 v[184:185], v171 offset:0x3400
	ds_read_b64_tr_b16 v[186:187], v171 offset:0x3c00
	s_waitcnt lgkmcnt(6)
	v_mfma_f32_32x32x16_bf16 v[80:95], v[156:159], v[96:99], v[32:47]
	s_waitcnt lgkmcnt(4)
	v_mfma_f32_32x32x16_bf16 v[80:95], v[160:163], v[100:103], v[80:95]
	s_waitcnt lgkmcnt(2)
	v_mfma_f32_32x32x16_bf16 v[80:95], v[172:175], v[180:183], v[80:95]
	ds_read_b64_tr_b16 v[180:181], v171 offset:0x600
	ds_read_b64_tr_b16 v[182:183], v171 offset:0xe00
	s_waitcnt lgkmcnt(2)
	v_mfma_f32_32x32x16_bf16 v[80:95], v[176:179], v[184:187], v[80:95]
	ds_read_b64_tr_b16 v[184:185], v171 offset:0x1600
	ds_read_b64_tr_b16 v[186:187], v171 offset:0x1e00
	ds_read_b64_tr_b16 v[188:189], v171 offset:0x2600
	ds_read_b64_tr_b16 v[190:191], v171 offset:0x2e00
	ds_read_b64_tr_b16 v[192:193], v171 offset:0x3600
	ds_read_b64_tr_b16 v[194:195], v171 offset:0x3e00
	s_waitcnt lgkmcnt(6)
	v_mfma_f32_32x32x16_bf16 v[88:103], v[156:159], v[180:183], v[16:31]
	s_mov_b64 s[20:21], 0
	s_waitcnt lgkmcnt(4)
	v_mfma_f32_32x32x16_bf16 v[88:103], v[160:163], v[184:187], v[88:103]
	s_waitcnt lgkmcnt(2)
	v_mfma_f32_32x32x16_bf16 v[88:103], v[172:175], v[188:191], v[88:103]
	s_waitcnt lgkmcnt(0)
	v_mfma_f32_32x32x16_bf16 v[88:103], v[176:179], v[192:195], v[88:103]
; __device__ __forceinline__ void finishSM(f32x16& p0, f32x16& p1, float& l_reg, bf16x8& pa0, bf16x8& pa1, bf16x8& pa2, bf16x8& pa3) {
; #pragma unroll
;   for (int r = 0; r < 16; ++r) p1[r] = __builtin_amdgcn_exp2f(p1[r]);
;   float ps = 0;
; #pragma unroll
;   for (int r = 0; r < 16; ++r) ps += p0[r];
; #pragma unroll
;   for (int r = 0; r < 16; ++r) ps += p1[r];
;   { auto rr = __builtin_amdgcn_permlane32_swap(__float_as_uint(ps), __float_as_uint(ps), false, false);
;     ps = __uint_as_float(rr[0]) + __uint_as_float(rr[1]); }
;   l_reg += ps;
;     ...
;   PK4(p0, 0, pa0); PK4(p0, 8, pa1); PK4(p1, 0, pa2); PK4(p1, 8, pa3);
;     ...
; }
; template <int DQK, int QL>
; __device__ __forceinline__ void qkt(f32x16& p0, f32x16& p1, const char* Ks, const bf16x8 (&qr)[DQK / 16 - QL], const char* qlds, const int (&kofs)[4], float negM) {
;   constexpr int QR = DQK / 16 - QL;
; #pragma unroll
;   for (int r = 0; r < 16; ++r) { p0[r] = negM; p1[r] = negM; }
; #pragma unroll
;   for (int d0 = 0; d0 < DQK / 16; ++d0) {
;     const char* kp = Ks + kofs[d0 & 3] + (d0 >> 2) * 128;
;     bf16x8 b0 = *reinterpret_cast<const bf16x8*>(kp);
;     bf16x8 b1 = *reinterpret_cast<const bf16x8*>(kp + 32 * DQK * 2);
;     bf16x8 qf;
;     if constexpr (QL > 0) { if (d0 < QR) qf = qr[d0 < QR ? d0 : 0]; else qf = *reinterpret_cast<const bf16x8*>(qlds + (d0 - QR) * 1024); }
;     else qf = qr[d0];
;     p0 = __builtin_amdgcn_mfma_f32_32x32x16_bf16(b0, qf, p0, 0, 0, 0);
;     p1 = __builtin_amdgcn_mfma_f32_32x32x16_bf16(b1, qf, p1, 0, 0, 0);
;   }
; }
; template <int NCB> __device__ __forceinline__ int v_st(int k, int c) {
;   const int kk = (k & ~0xC) | ((k & 4) << 1) | ((k & 8) >> 1);
;   return ((kk >> 3) * NCB + (c >> 5)) * 512 + ((kk & 7) * 32 + (c & 31)) * 2;
; }
; __device__ __forceinline__ int v_rd_base(int lane) { return ((lane & 3) << 3) | (((lane >> 2) & 3) << 6) | (((lane >> 4) & 1) << 5) | (((lane >> 5) & 1) << 8); }
; template <int OFF> __device__ __forceinline__ s16x4 tr_read(int vb) {
;   s16x4 r; asm volatile("ds_read_b64_tr_b16 %0, %1 offset:%2" : "=&v"(r) : "v"(vb), "i"(OFF) : "memory"); return r;
; }
; template <int NCB, int D0> __device__ __forceinline__ void pv_one(f32x16& od, int vb, bf16x8 pa0, bf16x8 pa1, bf16x8 pa2, bf16x8 pa3) {
;   constexpr int KSTEP = NCB * 1024, HALF = NCB * 512, B0 = D0 * 512;
.LBB0_411:
	s_andn2_b64 vcc, exec, s[20:21]
	s_cbranch_vccnz .LBB0_415
	s_nop 9
	ds_read_b128 v[96:99], v169 offset:40960
	ds_read_b128 v[100:103], v169 offset:45056
	v_mov_b64_e32 v[78:79], s[18:19]
	v_mov_b64_e32 v[76:77], s[16:17]
	v_mov_b64_e32 v[74:75], s[14:15]
	v_mov_b64_e32 v[72:73], s[12:13]
	v_mov_b64_e32 v[70:71], s[10:11]
	v_mov_b64_e32 v[68:69], s[8:9]
	v_mov_b64_e32 v[66:67], s[6:7]
	v_mov_b64_e32 v[64:65], s[4:5]
	s_waitcnt lgkmcnt(1)
	s_nop 0
	v_mfma_f32_32x32x16_bf16 v[80:95], v[96:99], v[142:145], v[64:79]
	s_waitcnt lgkmcnt(0)
	v_mfma_f32_32x32x16_bf16 v[64:79], v[100:103], v[142:145], v[64:79]
	ds_read_b128 v[96:99], v168 offset:40960
	ds_read_b128 v[100:103], v168 offset:45056
	s_waitcnt lgkmcnt(1)
	v_mfma_f32_32x32x16_bf16 v[80:95], v[96:99], v[138:141], v[80:95]
	s_waitcnt lgkmcnt(0)
	v_mfma_f32_32x32x16_bf16 v[64:79], v[100:103], v[138:141], v[64:79]
	ds_read_b128 v[96:99], v167 offset:40960
	ds_read_b128 v[100:103], v167 offset:45056
	s_waitcnt lgkmcnt(1)
	v_mfma_f32_32x32x16_bf16 v[80:95], v[96:99], v[134:137], v[80:95]
	s_waitcnt lgkmcnt(0)
	v_mfma_f32_32x32x16_bf16 v[64:79], v[100:103], v[134:137], v[64:79]
	ds_read_b128 v[96:99], v166 offset:40960
	ds_read_b128 v[100:103], v166 offset:45056
	s_waitcnt lgkmcnt(1)
	v_mfma_f32_32x32x16_bf16 v[80:95], v[96:99], v[130:133], v[80:95]
	v_add_f32_e32 v96, v150, v155
	v_add_f32_e32 v96, v151, v96
	v_add_f32_e32 v96, v148, v96
	v_add_f32_e32 v96, v149, v96
	v_add_f32_e32 v96, v146, v96
	v_add_f32_e32 v96, v147, v96
	v_add_f32_e32 v96, v110, v96
	v_add_f32_e32 v96, v111, v96
	v_add_f32_e32 v96, v108, v96
	v_add_f32_e32 v96, v109, v96
	v_add_f32_e32 v96, v106, v96
	v_add_f32_e32 v96, v107, v96
	v_add_f32_e32 v96, v104, v96
	v_add_f32_e32 v96, v105, v96
	v_add_f32_e32 v96, v121, v96
	v_add_f32_e32 v96, v122, v96
	v_add_f32_e32 v96, v123, v96
	v_add_f32_e32 v96, v124, v96
	v_add_f32_e32 v96, v125, v96
	v_add_f32_e32 v96, v126, v96
	v_add_f32_e32 v96, v127, v96
	v_add_f32_e32 v96, v154, v96
	v_add_f32_e32 v96, v113, v96
	v_add_f32_e32 v96, v114, v96
	s_waitcnt lgkmcnt(0)
	v_mfma_f32_32x32x16_bf16 v[64:79], v[100:103], v[130:133], v[64:79]
	v_add_f32_e32 v96, v115, v96
	v_add_f32_e32 v96, v116, v96
	v_add_f32_e32 v96, v117, v96
	v_add_f32_e32 v96, v118, v96
	v_add_f32_e32 v96, v119, v96
	v_add_f32_e32 v96, v120, v96
	v_mov_b32_e32 v97, v96
	s_nop 1
	v_permlane32_swap_b32_e32 v96, v97
	v_cvt_pk_bf16_f32 v98, v152, v153
	v_cvt_pk_bf16_f32 v99, v150, v151
	v_cvt_pk_bf16_f32 v100, v148, v149
	v_cvt_pk_bf16_f32 v101, v146, v147
	v_cvt_pk_bf16_f32 v130, v110, v111
	v_cvt_pk_bf16_f32 v131, v108, v109
	v_cvt_pk_bf16_f32 v132, v106, v107
	v_cvt_pk_bf16_f32 v133, v104, v105
	v_cvt_pk_bf16_f32 v102, v121, v122
	v_cvt_pk_bf16_f32 v103, v123, v124
	v_cvt_pk_bf16_f32 v104, v125, v126
	v_cvt_pk_bf16_f32 v105, v127, v154
	v_cvt_pk_bf16_f32 v106, v113, v114
	v_cvt_pk_bf16_f32 v107, v115, v116
	v_cvt_pk_bf16_f32 v108, v117, v118
	v_cvt_pk_bf16_f32 v109, v119, v120
	s_nop 0
	v_permlane32_swap_b32_e32 v98, v100
	v_permlane32_swap_b32_e32 v99, v101
	v_permlane32_swap_b32_e32 v130, v132
	v_permlane32_swap_b32_e32 v131, v133
	v_permlane32_swap_b32_e32 v102, v104
	v_permlane32_swap_b32_e32 v103, v105
	v_permlane32_swap_b32_e32 v106, v108
	v_permlane32_swap_b32_e32 v107, v109
	ds_read_b64_tr_b16 v[110:111], v171 offset:0
	ds_read_b64_tr_b16 v[112:113], v171 offset:0x800
	ds_read_b64_tr_b16 v[114:115], v171 offset:0x1000
	ds_read_b64_tr_b16 v[116:117], v171 offset:0x1800
	ds_read_b64_tr_b16 v[118:119], v171 offset:0x2000
	ds_read_b64_tr_b16 v[120:121], v171 offset:0x2800
	ds_read_b64_tr_b16 v[122:123], v171 offset:0x3000
	ds_read_b64_tr_b16 v[124:125], v171 offset:0x3800
	s_nop 0
	s_waitcnt lgkmcnt(6)
	v_mfma_f32_32x32x16_bf16 v[0:15], v[98:101], v[110:113], v[0:15]
	ds_read_b64_tr_b16 v[110:111], v171 offset:0x200
	ds_read_b64_tr_b16 v[112:113], v171 offset:0xa00
	s_waitcnt lgkmcnt(6)
	v_mfma_f32_32x32x16_bf16 v[0:15], v[130:133], v[114:117], v[0:15]
	ds_read_b64_tr_b16 v[114:115], v171 offset:0x1200
	ds_read_b64_tr_b16 v[116:117], v171 offset:0x1a00
	s_waitcnt lgkmcnt(6)
	v_mfma_f32_32x32x16_bf16 v[0:15], v[102:105], v[118:121], v[0:15]
	ds_read_b64_tr_b16 v[118:119], v171 offset:0x2200
	ds_read_b64_tr_b16 v[120:121], v171 offset:0x2a00
	s_waitcnt lgkmcnt(6)
	v_mfma_f32_32x32x16_bf16 v[0:15], v[106:109], v[122:125], v[0:15]
	ds_read_b64_tr_b16 v[122:123], v171 offset:0x3200
	ds_read_b64_tr_b16 v[124:125], v171 offset:0x3a00
	s_waitcnt lgkmcnt(6)
	v_mfma_f32_32x32x16_bf16 v[48:63], v[98:101], v[110:113], v[48:63]
	ds_read_b64_tr_b16 v[110:111], v171 offset:0x400
	ds_read_b64_tr_b16 v[112:113], v171 offset:0xc00
	s_waitcnt lgkmcnt(6)
	v_mfma_f32_32x32x16_bf16 v[48:63], v[130:133], v[114:117], v[48:63]
	ds_read_b64_tr_b16 v[114:115], v171 offset:0x1400
	ds_read_b64_tr_b16 v[116:117], v171 offset:0x1c00
	s_waitcnt lgkmcnt(6)
	v_mfma_f32_32x32x16_bf16 v[48:63], v[102:105], v[118:121], v[48:63]
	ds_read_b64_tr_b16 v[118:119], v171 offset:0x2400
	ds_read_b64_tr_b16 v[120:121], v171 offset:0x2c00
	s_waitcnt lgkmcnt(6)
	v_mfma_f32_32x32x16_bf16 v[48:63], v[106:109], v[122:125], v[48:63]
	ds_read_b64_tr_b16 v[122:123], v171 offset:0x3400
	ds_read_b64_tr_b16 v[124:125], v171 offset:0x3c00
	s_waitcnt lgkmcnt(6)
	v_mfma_f32_32x32x16_bf16 v[32:47], v[98:101], v[110:113], v[32:47]
	ds_read_b64_tr_b16 v[110:111], v171 offset:0x600
	ds_read_b64_tr_b16 v[112:113], v171 offset:0xe00
	s_waitcnt lgkmcnt(6)
	v_mfma_f32_32x32x16_bf16 v[32:47], v[130:133], v[114:117], v[32:47]
	ds_read_b64_tr_b16 v[114:115], v171 offset:0x1600
	ds_read_b64_tr_b16 v[116:117], v171 offset:0x1e00
	s_waitcnt lgkmcnt(6)
	v_mfma_f32_32x32x16_bf16 v[32:47], v[102:105], v[118:121], v[32:47]
	ds_read_b64_tr_b16 v[118:119], v171 offset:0x2600
	ds_read_b64_tr_b16 v[120:121], v171 offset:0x2e00
	s_waitcnt lgkmcnt(6)
	v_mfma_f32_32x32x16_bf16 v[32:47], v[106:109], v[122:125], v[32:47]
	ds_read_b64_tr_b16 v[122:123], v171 offset:0x3600
	ds_read_b64_tr_b16 v[124:125], v171 offset:0x3e00
	s_waitcnt lgkmcnt(6)
	v_mfma_f32_32x32x16_bf16 v[16:31], v[98:101], v[110:113], v[16:31]
	s_add_i32 s54, s54, s78
	s_lshl_b32 s3, s54, 6
	s_cmp_le_i32 s3, s59
	s_waitcnt lgkmcnt(4)
	v_mfma_f32_32x32x16_bf16 v[16:31], v[130:133], v[114:117], v[16:31]
	s_waitcnt lgkmcnt(2)
	v_mfma_f32_32x32x16_bf16 v[16:31], v[102:105], v[118:121], v[16:31]
	s_waitcnt lgkmcnt(0)
	v_mfma_f32_32x32x16_bf16 v[16:31], v[106:109], v[122:125], v[16:31]
	s_cbranch_scc1 .LBB0_414
; __device__ __forceinline__ int crow(int r, int hi) { return (r & 3) + 8 * (r >> 2) + 4 * hi; }
; template <bool GM>
; __device__ __forceinline__ void partialSM(f32x16& p0, f32x16& p1, bool mask, int kbase, int L, int qpos, int hi) {
;   if (mask) {
; #pragma unroll
;     for (int r = 0; r < 16; ++r) {
;       int k = kbase + crow(r, hi);
;       asm volatile("" : "+v"(k) : "v"(p0[r]));
;       bool ok = k < L;
;       if (GM) ok = ok && (k < 16 || abs(qpos - k) <= 128);
;       p0[r] = ok ? p0[r] : -1e30f;
;       int k2 = k + 32;
;       asm volatile("" : "+v"(k2) : "v"(p1[r]));
;       bool ok2 = k2 < L;
;       if (GM) ok2 = ok2 && (k2 < 16 || abs(qpos - k2) <= 128);
;       p1[r] = ok2 ? p1[r] : -1e30f;
;     }
;   }
	v_lshl_or_b32 v98, v128, 2, s3
	v_mov_b32_e32 v99, v98
	s_nop 0
	v_cmp_gt_i32_e32 vcc, s94, v99
	v_add_u32_e32 v99, 32, v99
	s_nop 0
	v_cndmask_b32_e32 v80, v233, v80, vcc
	v_cmp_gt_i32_e32 vcc, s94, v99
	v_or_b32_e32 v99, 1, v98
	s_nop 0
	v_cndmask_b32_e32 v64, v233, v64, vcc
	v_cmp_gt_i32_e32 vcc, s94, v99
	v_add_u32_e32 v99, 32, v99
	s_nop 0
	v_cndmask_b32_e32 v81, v233, v81, vcc
	v_cmp_gt_i32_e32 vcc, s94, v99
	v_or_b32_e32 v99, 2, v98
	s_nop 0
	v_cndmask_b32_e32 v65, v233, v65, vcc
	v_cmp_gt_i32_e32 vcc, s94, v99
	v_add_u32_e32 v99, 32, v99
	s_nop 0
	v_cndmask_b32_e32 v82, v233, v82, vcc
	v_cmp_gt_i32_e32 vcc, s94, v99
	v_or_b32_e32 v99, 3, v98
	s_nop 0
	v_cndmask_b32_e32 v66, v233, v66, vcc
	v_cmp_gt_i32_e32 vcc, s94, v99
	v_add_u32_e32 v99, 32, v99
	s_nop 0
	v_cndmask_b32_e32 v83, v233, v83, vcc
	v_cmp_gt_i32_e32 vcc, s94, v99
	v_or_b32_e32 v99, 8, v98
	s_nop 0
	v_cndmask_b32_e32 v67, v233, v67, vcc
	v_cmp_gt_i32_e32 vcc, s94, v99
	v_add_u32_e32 v99, 32, v99
	s_nop 0
	v_cndmask_b32_e32 v84, v233, v84, vcc
	v_cmp_gt_i32_e32 vcc, s94, v99
	v_or_b32_e32 v99, 9, v98
	s_nop 0
	v_cndmask_b32_e32 v68, v233, v68, vcc
	v_cmp_gt_i32_e32 vcc, s94, v99
	v_add_u32_e32 v99, 32, v99
	s_nop 0
	v_cndmask_b32_e32 v85, v233, v85, vcc
	v_cmp_gt_i32_e32 vcc, s94, v99
	v_or_b32_e32 v99, 10, v98
	s_nop 0
	v_cndmask_b32_e32 v69, v233, v69, vcc
	v_cmp_gt_i32_e32 vcc, s94, v99
	v_add_u32_e32 v99, 32, v99
	s_nop 0
	v_cndmask_b32_e32 v86, v233, v86, vcc
	v_cmp_gt_i32_e32 vcc, s94, v99
	v_or_b32_e32 v99, 11, v98
	s_nop 0
	v_cndmask_b32_e32 v70, v233, v70, vcc
	v_cmp_gt_i32_e32 vcc, s94, v99
	v_add_u32_e32 v99, 32, v99
	s_nop 0
	v_cndmask_b32_e32 v87, v233, v87, vcc
	v_cmp_gt_i32_e32 vcc, s94, v99
	v_or_b32_e32 v99, 16, v98
	s_nop 0
	v_cndmask_b32_e32 v71, v233, v71, vcc
	v_cmp_gt_i32_e32 vcc, s94, v99
	v_add_u32_e32 v99, 32, v99
	s_nop 0
	v_cndmask_b32_e32 v88, v233, v88, vcc
	v_cmp_gt_i32_e32 vcc, s94, v99
	v_or_b32_e32 v99, 17, v98
	s_nop 0
	v_cndmask_b32_e32 v72, v233, v72, vcc
	v_cmp_gt_i32_e32 vcc, s94, v99
	v_add_u32_e32 v99, 32, v99
	s_nop 0
	v_cndmask_b32_e32 v89, v233, v89, vcc
	v_cmp_gt_i32_e32 vcc, s94, v99
	v_or_b32_e32 v99, 18, v98
	s_nop 0
	v_cndmask_b32_e32 v73, v233, v73, vcc
	v_cmp_gt_i32_e32 vcc, s94, v99
	v_add_u32_e32 v99, 32, v99
	s_nop 0
	v_cndmask_b32_e32 v90, v233, v90, vcc
	v_cmp_gt_i32_e32 vcc, s94, v99
	v_or_b32_e32 v99, 19, v98
	s_nop 0
	v_cndmask_b32_e32 v74, v233, v74, vcc
	v_cmp_gt_i32_e32 vcc, s94, v99
	v_add_u32_e32 v99, 32, v99
	s_nop 0
	v_cndmask_b32_e32 v91, v233, v91, vcc
	v_cmp_gt_i32_e32 vcc, s94, v99
	v_or_b32_e32 v99, 24, v98
	s_nop 0
	v_cndmask_b32_e32 v75, v233, v75, vcc
	v_cmp_gt_i32_e32 vcc, s94, v99
	v_add_u32_e32 v99, 32, v99
	s_nop 0
	v_cndmask_b32_e32 v92, v233, v92, vcc
	v_cmp_gt_i32_e32 vcc, s94, v99
	v_or_b32_e32 v99, 25, v98
	s_nop 0
	v_cndmask_b32_e32 v76, v233, v76, vcc
	v_cmp_gt_i32_e32 vcc, s94, v99
	v_add_u32_e32 v99, 32, v99
	s_nop 0
	v_cndmask_b32_e32 v93, v233, v93, vcc
	v_cmp_gt_i32_e32 vcc, s94, v99
	v_or_b32_e32 v99, 26, v98
	v_or_b32_e32 v98, 27, v98
	v_cndmask_b32_e32 v77, v233, v77, vcc
	v_cmp_gt_i32_e32 vcc, s94, v99
	v_add_u32_e32 v99, 32, v99
	s_nop 0
	v_cndmask_b32_e32 v94, v233, v94, vcc
	v_cmp_gt_i32_e32 vcc, s94, v99
	s_nop 1
	v_cndmask_b32_e32 v78, v233, v78, vcc
	v_cmp_gt_i32_e32 vcc, s94, v98
	v_add_u32_e32 v98, 32, v98
	s_nop 0
	v_cndmask_b32_e32 v95, v233, v95, vcc
	v_cmp_gt_i32_e32 vcc, s94, v98
	s_nop 1
	v_cndmask_b32_e32 v79, v233, v79, vcc
; #define WAIT_L0() asm volatile("s_waitcnt lgkmcnt(0)" ::: "memory")
; #define SBAR() __builtin_amdgcn_sched_barrier(0)
; __device__ __forceinline__ void finishSM(f32x16& p0, f32x16& p1, float& l_reg, bf16x8& pa0, bf16x8& pa1, bf16x8& pa2, bf16x8& pa3) {
; #pragma unroll
;   for (int r = 0; r < 16; ++r) p1[r] = __builtin_amdgcn_exp2f(p1[r]);
;   float ps = 0;
; #pragma unroll
;   for (int r = 0; r < 16; ++r) ps += p0[r];
; #pragma unroll
;   for (int r = 0; r < 16; ++r) ps += p1[r];
;   { auto rr = __builtin_amdgcn_permlane32_swap(__float_as_uint(ps), __float_as_uint(ps), false, false);
;     ps = __uint_as_float(rr[0]) + __uint_as_float(rr[1]); }
;   l_reg += ps;
;     ...
;   PK4(p0, 0, pa0); PK4(p0, 8, pa1); PK4(p1, 0, pa2); PK4(p1, 8, pa3);
;     ...
; }
; template <int NCB, int D0> __device__ __forceinline__ void pv_one(f32x16& od, int vb, bf16x8 pa0, bf16x8 pa1, bf16x8 pa2, bf16x8 pa3) {
;   constexpr int KSTEP = NCB * 1024, HALF = NCB * 512, B0 = D0 * 512;
;   const s16x4 l0 = tr_read<B0>(vb), h0 = tr_read<B0 + HALF>(vb), l1 = tr_read<B0 + KSTEP>(vb), h1 = tr_read<B0 + KSTEP + HALF>(vb);
;   const s16x4 l2 = tr_read<B0 + 2 * KSTEP>(vb), h2 = tr_read<B0 + 2 * KSTEP + HALF>(vb), l3 = tr_read<B0 + 3 * KSTEP>(vb), h3 = tr_read<B0 + 3 * KSTEP + HALF>(vb);
;   WAIT_L0(); SBAR();
;     ...
;   od = __builtin_amdgcn_mfma_f32_32x32x16_bf16(pa0, PK(l0, h0), od, 0, 0, 0);
;   od = __builtin_amdgcn_mfma_f32_32x32x16_bf16(pa1, PK(l1, h1), od, 0, 0, 0);
;   od = __builtin_amdgcn_mfma_f32_32x32x16_bf16(pa2, PK(l2, h2), od, 0, 0, 0);
;   od = __builtin_amdgcn_mfma_f32_32x32x16_bf16(pa3, PK(l3, h3), od, 0, 0, 0);
;     ...
; }
.LBB0_414:
	v_exp_f32_e32 v80, v80
	v_exp_f32_e32 v81, v81
	v_exp_f32_e32 v82, v82
	v_exp_f32_e32 v83, v83
	v_add_f32_e32 v96, v96, v97
	v_exp_f32_e32 v84, v84
	v_exp_f32_e32 v97, v64
	v_add_f32_e32 v64, 0, v80
	v_exp_f32_e32 v85, v85
	v_add_f32_e32 v64, v81, v64
	v_exp_f32_e32 v86, v86
	v_add_f32_e32 v64, v82, v64
	v_exp_f32_e32 v87, v87
	v_add_f32_e32 v64, v83, v64
	v_exp_f32_e32 v88, v88
	v_add_f32_e32 v64, v84, v64
	v_exp_f32_e32 v89, v89
	v_add_f32_e32 v64, v85, v64
	v_exp_f32_e32 v90, v90
	v_add_f32_e32 v64, v86, v64
	v_exp_f32_e32 v91, v91
	v_add_f32_e32 v64, v87, v64
	v_exp_f32_e32 v92, v92
	v_add_f32_e32 v64, v88, v64
	v_exp_f32_e32 v93, v93
	v_add_f32_e32 v64, v89, v64
	v_exp_f32_e32 v94, v94
	v_add_f32_e32 v64, v90, v64
	v_exp_f32_e32 v95, v95
	v_add_f32_e32 v64, v91, v64
	v_add_f32_e32 v64, v92, v64
	v_exp_f32_e32 v98, v65
	v_add_f32_e32 v64, v93, v64
	v_exp_f32_e32 v99, v66
	v_add_f32_e32 v64, v94, v64
	v_exp_f32_e32 v100, v67
	v_add_f32_e32 v64, v95, v64
	v_exp_f32_e32 v101, v68
	v_add_f32_e32 v64, v97, v64
	v_exp_f32_e32 v102, v69
	v_add_f32_e32 v64, v98, v64
	v_exp_f32_e32 v103, v70
	v_add_f32_e32 v64, v99, v64
	v_exp_f32_e32 v104, v71
	v_add_f32_e32 v64, v100, v64
	v_exp_f32_e32 v105, v72
	v_add_f32_e32 v64, v101, v64
	v_exp_f32_e32 v106, v73
	v_add_f32_e32 v64, v102, v64
	v_exp_f32_e32 v107, v74
	v_add_f32_e32 v64, v103, v64
	v_exp_f32_e32 v108, v75
	v_add_f32_e32 v64, v104, v64
	v_exp_f32_e32 v76, v76
	v_add_f32_e32 v64, v105, v64
	v_exp_f32_e32 v77, v77
	v_add_f32_e32 v64, v106, v64
	v_exp_f32_e32 v78, v78
	v_add_f32_e32 v64, v107, v64
	v_exp_f32_e32 v79, v79
	v_add_f32_e32 v64, v108, v64
	v_add_f32_e32 v64, v76, v64
	v_add_f32_e32 v64, v77, v64
	v_add_f32_e32 v64, v78, v64
	v_add_f32_e32 v64, v79, v64
	v_mov_b32_e32 v65, v64
	s_nop 1
	v_permlane32_swap_b32_e32 v64, v65
	v_add_f32_e32 v96, v170, v96
	v_add_f32_e32 v64, v64, v65
	v_add_f32_e32 v112, v96, v64
	v_cvt_pk_bf16_f32 v64, v80, v81
	v_cvt_pk_bf16_f32 v65, v82, v83
	v_cvt_pk_bf16_f32 v66, v84, v85
	v_cvt_pk_bf16_f32 v67, v86, v87
	v_cvt_pk_bf16_f32 v68, v88, v89
	v_cvt_pk_bf16_f32 v69, v90, v91
	v_cvt_pk_bf16_f32 v70, v92, v93
	v_cvt_pk_bf16_f32 v71, v94, v95
	v_cvt_pk_bf16_f32 v72, v97, v98
	v_cvt_pk_bf16_f32 v73, v99, v100
	v_cvt_pk_bf16_f32 v74, v101, v102
	v_cvt_pk_bf16_f32 v75, v103, v104
	v_cvt_pk_bf16_f32 v88, v105, v106
	v_cvt_pk_bf16_f32 v89, v107, v108
	v_cvt_pk_bf16_f32 v90, v76, v77
	v_cvt_pk_bf16_f32 v91, v78, v79
	s_nop 0
	v_permlane32_swap_b32_e32 v64, v66
	v_permlane32_swap_b32_e32 v65, v67
	v_permlane32_swap_b32_e32 v68, v70
	v_permlane32_swap_b32_e32 v69, v71
	v_permlane32_swap_b32_e32 v72, v74
	v_permlane32_swap_b32_e32 v73, v75
	v_permlane32_swap_b32_e32 v88, v90
	v_permlane32_swap_b32_e32 v89, v91
	ds_read_b64_tr_b16 v[76:77], v165 offset:0
	ds_read_b64_tr_b16 v[78:79], v165 offset:0x800
	ds_read_b64_tr_b16 v[80:81], v165 offset:0x1000
	ds_read_b64_tr_b16 v[82:83], v165 offset:0x1800
	ds_read_b64_tr_b16 v[84:85], v165 offset:0x2000
	ds_read_b64_tr_b16 v[86:87], v165 offset:0x2800
	ds_read_b64_tr_b16 v[92:93], v165 offset:0x3000
	ds_read_b64_tr_b16 v[94:95], v165 offset:0x3800
	s_nop 0
	s_waitcnt lgkmcnt(6)
	v_mfma_f32_32x32x16_bf16 v[0:15], v[64:67], v[76:79], v[0:15]
	ds_read_b64_tr_b16 v[76:77], v165 offset:0x200
	ds_read_b64_tr_b16 v[78:79], v165 offset:0xa00
	s_waitcnt lgkmcnt(6)
	v_mfma_f32_32x32x16_bf16 v[0:15], v[68:71], v[80:83], v[0:15]
	ds_read_b64_tr_b16 v[80:81], v165 offset:0x1200
	ds_read_b64_tr_b16 v[82:83], v165 offset:0x1a00
	s_waitcnt lgkmcnt(6)
	v_mfma_f32_32x32x16_bf16 v[0:15], v[72:75], v[84:87], v[0:15]
	ds_read_b64_tr_b16 v[84:85], v165 offset:0x2200
	ds_read_b64_tr_b16 v[86:87], v165 offset:0x2a00
	s_waitcnt lgkmcnt(6)
	v_mfma_f32_32x32x16_bf16 v[0:15], v[88:91], v[92:95], v[0:15]
	ds_read_b64_tr_b16 v[92:93], v165 offset:0x3200
	ds_read_b64_tr_b16 v[94:95], v165 offset:0x3a00
	s_waitcnt lgkmcnt(6)
	v_mfma_f32_32x32x16_bf16 v[48:63], v[64:67], v[76:79], v[48:63]
	ds_read_b64_tr_b16 v[76:77], v165 offset:0x400
	ds_read_b64_tr_b16 v[78:79], v165 offset:0xc00
	s_waitcnt lgkmcnt(6)
	v_mfma_f32_32x32x16_bf16 v[48:63], v[68:71], v[80:83], v[48:63]
	ds_read_b64_tr_b16 v[80:81], v165 offset:0x1400
	ds_read_b64_tr_b16 v[82:83], v165 offset:0x1c00
	s_waitcnt lgkmcnt(6)
	v_mfma_f32_32x32x16_bf16 v[48:63], v[72:75], v[84:87], v[48:63]
	ds_read_b64_tr_b16 v[84:85], v165 offset:0x2400
	ds_read_b64_tr_b16 v[86:87], v165 offset:0x2c00
	s_waitcnt lgkmcnt(6)
	v_mfma_f32_32x32x16_bf16 v[48:63], v[88:91], v[92:95], v[48:63]
	ds_read_b64_tr_b16 v[92:93], v165 offset:0x3400
	ds_read_b64_tr_b16 v[94:95], v165 offset:0x3c00
	s_waitcnt lgkmcnt(6)
	v_mfma_f32_32x32x16_bf16 v[32:47], v[64:67], v[76:79], v[32:47]
	ds_read_b64_tr_b16 v[76:77], v165 offset:0x600
	ds_read_b64_tr_b16 v[78:79], v165 offset:0xe00
	s_waitcnt lgkmcnt(6)
	v_mfma_f32_32x32x16_bf16 v[32:47], v[68:71], v[80:83], v[32:47]
	ds_read_b64_tr_b16 v[80:81], v165 offset:0x1600
	ds_read_b64_tr_b16 v[82:83], v165 offset:0x1e00
	s_waitcnt lgkmcnt(6)
	v_mfma_f32_32x32x16_bf16 v[32:47], v[72:75], v[84:87], v[32:47]
	ds_read_b64_tr_b16 v[84:85], v165 offset:0x2600
	ds_read_b64_tr_b16 v[86:87], v165 offset:0x2e00
	s_waitcnt lgkmcnt(6)
	v_mfma_f32_32x32x16_bf16 v[32:47], v[88:91], v[92:95], v[32:47]
	ds_read_b64_tr_b16 v[92:93], v165 offset:0x3600
	ds_read_b64_tr_b16 v[94:95], v165 offset:0x3e00
	s_waitcnt lgkmcnt(6)
	v_mfma_f32_32x32x16_bf16 v[16:31], v[64:67], v[76:79], v[16:31]
	s_waitcnt lgkmcnt(4)
	v_mfma_f32_32x32x16_bf16 v[16:31], v[68:71], v[80:83], v[16:31]
	s_waitcnt lgkmcnt(2)
	v_mfma_f32_32x32x16_bf16 v[16:31], v[72:75], v[84:87], v[16:31]
	s_nop 0
	v_mov_b64_e32 v[78:79], v[14:15]
	v_mov_b64_e32 v[76:77], v[12:13]
	v_mov_b64_e32 v[74:75], v[10:11]
	v_mov_b64_e32 v[72:73], v[8:9]
	v_mov_b64_e32 v[86:87], v[62:63]
	v_mov_b64_e32 v[84:85], v[60:61]
	v_mov_b64_e32 v[82:83], v[58:59]
	s_waitcnt lgkmcnt(0)
	v_mfma_f32_32x32x16_bf16 v[16:31], v[88:91], v[92:95], v[16:31]
	v_mov_b64_e32 v[80:81], v[56:57]
	v_mov_b64_e32 v[94:95], v[46:47]
	v_mov_b64_e32 v[92:93], v[44:45]
	v_mov_b64_e32 v[90:91], v[42:43]
	v_mov_b64_e32 v[88:89], v[40:41]
	v_mov_b64_e32 v[70:71], v[6:7]
	v_mov_b64_e32 v[68:69], v[4:5]
	s_nop 4
	v_mov_b64_e32 v[102:103], v[30:31]
	v_mov_b64_e32 v[66:67], v[2:3]
	v_mov_b64_e32 v[64:65], v[0:1]
	v_mov_b64_e32 v[78:79], v[54:55]
	v_mov_b64_e32 v[76:77], v[52:53]
	v_mov_b64_e32 v[74:75], v[50:51]
	v_mov_b64_e32 v[72:73], v[48:49]
	v_mov_b64_e32 v[86:87], v[38:39]
	v_mov_b64_e32 v[84:85], v[36:37]
	v_mov_b64_e32 v[82:83], v[34:35]
	v_mov_b64_e32 v[80:81], v[32:33]
	v_mov_b64_e32 v[94:95], v[22:23]
	v_mov_b64_e32 v[92:93], v[20:21]
	v_mov_b64_e32 v[90:91], v[18:19]
	v_mov_b64_e32 v[88:89], v[16:17]
	v_mov_b64_e32 v[100:101], v[28:29]
	v_mov_b64_e32 v[98:99], v[26:27]
	v_mov_b64_e32 v[96:97], v[24:25]

; __device__ __forceinline__ void finishSM(f32x16& p0, f32x16& p1, float& l_reg, bf16x8& pa0, bf16x8& pa1, bf16x8& pa2, bf16x8& pa3) {
; #pragma unroll
;   for (int r = 0; r < 16; ++r) p1[r] = __builtin_amdgcn_exp2f(p1[r]);
;   float ps = 0;
; #pragma unroll
;   for (int r = 0; r < 16; ++r) ps += p0[r];
; #pragma unroll
;   for (int r = 0; r < 16; ++r) ps += p1[r];
;   { auto rr = __builtin_amdgcn_permlane32_swap(__float_as_uint(ps), __float_as_uint(ps), false, false);
;     ps = __uint_as_float(rr[0]) + __uint_as_float(rr[1]); }
;   l_reg += ps;
;     ...
;   PK4(p0, 0, pa0); PK4(p0, 8, pa1); PK4(p1, 0, pa2); PK4(p1, 8, pa3);
;     ...
; }
; template <int DQK, int QL>
; __device__ __forceinline__ void qkt(f32x16& p0, f32x16& p1, const char* Ks, const bf16x8 (&qr)[DQK / 16 - QL], const char* qlds, const int (&kofs)[4], float negM) {
;   constexpr int QR = DQK / 16 - QL;
; #pragma unroll
;   for (int r = 0; r < 16; ++r) { p0[r] = negM; p1[r] = negM; }
; #pragma unroll
;   for (int d0 = 0; d0 < DQK / 16; ++d0) {
;     const char* kp = Ks + kofs[d0 & 3] + (d0 >> 2) * 128;
;     bf16x8 b0 = *reinterpret_cast<const bf16x8*>(kp);
;     bf16x8 b1 = *reinterpret_cast<const bf16x8*>(kp + 32 * DQK * 2);
;     bf16x8 qf;
;     if constexpr (QL > 0) { if (d0 < QR) qf = qr[d0 < QR ? d0 : 0]; else qf = *reinterpret_cast<const bf16x8*>(qlds + (d0 - QR) * 1024); }
;     else qf = qr[d0];
;     p0 = __builtin_amdgcn_mfma_f32_32x32x16_bf16(b0, qf, p0, 0, 0, 0);
;     p1 = __builtin_amdgcn_mfma_f32_32x32x16_bf16(b1, qf, p1, 0, 0, 0);
;   }
; }
.LBB0_430:
	v_add_f32_e32 v80, 0, v132
	v_add_f32_e32 v80, v133, v80
	v_add_f32_e32 v80, v130, v80
	v_add_f32_e32 v80, v131, v80
	v_add_f32_e32 v80, v126, v80
	v_add_f32_e32 v80, v127, v80
	v_add_f32_e32 v80, v124, v80
	v_add_f32_e32 v80, v125, v80
	v_add_f32_e32 v80, v110, v80
	v_add_f32_e32 v80, v111, v80
	v_add_f32_e32 v80, v108, v80
	v_add_f32_e32 v80, v109, v80
	v_exp_f32_e32 v64, v64
	v_add_f32_e32 v80, v106, v80
	v_exp_f32_e32 v65, v65
	v_add_f32_e32 v80, v107, v80
	v_exp_f32_e32 v66, v66
	v_add_f32_e32 v80, v104, v80
	v_exp_f32_e32 v67, v67
	v_add_f32_e32 v80, v105, v80
	v_exp_f32_e32 v68, v68
	v_add_f32_e32 v80, v64, v80
	v_exp_f32_e32 v69, v69
	v_add_f32_e32 v80, v65, v80
	v_exp_f32_e32 v70, v70
	v_add_f32_e32 v80, v66, v80
	v_exp_f32_e32 v71, v71
	v_add_f32_e32 v80, v67, v80
	v_exp_f32_e32 v72, v72
	v_add_f32_e32 v80, v68, v80
	v_exp_f32_e32 v73, v73
	v_add_f32_e32 v80, v69, v80
	v_exp_f32_e32 v74, v74
	v_add_f32_e32 v80, v70, v80
	v_exp_f32_e32 v75, v75
	v_add_f32_e32 v80, v71, v80
	v_exp_f32_e32 v76, v76
	v_add_f32_e32 v80, v72, v80
	v_exp_f32_e32 v77, v77
	v_add_f32_e32 v80, v73, v80
	v_exp_f32_e32 v78, v78
	v_add_f32_e32 v80, v74, v80
	v_exp_f32_e32 v79, v79
	v_add_f32_e32 v80, v75, v80
	v_add_f32_e32 v80, v76, v80
	v_add_f32_e32 v80, v77, v80
	v_add_f32_e32 v80, v78, v80
	v_add_f32_e32 v168, v79, v80
	v_mov_b32_e32 v169, v168
	s_nop 1
	v_permlane32_swap_b32_e32 v168, v169
	v_cvt_pk_bf16_f32 v134, v132, v133
	v_cvt_pk_bf16_f32 v135, v130, v131
	v_cvt_pk_bf16_f32 v136, v126, v127
	v_cvt_pk_bf16_f32 v137, v124, v125
	v_cvt_pk_bf16_f32 v138, v110, v111
	v_cvt_pk_bf16_f32 v139, v108, v109
	v_cvt_pk_bf16_f32 v140, v106, v107
	v_cvt_pk_bf16_f32 v141, v104, v105
	v_cvt_pk_bf16_f32 v146, v64, v65
	v_cvt_pk_bf16_f32 v147, v66, v67
	v_cvt_pk_bf16_f32 v148, v68, v69
	v_cvt_pk_bf16_f32 v149, v70, v71
	v_cvt_pk_bf16_f32 v142, v72, v73
	v_cvt_pk_bf16_f32 v143, v74, v75
	v_cvt_pk_bf16_f32 v144, v76, v77
	v_cvt_pk_bf16_f32 v145, v78, v79
	s_nop 0
	v_permlane32_swap_b32_e32 v134, v136
	v_permlane32_swap_b32_e32 v135, v137
	v_permlane32_swap_b32_e32 v138, v140
	v_permlane32_swap_b32_e32 v139, v141
	v_permlane32_swap_b32_e32 v146, v148
	v_permlane32_swap_b32_e32 v147, v149
	v_permlane32_swap_b32_e32 v142, v144
	v_permlane32_swap_b32_e32 v143, v145
	ds_read_b128 v[80:83], v153 offset:57344
	ds_read_b128 v[84:87], v153 offset:57472
	v_mov_b64_e32 v[110:111], s[18:19]
	v_mov_b64_e32 v[108:109], s[16:17]
	v_mov_b64_e32 v[106:107], s[14:15]
	v_mov_b64_e32 v[104:105], s[12:13]
	v_mov_b64_e32 v[102:103], s[10:11]
	v_mov_b64_e32 v[100:101], s[8:9]
	v_mov_b64_e32 v[98:99], s[6:7]
	v_mov_b64_e32 v[96:97], s[4:5]
	v_add_u32_e32 v171, v155, v154
	s_waitcnt lgkmcnt(1)
	v_mfma_f32_32x32x16_bf16 v[64:79], v[80:83], v[120:123], v[96:111]
	ds_read_b128 v[80:83], v152 offset:57344
	ds_read_b128 v[88:91], v153 offset:57600
	s_waitcnt lgkmcnt(1)
	v_mfma_f32_32x32x16_bf16 v[64:79], v[80:83], v[116:119], v[64:79]
	ds_read_b128 v[80:83], v151 offset:57344
	ds_read_b128 v[92:95], v151 offset:57472
	s_waitcnt lgkmcnt(1)
	v_mfma_f32_32x32x16_bf16 v[64:79], v[80:83], v[112:115], v[64:79]
	ds_read_b128 v[80:83], v150 offset:57344
	ds_read_b128 v[124:127], v171
	ds_read_b128 v[130:133], v151 offset:57600
	ds_read_b128 v[172:175], v171 offset:1024
	s_waitcnt lgkmcnt(2)
	v_mfma_f32_32x32x16_bf16 v[64:79], v[80:83], v[124:127], v[64:79]
	s_waitcnt lgkmcnt(0)
	v_mfma_f32_32x32x16_bf16 v[64:79], v[84:87], v[172:175], v[64:79]
	ds_read_b128 v[80:83], v152 offset:57472
	ds_read_b128 v[176:179], v171 offset:2048
	ds_read_b128 v[84:87], v152 offset:57600
	ds_read_b128 v[180:183], v171 offset:3072
	s_waitcnt lgkmcnt(2)
	v_mfma_f32_32x32x16_bf16 v[64:79], v[80:83], v[176:179], v[64:79]
	s_waitcnt lgkmcnt(0)
	v_mfma_f32_32x32x16_bf16 v[64:79], v[92:95], v[180:183], v[64:79]
	ds_read_b128 v[80:83], v150 offset:57472
	ds_read_b128 v[184:187], v171 offset:4096
	ds_read_b128 v[188:191], v171 offset:5120
	ds_read_b128 v[92:95], v150 offset:57600
	ds_read_b128 v[192:195], v171 offset:6144
	ds_read_b128 v[196:199], v171 offset:7168
	ds_read_b128 v[200:203], v165 offset:12288
	ds_read_b128 v[204:207], v165 offset:12416
	ds_read_b128 v[208:211], v163 offset:12288
	ds_read_b128 v[212:215], v163 offset:12416
	ds_read_b128 v[216:219], v166 offset:12416
	ds_read_b128 v[220:223], v166 offset:12544
	s_waitcnt lgkmcnt(10)
	v_mfma_f32_32x32x16_bf16 v[64:79], v[80:83], v[184:187], v[64:79]
	s_waitcnt lgkmcnt(9)
	v_mfma_f32_32x32x16_bf16 v[64:79], v[88:91], v[188:191], v[64:79]
	s_waitcnt lgkmcnt(7)
	v_mfma_f32_32x32x16_bf16 v[64:79], v[84:87], v[192:195], v[64:79]
	s_waitcnt lgkmcnt(6)
	v_mfma_f32_32x32x16_bf16 v[64:79], v[130:133], v[196:199], v[64:79]
	ds_read_b128 v[130:133], v166 offset:12288
	ds_read_b128 v[224:227], v171 offset:8192
	ds_read_b128 v[228:231], v164 offset:12288
	ds_read_b128 v[238:241], v165 offset:12544
	ds_read_b128 v[242:245], v164 offset:12416
	ds_read_b128 v[246:249], v164 offset:12544
	ds_read_b128 v[250:253], v163 offset:12544
	s_waitcnt lgkmcnt(5)
; #define WAIT_L0() asm volatile("s_waitcnt lgkmcnt(0)" ::: "memory")
; #define SBAR() __builtin_amdgcn_sched_barrier(0)
; __device__ __forceinline__ int v_rd_base(int lane) { return ((lane & 3) << 3) | (((lane >> 2) & 3) << 6) | (((lane >> 4) & 1) << 5) | (((lane >> 5) & 1) << 8); }
; #define V_COORDS(T) do { if constexpr (VC == 2) { const int sr = (T) >> 4, sc = ((T) & 15) * 8; vgo[0] = sr * LDV + sc; vgo[VC - 1] = (32 + sr) * LDV + sc; vlo[0] = v_st<NCB>(sr, sc); vlo[VC - 1] = v_st<NCB>(32 + sr, sc); } \
;     else { const int sr = (T) >> 3, sc = ((T) & 7) * 8; vgo[0] = sr * LDV + sc; vlo[0] = v_st<NCB>(sr, sc); } } while (0)
; template <int NCB, int D0> __device__ __forceinline__ void pv_one(f32x16& od, int vb, bf16x8 pa0, bf16x8 pa1, bf16x8 pa2, bf16x8 pa3) {
;   constexpr int KSTEP = NCB * 1024, HALF = NCB * 512, B0 = D0 * 512;
;   const s16x4 l0 = tr_read<B0>(vb), h0 = tr_read<B0 + HALF>(vb), l1 = tr_read<B0 + KSTEP>(vb), h1 = tr_read<B0 + KSTEP + HALF>(vb);
;   const s16x4 l2 = tr_read<B0 + 2 * KSTEP>(vb), h2 = tr_read<B0 + 2 * KSTEP + HALF>(vb), l3 = tr_read<B0 + 3 * KSTEP>(vb), h3 = tr_read<B0 + 3 * KSTEP + HALF>(vb);
;   WAIT_L0(); SBAR();
;     ...
;   od = __builtin_amdgcn_mfma_f32_32x32x16_bf16(pa0, PK(l0, h0), od, 0, 0, 0);
;   od = __builtin_amdgcn_mfma_f32_32x32x16_bf16(pa1, PK(l1, h1), od, 0, 0, 0);
;   od = __builtin_amdgcn_mfma_f32_32x32x16_bf16(pa2, PK(l2, h2), od, 0, 0, 0);
;   od = __builtin_amdgcn_mfma_f32_32x32x16_bf16(pa3, PK(l3, h3), od, 0, 0, 0);
;     ...
; }
;     ...
;   if constexpr (KDMA) {
;   } else {
; #pragma unroll
;     for (int i = 0; i < KC; ++i) { const int c = tid + i * 512, row = c / CPR, cc = c % CPR; kgo[i] = row * LDK + cc * 8; klo[i] = K_OFF + KSWZ(KRS, row, cc * 16); }
;     V_COORDS(tid);
;   }
;   const int vb0 = (int)(uintptr_t)shm + v_rd_base(lane);
;   int kofs[4];
; #pragma unroll
;   for (int b = 0; b < 4; ++b) kofs[b] = (r32 ^ ((r32 >> 3) & 1)) * KRS + ((b * 32 + hi * 16) ^ ((r32 & 7) << 4));
;   bf16x8 ks[KC], vs[VC];
	v_mfma_f32_32x32x16_bf16 v[64:79], v[92:95], v[224:227], v[64:79]
	v_mfma_f32_32x32x16_bf16 v[80:95], v[130:133], v[120:123], v[96:111]
	s_add_i32 s68, s23, 0x80
	s_ashr_i32 s69, s68, 31
	s_mul_i32 s20, s68, 0x600
	s_mul_hi_i32 s21, s68, 0x600
	s_add_u32 s20, s3, s20
	s_nop 1
	v_mov_b32_e32 v97, v157
	v_mfma_f32_32x32x16_bf16 v[80:95], v[200:203], v[116:119], v[80:95]
	v_mul_hi_i32 v99, v97, s82
	v_lshrrev_b32_e32 v100, 31, v99
	v_ashrrev_i32_e32 v99, 2, v99
	v_add_u32_e32 v99, v99, v100
	v_lshrrev_b32_e32 v101, 3, v99
	v_mul_lo_u32 v100, v99, 24
	v_bitop3_b32 v99, v101, v99, 1 bitop3:0x6c
	v_add_u32_e32 v101, 0x200, v97
	v_mul_hi_i32 v102, v101, s82
	v_sub_u32_e32 v100, v97, v100
	v_lshrrev_b32_e32 v103, 31, v102
	v_ashrrev_i32_e32 v102, 2, v102
	v_bitop3_b32 v100, v99, v100, 7 bitop3:0x6c
	v_mul_lo_u32 v99, v99, s85
	v_add_u32_e32 v102, v102, v103
	v_lshl_add_u32 v100, v100, 3, v99
	v_mul_lo_u32 v99, v102, 24
	v_lshlrev_b32_e32 v96, 3, v97
	v_lshlrev_b32_e32 v98, 5, v97
	v_sub_u32_e32 v99, v101, v99
	v_lshrrev_b32_e32 v101, 3, v102
	v_add_u32_e32 v97, 0x400, v97
	v_bitop3_b32 v101, v101, v102, 1 bitop3:0x6c
	v_mul_hi_i32 v102, v97, s82
	v_lshrrev_b32_e32 v103, 31, v102
	v_ashrrev_i32_e32 v102, 2, v102
	v_add_u32_e32 v103, v102, v103
	v_bitop3_b32 v99, v101, v99, 7 bitop3:0x6c
	v_mul_lo_u32 v101, v101, s85
	v_mul_lo_u32 v102, v103, 24
	v_sub_u32_e32 v97, v97, v102
	v_lshl_add_u32 v102, v99, 3, v101
	v_lshrrev_b32_e32 v99, 3, v103
	s_waitcnt lgkmcnt(4)
	v_mfma_f32_32x32x16_bf16 v[80:95], v[228:231], v[112:115], v[80:95]
	v_bitop3_b32 v99, v99, v103, 1 bitop3:0x6c
	v_bitop3_b32 v97, v99, v97, 7 bitop3:0x6c
	v_mul_lo_u32 v99, v99, s85
	s_addc_u32 s21, s36, s21
	v_ashrrev_i32_e32 v101, 31, v100
	v_readfirstlane_b32 s38, v160
	v_lshl_add_u32 v104, v97, 3, v99
	v_lshl_add_u64 v[100:101], v[100:101], 1, s[20:21]
	s_mov_b32 m0, s38
	v_ashrrev_i32_e32 v103, 31, v102
	v_readfirstlane_b32 s38, v161
	global_load_lds_dwordx4 v[100:101], off
	v_lshl_add_u64 v[100:101], v[102:103], 1, s[20:21]
	s_mov_b32 m0, s38
	v_ashrrev_i32_e32 v105, 31, v104
	v_and_b32_e32 v96, 0x78, v96
	global_load_lds_dwordx4 v[100:101], off
	v_lshl_add_u64 v[100:101], v[104:105], 1, s[20:21]
	s_lshl_b64 s[20:21], s[68:69], 10
	v_and_or_b32 v96, v98, s24, v96
	v_readfirstlane_b32 s38, v162
	s_add_u32 s20, s83, s20
	v_add_u32_e32 v98, 0x4000, v96
	s_mov_b32 m0, s38
	s_addc_u32 s21, s93, s21
	v_ashrrev_i32_e32 v97, 31, v96
	global_load_lds_dwordx4 v[100:101], off
	v_lshl_add_u64 v[96:97], v[96:97], 1, s[20:21]
	v_ashrrev_i32_e32 v99, 31, v98
	v_mfma_f32_32x32x16_bf16 v[80:95], v[208:211], v[124:127], v[80:95]
	v_lshl_add_u64 v[98:99], v[98:99], 1, s[20:21]
	global_load_dwordx4 v[130:133], v[96:97], off
	global_load_dwordx4 v[124:127], v[98:99], off
	v_mfma_f32_32x32x16_bf16 v[80:95], v[216:219], v[172:175], v[80:95]
	v_mfma_f32_32x32x16_bf16 v[80:95], v[204:207], v[176:179], v[80:95]
	s_waitcnt lgkmcnt(0)
	v_mfma_f32_32x32x16_bf16 v[80:95], v[242:245], v[180:183], v[80:95]
	v_mfma_f32_32x32x16_bf16 v[80:95], v[212:215], v[184:187], v[80:95]
	v_mfma_f32_32x32x16_bf16 v[80:95], v[220:223], v[188:191], v[80:95]
	v_mfma_f32_32x32x16_bf16 v[80:95], v[238:241], v[192:195], v[80:95]
	v_mfma_f32_32x32x16_bf16 v[80:95], v[246:249], v[196:199], v[80:95]
	v_mfma_f32_32x32x16_bf16 v[80:95], v[250:253], v[224:227], v[80:95]
	ds_read_b64_tr_b16 v[96:97], v159 offset:0
	ds_read_b64_tr_b16 v[98:99], v159 offset:0x800
	ds_read_b64_tr_b16 v[100:101], v159 offset:0x1000
	ds_read_b64_tr_b16 v[102:103], v159 offset:0x1800
	ds_read_b64_tr_b16 v[104:105], v159 offset:0x2000
	ds_read_b64_tr_b16 v[106:107], v159 offset:0x2800
	ds_read_b64_tr_b16 v[108:109], v159 offset:0x3000
	ds_read_b64_tr_b16 v[110:111], v159 offset:0x3800
	s_nop 0
	s_waitcnt lgkmcnt(6)
	v_mfma_f32_32x32x16_bf16 v[0:15], v[134:137], v[96:99], v[0:15]
	ds_read_b64_tr_b16 v[96:97], v159 offset:0x200
	ds_read_b64_tr_b16 v[98:99], v159 offset:0xa00
	s_waitcnt lgkmcnt(6)
	v_mfma_f32_32x32x16_bf16 v[0:15], v[138:141], v[100:103], v[0:15]
	ds_read_b64_tr_b16 v[100:101], v159 offset:0x1200
	ds_read_b64_tr_b16 v[102:103], v159 offset:0x1a00
	s_waitcnt lgkmcnt(6)
	v_mfma_f32_32x32x16_bf16 v[0:15], v[146:149], v[104:107], v[0:15]
	ds_read_b64_tr_b16 v[104:105], v159 offset:0x2200
	ds_read_b64_tr_b16 v[106:107], v159 offset:0x2a00
	s_waitcnt lgkmcnt(6)
	v_mfma_f32_32x32x16_bf16 v[0:15], v[142:145], v[108:111], v[0:15]
	ds_read_b64_tr_b16 v[108:109], v159 offset:0x3200
	ds_read_b64_tr_b16 v[110:111], v159 offset:0x3a00
	s_waitcnt lgkmcnt(6)
	v_mfma_f32_32x32x16_bf16 v[48:63], v[134:137], v[96:99], v[48:63]
	ds_read_b64_tr_b16 v[96:97], v159 offset:0x400
	ds_read_b64_tr_b16 v[98:99], v159 offset:0xc00
	s_waitcnt lgkmcnt(6)
	v_mfma_f32_32x32x16_bf16 v[48:63], v[138:141], v[100:103], v[48:63]
	ds_read_b64_tr_b16 v[100:101], v159 offset:0x1400
	ds_read_b64_tr_b16 v[102:103], v159 offset:0x1c00
	s_waitcnt lgkmcnt(6)
	v_mfma_f32_32x32x16_bf16 v[48:63], v[146:149], v[104:107], v[48:63]
	ds_read_b64_tr_b16 v[104:105], v159 offset:0x2400
	ds_read_b64_tr_b16 v[106:107], v159 offset:0x2c00
	s_waitcnt lgkmcnt(6)
	v_mfma_f32_32x32x16_bf16 v[48:63], v[142:145], v[108:111], v[48:63]
	ds_read_b64_tr_b16 v[108:109], v159 offset:0x3400
	ds_read_b64_tr_b16 v[110:111], v159 offset:0x3c00
	s_waitcnt lgkmcnt(6)
	v_mfma_f32_32x32x16_bf16 v[32:47], v[134:137], v[96:99], v[32:47]
	ds_read_b64_tr_b16 v[96:97], v159 offset:0x600
	ds_read_b64_tr_b16 v[98:99], v159 offset:0xe00
	s_waitcnt lgkmcnt(6)
	v_mfma_f32_32x32x16_bf16 v[32:47], v[138:141], v[100:103], v[32:47]
	ds_read_b64_tr_b16 v[100:101], v159 offset:0x1600
	ds_read_b64_tr_b16 v[102:103], v159 offset:0x1e00
	s_waitcnt lgkmcnt(6)
	v_mfma_f32_32x32x16_bf16 v[32:47], v[146:149], v[104:107], v[32:47]
	ds_read_b64_tr_b16 v[104:105], v159 offset:0x2600
	ds_read_b64_tr_b16 v[106:107], v159 offset:0x2e00
	s_waitcnt lgkmcnt(6)
	v_mfma_f32_32x32x16_bf16 v[32:47], v[142:145], v[108:111], v[32:47]
	ds_read_b64_tr_b16 v[108:109], v159 offset:0x3600
	ds_read_b64_tr_b16 v[110:111], v159 offset:0x3e00
	s_waitcnt lgkmcnt(6)
	v_mfma_f32_32x32x16_bf16 v[16:31], v[134:137], v[96:99], v[16:31]
	s_add_i32 s20, s23, 64
	v_lshlrev_b32_e32 v96, 2, v128
	s_cmp_le_i32 s20, s59
	v_add_u32_e32 v170, s23, v96
	s_waitcnt lgkmcnt(4)
	v_mfma_f32_32x32x16_bf16 v[16:31], v[138:141], v[100:103], v[16:31]
	s_waitcnt lgkmcnt(2)
	v_mfma_f32_32x32x16_bf16 v[16:31], v[146:149], v[104:107], v[16:31]
	s_waitcnt lgkmcnt(0)
	v_mfma_f32_32x32x16_bf16 v[16:31], v[142:145], v[108:111], v[16:31]
	s_cbranch_scc1 .LBB0_432
; __device__ __forceinline__ int crow(int r, int hi) { return (r & 3) + 8 * (r >> 2) + 4 * hi; }
; template <bool GM>
; __device__ __forceinline__ void partialSM(f32x16& p0, f32x16& p1, bool mask, int kbase, int L, int qpos, int hi) {
;   if (mask) {
; #pragma unroll
;     for (int r = 0; r < 16; ++r) {
;       int k = kbase + crow(r, hi);
;       asm volatile("" : "+v"(k) : "v"(p0[r]));
;       bool ok = k < L;
;       if (GM) ok = ok && (k < 16 || abs(qpos - k) <= 128);
;       p0[r] = ok ? p0[r] : -1e30f;
;       int k2 = k + 32;
;       asm volatile("" : "+v"(k2) : "v"(p1[r]));
;       bool ok2 = k2 < L;
;       if (GM) ok2 = ok2 && (k2 < 16 || abs(qpos - k2) <= 128);
;       p1[r] = ok2 ? p1[r] : -1e30f;
;     }
;   }
	v_add_u32_e32 v96, 64, v170
	s_nop 0
	v_cmp_gt_i32_e32 vcc, s94, v96
	v_add_u32_e32 v96, 32, v96
	s_nop 0
	v_cndmask_b32_e32 v64, v233, v64, vcc
	v_cmp_gt_i32_e32 vcc, s94, v96
	v_add_u32_e32 v96, 0x41, v170
	s_nop 0
	v_cndmask_b32_e32 v80, v233, v80, vcc
	v_cmp_gt_i32_e32 vcc, s94, v96
	v_add_u32_e32 v96, 32, v96
	s_nop 0
	v_cndmask_b32_e32 v65, v233, v65, vcc
	v_cmp_gt_i32_e32 vcc, s94, v96
	v_add_u32_e32 v96, 0x42, v170
	s_nop 0
	v_cndmask_b32_e32 v81, v233, v81, vcc
	v_cmp_gt_i32_e32 vcc, s94, v96
	v_add_u32_e32 v96, 32, v96
	s_nop 0
	v_cndmask_b32_e32 v66, v233, v66, vcc
	v_cmp_gt_i32_e32 vcc, s94, v96
	v_add_u32_e32 v96, 0x43, v170
	s_nop 0
	v_cndmask_b32_e32 v82, v233, v82, vcc
	v_cmp_gt_i32_e32 vcc, s94, v96
	v_add_u32_e32 v96, 32, v96
	s_nop 0
	v_cndmask_b32_e32 v67, v233, v67, vcc
	v_cmp_gt_i32_e32 vcc, s94, v96
	v_add_u32_e32 v96, 0x48, v170
	s_nop 0
	v_cndmask_b32_e32 v83, v233, v83, vcc
	v_cmp_gt_i32_e32 vcc, s94, v96
	v_add_u32_e32 v96, 32, v96
	s_nop 0
	v_cndmask_b32_e32 v68, v233, v68, vcc
	v_cmp_gt_i32_e32 vcc, s94, v96
	v_add_u32_e32 v96, 0x49, v170
	s_nop 0
	v_cndmask_b32_e32 v84, v233, v84, vcc
	v_cmp_gt_i32_e32 vcc, s94, v96
	v_add_u32_e32 v96, 32, v96
	s_nop 0
	v_cndmask_b32_e32 v69, v233, v69, vcc
	v_cmp_gt_i32_e32 vcc, s94, v96
	v_add_u32_e32 v96, 0x4a, v170
	s_nop 0
	v_cndmask_b32_e32 v85, v233, v85, vcc
	v_cmp_gt_i32_e32 vcc, s94, v96
	v_add_u32_e32 v96, 32, v96
	s_nop 0
	v_cndmask_b32_e32 v70, v233, v70, vcc
	v_cmp_gt_i32_e32 vcc, s94, v96
	v_add_u32_e32 v96, 0x4b, v170
	s_nop 0
	v_cndmask_b32_e32 v86, v233, v86, vcc
	v_cmp_gt_i32_e32 vcc, s94, v96
	v_add_u32_e32 v96, 32, v96
	s_nop 0
	v_cndmask_b32_e32 v71, v233, v71, vcc
	v_cmp_gt_i32_e32 vcc, s94, v96
	v_add_u32_e32 v96, 0x50, v170
	s_nop 0
	v_cndmask_b32_e32 v87, v233, v87, vcc
	v_cmp_gt_i32_e32 vcc, s94, v96
	v_add_u32_e32 v96, 32, v96
	s_nop 0
	v_cndmask_b32_e32 v72, v233, v72, vcc
	v_cmp_gt_i32_e32 vcc, s94, v96
	v_add_u32_e32 v96, 0x51, v170
	s_nop 0
	v_cndmask_b32_e32 v88, v233, v88, vcc
	v_cmp_gt_i32_e32 vcc, s94, v96
	v_add_u32_e32 v96, 32, v96
	s_nop 0
	v_cndmask_b32_e32 v73, v233, v73, vcc
	v_cmp_gt_i32_e32 vcc, s94, v96
	v_add_u32_e32 v96, 0x52, v170
	s_nop 0
	v_cndmask_b32_e32 v89, v233, v89, vcc
	v_cmp_gt_i32_e32 vcc, s94, v96
	v_add_u32_e32 v96, 32, v96
	s_nop 0
	v_cndmask_b32_e32 v74, v233, v74, vcc
	v_cmp_gt_i32_e32 vcc, s94, v96
	v_add_u32_e32 v96, 0x53, v170
	s_nop 0
	v_cndmask_b32_e32 v90, v233, v90, vcc
	v_cmp_gt_i32_e32 vcc, s94, v96
	v_add_u32_e32 v96, 32, v96
	s_nop 0
	v_cndmask_b32_e32 v75, v233, v75, vcc
	v_cmp_gt_i32_e32 vcc, s94, v96
	v_add_u32_e32 v96, 0x58, v170
	s_nop 0
	v_cndmask_b32_e32 v91, v233, v91, vcc
	v_cmp_gt_i32_e32 vcc, s94, v96
	v_add_u32_e32 v96, 32, v96
	s_nop 0
	v_cndmask_b32_e32 v76, v233, v76, vcc
	v_cmp_gt_i32_e32 vcc, s94, v96
	v_add_u32_e32 v96, 0x59, v170
	s_nop 0
	v_cndmask_b32_e32 v92, v233, v92, vcc
	v_cmp_gt_i32_e32 vcc, s94, v96
	v_add_u32_e32 v96, 32, v96
	s_nop 0
	v_cndmask_b32_e32 v77, v233, v77, vcc
	v_cmp_gt_i32_e32 vcc, s94, v96
	v_add_u32_e32 v96, 0x5a, v170
	s_nop 0
	v_cndmask_b32_e32 v93, v233, v93, vcc
	v_cmp_gt_i32_e32 vcc, s94, v96
	v_add_u32_e32 v96, 32, v96
	s_nop 0
	v_cndmask_b32_e32 v78, v233, v78, vcc
	v_cmp_gt_i32_e32 vcc, s94, v96
	v_add_u32_e32 v96, 0x5b, v170
	s_nop 0
	v_cndmask_b32_e32 v94, v233, v94, vcc
	v_cmp_gt_i32_e32 vcc, s94, v96
	v_add_u32_e32 v96, 32, v96
	s_nop 0
	v_cndmask_b32_e32 v79, v233, v79, vcc
	v_cmp_gt_i32_e32 vcc, s94, v96
	s_nop 1
	v_cndmask_b32_e32 v95, v233, v95, vcc

; #define WAIT_L0() asm volatile("s_waitcnt lgkmcnt(0)" ::: "memory")
; #define SBAR() __builtin_amdgcn_sched_barrier(0)
; __device__ __forceinline__ int crow(int r, int hi) { return (r & 3) + 8 * (r >> 2) + 4 * hi; }
; template <bool GM>
; __device__ __forceinline__ void partialSM(f32x16& p0, f32x16& p1, bool mask, int kbase, int L, int qpos, int hi) {
;   if (mask) {
; #pragma unroll
;     for (int r = 0; r < 16; ++r) {
;       int k = kbase + crow(r, hi);
;       asm volatile("" : "+v"(k) : "v"(p0[r]));
;       bool ok = k < L;
;       if (GM) ok = ok && (k < 16 || abs(qpos - k) <= 128);
;       p0[r] = ok ? p0[r] : -1e30f;
;       int k2 = k + 32;
;       asm volatile("" : "+v"(k2) : "v"(p1[r]));
;       bool ok2 = k2 < L;
;       if (GM) ok2 = ok2 && (k2 < 16 || abs(qpos - k2) <= 128);
;       p1[r] = ok2 ? p1[r] : -1e30f;
;     }
; template <int NCB, int D0> __device__ __forceinline__ void pv_one(f32x16& od, int vb, bf16x8 pa0, bf16x8 pa1, bf16x8 pa2, bf16x8 pa3) {
;   constexpr int KSTEP = NCB * 1024, HALF = NCB * 512, B0 = D0 * 512;
;   const s16x4 l0 = tr_read<B0>(vb), h0 = tr_read<B0 + HALF>(vb), l1 = tr_read<B0 + KSTEP>(vb), h1 = tr_read<B0 + KSTEP + HALF>(vb);
;   const s16x4 l2 = tr_read<B0 + 2 * KSTEP>(vb), h2 = tr_read<B0 + 2 * KSTEP + HALF>(vb), l3 = tr_read<B0 + 3 * KSTEP>(vb), h3 = tr_read<B0 + 3 * KSTEP + HALF>(vb);
;   WAIT_L0(); SBAR();
;     ...
;   od = __builtin_amdgcn_mfma_f32_32x32x16_bf16(pa0, PK(l0, h0), od, 0, 0, 0);
;   od = __builtin_amdgcn_mfma_f32_32x32x16_bf16(pa1, PK(l1, h1), od, 0, 0, 0);
;   od = __builtin_amdgcn_mfma_f32_32x32x16_bf16(pa2, PK(l2, h2), od, 0, 0, 0);
;   od = __builtin_amdgcn_mfma_f32_32x32x16_bf16(pa3, PK(l3, h3), od, 0, 0, 0);
;     ...
; }
; template <int NCB> __device__ __forceinline__ void pv_all(f32x16 (&o)[NCB], int vb, bf16x8 pa0, bf16x8 pa1, bf16x8 pa2, bf16x8 pa3) {
;   pv_one<NCB, 0>(o[0], vb, pa0, pa1, pa2, pa3); pv_one<NCB, 1>(o[1], vb, pa0, pa1, pa2, pa3);
;   if constexpr (NCB == 4) { pv_one<NCB, 2>(o[2], vb, pa0, pa1, pa2, pa3); pv_one<NCB, 3>(o[3], vb, pa0, pa1, pa2, pa3); }
; }
.LBB0_434:
	ds_read_b64_tr_b16 v[96:97], v156 offset:0
	ds_read_b64_tr_b16 v[98:99], v156 offset:0x800
	ds_read_b64_tr_b16 v[100:101], v156 offset:0x1000
	ds_read_b64_tr_b16 v[102:103], v156 offset:0x1800
	ds_read_b64_tr_b16 v[104:105], v156 offset:0x2000
	ds_read_b64_tr_b16 v[106:107], v156 offset:0x2800
	ds_read_b64_tr_b16 v[108:109], v156 offset:0x3000
	ds_read_b64_tr_b16 v[110:111], v156 offset:0x3800
	s_nop 0
	s_waitcnt lgkmcnt(6)
	v_mfma_f32_32x32x16_bf16 v[0:15], v[134:137], v[96:99], v[0:15]
	ds_read_b64_tr_b16 v[96:97], v156 offset:0x200
	ds_read_b64_tr_b16 v[98:99], v156 offset:0xa00
	s_waitcnt lgkmcnt(6)
	v_mfma_f32_32x32x16_bf16 v[0:15], v[138:141], v[100:103], v[0:15]
	ds_read_b64_tr_b16 v[100:101], v156 offset:0x1200
	ds_read_b64_tr_b16 v[102:103], v156 offset:0x1a00
	s_waitcnt lgkmcnt(6)
	v_mfma_f32_32x32x16_bf16 v[0:15], v[142:145], v[104:107], v[0:15]
	ds_read_b64_tr_b16 v[104:105], v156 offset:0x2200
	ds_read_b64_tr_b16 v[106:107], v156 offset:0x2a00
	s_waitcnt lgkmcnt(6)
	v_mfma_f32_32x32x16_bf16 v[0:15], v[146:149], v[108:111], v[0:15]
	ds_read_b64_tr_b16 v[108:109], v156 offset:0x3200
	ds_read_b64_tr_b16 v[110:111], v156 offset:0x3a00
	s_waitcnt lgkmcnt(6)
	v_mfma_f32_32x32x16_bf16 v[48:63], v[134:137], v[96:99], v[48:63]
	ds_read_b64_tr_b16 v[96:97], v156 offset:0x400
	ds_read_b64_tr_b16 v[98:99], v156 offset:0xc00
	s_waitcnt lgkmcnt(6)
	v_mfma_f32_32x32x16_bf16 v[48:63], v[138:141], v[100:103], v[48:63]
	ds_read_b64_tr_b16 v[100:101], v156 offset:0x1400
	ds_read_b64_tr_b16 v[102:103], v156 offset:0x1c00
	s_waitcnt lgkmcnt(6)
	v_mfma_f32_32x32x16_bf16 v[48:63], v[142:145], v[104:107], v[48:63]
	ds_read_b64_tr_b16 v[104:105], v156 offset:0x2400
	ds_read_b64_tr_b16 v[106:107], v156 offset:0x2c00
	s_waitcnt lgkmcnt(6)
	v_mfma_f32_32x32x16_bf16 v[48:63], v[146:149], v[108:111], v[48:63]
	ds_read_b64_tr_b16 v[108:109], v156 offset:0x3400
	ds_read_b64_tr_b16 v[110:111], v156 offset:0x3c00
	s_waitcnt lgkmcnt(6)
	v_mfma_f32_32x32x16_bf16 v[32:47], v[134:137], v[96:99], v[32:47]
	ds_read_b64_tr_b16 v[96:97], v156 offset:0x600
	ds_read_b64_tr_b16 v[98:99], v156 offset:0xe00
	s_waitcnt lgkmcnt(6)
	v_mfma_f32_32x32x16_bf16 v[32:47], v[138:141], v[100:103], v[32:47]
	ds_read_b64_tr_b16 v[100:101], v156 offset:0x1600
	ds_read_b64_tr_b16 v[102:103], v156 offset:0x1e00
	s_waitcnt lgkmcnt(6)
	v_mfma_f32_32x32x16_bf16 v[32:47], v[142:145], v[104:107], v[32:47]
	ds_read_b64_tr_b16 v[104:105], v156 offset:0x2600
	ds_read_b64_tr_b16 v[106:107], v156 offset:0x2e00
	s_waitcnt lgkmcnt(6)
	v_mfma_f32_32x32x16_bf16 v[32:47], v[146:149], v[108:111], v[32:47]
	ds_read_b64_tr_b16 v[108:109], v156 offset:0x3600
	ds_read_b64_tr_b16 v[110:111], v156 offset:0x3e00
	s_waitcnt lgkmcnt(6)
	v_mfma_f32_32x32x16_bf16 v[16:31], v[134:137], v[96:99], v[16:31]
	s_cmp_le_i32 s68, s59
	s_waitcnt lgkmcnt(4)
	v_mfma_f32_32x32x16_bf16 v[16:31], v[138:141], v[100:103], v[16:31]
	s_waitcnt lgkmcnt(2)
	v_mfma_f32_32x32x16_bf16 v[16:31], v[142:145], v[104:107], v[16:31]
	s_waitcnt lgkmcnt(0)
	v_mfma_f32_32x32x16_bf16 v[16:31], v[146:149], v[108:111], v[16:31]
	s_cbranch_scc1 .LBB0_436
	v_add_u32_e32 v96, 0x80, v170
	s_nop 0
	v_cmp_gt_i32_e32 vcc, s94, v96
	v_add_u32_e32 v96, 32, v96
	s_nop 0
	v_cndmask_b32_e32 v80, v233, v80, vcc
	v_cmp_gt_i32_e32 vcc, s94, v96
	v_add_u32_e32 v96, 0x81, v170
	s_nop 0
	v_cndmask_b32_e32 v64, v233, v64, vcc
	v_cmp_gt_i32_e32 vcc, s94, v96
	v_add_u32_e32 v96, 32, v96
	s_nop 0
	v_cndmask_b32_e32 v81, v233, v81, vcc
	v_cmp_gt_i32_e32 vcc, s94, v96
	v_add_u32_e32 v96, 0x82, v170
	s_nop 0
	v_cndmask_b32_e32 v65, v233, v65, vcc
	v_cmp_gt_i32_e32 vcc, s94, v96
	v_add_u32_e32 v96, 32, v96
	s_nop 0
	v_cndmask_b32_e32 v82, v233, v82, vcc
	v_cmp_gt_i32_e32 vcc, s94, v96
	v_add_u32_e32 v96, 0x83, v170
	s_nop 0
	v_cndmask_b32_e32 v66, v233, v66, vcc
	v_cmp_gt_i32_e32 vcc, s94, v96
	v_add_u32_e32 v96, 32, v96
	s_nop 0
	v_cndmask_b32_e32 v83, v233, v83, vcc
	v_cmp_gt_i32_e32 vcc, s94, v96
	v_add_u32_e32 v96, 0x88, v170
	s_nop 0
	v_cndmask_b32_e32 v67, v233, v67, vcc
	v_cmp_gt_i32_e32 vcc, s94, v96
	v_add_u32_e32 v96, 32, v96
	s_nop 0
	v_cndmask_b32_e32 v84, v233, v84, vcc
	v_cmp_gt_i32_e32 vcc, s94, v96
	v_add_u32_e32 v96, 0x89, v170
	s_nop 0
	v_cndmask_b32_e32 v68, v233, v68, vcc
	v_cmp_gt_i32_e32 vcc, s94, v96
	v_add_u32_e32 v96, 32, v96
	s_nop 0
	v_cndmask_b32_e32 v85, v233, v85, vcc
	v_cmp_gt_i32_e32 vcc, s94, v96
	v_add_u32_e32 v96, 0x8a, v170
	s_nop 0
	v_cndmask_b32_e32 v69, v233, v69, vcc
	v_cmp_gt_i32_e32 vcc, s94, v96
	v_add_u32_e32 v96, 32, v96
	s_nop 0
	v_cndmask_b32_e32 v86, v233, v86, vcc
	v_cmp_gt_i32_e32 vcc, s94, v96
	v_add_u32_e32 v96, 0x8b, v170
	s_nop 0
	v_cndmask_b32_e32 v70, v233, v70, vcc
	v_cmp_gt_i32_e32 vcc, s94, v96
	v_add_u32_e32 v96, 32, v96
	s_nop 0
	v_cndmask_b32_e32 v87, v233, v87, vcc
	v_cmp_gt_i32_e32 vcc, s94, v96
	v_add_u32_e32 v96, 0x90, v170
	s_nop 0
	v_cndmask_b32_e32 v71, v233, v71, vcc
	v_cmp_gt_i32_e32 vcc, s94, v96
	v_add_u32_e32 v96, 32, v96
	s_nop 0
	v_cndmask_b32_e32 v88, v233, v88, vcc
	v_cmp_gt_i32_e32 vcc, s94, v96
	v_add_u32_e32 v96, 0x91, v170
	s_nop 0
	v_cndmask_b32_e32 v72, v233, v72, vcc
	v_cmp_gt_i32_e32 vcc, s94, v96
	v_add_u32_e32 v96, 32, v96
	s_nop 0
	v_cndmask_b32_e32 v89, v233, v89, vcc
	v_cmp_gt_i32_e32 vcc, s94, v96
	v_add_u32_e32 v96, 0x92, v170
	s_nop 0
	v_cndmask_b32_e32 v73, v233, v73, vcc
	v_cmp_gt_i32_e32 vcc, s94, v96
	v_add_u32_e32 v96, 32, v96
	s_nop 0
	v_cndmask_b32_e32 v90, v233, v90, vcc
	v_cmp_gt_i32_e32 vcc, s94, v96
	v_add_u32_e32 v96, 0x93, v170
	s_nop 0
	v_cndmask_b32_e32 v74, v233, v74, vcc
	v_cmp_gt_i32_e32 vcc, s94, v96
	v_add_u32_e32 v96, 32, v96
	s_nop 0
	v_cndmask_b32_e32 v91, v233, v91, vcc
	v_cmp_gt_i32_e32 vcc, s94, v96
	v_add_u32_e32 v96, 0x98, v170
	s_nop 0
	v_cndmask_b32_e32 v75, v233, v75, vcc
	v_cmp_gt_i32_e32 vcc, s94, v96
	v_add_u32_e32 v96, 32, v96
	s_nop 0
	v_cndmask_b32_e32 v92, v233, v92, vcc
	v_cmp_gt_i32_e32 vcc, s94, v96
	v_add_u32_e32 v96, 0x99, v170
	s_nop 0
	v_cndmask_b32_e32 v76, v233, v76, vcc
	v_cmp_gt_i32_e32 vcc, s94, v96
	v_add_u32_e32 v96, 32, v96
	s_nop 0
	v_cndmask_b32_e32 v93, v233, v93, vcc
	v_cmp_gt_i32_e32 vcc, s94, v96
	v_add_u32_e32 v96, 0x9a, v170
	s_nop 0
	v_cndmask_b32_e32 v77, v233, v77, vcc
	v_cmp_gt_i32_e32 vcc, s94, v96
	v_add_u32_e32 v96, 32, v96
	s_nop 0
	v_cndmask_b32_e32 v94, v233, v94, vcc
	v_cmp_gt_i32_e32 vcc, s94, v96
	v_add_u32_e32 v96, 0x9b, v170
	s_nop 0
	v_cndmask_b32_e32 v78, v233, v78, vcc
	v_cmp_gt_i32_e32 vcc, s94, v96
	v_add_u32_e32 v96, 32, v96
	s_nop 0
	v_cndmask_b32_e32 v95, v233, v95, vcc
	v_cmp_gt_i32_e32 vcc, s94, v96
	s_nop 1
	v_cndmask_b32_e32 v79, v233, v79, vcc

; #define WAIT_L0() asm volatile("s_waitcnt lgkmcnt(0)" ::: "memory")
; #define SBAR() __builtin_amdgcn_sched_barrier(0)
; __device__ __forceinline__ void finishSM(f32x16& p0, f32x16& p1, float& l_reg, bf16x8& pa0, bf16x8& pa1, bf16x8& pa2, bf16x8& pa3) {
; #pragma unroll
;   for (int r = 0; r < 16; ++r) p1[r] = __builtin_amdgcn_exp2f(p1[r]);
;   float ps = 0;
; #pragma unroll
;   for (int r = 0; r < 16; ++r) ps += p0[r];
; #pragma unroll
;   for (int r = 0; r < 16; ++r) ps += p1[r];
;   { auto rr = __builtin_amdgcn_permlane32_swap(__float_as_uint(ps), __float_as_uint(ps), false, false);
;     ps = __uint_as_float(rr[0]) + __uint_as_float(rr[1]); }
;   l_reg += ps;
;     ...
;   PK4(p0, 0, pa0); PK4(p0, 8, pa1); PK4(p1, 0, pa2); PK4(p1, 8, pa3);
;     ...
; }
; template <int NCB, int D0> __device__ __forceinline__ void pv_one(f32x16& od, int vb, bf16x8 pa0, bf16x8 pa1, bf16x8 pa2, bf16x8 pa3) {
;   constexpr int KSTEP = NCB * 1024, HALF = NCB * 512, B0 = D0 * 512;
;   const s16x4 l0 = tr_read<B0>(vb), h0 = tr_read<B0 + HALF>(vb), l1 = tr_read<B0 + KSTEP>(vb), h1 = tr_read<B0 + KSTEP + HALF>(vb);
;   const s16x4 l2 = tr_read<B0 + 2 * KSTEP>(vb), h2 = tr_read<B0 + 2 * KSTEP + HALF>(vb), l3 = tr_read<B0 + 3 * KSTEP>(vb), h3 = tr_read<B0 + 3 * KSTEP + HALF>(vb);
;   WAIT_L0(); SBAR();
;     ...
;   od = __builtin_amdgcn_mfma_f32_32x32x16_bf16(pa0, PK(l0, h0), od, 0, 0, 0);
;   od = __builtin_amdgcn_mfma_f32_32x32x16_bf16(pa1, PK(l1, h1), od, 0, 0, 0);
;   od = __builtin_amdgcn_mfma_f32_32x32x16_bf16(pa2, PK(l2, h2), od, 0, 0, 0);
;   od = __builtin_amdgcn_mfma_f32_32x32x16_bf16(pa3, PK(l3, h3), od, 0, 0, 0);
;     ...
; }
; template <int NCB> __device__ __forceinline__ void pv_all(f32x16 (&o)[NCB], int vb, bf16x8 pa0, bf16x8 pa1, bf16x8 pa2, bf16x8 pa3) {
;   pv_one<NCB, 0>(o[0], vb, pa0, pa1, pa2, pa3); pv_one<NCB, 1>(o[1], vb, pa0, pa1, pa2, pa3);
;   if constexpr (NCB == 4) { pv_one<NCB, 2>(o[2], vb, pa0, pa1, pa2, pa3); pv_one<NCB, 3>(o[3], vb, pa0, pa1, pa2, pa3); }
; }
.LBB0_441:
	v_exp_f32_e32 v144, v64
	v_exp_f32_e32 v145, v65
	v_exp_f32_e32 v146, v66
	v_exp_f32_e32 v147, v67
	v_exp_f32_e32 v148, v68
	v_exp_f32_e32 v149, v69
	v_exp_f32_e32 v157, v70
	v_exp_f32_e32 v160, v71
	v_exp_f32_e32 v136, v72
	v_exp_f32_e32 v137, v73
	v_exp_f32_e32 v138, v74
	v_exp_f32_e32 v139, v75
	v_exp_f32_e32 v140, v76
	v_exp_f32_e32 v141, v77
	v_exp_f32_e32 v142, v78
	v_exp_f32_e32 v143, v79
	v_add_f32_e32 v64, 0, v132
	v_add_f32_e32 v135, v133, v64
	s_movk_i32 s93, 0x1000
	s_mov_b64 s[20:21], -1
	s_cmp_ge_i32 s22, s54
	s_cbranch_scc0 .LBB0_443
	v_add_f32_e32 v64, v130, v135
	v_add_f32_e32 v64, v131, v64
	v_add_f32_e32 v64, v126, v64
	v_add_f32_e32 v64, v127, v64
	v_add_f32_e32 v64, v124, v64
	v_add_f32_e32 v64, v125, v64
	v_add_f32_e32 v64, v110, v64
	v_add_f32_e32 v64, v111, v64
	v_add_f32_e32 v64, v108, v64
	v_add_f32_e32 v64, v109, v64
	v_add_f32_e32 v64, v106, v64
	v_add_f32_e32 v64, v107, v64
	v_add_f32_e32 v64, v104, v64
	v_add_f32_e32 v64, v105, v64
	v_add_f32_e32 v64, v144, v64
	v_add_f32_e32 v64, v145, v64
	v_add_f32_e32 v64, v146, v64
	v_add_f32_e32 v64, v147, v64
	v_add_f32_e32 v64, v148, v64
	v_add_f32_e32 v64, v149, v64
	v_add_f32_e32 v64, v157, v64
	v_add_f32_e32 v64, v160, v64
	v_add_f32_e32 v64, v136, v64
	v_add_f32_e32 v64, v137, v64
	v_add_f32_e32 v64, v138, v64
	v_add_f32_e32 v64, v139, v64
	v_add_f32_e32 v64, v140, v64
	v_add_f32_e32 v64, v141, v64
	v_add_f32_e32 v64, v142, v64
	v_add_f32_e32 v64, v143, v64
	v_mov_b32_e32 v65, v64
	s_nop 1
	v_permlane32_swap_b32_e32 v64, v65
	v_add_f32_e32 v64, v64, v65
	v_add_f32_e32 v134, v158, v64
	v_cvt_pk_bf16_f32 v168, v132, v133
	v_cvt_pk_bf16_f32 v169, v130, v131
	v_cvt_pk_bf16_f32 v170, v126, v127
	v_cvt_pk_bf16_f32 v171, v124, v125
	v_cvt_pk_bf16_f32 v172, v110, v111
	v_cvt_pk_bf16_f32 v173, v108, v109
	v_cvt_pk_bf16_f32 v174, v106, v107
	v_cvt_pk_bf16_f32 v175, v104, v105
	v_cvt_pk_bf16_f32 v176, v144, v145
	v_cvt_pk_bf16_f32 v177, v146, v147
	v_cvt_pk_bf16_f32 v178, v148, v149
	v_cvt_pk_bf16_f32 v179, v157, v160
	v_cvt_pk_bf16_f32 v180, v136, v137
	v_cvt_pk_bf16_f32 v181, v138, v139
	v_cvt_pk_bf16_f32 v182, v140, v141
	v_cvt_pk_bf16_f32 v183, v142, v143
	s_nop 0
	v_permlane32_swap_b32_e32 v168, v170
	v_permlane32_swap_b32_e32 v169, v171
	v_permlane32_swap_b32_e32 v172, v174
	v_permlane32_swap_b32_e32 v173, v175
	v_permlane32_swap_b32_e32 v176, v178
	v_permlane32_swap_b32_e32 v177, v179
	v_permlane32_swap_b32_e32 v180, v182
	v_permlane32_swap_b32_e32 v181, v183
	ds_read_b64_tr_b16 v[80:81], v159 offset:0
	ds_read_b64_tr_b16 v[82:83], v159 offset:0x800
	ds_read_b64_tr_b16 v[84:85], v159 offset:0x1000
	ds_read_b64_tr_b16 v[86:87], v159 offset:0x1800
	ds_read_b64_tr_b16 v[88:89], v159 offset:0x2000
	ds_read_b64_tr_b16 v[90:91], v159 offset:0x2800
	ds_read_b64_tr_b16 v[92:93], v159 offset:0x3000
	ds_read_b64_tr_b16 v[94:95], v159 offset:0x3800
	s_nop 0
	s_waitcnt lgkmcnt(6)
	v_mfma_f32_32x32x16_bf16 v[64:79], v[168:171], v[80:83], v[0:15]
	s_waitcnt lgkmcnt(4)
	v_mfma_f32_32x32x16_bf16 v[64:79], v[172:175], v[84:87], v[64:79]
	s_waitcnt lgkmcnt(2)
	v_mfma_f32_32x32x16_bf16 v[64:79], v[176:179], v[88:91], v[64:79]
	ds_read_b64_tr_b16 v[88:89], v159 offset:0x200
	ds_read_b64_tr_b16 v[90:91], v159 offset:0xa00
	s_waitcnt lgkmcnt(2)
	v_mfma_f32_32x32x16_bf16 v[64:79], v[180:183], v[92:95], v[64:79]
	ds_read_b64_tr_b16 v[92:93], v159 offset:0x1200
	ds_read_b64_tr_b16 v[94:95], v159 offset:0x1a00
	ds_read_b64_tr_b16 v[96:97], v159 offset:0x2200
	ds_read_b64_tr_b16 v[98:99], v159 offset:0x2a00
	ds_read_b64_tr_b16 v[100:101], v159 offset:0x3200
	ds_read_b64_tr_b16 v[102:103], v159 offset:0x3a00
	s_waitcnt lgkmcnt(6)
	v_mfma_f32_32x32x16_bf16 v[72:87], v[168:171], v[88:91], v[48:63]
	s_waitcnt lgkmcnt(4)
	v_mfma_f32_32x32x16_bf16 v[72:87], v[172:175], v[92:95], v[72:87]
	s_waitcnt lgkmcnt(2)
	v_mfma_f32_32x32x16_bf16 v[72:87], v[176:179], v[96:99], v[72:87]
	ds_read_b64_tr_b16 v[96:97], v159 offset:0x400
	ds_read_b64_tr_b16 v[98:99], v159 offset:0xc00
	s_waitcnt lgkmcnt(2)
	v_mfma_f32_32x32x16_bf16 v[72:87], v[180:183], v[100:103], v[72:87]
	ds_read_b64_tr_b16 v[100:101], v159 offset:0x1400
	ds_read_b64_tr_b16 v[102:103], v159 offset:0x1c00
	ds_read_b64_tr_b16 v[184:185], v159 offset:0x2400
	ds_read_b64_tr_b16 v[186:187], v159 offset:0x2c00
	ds_read_b64_tr_b16 v[188:189], v159 offset:0x3400
	ds_read_b64_tr_b16 v[190:191], v159 offset:0x3c00
	s_waitcnt lgkmcnt(6)
	v_mfma_f32_32x32x16_bf16 v[80:95], v[168:171], v[96:99], v[32:47]
	s_waitcnt lgkmcnt(4)
	v_mfma_f32_32x32x16_bf16 v[80:95], v[172:175], v[100:103], v[80:95]
	s_waitcnt lgkmcnt(2)
	v_mfma_f32_32x32x16_bf16 v[80:95], v[176:179], v[184:187], v[80:95]
	ds_read_b64_tr_b16 v[184:185], v159 offset:0x600
	ds_read_b64_tr_b16 v[186:187], v159 offset:0xe00
	s_waitcnt lgkmcnt(2)
	v_mfma_f32_32x32x16_bf16 v[80:95], v[180:183], v[188:191], v[80:95]
	ds_read_b64_tr_b16 v[188:189], v159 offset:0x1600
	ds_read_b64_tr_b16 v[190:191], v159 offset:0x1e00
	ds_read_b64_tr_b16 v[192:193], v159 offset:0x2600
	ds_read_b64_tr_b16 v[194:195], v159 offset:0x2e00
	ds_read_b64_tr_b16 v[196:197], v159 offset:0x3600
	ds_read_b64_tr_b16 v[198:199], v159 offset:0x3e00
	s_waitcnt lgkmcnt(6)
	v_mfma_f32_32x32x16_bf16 v[88:103], v[168:171], v[184:187], v[16:31]
	s_mov_b64 s[20:21], 0
	s_waitcnt lgkmcnt(4)
	v_mfma_f32_32x32x16_bf16 v[88:103], v[172:175], v[188:191], v[88:103]
	s_waitcnt lgkmcnt(2)
	v_mfma_f32_32x32x16_bf16 v[88:103], v[176:179], v[192:195], v[88:103]
	s_waitcnt lgkmcnt(0)
	v_mfma_f32_32x32x16_bf16 v[88:103], v[180:183], v[196:199], v[88:103]
; __device__ __forceinline__ void finishSM(f32x16& p0, f32x16& p1, float& l_reg, bf16x8& pa0, bf16x8& pa1, bf16x8& pa2, bf16x8& pa3) {
; #pragma unroll
;   for (int r = 0; r < 16; ++r) p1[r] = __builtin_amdgcn_exp2f(p1[r]);
;   float ps = 0;
; #pragma unroll
;   for (int r = 0; r < 16; ++r) ps += p0[r];
; #pragma unroll
;   for (int r = 0; r < 16; ++r) ps += p1[r];
;   { auto rr = __builtin_amdgcn_permlane32_swap(__float_as_uint(ps), __float_as_uint(ps), false, false);
;     ps = __uint_as_float(rr[0]) + __uint_as_float(rr[1]); }
;   l_reg += ps;
;     ...
;   PK4(p0, 0, pa0); PK4(p0, 8, pa1); PK4(p1, 0, pa2); PK4(p1, 8, pa3);
;     ...
; }
; template <int DQK, int QL>
; __device__ __forceinline__ void qkt(f32x16& p0, f32x16& p1, const char* Ks, const bf16x8 (&qr)[DQK / 16 - QL], const char* qlds, const int (&kofs)[4], float negM) {
;   constexpr int QR = DQK / 16 - QL;
; #pragma unroll
;   for (int r = 0; r < 16; ++r) { p0[r] = negM; p1[r] = negM; }
; #pragma unroll
;   for (int d0 = 0; d0 < DQK / 16; ++d0) {
;     const char* kp = Ks + kofs[d0 & 3] + (d0 >> 2) * 128;
;     bf16x8 b0 = *reinterpret_cast<const bf16x8*>(kp);
;     bf16x8 b1 = *reinterpret_cast<const bf16x8*>(kp + 32 * DQK * 2);
;     bf16x8 qf;
;     if constexpr (QL > 0) { if (d0 < QR) qf = qr[d0 < QR ? d0 : 0]; else qf = *reinterpret_cast<const bf16x8*>(qlds + (d0 - QR) * 1024); }
;     else qf = qr[d0];
;     p0 = __builtin_amdgcn_mfma_f32_32x32x16_bf16(b0, qf, p0, 0, 0, 0);
;     p1 = __builtin_amdgcn_mfma_f32_32x32x16_bf16(b1, qf, p1, 0, 0, 0);
;   }
; }
.LBB0_443:
	s_andn2_b64 vcc, exec, s[20:21]
	s_cbranch_vccnz .LBB0_447
	v_add_f32_e32 v64, v130, v135
	v_add_f32_e32 v64, v131, v64
	v_add_f32_e32 v64, v126, v64
	v_add_f32_e32 v64, v127, v64
	v_add_f32_e32 v64, v124, v64
	v_add_f32_e32 v64, v125, v64
	v_add_f32_e32 v64, v110, v64
	v_add_f32_e32 v64, v111, v64
	v_add_f32_e32 v64, v108, v64
	v_add_f32_e32 v64, v109, v64
	v_add_f32_e32 v64, v106, v64
	v_add_f32_e32 v64, v107, v64
	v_add_f32_e32 v64, v104, v64
	v_add_f32_e32 v64, v105, v64
	v_add_f32_e32 v64, v144, v64
	v_add_f32_e32 v64, v145, v64
	v_add_f32_e32 v64, v146, v64
	v_add_f32_e32 v64, v147, v64
	v_add_f32_e32 v64, v148, v64
	v_add_f32_e32 v64, v149, v64
	v_add_f32_e32 v64, v157, v64
	v_add_f32_e32 v64, v160, v64
	v_add_f32_e32 v64, v136, v64
	v_add_f32_e32 v64, v137, v64
	v_add_f32_e32 v64, v138, v64
	v_add_f32_e32 v64, v139, v64
	v_add_f32_e32 v64, v140, v64
	v_add_f32_e32 v64, v141, v64
	v_add_f32_e32 v64, v142, v64
	v_add_f32_e32 v134, v143, v64
	v_mov_b32_e32 v135, v134
	s_nop 1
	v_permlane32_swap_b32_e32 v134, v135
	v_cvt_pk_bf16_f32 v96, v132, v133
	v_cvt_pk_bf16_f32 v97, v130, v131
	v_cvt_pk_bf16_f32 v98, v126, v127
	v_cvt_pk_bf16_f32 v99, v124, v125
	v_cvt_pk_bf16_f32 v100, v110, v111
	v_cvt_pk_bf16_f32 v101, v108, v109
	v_cvt_pk_bf16_f32 v102, v106, v107
	v_cvt_pk_bf16_f32 v103, v104, v105
	v_cvt_pk_bf16_f32 v104, v144, v145
	v_cvt_pk_bf16_f32 v105, v146, v147
	v_cvt_pk_bf16_f32 v106, v148, v149
	v_cvt_pk_bf16_f32 v107, v157, v160
	v_cvt_pk_bf16_f32 v108, v136, v137
	v_cvt_pk_bf16_f32 v109, v138, v139
	v_cvt_pk_bf16_f32 v110, v140, v141
	v_cvt_pk_bf16_f32 v111, v142, v143
	s_nop 0
	v_permlane32_swap_b32_e32 v96, v98
	v_permlane32_swap_b32_e32 v97, v99
	v_permlane32_swap_b32_e32 v100, v102
	v_permlane32_swap_b32_e32 v101, v103
	v_permlane32_swap_b32_e32 v104, v106
	v_permlane32_swap_b32_e32 v105, v107
	v_permlane32_swap_b32_e32 v108, v110
	v_permlane32_swap_b32_e32 v109, v111
	ds_read_b128 v[124:127], v153 offset:57344
	v_mov_b64_e32 v[78:79], s[18:19]
	v_mov_b64_e32 v[76:77], s[16:17]
	v_mov_b64_e32 v[74:75], s[14:15]
	v_mov_b64_e32 v[72:73], s[12:13]
	v_mov_b64_e32 v[70:71], s[10:11]
	v_mov_b64_e32 v[68:69], s[8:9]
	v_mov_b64_e32 v[66:67], s[6:7]
	v_mov_b64_e32 v[64:65], s[4:5]
	s_waitcnt lgkmcnt(0)
	s_nop 0
	v_mfma_f32_32x32x16_bf16 v[80:95], v[124:127], v[120:123], v[64:79]
	ds_read_b128 v[124:127], v166 offset:12288
	s_waitcnt lgkmcnt(0)
	v_mfma_f32_32x32x16_bf16 v[64:79], v[124:127], v[120:123], v[64:79]
	ds_read_b128 v[120:123], v152 offset:57344
	s_waitcnt lgkmcnt(0)
	v_mfma_f32_32x32x16_bf16 v[80:95], v[120:123], v[116:119], v[80:95]
	ds_read_b128 v[120:123], v165 offset:12288
	s_waitcnt lgkmcnt(0)
	v_mfma_f32_32x32x16_bf16 v[64:79], v[120:123], v[116:119], v[64:79]
	ds_read_b128 v[116:119], v151 offset:57344
	v_add_u32_e32 v120, v155, v154
	s_waitcnt lgkmcnt(0)
	v_mfma_f32_32x32x16_bf16 v[80:95], v[116:119], v[112:115], v[80:95]
	ds_read_b128 v[116:119], v164 offset:12288
	s_waitcnt lgkmcnt(0)
	v_mfma_f32_32x32x16_bf16 v[64:79], v[116:119], v[112:115], v[64:79]
	ds_read_b128 v[112:115], v150 offset:57344
	ds_read_b128 v[116:119], v120
	s_waitcnt lgkmcnt(0)
	v_mfma_f32_32x32x16_bf16 v[80:95], v[112:115], v[116:119], v[80:95]
	ds_read_b128 v[112:115], v163 offset:12288
	s_waitcnt lgkmcnt(0)
	v_mfma_f32_32x32x16_bf16 v[64:79], v[112:115], v[116:119], v[64:79]
	ds_read_b128 v[112:115], v153 offset:57472
	ds_read_b128 v[116:119], v120 offset:1024
	s_waitcnt lgkmcnt(0)
	v_mfma_f32_32x32x16_bf16 v[80:95], v[112:115], v[116:119], v[80:95]
	ds_read_b128 v[112:115], v166 offset:12416
	s_waitcnt lgkmcnt(0)
	v_mfma_f32_32x32x16_bf16 v[64:79], v[112:115], v[116:119], v[64:79]
	ds_read_b128 v[112:115], v152 offset:57472
	ds_read_b128 v[116:119], v120 offset:2048
	s_waitcnt lgkmcnt(0)
	v_mfma_f32_32x32x16_bf16 v[80:95], v[112:115], v[116:119], v[80:95]
	ds_read_b128 v[112:115], v165 offset:12416
	s_waitcnt lgkmcnt(0)
	v_mfma_f32_32x32x16_bf16 v[64:79], v[112:115], v[116:119], v[64:79]
	ds_read_b128 v[112:115], v151 offset:57472
	ds_read_b128 v[116:119], v120 offset:3072
	s_waitcnt lgkmcnt(0)
	v_mfma_f32_32x32x16_bf16 v[80:95], v[112:115], v[116:119], v[80:95]
	ds_read_b128 v[112:115], v164 offset:12416
	s_waitcnt lgkmcnt(0)
	v_mfma_f32_32x32x16_bf16 v[64:79], v[112:115], v[116:119], v[64:79]
	ds_read_b128 v[112:115], v150 offset:57472
	ds_read_b128 v[116:119], v120 offset:4096
	s_waitcnt lgkmcnt(0)
	v_mfma_f32_32x32x16_bf16 v[80:95], v[112:115], v[116:119], v[80:95]
	ds_read_b128 v[112:115], v163 offset:12416
	s_waitcnt lgkmcnt(0)
	v_mfma_f32_32x32x16_bf16 v[64:79], v[112:115], v[116:119], v[64:79]
	ds_read_b128 v[112:115], v153 offset:57600
	ds_read_b128 v[116:119], v120 offset:5120
	s_waitcnt lgkmcnt(0)
	v_mfma_f32_32x32x16_bf16 v[80:95], v[112:115], v[116:119], v[80:95]
	ds_read_b128 v[112:115], v166 offset:12544
	s_waitcnt lgkmcnt(0)
	v_mfma_f32_32x32x16_bf16 v[64:79], v[112:115], v[116:119], v[64:79]
	ds_read_b128 v[112:115], v152 offset:57600
	ds_read_b128 v[116:119], v120 offset:6144
	s_waitcnt lgkmcnt(0)
	v_mfma_f32_32x32x16_bf16 v[80:95], v[112:115], v[116:119], v[80:95]
	ds_read_b128 v[112:115], v165 offset:12544
	s_waitcnt lgkmcnt(0)
	v_mfma_f32_32x32x16_bf16 v[64:79], v[112:115], v[116:119], v[64:79]
	ds_read_b128 v[112:115], v151 offset:57600
	ds_read_b128 v[116:119], v120 offset:7168
	s_waitcnt lgkmcnt(0)
	v_mfma_f32_32x32x16_bf16 v[80:95], v[112:115], v[116:119], v[80:95]
	ds_read_b128 v[112:115], v164 offset:12544
	s_waitcnt lgkmcnt(0)
	v_mfma_f32_32x32x16_bf16 v[64:79], v[112:115], v[116:119], v[64:79]
	ds_read_b128 v[112:115], v150 offset:57600
	ds_read_b128 v[116:119], v120 offset:8192
	s_waitcnt lgkmcnt(0)
; #define WAIT_L0() asm volatile("s_waitcnt lgkmcnt(0)" ::: "memory")
; #define SBAR() __builtin_amdgcn_sched_barrier(0)
; __device__ __forceinline__ int crow(int r, int hi) { return (r & 3) + 8 * (r >> 2) + 4 * hi; }
; template <bool GM>
; __device__ __forceinline__ void partialSM(f32x16& p0, f32x16& p1, bool mask, int kbase, int L, int qpos, int hi) {
;   if (mask) {
; #pragma unroll
;     for (int r = 0; r < 16; ++r) {
;       int k = kbase + crow(r, hi);
;       asm volatile("" : "+v"(k) : "v"(p0[r]));
;       bool ok = k < L;
;       if (GM) ok = ok && (k < 16 || abs(qpos - k) <= 128);
;       p0[r] = ok ? p0[r] : -1e30f;
;       int k2 = k + 32;
;       asm volatile("" : "+v"(k2) : "v"(p1[r]));
;       bool ok2 = k2 < L;
;       if (GM) ok2 = ok2 && (k2 < 16 || abs(qpos - k2) <= 128);
;       p1[r] = ok2 ? p1[r] : -1e30f;
;     }
; template <int NCB, int D0> __device__ __forceinline__ void pv_one(f32x16& od, int vb, bf16x8 pa0, bf16x8 pa1, bf16x8 pa2, bf16x8 pa3) {
;   constexpr int KSTEP = NCB * 1024, HALF = NCB * 512, B0 = D0 * 512;
;   const s16x4 l0 = tr_read<B0>(vb), h0 = tr_read<B0 + HALF>(vb), l1 = tr_read<B0 + KSTEP>(vb), h1 = tr_read<B0 + KSTEP + HALF>(vb);
;   const s16x4 l2 = tr_read<B0 + 2 * KSTEP>(vb), h2 = tr_read<B0 + 2 * KSTEP + HALF>(vb), l3 = tr_read<B0 + 3 * KSTEP>(vb), h3 = tr_read<B0 + 3 * KSTEP + HALF>(vb);
;   WAIT_L0(); SBAR();
;     ...
;   od = __builtin_amdgcn_mfma_f32_32x32x16_bf16(pa0, PK(l0, h0), od, 0, 0, 0);
;   od = __builtin_amdgcn_mfma_f32_32x32x16_bf16(pa1, PK(l1, h1), od, 0, 0, 0);
;   od = __builtin_amdgcn_mfma_f32_32x32x16_bf16(pa2, PK(l2, h2), od, 0, 0, 0);
;   od = __builtin_amdgcn_mfma_f32_32x32x16_bf16(pa3, PK(l3, h3), od, 0, 0, 0);
;     ...
; }
; template <int NCB> __device__ __forceinline__ void pv_all(f32x16 (&o)[NCB], int vb, bf16x8 pa0, bf16x8 pa1, bf16x8 pa2, bf16x8 pa3) {
;   pv_one<NCB, 0>(o[0], vb, pa0, pa1, pa2, pa3); pv_one<NCB, 1>(o[1], vb, pa0, pa1, pa2, pa3);
;   if constexpr (NCB == 4) { pv_one<NCB, 2>(o[2], vb, pa0, pa1, pa2, pa3); pv_one<NCB, 3>(o[3], vb, pa0, pa1, pa2, pa3); }
; }
	v_mfma_f32_32x32x16_bf16 v[80:95], v[112:115], v[116:119], v[80:95]
	ds_read_b128 v[112:115], v163 offset:12544
	s_waitcnt lgkmcnt(0)
	v_mfma_f32_32x32x16_bf16 v[64:79], v[112:115], v[116:119], v[64:79]
	ds_read_b64_tr_b16 v[112:113], v159 offset:0
	ds_read_b64_tr_b16 v[114:115], v159 offset:0x800
	ds_read_b64_tr_b16 v[116:117], v159 offset:0x1000
	ds_read_b64_tr_b16 v[118:119], v159 offset:0x1800
	ds_read_b64_tr_b16 v[120:121], v159 offset:0x2000
	ds_read_b64_tr_b16 v[122:123], v159 offset:0x2800
	ds_read_b64_tr_b16 v[124:125], v159 offset:0x3000
	ds_read_b64_tr_b16 v[126:127], v159 offset:0x3800
	s_nop 0
	s_waitcnt lgkmcnt(6)
	v_mfma_f32_32x32x16_bf16 v[0:15], v[96:99], v[112:115], v[0:15]
	ds_read_b64_tr_b16 v[112:113], v159 offset:0x200
	ds_read_b64_tr_b16 v[114:115], v159 offset:0xa00
	s_waitcnt lgkmcnt(6)
	v_mfma_f32_32x32x16_bf16 v[0:15], v[100:103], v[116:119], v[0:15]
	ds_read_b64_tr_b16 v[116:117], v159 offset:0x1200
	ds_read_b64_tr_b16 v[118:119], v159 offset:0x1a00
	s_waitcnt lgkmcnt(6)
	v_mfma_f32_32x32x16_bf16 v[0:15], v[104:107], v[120:123], v[0:15]
	ds_read_b64_tr_b16 v[120:121], v159 offset:0x2200
	ds_read_b64_tr_b16 v[122:123], v159 offset:0x2a00
	s_waitcnt lgkmcnt(6)
	v_mfma_f32_32x32x16_bf16 v[0:15], v[108:111], v[124:127], v[0:15]
	ds_read_b64_tr_b16 v[124:125], v159 offset:0x3200
	ds_read_b64_tr_b16 v[126:127], v159 offset:0x3a00
	s_waitcnt lgkmcnt(6)
	v_mfma_f32_32x32x16_bf16 v[48:63], v[96:99], v[112:115], v[48:63]
	ds_read_b64_tr_b16 v[112:113], v159 offset:0x400
	ds_read_b64_tr_b16 v[114:115], v159 offset:0xc00
	s_waitcnt lgkmcnt(6)
	v_mfma_f32_32x32x16_bf16 v[48:63], v[100:103], v[116:119], v[48:63]
	ds_read_b64_tr_b16 v[116:117], v159 offset:0x1400
	ds_read_b64_tr_b16 v[118:119], v159 offset:0x1c00
	s_waitcnt lgkmcnt(6)
	v_mfma_f32_32x32x16_bf16 v[48:63], v[104:107], v[120:123], v[48:63]
	ds_read_b64_tr_b16 v[120:121], v159 offset:0x2400
	ds_read_b64_tr_b16 v[122:123], v159 offset:0x2c00
	s_waitcnt lgkmcnt(6)
	v_mfma_f32_32x32x16_bf16 v[48:63], v[108:111], v[124:127], v[48:63]
	ds_read_b64_tr_b16 v[124:125], v159 offset:0x3400
	ds_read_b64_tr_b16 v[126:127], v159 offset:0x3c00
	s_waitcnt lgkmcnt(6)
	v_mfma_f32_32x32x16_bf16 v[32:47], v[96:99], v[112:115], v[32:47]
	ds_read_b64_tr_b16 v[112:113], v159 offset:0x600
	ds_read_b64_tr_b16 v[114:115], v159 offset:0xe00
	s_waitcnt lgkmcnt(6)
	v_mfma_f32_32x32x16_bf16 v[32:47], v[100:103], v[116:119], v[32:47]
	ds_read_b64_tr_b16 v[116:117], v159 offset:0x1600
	ds_read_b64_tr_b16 v[118:119], v159 offset:0x1e00
	s_waitcnt lgkmcnt(6)
	v_mfma_f32_32x32x16_bf16 v[32:47], v[104:107], v[120:123], v[32:47]
	ds_read_b64_tr_b16 v[120:121], v159 offset:0x2600
	ds_read_b64_tr_b16 v[122:123], v159 offset:0x2e00
	s_waitcnt lgkmcnt(6)
	v_mfma_f32_32x32x16_bf16 v[32:47], v[108:111], v[124:127], v[32:47]
	ds_read_b64_tr_b16 v[124:125], v159 offset:0x3600
	ds_read_b64_tr_b16 v[126:127], v159 offset:0x3e00
	s_waitcnt lgkmcnt(6)
	v_mfma_f32_32x32x16_bf16 v[16:31], v[96:99], v[112:115], v[16:31]
	s_add_i32 s22, s22, s97
	s_lshl_b32 s3, s22, 6
	s_cmp_le_i32 s3, s59
	s_waitcnt lgkmcnt(4)
	v_mfma_f32_32x32x16_bf16 v[16:31], v[100:103], v[116:119], v[16:31]
	s_waitcnt lgkmcnt(2)
	v_mfma_f32_32x32x16_bf16 v[16:31], v[104:107], v[120:123], v[16:31]
	s_waitcnt lgkmcnt(0)
	v_mfma_f32_32x32x16_bf16 v[16:31], v[108:111], v[124:127], v[16:31]
	s_cbranch_scc1 .LBB0_446
	v_lshl_or_b32 v96, v128, 2, s3
	v_mov_b32_e32 v97, v96
	s_nop 0
	v_cmp_gt_i32_e32 vcc, s94, v97
	v_add_u32_e32 v97, 32, v97
	s_nop 0
	v_cndmask_b32_e32 v80, v233, v80, vcc
	v_cmp_gt_i32_e32 vcc, s94, v97
	v_or_b32_e32 v97, 1, v96
	s_nop 0
	v_cndmask_b32_e32 v64, v233, v64, vcc
	v_cmp_gt_i32_e32 vcc, s94, v97
	v_add_u32_e32 v97, 32, v97
	s_nop 0
	v_cndmask_b32_e32 v81, v233, v81, vcc
	v_cmp_gt_i32_e32 vcc, s94, v97
	v_or_b32_e32 v97, 2, v96
	s_nop 0
	v_cndmask_b32_e32 v65, v233, v65, vcc
	v_cmp_gt_i32_e32 vcc, s94, v97
	v_add_u32_e32 v97, 32, v97
	s_nop 0
	v_cndmask_b32_e32 v82, v233, v82, vcc
	v_cmp_gt_i32_e32 vcc, s94, v97
	v_or_b32_e32 v97, 3, v96
	s_nop 0
	v_cndmask_b32_e32 v66, v233, v66, vcc
	v_cmp_gt_i32_e32 vcc, s94, v97
	v_add_u32_e32 v97, 32, v97
	s_nop 0
	v_cndmask_b32_e32 v83, v233, v83, vcc
	v_cmp_gt_i32_e32 vcc, s94, v97
	v_or_b32_e32 v97, 8, v96
	s_nop 0
	v_cndmask_b32_e32 v67, v233, v67, vcc
	v_cmp_gt_i32_e32 vcc, s94, v97
	v_add_u32_e32 v97, 32, v97
	s_nop 0
	v_cndmask_b32_e32 v84, v233, v84, vcc
	v_cmp_gt_i32_e32 vcc, s94, v97
	v_or_b32_e32 v97, 9, v96
	s_nop 0
	v_cndmask_b32_e32 v68, v233, v68, vcc
	v_cmp_gt_i32_e32 vcc, s94, v97
	v_add_u32_e32 v97, 32, v97
	s_nop 0
	v_cndmask_b32_e32 v85, v233, v85, vcc
	v_cmp_gt_i32_e32 vcc, s94, v97
	v_or_b32_e32 v97, 10, v96
	s_nop 0
	v_cndmask_b32_e32 v69, v233, v69, vcc
	v_cmp_gt_i32_e32 vcc, s94, v97
	v_add_u32_e32 v97, 32, v97
	s_nop 0
	v_cndmask_b32_e32 v86, v233, v86, vcc
	v_cmp_gt_i32_e32 vcc, s94, v97
	v_or_b32_e32 v97, 11, v96
	s_nop 0
	v_cndmask_b32_e32 v70, v233, v70, vcc
	v_cmp_gt_i32_e32 vcc, s94, v97
	v_add_u32_e32 v97, 32, v97
	s_nop 0
	v_cndmask_b32_e32 v87, v233, v87, vcc
	v_cmp_gt_i32_e32 vcc, s94, v97
	v_or_b32_e32 v97, 16, v96
	s_nop 0
	v_cndmask_b32_e32 v71, v233, v71, vcc
	v_cmp_gt_i32_e32 vcc, s94, v97
	v_add_u32_e32 v97, 32, v97
	s_nop 0
	v_cndmask_b32_e32 v88, v233, v88, vcc
	v_cmp_gt_i32_e32 vcc, s94, v97
	v_or_b32_e32 v97, 17, v96
	s_nop 0
	v_cndmask_b32_e32 v72, v233, v72, vcc
	v_cmp_gt_i32_e32 vcc, s94, v97
	v_add_u32_e32 v97, 32, v97
	s_nop 0
	v_cndmask_b32_e32 v89, v233, v89, vcc
	v_cmp_gt_i32_e32 vcc, s94, v97
	v_or_b32_e32 v97, 18, v96
	s_nop 0
	v_cndmask_b32_e32 v73, v233, v73, vcc
	v_cmp_gt_i32_e32 vcc, s94, v97
	v_add_u32_e32 v97, 32, v97
	s_nop 0
	v_cndmask_b32_e32 v90, v233, v90, vcc
	v_cmp_gt_i32_e32 vcc, s94, v97
	v_or_b32_e32 v97, 19, v96
	s_nop 0
	v_cndmask_b32_e32 v74, v233, v74, vcc
	v_cmp_gt_i32_e32 vcc, s94, v97
	v_add_u32_e32 v97, 32, v97
	s_nop 0
	v_cndmask_b32_e32 v91, v233, v91, vcc
	v_cmp_gt_i32_e32 vcc, s94, v97
	v_or_b32_e32 v97, 24, v96
	s_nop 0
	v_cndmask_b32_e32 v75, v233, v75, vcc
	v_cmp_gt_i32_e32 vcc, s94, v97
	v_add_u32_e32 v97, 32, v97
	s_nop 0
	v_cndmask_b32_e32 v92, v233, v92, vcc
	v_cmp_gt_i32_e32 vcc, s94, v97
	v_or_b32_e32 v97, 25, v96
	s_nop 0
	v_cndmask_b32_e32 v76, v233, v76, vcc
	v_cmp_gt_i32_e32 vcc, s94, v97
	v_add_u32_e32 v97, 32, v97
	s_nop 0
	v_cndmask_b32_e32 v93, v233, v93, vcc
	v_cmp_gt_i32_e32 vcc, s94, v97
	v_or_b32_e32 v97, 26, v96
	v_or_b32_e32 v96, 27, v96
	v_cndmask_b32_e32 v77, v233, v77, vcc
	v_cmp_gt_i32_e32 vcc, s94, v97
	v_add_u32_e32 v97, 32, v97
	s_nop 0
	v_cndmask_b32_e32 v94, v233, v94, vcc
	v_cmp_gt_i32_e32 vcc, s94, v97
	s_nop 1
	v_cndmask_b32_e32 v78, v233, v78, vcc
	v_cmp_gt_i32_e32 vcc, s94, v96
	v_add_u32_e32 v96, 32, v96
	s_nop 0
	v_cndmask_b32_e32 v95, v233, v95, vcc
	v_cmp_gt_i32_e32 vcc, s94, v96
	s_nop 1
	v_cndmask_b32_e32 v79, v233, v79, vcc
; #define WAIT_L0() asm volatile("s_waitcnt lgkmcnt(0)" ::: "memory")
; #define SBAR() __builtin_amdgcn_sched_barrier(0)
; __device__ __forceinline__ void finishSM(f32x16& p0, f32x16& p1, float& l_reg, bf16x8& pa0, bf16x8& pa1, bf16x8& pa2, bf16x8& pa3) {
; #pragma unroll
;   for (int r = 0; r < 16; ++r) p1[r] = __builtin_amdgcn_exp2f(p1[r]);
;   float ps = 0;
; #pragma unroll
;   for (int r = 0; r < 16; ++r) ps += p0[r];
; #pragma unroll
;   for (int r = 0; r < 16; ++r) ps += p1[r];
;   { auto rr = __builtin_amdgcn_permlane32_swap(__float_as_uint(ps), __float_as_uint(ps), false, false);
;     ps = __uint_as_float(rr[0]) + __uint_as_float(rr[1]); }
;   l_reg += ps;
;     ...
;   PK4(p0, 0, pa0); PK4(p0, 8, pa1); PK4(p1, 0, pa2); PK4(p1, 8, pa3);
;     ...
; }
; template <int NCB, int D0> __device__ __forceinline__ void pv_one(f32x16& od, int vb, bf16x8 pa0, bf16x8 pa1, bf16x8 pa2, bf16x8 pa3) {
;   constexpr int KSTEP = NCB * 1024, HALF = NCB * 512, B0 = D0 * 512;
;   const s16x4 l0 = tr_read<B0>(vb), h0 = tr_read<B0 + HALF>(vb), l1 = tr_read<B0 + KSTEP>(vb), h1 = tr_read<B0 + KSTEP + HALF>(vb);
;   const s16x4 l2 = tr_read<B0 + 2 * KSTEP>(vb), h2 = tr_read<B0 + 2 * KSTEP + HALF>(vb), l3 = tr_read<B0 + 3 * KSTEP>(vb), h3 = tr_read<B0 + 3 * KSTEP + HALF>(vb);
;   WAIT_L0(); SBAR();
;     ...
;   od = __builtin_amdgcn_mfma_f32_32x32x16_bf16(pa0, PK(l0, h0), od, 0, 0, 0);
;   od = __builtin_amdgcn_mfma_f32_32x32x16_bf16(pa1, PK(l1, h1), od, 0, 0, 0);
;   od = __builtin_amdgcn_mfma_f32_32x32x16_bf16(pa2, PK(l2, h2), od, 0, 0, 0);
;   od = __builtin_amdgcn_mfma_f32_32x32x16_bf16(pa3, PK(l3, h3), od, 0, 0, 0);
;     ...
; }
; template <int NCB> __device__ __forceinline__ void pv_all(f32x16 (&o)[NCB], int vb, bf16x8 pa0, bf16x8 pa1, bf16x8 pa2, bf16x8 pa3) {
;   pv_one<NCB, 0>(o[0], vb, pa0, pa1, pa2, pa3); pv_one<NCB, 1>(o[1], vb, pa0, pa1, pa2, pa3);
;   if constexpr (NCB == 4) { pv_one<NCB, 2>(o[2], vb, pa0, pa1, pa2, pa3); pv_one<NCB, 3>(o[3], vb, pa0, pa1, pa2, pa3); }
; }
.LBB0_446:
	v_exp_f32_e32 v80, v80
	v_exp_f32_e32 v81, v81
	v_exp_f32_e32 v82, v82
	v_exp_f32_e32 v83, v83
	v_exp_f32_e32 v84, v84
	v_exp_f32_e32 v97, v64
	v_add_f32_e32 v64, 0, v80
	v_exp_f32_e32 v85, v85
	v_add_f32_e32 v64, v81, v64
	v_exp_f32_e32 v86, v86
	v_add_f32_e32 v64, v82, v64
	v_exp_f32_e32 v87, v87
	v_add_f32_e32 v64, v83, v64
	v_exp_f32_e32 v88, v88
	v_add_f32_e32 v64, v84, v64
	v_exp_f32_e32 v89, v89
	v_add_f32_e32 v64, v85, v64
	v_exp_f32_e32 v90, v90
	v_add_f32_e32 v64, v86, v64
	v_exp_f32_e32 v91, v91
	v_add_f32_e32 v64, v87, v64
	v_exp_f32_e32 v92, v92
	v_add_f32_e32 v64, v88, v64
	v_exp_f32_e32 v93, v93
	v_add_f32_e32 v64, v89, v64
	v_exp_f32_e32 v94, v94
	v_add_f32_e32 v64, v90, v64
	v_exp_f32_e32 v95, v95
	v_add_f32_e32 v64, v91, v64
	v_add_f32_e32 v64, v92, v64
	v_exp_f32_e32 v98, v65
	v_add_f32_e32 v64, v93, v64
	v_exp_f32_e32 v99, v66
	v_add_f32_e32 v64, v94, v64
	v_exp_f32_e32 v100, v67
	v_add_f32_e32 v64, v95, v64
	v_exp_f32_e32 v101, v68
	v_add_f32_e32 v64, v97, v64
	v_exp_f32_e32 v102, v69
	v_add_f32_e32 v64, v98, v64
	v_exp_f32_e32 v103, v70
	v_add_f32_e32 v64, v99, v64
	v_exp_f32_e32 v104, v71
	v_add_f32_e32 v64, v100, v64
	v_exp_f32_e32 v105, v72
	v_add_f32_e32 v64, v101, v64
	v_exp_f32_e32 v106, v73
	v_add_f32_e32 v64, v102, v64
	v_exp_f32_e32 v107, v74
	v_add_f32_e32 v64, v103, v64
	v_exp_f32_e32 v108, v75
	v_add_f32_e32 v64, v104, v64
	v_exp_f32_e32 v76, v76
	v_add_f32_e32 v64, v105, v64
	v_exp_f32_e32 v77, v77
	v_add_f32_e32 v64, v106, v64
	v_exp_f32_e32 v78, v78
	v_add_f32_e32 v64, v107, v64
	v_exp_f32_e32 v79, v79
	v_add_f32_e32 v64, v108, v64
	v_add_f32_e32 v64, v76, v64
	v_add_f32_e32 v64, v77, v64
	v_add_f32_e32 v64, v78, v64
	v_add_f32_e32 v64, v79, v64
	v_mov_b32_e32 v65, v64
	v_add_f32_e32 v96, v134, v135
	s_nop 0
	v_permlane32_swap_b32_e32 v64, v65
	v_add_f32_e32 v96, v158, v96
	v_add_f32_e32 v64, v64, v65
	v_add_f32_e32 v134, v96, v64
	v_cvt_pk_bf16_f32 v64, v80, v81
	v_cvt_pk_bf16_f32 v65, v82, v83
	v_cvt_pk_bf16_f32 v66, v84, v85
	v_cvt_pk_bf16_f32 v67, v86, v87
	v_cvt_pk_bf16_f32 v68, v88, v89
	v_cvt_pk_bf16_f32 v69, v90, v91
	v_cvt_pk_bf16_f32 v70, v92, v93
	v_cvt_pk_bf16_f32 v71, v94, v95
	v_cvt_pk_bf16_f32 v72, v97, v98
	v_cvt_pk_bf16_f32 v73, v99, v100
	v_cvt_pk_bf16_f32 v74, v101, v102
	v_cvt_pk_bf16_f32 v75, v103, v104
	v_cvt_pk_bf16_f32 v88, v105, v106
	v_cvt_pk_bf16_f32 v89, v107, v108
	v_cvt_pk_bf16_f32 v90, v76, v77
	v_cvt_pk_bf16_f32 v91, v78, v79
	s_nop 0
	v_permlane32_swap_b32_e32 v64, v66
	v_permlane32_swap_b32_e32 v65, v67
	v_permlane32_swap_b32_e32 v68, v70
	v_permlane32_swap_b32_e32 v69, v71
	v_permlane32_swap_b32_e32 v72, v74
	v_permlane32_swap_b32_e32 v73, v75
	v_permlane32_swap_b32_e32 v88, v90
	v_permlane32_swap_b32_e32 v89, v91
	ds_read_b64_tr_b16 v[76:77], v156 offset:0
	ds_read_b64_tr_b16 v[78:79], v156 offset:0x800
	ds_read_b64_tr_b16 v[80:81], v156 offset:0x1000
	ds_read_b64_tr_b16 v[82:83], v156 offset:0x1800
	ds_read_b64_tr_b16 v[84:85], v156 offset:0x2000
	ds_read_b64_tr_b16 v[86:87], v156 offset:0x2800
	ds_read_b64_tr_b16 v[92:93], v156 offset:0x3000
	ds_read_b64_tr_b16 v[94:95], v156 offset:0x3800
	s_nop 0
	s_waitcnt lgkmcnt(6)
	v_mfma_f32_32x32x16_bf16 v[0:15], v[64:67], v[76:79], v[0:15]
	ds_read_b64_tr_b16 v[76:77], v156 offset:0x200
	ds_read_b64_tr_b16 v[78:79], v156 offset:0xa00
	s_waitcnt lgkmcnt(6)
	v_mfma_f32_32x32x16_bf16 v[0:15], v[68:71], v[80:83], v[0:15]
	ds_read_b64_tr_b16 v[80:81], v156 offset:0x1200
	ds_read_b64_tr_b16 v[82:83], v156 offset:0x1a00
	s_waitcnt lgkmcnt(6)
	v_mfma_f32_32x32x16_bf16 v[0:15], v[72:75], v[84:87], v[0:15]
	ds_read_b64_tr_b16 v[84:85], v156 offset:0x2200
	ds_read_b64_tr_b16 v[86:87], v156 offset:0x2a00
	s_waitcnt lgkmcnt(6)
	v_mfma_f32_32x32x16_bf16 v[0:15], v[88:91], v[92:95], v[0:15]
	ds_read_b64_tr_b16 v[92:93], v156 offset:0x3200
	ds_read_b64_tr_b16 v[94:95], v156 offset:0x3a00
	s_waitcnt lgkmcnt(6)
	v_mfma_f32_32x32x16_bf16 v[48:63], v[64:67], v[76:79], v[48:63]
	ds_read_b64_tr_b16 v[76:77], v156 offset:0x400
	ds_read_b64_tr_b16 v[78:79], v156 offset:0xc00
	s_waitcnt lgkmcnt(6)
	v_mfma_f32_32x32x16_bf16 v[48:63], v[68:71], v[80:83], v[48:63]
	ds_read_b64_tr_b16 v[80:81], v156 offset:0x1400
	ds_read_b64_tr_b16 v[82:83], v156 offset:0x1c00
	s_waitcnt lgkmcnt(6)
	v_mfma_f32_32x32x16_bf16 v[48:63], v[72:75], v[84:87], v[48:63]
	ds_read_b64_tr_b16 v[84:85], v156 offset:0x2400
	ds_read_b64_tr_b16 v[86:87], v156 offset:0x2c00
	s_waitcnt lgkmcnt(6)
	v_mfma_f32_32x32x16_bf16 v[48:63], v[88:91], v[92:95], v[48:63]
	ds_read_b64_tr_b16 v[92:93], v156 offset:0x3400
	ds_read_b64_tr_b16 v[94:95], v156 offset:0x3c00
	s_waitcnt lgkmcnt(6)
	v_mfma_f32_32x32x16_bf16 v[32:47], v[64:67], v[76:79], v[32:47]
	ds_read_b64_tr_b16 v[76:77], v156 offset:0x600
	ds_read_b64_tr_b16 v[78:79], v156 offset:0xe00
	s_waitcnt lgkmcnt(6)
	v_mfma_f32_32x32x16_bf16 v[32:47], v[68:71], v[80:83], v[32:47]
	ds_read_b64_tr_b16 v[80:81], v156 offset:0x1600
	ds_read_b64_tr_b16 v[82:83], v156 offset:0x1e00
	s_waitcnt lgkmcnt(6)
	v_mfma_f32_32x32x16_bf16 v[32:47], v[72:75], v[84:87], v[32:47]
	ds_read_b64_tr_b16 v[84:85], v156 offset:0x2600
	ds_read_b64_tr_b16 v[86:87], v156 offset:0x2e00
	s_waitcnt lgkmcnt(6)
	v_mfma_f32_32x32x16_bf16 v[32:47], v[88:91], v[92:95], v[32:47]
	ds_read_b64_tr_b16 v[92:93], v156 offset:0x3600
	ds_read_b64_tr_b16 v[94:95], v156 offset:0x3e00
	s_waitcnt lgkmcnt(6)
	v_mfma_f32_32x32x16_bf16 v[16:31], v[64:67], v[76:79], v[16:31]
	s_waitcnt lgkmcnt(4)
	v_mfma_f32_32x32x16_bf16 v[16:31], v[68:71], v[80:83], v[16:31]
	s_waitcnt lgkmcnt(2)
	v_mfma_f32_32x32x16_bf16 v[16:31], v[72:75], v[84:87], v[16:31]
	s_nop 0
	v_mov_b64_e32 v[78:79], v[14:15]
	v_mov_b64_e32 v[76:77], v[12:13]
	v_mov_b64_e32 v[74:75], v[10:11]
	v_mov_b64_e32 v[72:73], v[8:9]
	v_mov_b64_e32 v[86:87], v[62:63]
	v_mov_b64_e32 v[84:85], v[60:61]
	v_mov_b64_e32 v[82:83], v[58:59]
	s_waitcnt lgkmcnt(0)
	v_mfma_f32_32x32x16_bf16 v[16:31], v[88:91], v[92:95], v[16:31]
	v_mov_b64_e32 v[80:81], v[56:57]
	v_mov_b64_e32 v[94:95], v[46:47]
	v_mov_b64_e32 v[92:93], v[44:45]
	v_mov_b64_e32 v[90:91], v[42:43]
	v_mov_b64_e32 v[88:89], v[40:41]
	v_mov_b64_e32 v[70:71], v[6:7]
	v_mov_b64_e32 v[68:69], v[4:5]
	s_nop 4
	v_mov_b64_e32 v[102:103], v[30:31]
	v_mov_b64_e32 v[66:67], v[2:3]
	v_mov_b64_e32 v[64:65], v[0:1]
	v_mov_b64_e32 v[78:79], v[54:55]
	v_mov_b64_e32 v[76:77], v[52:53]
	v_mov_b64_e32 v[74:75], v[50:51]
	v_mov_b64_e32 v[72:73], v[48:49]
	v_mov_b64_e32 v[86:87], v[38:39]
	v_mov_b64_e32 v[84:85], v[36:37]
	v_mov_b64_e32 v[82:83], v[34:35]
	v_mov_b64_e32 v[80:81], v[32:33]
	v_mov_b64_e32 v[94:95], v[22:23]
	v_mov_b64_e32 v[92:93], v[20:21]
	v_mov_b64_e32 v[90:91], v[18:19]
	v_mov_b64_e32 v[88:89], v[16:17]
	v_mov_b64_e32 v[100:101], v[28:29]
	v_mov_b64_e32 v[98:99], v[26:27]
	v_mov_b64_e32 v[96:97], v[24:25]

; __device__ __forceinline__ void finishSM(f32x16& p0, f32x16& p1, float& l_reg, bf16x8& pa0, bf16x8& pa1, bf16x8& pa2, bf16x8& pa3) {
; #pragma unroll
;   for (int r = 0; r < 16; ++r) p1[r] = __builtin_amdgcn_exp2f(p1[r]);
;   float ps = 0;
; #pragma unroll
;   for (int r = 0; r < 16; ++r) ps += p0[r];
; #pragma unroll
;   for (int r = 0; r < 16; ++r) ps += p1[r];
;   { auto rr = __builtin_amdgcn_permlane32_swap(__float_as_uint(ps), __float_as_uint(ps), false, false);
;     ps = __uint_as_float(rr[0]) + __uint_as_float(rr[1]); }
;   l_reg += ps;
;     ...
;   PK4(p0, 0, pa0); PK4(p0, 8, pa1); PK4(p1, 0, pa2); PK4(p1, 8, pa3);
;     ...
; }
; template <int DQK, int QL>
; __device__ __forceinline__ void qkt(f32x16& p0, f32x16& p1, const char* Ks, const bf16x8 (&qr)[DQK / 16 - QL], const char* qlds, const int (&kofs)[4], float negM) {
;   constexpr int QR = DQK / 16 - QL;
; #pragma unroll
;   for (int r = 0; r < 16; ++r) { p0[r] = negM; p1[r] = negM; }
; #pragma unroll
;   for (int d0 = 0; d0 < DQK / 16; ++d0) {
;     const char* kp = Ks + kofs[d0 & 3] + (d0 >> 2) * 128;
;     bf16x8 b0 = *reinterpret_cast<const bf16x8*>(kp);
;     bf16x8 b1 = *reinterpret_cast<const bf16x8*>(kp + 32 * DQK * 2);
;     bf16x8 qf;
;     if constexpr (QL > 0) { if (d0 < QR) qf = qr[d0 < QR ? d0 : 0]; else qf = *reinterpret_cast<const bf16x8*>(qlds + (d0 - QR) * 1024); }
;     else qf = qr[d0];
;     p0 = __builtin_amdgcn_mfma_f32_32x32x16_bf16(b0, qf, p0, 0, 0, 0);
;     p1 = __builtin_amdgcn_mfma_f32_32x32x16_bf16(b1, qf, p1, 0, 0, 0);
;   }
; }
; template <int NCB> __device__ __forceinline__ int v_st(int k, int c) {
;   const int kk = (k & ~0xC) | ((k & 4) << 1) | ((k & 8) >> 1);
;   return ((kk >> 3) * NCB + (c >> 5)) * 512 + ((kk & 7) * 32 + (c & 31)) * 2;
; }
; __device__ __forceinline__ int v_rd_base(int lane) { return ((lane & 3) << 3) | (((lane >> 2) & 3) << 6) | (((lane >> 4) & 1) << 5) | (((lane >> 5) & 1) << 8); }
; template <int OFF> __device__ __forceinline__ s16x4 tr_read(int vb) {
;   s16x4 r; asm volatile("ds_read_b64_tr_b16 %0, %1 offset:%2" : "=&v"(r) : "v"(vb), "i"(OFF) : "memory"); return r;
; }
; template <int NCB, int D0> __device__ __forceinline__ void pv_one(f32x16& od, int vb, bf16x8 pa0, bf16x8 pa1, bf16x8 pa2, bf16x8 pa3) {
;   constexpr int KSTEP = NCB * 1024, HALF = NCB * 512, B0 = D0 * 512;
.LBB0_650:
	ds_read_b128 v[40:43], v150 offset:40960
	ds_read_b128 v[158:161], v150 offset:45056
	s_waitcnt vmcnt(0)
	v_mov_b64_e32 v[110:111], s[18:19]
	v_mov_b64_e32 v[108:109], s[16:17]
	v_mov_b64_e32 v[106:107], s[14:15]
	v_mov_b64_e32 v[104:105], s[12:13]
	v_mov_b64_e32 v[102:103], s[10:11]
	v_mov_b64_e32 v[100:101], s[8:9]
	v_mov_b64_e32 v[98:99], s[6:7]
	v_mov_b64_e32 v[96:97], s[4:5]
	s_waitcnt lgkmcnt(1)
	s_nop 0
	v_mfma_f32_32x32x16_bf16 v[56:71], v[40:43], v[124:127], v[96:111]
	s_waitcnt lgkmcnt(0)
	v_mfma_f32_32x32x16_bf16 v[40:55], v[158:161], v[124:127], v[96:111]
	s_nop 6
	ds_read_b128 v[96:99], v148 offset:40960
	ds_read_b128 v[100:103], v148 offset:45056
	s_waitcnt lgkmcnt(1)
	v_mfma_f32_32x32x16_bf16 v[56:71], v[96:99], v[120:123], v[56:71]
	s_waitcnt lgkmcnt(0)
	v_mfma_f32_32x32x16_bf16 v[40:55], v[100:103], v[120:123], v[40:55]
	ds_read_b128 v[96:99], v147 offset:40960
	ds_read_b128 v[100:103], v147 offset:45056
	s_waitcnt lgkmcnt(1)
	v_mfma_f32_32x32x16_bf16 v[56:71], v[96:99], v[116:119], v[56:71]
	s_waitcnt lgkmcnt(0)
	v_mfma_f32_32x32x16_bf16 v[40:55], v[100:103], v[116:119], v[40:55]
	ds_read_b128 v[96:99], v146 offset:40960
	ds_read_b128 v[100:103], v146 offset:45056
	s_waitcnt lgkmcnt(1)
	v_mfma_f32_32x32x16_bf16 v[56:71], v[96:99], v[112:115], v[56:71]
	v_exp_f32_e32 v96, v32
	v_add_f32_e32 v32, 0, v90
	v_add_f32_e32 v32, v91, v32
	v_add_f32_e32 v32, v88, v32
	v_add_f32_e32 v32, v87, v32
	v_add_f32_e32 v32, v86, v32
	v_add_f32_e32 v32, v85, v32
	v_add_f32_e32 v32, v82, v32
	v_add_f32_e32 v32, v81, v32
	v_add_f32_e32 v32, v74, v32
	v_add_f32_e32 v32, v75, v32
	v_add_f32_e32 v32, v76, v32
	v_add_f32_e32 v32, v77, v32
	v_add_f32_e32 v32, v78, v32
	v_exp_f32_e32 v97, v33
	v_add_f32_e32 v32, v79, v32
	v_exp_f32_e32 v98, v34
	v_add_f32_e32 v32, v80, v32
	v_exp_f32_e32 v99, v35
	v_add_f32_e32 v32, v83, v32
	s_waitcnt lgkmcnt(0)
	v_mfma_f32_32x32x16_bf16 v[40:55], v[100:103], v[112:115], v[40:55]
	v_exp_f32_e32 v100, v36
	v_add_f32_e32 v32, v96, v32
	v_exp_f32_e32 v101, v37
	v_add_f32_e32 v32, v97, v32
	v_exp_f32_e32 v102, v38
	v_add_f32_e32 v32, v98, v32
	v_exp_f32_e32 v103, v39
	v_add_f32_e32 v32, v99, v32
	v_exp_f32_e32 v36, v72
	v_add_f32_e32 v32, v100, v32
	v_exp_f32_e32 v37, v73
	v_add_f32_e32 v32, v101, v32
	v_exp_f32_e32 v38, v84
	v_add_f32_e32 v32, v102, v32
	v_exp_f32_e32 v39, v89
	v_add_f32_e32 v32, v103, v32
	v_exp_f32_e32 v72, v92
	v_add_f32_e32 v32, v36, v32
	v_exp_f32_e32 v73, v93
	v_add_f32_e32 v32, v37, v32
	v_exp_f32_e32 v84, v94
	v_add_f32_e32 v32, v38, v32
	v_exp_f32_e32 v89, v95
	v_add_f32_e32 v32, v39, v32
	v_add_f32_e32 v32, v72, v32
	v_add_f32_e32 v32, v73, v32
	v_add_f32_e32 v32, v84, v32
	v_add_f32_e32 v104, v89, v32
	v_mov_b32_e32 v105, v104
	v_cvt_pk_bf16_f32 v32, v90, v91
	v_cvt_pk_bf16_f32 v33, v88, v87
	v_cvt_pk_bf16_f32 v34, v86, v85
	v_cvt_pk_bf16_f32 v35, v82, v81
	s_nop 1
	v_permlane32_swap_b32_e32 v104, v105
	v_permlane32_swap_b32_e32 v32, v34
	v_permlane32_swap_b32_e32 v33, v35
	v_cvt_pk_bf16_f32 v74, v74, v75
	v_cvt_pk_bf16_f32 v75, v76, v77
	v_cvt_pk_bf16_f32 v76, v78, v79
	v_cvt_pk_bf16_f32 v77, v80, v83
	v_cvt_pk_bf16_f32 v78, v96, v97
	v_cvt_pk_bf16_f32 v79, v98, v99
	v_cvt_pk_bf16_f32 v80, v100, v101
	v_cvt_pk_bf16_f32 v81, v102, v103
	v_cvt_pk_bf16_f32 v36, v36, v37
	v_cvt_pk_bf16_f32 v37, v38, v39
	v_cvt_pk_bf16_f32 v38, v72, v73
	v_cvt_pk_bf16_f32 v39, v84, v89
	s_nop 0
	v_permlane32_swap_b32_e32 v74, v76
	v_permlane32_swap_b32_e32 v75, v77
	v_permlane32_swap_b32_e32 v78, v80
	v_permlane32_swap_b32_e32 v79, v81
	v_permlane32_swap_b32_e32 v36, v38
	v_permlane32_swap_b32_e32 v37, v39
	v_mad_i64_i32 v[72:73], s[20:21], s97, v237, v[134:135]
	v_mad_i64_i32 v[82:83], s[20:21], s97, v237, v[136:137]
	global_load_dwordx4 v[96:99], v[72:73], off offset:1024
	global_load_dwordx4 v[100:103], v[82:83], off offset:1280
	ds_read_b64_tr_b16 v[82:83], v156 offset:0
	ds_read_b64_tr_b16 v[84:85], v156 offset:0x400
	ds_read_b64_tr_b16 v[86:87], v156 offset:0x800
	ds_read_b64_tr_b16 v[88:89], v156 offset:0xc00
	ds_read_b64_tr_b16 v[90:91], v156 offset:0x1000
	ds_read_b64_tr_b16 v[92:93], v156 offset:0x1400
	ds_read_b64_tr_b16 v[106:107], v156 offset:0x1800
	ds_read_b64_tr_b16 v[108:109], v156 offset:0x1c00
	s_nop 0
	s_waitcnt lgkmcnt(6)
	v_mfma_f32_32x32x16_bf16 v[0:15], v[32:35], v[82:85], v[0:15]
	ds_read_b64_tr_b16 v[82:83], v156 offset:0x200
	ds_read_b64_tr_b16 v[84:85], v156 offset:0x600
	s_waitcnt lgkmcnt(6)
	v_mfma_f32_32x32x16_bf16 v[0:15], v[74:77], v[86:89], v[0:15]
	ds_read_b64_tr_b16 v[86:87], v156 offset:0xa00
	ds_read_b64_tr_b16 v[88:89], v156 offset:0xe00
	s_waitcnt lgkmcnt(6)
	v_mfma_f32_32x32x16_bf16 v[0:15], v[78:81], v[90:93], v[0:15]
	ds_read_b64_tr_b16 v[90:91], v156 offset:0x1200
	ds_read_b64_tr_b16 v[92:93], v156 offset:0x1600
	s_waitcnt lgkmcnt(6)
	v_mfma_f32_32x32x16_bf16 v[0:15], v[36:39], v[106:109], v[0:15]
	ds_read_b64_tr_b16 v[106:107], v156 offset:0x1a00
	ds_read_b64_tr_b16 v[108:109], v156 offset:0x1e00
	s_waitcnt lgkmcnt(6)
	v_mfma_f32_32x32x16_bf16 v[16:31], v[32:35], v[82:85], v[16:31]
	v_add_u32_e32 v82, s97, v151
	v_subrev_u32_e32 v34, 64, v82
	v_mov_b32_e32 v32, 0xf149f2ca
	v_cmp_gt_i32_e32 vcc, s94, v34
	v_mov_b32_e32 v33, 0xf149f2ca
	s_waitcnt lgkmcnt(4)
	v_mfma_f32_32x32x16_bf16 v[16:31], v[74:77], v[86:89], v[16:31]
	s_waitcnt lgkmcnt(2)
	v_mfma_f32_32x32x16_bf16 v[16:31], v[78:81], v[90:93], v[16:31]
	s_waitcnt lgkmcnt(0)
	v_mfma_f32_32x32x16_bf16 v[16:31], v[36:39], v[106:109], v[16:31]
	s_and_saveexec_b64 s[20:21], vcc
	s_cbranch_execz .LBB0_656
	v_cmp_gt_i32_e64 s[22:23], 16, v34
	v_cmp_lt_i32_e32 vcc, 15, v34
	s_and_saveexec_b64 s[72:73], vcc
	v_sub_u32_e32 v33, v145, v34
	v_sub_u32_e32 v35, 0, v33
	v_max_i32_e32 v33, v33, v35
	v_cmp_gt_u32_e32 vcc, s91, v33
	s_andn2_b64 s[22:23], s[22:23], exec
	s_and_b64 s[38:39], vcc, exec
	s_or_b64 s[22:23], s[22:23], s[38:39]
	s_or_b64 exec, exec, s[72:73]
	v_mov_b32_e32 v33, 0xf149f2ca
	s_and_saveexec_b64 s[72:73], s[22:23]
	v_mov_b32_e32 v33, v56
	s_or_b64 exec, exec, s[72:73]

; #define WAIT_L0() asm volatile("s_waitcnt lgkmcnt(0)" ::: "memory")
; #define SBAR() __builtin_amdgcn_sched_barrier(0)
; __device__ __forceinline__ int crow(int r, int hi) { return (r & 3) + 8 * (r >> 2) + 4 * hi; }
; template <bool GM>
; __device__ __forceinline__ void partialSM(f32x16& p0, f32x16& p1, bool mask, int kbase, int L, int qpos, int hi) {
;   if (mask) {
; #pragma unroll
;     for (int r = 0; r < 16; ++r) {
;       int k = kbase + crow(r, hi);
;       asm volatile("" : "+v"(k) : "v"(p0[r]));
;       bool ok = k < L;
;       if (GM) ok = ok && (k < 16 || abs(qpos - k) <= 128);
;       p0[r] = ok ? p0[r] : -1e30f;
;       int k2 = k + 32;
;       asm volatile("" : "+v"(k2) : "v"(p1[r]));
;       bool ok2 = k2 < L;
;       if (GM) ok2 = ok2 && (k2 < 16 || abs(qpos - k2) <= 128);
;       p1[r] = ok2 ? p1[r] : -1e30f;
;     }
; template <int NCB, int D0> __device__ __forceinline__ void pv_one(f32x16& od, int vb, bf16x8 pa0, bf16x8 pa1, bf16x8 pa2, bf16x8 pa3) {
;   constexpr int KSTEP = NCB * 1024, HALF = NCB * 512, B0 = D0 * 512;
;   const s16x4 l0 = tr_read<B0>(vb), h0 = tr_read<B0 + HALF>(vb), l1 = tr_read<B0 + KSTEP>(vb), h1 = tr_read<B0 + KSTEP + HALF>(vb);
;   const s16x4 l2 = tr_read<B0 + 2 * KSTEP>(vb), h2 = tr_read<B0 + 2 * KSTEP + HALF>(vb), l3 = tr_read<B0 + 3 * KSTEP>(vb), h3 = tr_read<B0 + 3 * KSTEP + HALF>(vb);
;   WAIT_L0(); SBAR();
;     ...
;   od = __builtin_amdgcn_mfma_f32_32x32x16_bf16(pa0, PK(l0, h0), od, 0, 0, 0);
;   od = __builtin_amdgcn_mfma_f32_32x32x16_bf16(pa1, PK(l1, h1), od, 0, 0, 0);
;   od = __builtin_amdgcn_mfma_f32_32x32x16_bf16(pa2, PK(l2, h2), od, 0, 0, 0);
;   od = __builtin_amdgcn_mfma_f32_32x32x16_bf16(pa3, PK(l3, h3), od, 0, 0, 0);
;     ...
; }
; template <int NCB> __device__ __forceinline__ void pv_all(f32x16 (&o)[NCB], int vb, bf16x8 pa0, bf16x8 pa1, bf16x8 pa2, bf16x8 pa3) {
;   pv_one<NCB, 0>(o[0], vb, pa0, pa1, pa2, pa3); pv_one<NCB, 1>(o[1], vb, pa0, pa1, pa2, pa3);
;   if constexpr (NCB == 4) { pv_one<NCB, 2>(o[2], vb, pa0, pa1, pa2, pa3); pv_one<NCB, 3>(o[3], vb, pa0, pa1, pa2, pa3); }
; }
.LBB0_844:
	ds_read_b64_tr_b16 v[84:85], v149 offset:0
	ds_read_b64_tr_b16 v[86:87], v149 offset:0x400
	ds_read_b64_tr_b16 v[88:89], v149 offset:0x800
	ds_read_b64_tr_b16 v[90:91], v149 offset:0xc00
	ds_read_b64_tr_b16 v[92:93], v149 offset:0x1000
	ds_read_b64_tr_b16 v[94:95], v149 offset:0x1400
	ds_read_b64_tr_b16 v[108:109], v149 offset:0x1800
	ds_read_b64_tr_b16 v[110:111], v149 offset:0x1c00
	s_nop 0
	s_waitcnt lgkmcnt(6)
	v_mfma_f32_32x32x16_bf16 v[0:15], v[66:69], v[84:87], v[0:15]
	ds_read_b64_tr_b16 v[84:85], v149 offset:0x200
	ds_read_b64_tr_b16 v[86:87], v149 offset:0x600
	s_waitcnt lgkmcnt(6)
	v_mfma_f32_32x32x16_bf16 v[0:15], v[74:77], v[88:91], v[0:15]
	ds_read_b64_tr_b16 v[88:89], v149 offset:0xa00
	ds_read_b64_tr_b16 v[90:91], v149 offset:0xe00
	s_waitcnt lgkmcnt(6)
	v_mfma_f32_32x32x16_bf16 v[0:15], v[78:81], v[92:95], v[0:15]
	ds_read_b64_tr_b16 v[92:93], v149 offset:0x1200
	ds_read_b64_tr_b16 v[94:95], v149 offset:0x1600
	s_waitcnt lgkmcnt(6)
	v_mfma_f32_32x32x16_bf16 v[0:15], v[70:73], v[108:111], v[0:15]
	ds_read_b64_tr_b16 v[108:109], v149 offset:0x1a00
	ds_read_b64_tr_b16 v[110:111], v149 offset:0x1e00
	s_waitcnt lgkmcnt(6)
	v_mfma_f32_32x32x16_bf16 v[16:31], v[66:69], v[84:87], v[16:31]
	v_mov_b32_e32 v33, v82
	v_mov_b32_e32 v32, 0xf149f2ca
	v_cmp_gt_i32_e32 vcc, s94, v33
	v_mov_b32_e32 v66, 0xf149f2ca
	s_waitcnt lgkmcnt(4)
	v_mfma_f32_32x32x16_bf16 v[16:31], v[74:77], v[88:91], v[16:31]
	s_waitcnt lgkmcnt(2)
	v_mfma_f32_32x32x16_bf16 v[16:31], v[78:81], v[92:95], v[16:31]
	s_waitcnt lgkmcnt(0)
	v_mfma_f32_32x32x16_bf16 v[16:31], v[70:73], v[108:111], v[16:31]
	s_and_saveexec_b64 s[20:21], vcc
	s_cbranch_execz .LBB0_850
	v_cmp_gt_i32_e64 s[22:23], 16, v33
	v_cmp_lt_i32_e32 vcc, 15, v33
	s_and_saveexec_b64 s[74:75], vcc
	v_sub_u32_e32 v66, v145, v33
	v_sub_u32_e32 v67, 0, v66
	v_max_i32_e32 v66, v66, v67
	v_cmp_gt_u32_e32 vcc, s91, v66
	s_andn2_b64 s[22:23], s[22:23], exec
	s_and_b64 s[38:39], vcc, exec
	s_or_b64 s[22:23], s[22:23], s[38:39]
	s_or_b64 exec, exec, s[74:75]
	v_mov_b32_e32 v66, 0xf149f2ca
	s_and_saveexec_b64 s[74:75], s[22:23]
	v_mov_b32_e32 v66, v50
	s_or_b64 exec, exec, s[74:75]

; #define WAIT_L0() asm volatile("s_waitcnt lgkmcnt(0)" ::: "memory")
; #define SBAR() __builtin_amdgcn_sched_barrier(0)
; __device__ __forceinline__ void finishSM(f32x16& p0, f32x16& p1, float& l_reg, bf16x8& pa0, bf16x8& pa1, bf16x8& pa2, bf16x8& pa3) {
; #pragma unroll
;   for (int r = 0; r < 16; ++r) p1[r] = __builtin_amdgcn_exp2f(p1[r]);
;   float ps = 0;
; #pragma unroll
;   for (int r = 0; r < 16; ++r) ps += p0[r];
; #pragma unroll
;   for (int r = 0; r < 16; ++r) ps += p1[r];
;   { auto rr = __builtin_amdgcn_permlane32_swap(__float_as_uint(ps), __float_as_uint(ps), false, false);
;     ps = __uint_as_float(rr[0]) + __uint_as_float(rr[1]); }
;   l_reg += ps;
;     ...
;   PK4(p0, 0, pa0); PK4(p0, 8, pa1); PK4(p1, 0, pa2); PK4(p1, 8, pa3);
;     ...
; }
; template <int NCB, int D0> __device__ __forceinline__ void pv_one(f32x16& od, int vb, bf16x8 pa0, bf16x8 pa1, bf16x8 pa2, bf16x8 pa3) {
;   constexpr int KSTEP = NCB * 1024, HALF = NCB * 512, B0 = D0 * 512;
;   const s16x4 l0 = tr_read<B0>(vb), h0 = tr_read<B0 + HALF>(vb), l1 = tr_read<B0 + KSTEP>(vb), h1 = tr_read<B0 + KSTEP + HALF>(vb);
;   const s16x4 l2 = tr_read<B0 + 2 * KSTEP>(vb), h2 = tr_read<B0 + 2 * KSTEP + HALF>(vb), l3 = tr_read<B0 + 3 * KSTEP>(vb), h3 = tr_read<B0 + 3 * KSTEP + HALF>(vb);
;   WAIT_L0(); SBAR();
;     ...
;   od = __builtin_amdgcn_mfma_f32_32x32x16_bf16(pa0, PK(l0, h0), od, 0, 0, 0);
;   od = __builtin_amdgcn_mfma_f32_32x32x16_bf16(pa1, PK(l1, h1), od, 0, 0, 0);
;   od = __builtin_amdgcn_mfma_f32_32x32x16_bf16(pa2, PK(l2, h2), od, 0, 0, 0);
;   od = __builtin_amdgcn_mfma_f32_32x32x16_bf16(pa3, PK(l3, h3), od, 0, 0, 0);
;     ...
; }
; template <int NCB> __device__ __forceinline__ void pv_all(f32x16 (&o)[NCB], int vb, bf16x8 pa0, bf16x8 pa1, bf16x8 pa2, bf16x8 pa3) {
;   pv_one<NCB, 0>(o[0], vb, pa0, pa1, pa2, pa3); pv_one<NCB, 1>(o[1], vb, pa0, pa1, pa2, pa3);
;   if constexpr (NCB == 4) { pv_one<NCB, 2>(o[2], vb, pa0, pa1, pa2, pa3); pv_one<NCB, 3>(o[3], vb, pa0, pa1, pa2, pa3); }
; }
.LBB0_1041:
	s_waitcnt vmcnt(1)
	v_exp_f32_e32 v96, v32
	v_exp_f32_e32 v97, v33
	v_exp_f32_e32 v98, v34
	v_exp_f32_e32 v99, v35
	s_waitcnt vmcnt(0)
	v_exp_f32_e32 v100, v36
	v_exp_f32_e32 v101, v37
	v_exp_f32_e32 v102, v38
	v_exp_f32_e32 v103, v39
	v_exp_f32_e32 v70, v72
	v_exp_f32_e32 v71, v73
	v_exp_f32_e32 v72, v84
	v_exp_f32_e32 v73, v89
	v_exp_f32_e32 v84, v92
	v_exp_f32_e32 v89, v93
	v_exp_f32_e32 v92, v94
	v_exp_f32_e32 v93, v95
	s_mov_b64 s[20:21], -1
	s_cmp_ge_i32 s87, s89
	v_add_f32_e32 v65, 0, v90
	s_cbranch_scc0 .LBB0_1077
	v_add_f32_e32 v32, v91, v65
	v_add_f32_e32 v32, v88, v32
	v_add_f32_e32 v32, v87, v32
	v_add_f32_e32 v32, v86, v32
	v_add_f32_e32 v32, v85, v32
	v_add_f32_e32 v32, v82, v32
	v_add_f32_e32 v32, v81, v32
	v_add_f32_e32 v32, v74, v32
	v_add_f32_e32 v32, v75, v32
	v_add_f32_e32 v32, v76, v32
	v_add_f32_e32 v32, v77, v32
	v_add_f32_e32 v32, v78, v32
	v_add_f32_e32 v32, v79, v32
	v_add_f32_e32 v32, v80, v32
	v_add_f32_e32 v32, v83, v32
	v_add_f32_e32 v32, v96, v32
	v_add_f32_e32 v32, v97, v32
	v_add_f32_e32 v32, v98, v32
	v_add_f32_e32 v32, v99, v32
	v_add_f32_e32 v32, v100, v32
	v_add_f32_e32 v32, v101, v32
	v_add_f32_e32 v32, v102, v32
	v_add_f32_e32 v32, v103, v32
	v_add_f32_e32 v32, v70, v32
	v_add_f32_e32 v32, v71, v32
	v_add_f32_e32 v32, v72, v32
	v_add_f32_e32 v32, v73, v32
	v_add_f32_e32 v32, v84, v32
	v_add_f32_e32 v32, v89, v32
	v_add_f32_e32 v32, v92, v32
	v_add_f32_e32 v32, v93, v32
	v_mov_b32_e32 v33, v32
	s_nop 1
	v_permlane32_swap_b32_e32 v32, v33
	v_add_f32_e32 v32, v32, v33
	v_add_f32_e32 v64, v152, v32
	v_cvt_pk_bf16_f32 v66, v90, v91
	v_cvt_pk_bf16_f32 v67, v88, v87
	v_cvt_pk_bf16_f32 v68, v86, v85
	v_cvt_pk_bf16_f32 v69, v82, v81
	v_cvt_pk_bf16_f32 v104, v74, v75
	v_cvt_pk_bf16_f32 v105, v76, v77
	v_cvt_pk_bf16_f32 v106, v78, v79
	v_cvt_pk_bf16_f32 v107, v80, v83
	v_cvt_pk_bf16_f32 v108, v96, v97
	v_cvt_pk_bf16_f32 v109, v98, v99
	v_cvt_pk_bf16_f32 v110, v100, v101
	v_cvt_pk_bf16_f32 v111, v102, v103
	v_cvt_pk_bf16_f32 v134, v70, v71
	v_cvt_pk_bf16_f32 v135, v72, v73
	v_cvt_pk_bf16_f32 v136, v84, v89
	v_cvt_pk_bf16_f32 v137, v92, v93
	s_nop 0
	v_permlane32_swap_b32_e32 v66, v68
	v_permlane32_swap_b32_e32 v67, v69
	v_permlane32_swap_b32_e32 v104, v106
	v_permlane32_swap_b32_e32 v105, v107
	v_permlane32_swap_b32_e32 v108, v110
	v_permlane32_swap_b32_e32 v109, v111
	v_permlane32_swap_b32_e32 v134, v136
	v_permlane32_swap_b32_e32 v135, v137
	ds_read_b64_tr_b16 v[48:49], v156 offset:0
	ds_read_b64_tr_b16 v[50:51], v156 offset:0x400
	ds_read_b64_tr_b16 v[52:53], v156 offset:0x800
	ds_read_b64_tr_b16 v[54:55], v156 offset:0xc00
	ds_read_b64_tr_b16 v[56:57], v156 offset:0x1000
	ds_read_b64_tr_b16 v[58:59], v156 offset:0x1400
	ds_read_b64_tr_b16 v[60:61], v156 offset:0x1800
	ds_read_b64_tr_b16 v[62:63], v156 offset:0x1c00
	s_nop 0
	s_waitcnt lgkmcnt(6)
	v_mfma_f32_32x32x16_bf16 v[32:47], v[66:69], v[48:51], v[0:15]
	ds_read_b64_tr_b16 v[158:159], v156 offset:0x200
	ds_read_b64_tr_b16 v[160:161], v156 offset:0x600
	ds_read_b64_tr_b16 v[162:163], v156 offset:0xa00
	ds_read_b64_tr_b16 v[164:165], v156 offset:0xe00
	ds_read_b64_tr_b16 v[166:167], v156 offset:0x1200
	ds_read_b64_tr_b16 v[168:169], v156 offset:0x1600
	ds_read_b64_tr_b16 v[170:171], v156 offset:0x1a00
	s_waitcnt lgkmcnt(11)
	v_mfma_f32_32x32x16_bf16 v[32:47], v[104:107], v[52:55], v[32:47]
	ds_read_b64_tr_b16 v[172:173], v156 offset:0x1e00
	s_waitcnt lgkmcnt(10)
	v_mfma_f32_32x32x16_bf16 v[32:47], v[108:111], v[56:59], v[32:47]
	s_waitcnt lgkmcnt(8)
	v_mfma_f32_32x32x16_bf16 v[32:47], v[134:137], v[60:63], v[32:47]
	s_waitcnt lgkmcnt(6)
	v_mfma_f32_32x32x16_bf16 v[48:63], v[66:69], v[158:161], v[16:31]
	s_waitcnt lgkmcnt(4)
	v_mfma_f32_32x32x16_bf16 v[48:63], v[104:107], v[162:165], v[48:63]
	s_waitcnt lgkmcnt(2)
	v_mfma_f32_32x32x16_bf16 v[48:63], v[108:111], v[166:169], v[48:63]
	s_waitcnt lgkmcnt(0)
	v_mfma_f32_32x32x16_bf16 v[48:63], v[134:137], v[170:173], v[48:63]
	s_cbranch_execz .LBB0_1078

; __device__ __forceinline__ void finishSM(f32x16& p0, f32x16& p1, float& l_reg, bf16x8& pa0, bf16x8& pa1, bf16x8& pa2, bf16x8& pa3) {
; #pragma unroll
;   for (int r = 0; r < 16; ++r) p1[r] = __builtin_amdgcn_exp2f(p1[r]);
;   float ps = 0;
; #pragma unroll
;   for (int r = 0; r < 16; ++r) ps += p0[r];
; #pragma unroll
;   for (int r = 0; r < 16; ++r) ps += p1[r];
;   { auto rr = __builtin_amdgcn_permlane32_swap(__float_as_uint(ps), __float_as_uint(ps), false, false);
;     ps = __uint_as_float(rr[0]) + __uint_as_float(rr[1]); }
;   l_reg += ps;
;     ...
;   PK4(p0, 0, pa0); PK4(p0, 8, pa1); PK4(p1, 0, pa2); PK4(p1, 8, pa3);
;     ...
; }
; template <int DQK, int QL>
; __device__ __forceinline__ void qkt(f32x16& p0, f32x16& p1, const char* Ks, const bf16x8 (&qr)[DQK / 16 - QL], const char* qlds, const int (&kofs)[4], float negM) {
;   constexpr int QR = DQK / 16 - QL;
; #pragma unroll
;   for (int r = 0; r < 16; ++r) { p0[r] = negM; p1[r] = negM; }
; #pragma unroll
;   for (int d0 = 0; d0 < DQK / 16; ++d0) {
;     const char* kp = Ks + kofs[d0 & 3] + (d0 >> 2) * 128;
;     bf16x8 b0 = *reinterpret_cast<const bf16x8*>(kp);
;     bf16x8 b1 = *reinterpret_cast<const bf16x8*>(kp + 32 * DQK * 2);
;     bf16x8 qf;
;     if constexpr (QL > 0) { if (d0 < QR) qf = qr[d0 < QR ? d0 : 0]; else qf = *reinterpret_cast<const bf16x8*>(qlds + (d0 - QR) * 1024); }
;     else qf = qr[d0];
;     p0 = __builtin_amdgcn_mfma_f32_32x32x16_bf16(b0, qf, p0, 0, 0, 0);
;     p1 = __builtin_amdgcn_mfma_f32_32x32x16_bf16(b1, qf, p1, 0, 0, 0);
;   }
; }
; template <int NCB> __device__ __forceinline__ int v_st(int k, int c) {
;   const int kk = (k & ~0xC) | ((k & 4) << 1) | ((k & 8) >> 1);
;   return ((kk >> 3) * NCB + (c >> 5)) * 512 + ((kk & 7) * 32 + (c & 31)) * 2;
; }
; __device__ __forceinline__ int v_rd_base(int lane) { return ((lane & 3) << 3) | (((lane >> 2) & 3) << 6) | (((lane >> 4) & 1) << 5) | (((lane >> 5) & 1) << 8); }
; template <int OFF> __device__ __forceinline__ s16x4 tr_read(int vb) {
;   s16x4 r; asm volatile("ds_read_b64_tr_b16 %0, %1 offset:%2" : "=&v"(r) : "v"(vb), "i"(OFF) : "memory"); return r;
; }
; template <int NCB, int D0> __device__ __forceinline__ void pv_one(f32x16& od, int vb, bf16x8 pa0, bf16x8 pa1, bf16x8 pa2, bf16x8 pa3) {
;   constexpr int KSTEP = NCB * 1024, HALF = NCB * 512, B0 = D0 * 512;
.LBB0_1078:
	ds_read_b128 v[66:69], v150 offset:40960
	ds_read_b128 v[104:107], v150 offset:45056
	s_nop 4
	v_mov_b64_e32 v[46:47], s[18:19]
	v_mov_b64_e32 v[44:45], s[16:17]
	v_mov_b64_e32 v[42:43], s[14:15]
	v_mov_b64_e32 v[40:41], s[12:13]
	v_mov_b64_e32 v[38:39], s[10:11]
	v_mov_b64_e32 v[36:37], s[8:9]
	v_mov_b64_e32 v[34:35], s[6:7]
	v_mov_b64_e32 v[32:33], s[4:5]
	v_add_f32_e32 v64, v91, v65
	v_add_f32_e32 v64, v88, v64
	s_waitcnt lgkmcnt(1)
	v_mfma_f32_32x32x16_bf16 v[48:63], v[66:69], v[124:127], v[32:47]
	v_add_f32_e32 v64, v87, v64
	v_add_f32_e32 v64, v86, v64
	v_add_f32_e32 v64, v85, v64
	v_add_f32_e32 v64, v82, v64
	v_add_f32_e32 v64, v81, v64
	v_add_f32_e32 v64, v74, v64
	v_add_f32_e32 v64, v75, v64
	s_waitcnt lgkmcnt(0)
	v_mfma_f32_32x32x16_bf16 v[32:47], v[104:107], v[124:127], v[32:47]
	ds_read_b128 v[66:69], v148 offset:40960
	ds_read_b128 v[104:107], v148 offset:45056
	v_add_f32_e32 v64, v76, v64
	v_add_f32_e32 v64, v77, v64
	v_add_f32_e32 v64, v78, v64
	v_add_f32_e32 v64, v79, v64
	v_add_f32_e32 v64, v80, v64
	v_add_f32_e32 v64, v83, v64
	s_waitcnt lgkmcnt(1)
	v_mfma_f32_32x32x16_bf16 v[48:63], v[66:69], v[120:123], v[48:63]
	v_add_f32_e32 v64, v96, v64
	v_add_f32_e32 v64, v97, v64
	v_add_f32_e32 v64, v98, v64
	v_add_f32_e32 v64, v99, v64
	v_add_f32_e32 v64, v100, v64
	v_add_f32_e32 v64, v101, v64
	v_add_f32_e32 v64, v102, v64
	s_waitcnt lgkmcnt(0)
	v_mfma_f32_32x32x16_bf16 v[32:47], v[104:107], v[120:123], v[32:47]
	ds_read_b128 v[66:69], v147 offset:40960
	ds_read_b128 v[104:107], v147 offset:45056
	v_add_f32_e32 v64, v103, v64
	v_add_f32_e32 v64, v70, v64
	v_add_f32_e32 v64, v71, v64
	v_add_f32_e32 v64, v72, v64
	v_add_f32_e32 v64, v73, v64
	v_add_f32_e32 v64, v84, v64
	s_waitcnt lgkmcnt(1)
	v_mfma_f32_32x32x16_bf16 v[48:63], v[66:69], v[116:119], v[48:63]
	v_add_f32_e32 v64, v89, v64
	v_add_f32_e32 v64, v92, v64
	s_waitcnt lgkmcnt(0)
	v_mfma_f32_32x32x16_bf16 v[32:47], v[104:107], v[116:119], v[32:47]
	ds_read_b128 v[66:69], v146 offset:40960
	ds_read_b128 v[104:107], v146 offset:45056
	s_waitcnt lgkmcnt(1)
	v_mfma_f32_32x32x16_bf16 v[48:63], v[66:69], v[112:115], v[48:63]
	v_add_f32_e32 v68, v93, v64
	v_mov_b32_e32 v69, v68
	v_cvt_pk_bf16_f32 v64, v90, v91
	v_cvt_pk_bf16_f32 v65, v88, v87
	v_cvt_pk_bf16_f32 v66, v86, v85
	v_cvt_pk_bf16_f32 v67, v82, v81
	s_nop 1
	v_permlane32_swap_b32_e32 v68, v69
	s_waitcnt lgkmcnt(0)
	v_mfma_f32_32x32x16_bf16 v[32:47], v[104:107], v[112:115], v[32:47]
	v_permlane32_swap_b32_e32 v64, v66
	v_permlane32_swap_b32_e32 v65, v67
	v_cvt_pk_bf16_f32 v74, v74, v75
	v_cvt_pk_bf16_f32 v75, v76, v77
	v_cvt_pk_bf16_f32 v76, v78, v79
	v_cvt_pk_bf16_f32 v77, v80, v83
	v_cvt_pk_bf16_f32 v78, v96, v97
	v_cvt_pk_bf16_f32 v79, v98, v99
	v_cvt_pk_bf16_f32 v80, v100, v101
	v_cvt_pk_bf16_f32 v81, v102, v103
	v_cvt_pk_bf16_f32 v70, v70, v71
	v_cvt_pk_bf16_f32 v71, v72, v73
	v_cvt_pk_bf16_f32 v72, v84, v89
	v_cvt_pk_bf16_f32 v73, v92, v93
	s_nop 0
	v_permlane32_swap_b32_e32 v74, v76
	v_permlane32_swap_b32_e32 v75, v77
	v_permlane32_swap_b32_e32 v78, v80
	v_permlane32_swap_b32_e32 v79, v81
	v_permlane32_swap_b32_e32 v70, v72
	v_permlane32_swap_b32_e32 v71, v73
	ds_read_b64_tr_b16 v[82:83], v156 offset:0
	ds_read_b64_tr_b16 v[84:85], v156 offset:0x400
	ds_read_b64_tr_b16 v[86:87], v156 offset:0x800
	ds_read_b64_tr_b16 v[88:89], v156 offset:0xc00
	ds_read_b64_tr_b16 v[90:91], v156 offset:0x1000
	ds_read_b64_tr_b16 v[92:93], v156 offset:0x1400
	ds_read_b64_tr_b16 v[94:95], v156 offset:0x1800
	ds_read_b64_tr_b16 v[96:97], v156 offset:0x1c00
	s_nop 0
	s_waitcnt lgkmcnt(6)
	v_mfma_f32_32x32x16_bf16 v[0:15], v[64:67], v[82:85], v[0:15]
	ds_read_b64_tr_b16 v[82:83], v156 offset:0x200
	ds_read_b64_tr_b16 v[84:85], v156 offset:0x600
	s_waitcnt lgkmcnt(6)
	v_mfma_f32_32x32x16_bf16 v[0:15], v[74:77], v[86:89], v[0:15]
	ds_read_b64_tr_b16 v[86:87], v156 offset:0xa00
	ds_read_b64_tr_b16 v[88:89], v156 offset:0xe00
	s_waitcnt lgkmcnt(6)
	v_mfma_f32_32x32x16_bf16 v[0:15], v[78:81], v[90:93], v[0:15]
	ds_read_b64_tr_b16 v[90:91], v156 offset:0x1200
	ds_read_b64_tr_b16 v[92:93], v156 offset:0x1600
	s_waitcnt lgkmcnt(6)
	v_mfma_f32_32x32x16_bf16 v[0:15], v[70:73], v[94:97], v[0:15]
	ds_read_b64_tr_b16 v[94:95], v156 offset:0x1a00
	ds_read_b64_tr_b16 v[96:97], v156 offset:0x1e00
	s_waitcnt lgkmcnt(6)
	v_mfma_f32_32x32x16_bf16 v[16:31], v[64:67], v[82:85], v[16:31]
	v_sub_u32_e32 v64, s65, v155
	v_add_u32_e32 v64, s87, v64
	v_lshl_or_b32 v66, v64, 6, v151
	v_mov_b32_e32 v67, v66
	v_mov_b32_e32 v64, 0xf149f2ca
	v_cmp_gt_i32_e32 vcc, s94, v67
	s_waitcnt lgkmcnt(4)
	v_mfma_f32_32x32x16_bf16 v[16:31], v[74:77], v[86:89], v[16:31]
	v_mov_b32_e32 v65, 0xf149f2ca
	s_waitcnt lgkmcnt(2)
	v_mfma_f32_32x32x16_bf16 v[16:31], v[78:81], v[90:93], v[16:31]
	s_waitcnt lgkmcnt(0)
	v_mfma_f32_32x32x16_bf16 v[16:31], v[70:73], v[94:97], v[16:31]
	s_and_saveexec_b64 s[4:5], vcc
	s_cbranch_execz .LBB0_1084
	v_cmp_gt_i32_e64 s[6:7], 16, v67
	v_cmp_lt_i32_e32 vcc, 15, v67
	s_and_saveexec_b64 s[8:9], vcc
	v_sub_u32_e32 v65, v145, v67
	v_sub_u32_e32 v70, 0, v65
	v_max_i32_e32 v65, v65, v70
	v_cmp_gt_u32_e32 vcc, s91, v65
	s_andn2_b64 s[6:7], s[6:7], exec
	s_and_b64 s[10:11], vcc, exec
	s_or_b64 s[6:7], s[6:7], s[10:11]
	s_or_b64 exec, exec, s[8:9]
	v_mov_b32_e32 v65, 0xf149f2ca
	s_and_saveexec_b64 s[8:9], s[6:7]
	v_mov_b32_e32 v65, v48
	s_or_b64 exec, exec, s[8:9]

; #define WAIT_L0() asm volatile("s_waitcnt lgkmcnt(0)" ::: "memory")
; #define SBAR() __builtin_amdgcn_sched_barrier(0)
; __device__ __forceinline__ void finishSM(f32x16& p0, f32x16& p1, float& l_reg, bf16x8& pa0, bf16x8& pa1, bf16x8& pa2, bf16x8& pa3) {
; #pragma unroll
;   for (int r = 0; r < 16; ++r) p1[r] = __builtin_amdgcn_exp2f(p1[r]);
;   float ps = 0;
; #pragma unroll
;   for (int r = 0; r < 16; ++r) ps += p0[r];
; #pragma unroll
;   for (int r = 0; r < 16; ++r) ps += p1[r];
;   { auto rr = __builtin_amdgcn_permlane32_swap(__float_as_uint(ps), __float_as_uint(ps), false, false);
;     ps = __uint_as_float(rr[0]) + __uint_as_float(rr[1]); }
;   l_reg += ps;
;     ...
;   PK4(p0, 0, pa0); PK4(p0, 8, pa1); PK4(p1, 0, pa2); PK4(p1, 8, pa3);
;     ...
; }
; template <int NCB, int D0> __device__ __forceinline__ void pv_one(f32x16& od, int vb, bf16x8 pa0, bf16x8 pa1, bf16x8 pa2, bf16x8 pa3) {
;   constexpr int KSTEP = NCB * 1024, HALF = NCB * 512, B0 = D0 * 512;
;   const s16x4 l0 = tr_read<B0>(vb), h0 = tr_read<B0 + HALF>(vb), l1 = tr_read<B0 + KSTEP>(vb), h1 = tr_read<B0 + KSTEP + HALF>(vb);
;   const s16x4 l2 = tr_read<B0 + 2 * KSTEP>(vb), h2 = tr_read<B0 + 2 * KSTEP + HALF>(vb), l3 = tr_read<B0 + 3 * KSTEP>(vb), h3 = tr_read<B0 + 3 * KSTEP + HALF>(vb);
;   WAIT_L0(); SBAR();
;     ...
;   od = __builtin_amdgcn_mfma_f32_32x32x16_bf16(pa0, PK(l0, h0), od, 0, 0, 0);
;   od = __builtin_amdgcn_mfma_f32_32x32x16_bf16(pa1, PK(l1, h1), od, 0, 0, 0);
;   od = __builtin_amdgcn_mfma_f32_32x32x16_bf16(pa2, PK(l2, h2), od, 0, 0, 0);
;   od = __builtin_amdgcn_mfma_f32_32x32x16_bf16(pa3, PK(l3, h3), od, 0, 0, 0);
;     ...
; }
; template <int NCB> __device__ __forceinline__ void pv_all(f32x16 (&o)[NCB], int vb, bf16x8 pa0, bf16x8 pa1, bf16x8 pa2, bf16x8 pa3) {
;   pv_one<NCB, 0>(o[0], vb, pa0, pa1, pa2, pa3); pv_one<NCB, 1>(o[1], vb, pa0, pa1, pa2, pa3);
;   if constexpr (NCB == 4) { pv_one<NCB, 2>(o[2], vb, pa0, pa1, pa2, pa3); pv_one<NCB, 3>(o[3], vb, pa0, pa1, pa2, pa3); }
; }
.LBB0_1270:
	s_or_b64 exec, exec, s[4:5]
	v_exp_f32_e32 v63, v65
	v_exp_f32_e32 v48, v48
	v_exp_f32_e32 v49, v49
	v_exp_f32_e32 v50, v50
	v_exp_f32_e32 v51, v51
	v_exp_f32_e32 v66, v32
	v_add_f32_e32 v32, 0, v63
	v_exp_f32_e32 v52, v52
	v_add_f32_e32 v32, v32, v48
	v_exp_f32_e32 v53, v53
	v_add_f32_e32 v32, v32, v49
	v_exp_f32_e32 v54, v54
	v_add_f32_e32 v32, v32, v50
	v_exp_f32_e32 v55, v55
	v_add_f32_e32 v32, v32, v51
	v_exp_f32_e32 v56, v56
	v_add_f32_e32 v32, v32, v52
	v_exp_f32_e32 v57, v57
	v_add_f32_e32 v32, v32, v53
	v_exp_f32_e32 v58, v58
	v_add_f32_e32 v32, v32, v54
	v_exp_f32_e32 v59, v59
	v_add_f32_e32 v32, v32, v55
	v_exp_f32_e32 v60, v60
	v_add_f32_e32 v32, v32, v56
	v_exp_f32_e32 v61, v61
	v_add_f32_e32 v32, v32, v57
	v_exp_f32_e32 v62, v62
	v_add_f32_e32 v32, v32, v58
	v_exp_f32_e32 v65, v64
	v_add_f32_e32 v32, v32, v59
	v_add_f32_e32 v32, v32, v60
	v_exp_f32_e32 v67, v33
	v_add_f32_e32 v32, v32, v61
	v_add_f32_e32 v47, v68, v69
	v_exp_f32_e32 v68, v34
	v_add_f32_e32 v32, v32, v62
	v_exp_f32_e32 v69, v35
	v_add_f32_e32 v32, v65, v32
	v_exp_f32_e32 v70, v36
	v_add_f32_e32 v32, v66, v32
	v_exp_f32_e32 v71, v37
	v_add_f32_e32 v32, v67, v32
	v_exp_f32_e32 v72, v38
	v_add_f32_e32 v32, v68, v32
	v_exp_f32_e32 v73, v39
	v_add_f32_e32 v32, v69, v32
	v_exp_f32_e32 v40, v40
	v_add_f32_e32 v32, v70, v32
	v_exp_f32_e32 v41, v41
	v_add_f32_e32 v32, v71, v32
	v_exp_f32_e32 v42, v42
	v_add_f32_e32 v32, v72, v32
	v_exp_f32_e32 v43, v43
	v_add_f32_e32 v32, v73, v32
	v_exp_f32_e32 v44, v44
	v_add_f32_e32 v32, v40, v32
	v_exp_f32_e32 v45, v45
	v_add_f32_e32 v32, v41, v32
	v_exp_f32_e32 v46, v46
	v_add_f32_e32 v32, v42, v32
	v_add_f32_e32 v32, v43, v32
	v_add_f32_e32 v32, v44, v32
	v_add_f32_e32 v32, v45, v32
	v_add_f32_e32 v32, v32, v46
	v_mov_b32_e32 v33, v32
	s_nop 1
	v_permlane32_swap_b32_e32 v32, v33
	v_add_f32_e32 v47, v152, v47
	v_add_f32_e32 v32, v32, v33
	v_add_f32_e32 v64, v47, v32
	v_cvt_pk_bf16_f32 v32, v63, v48
	v_cvt_pk_bf16_f32 v33, v49, v50
	v_cvt_pk_bf16_f32 v34, v51, v52
	v_cvt_pk_bf16_f32 v35, v53, v54
	v_cvt_pk_bf16_f32 v36, v55, v56
	v_cvt_pk_bf16_f32 v37, v57, v58
	v_cvt_pk_bf16_f32 v38, v59, v60
	v_cvt_pk_bf16_f32 v39, v61, v62
	v_cvt_pk_bf16_f32 v48, v65, v66
	v_cvt_pk_bf16_f32 v49, v67, v68
	v_cvt_pk_bf16_f32 v50, v69, v70
	v_cvt_pk_bf16_f32 v51, v71, v72
	v_cvt_pk_bf16_f32 v52, v73, v40
	v_cvt_pk_bf16_f32 v53, v41, v42
	v_cvt_pk_bf16_f32 v54, v43, v44
	v_cvt_pk_bf16_f32 v55, v45, v46
	s_nop 0
	v_permlane32_swap_b32_e32 v32, v34
	v_permlane32_swap_b32_e32 v33, v35
	v_permlane32_swap_b32_e32 v36, v38
	v_permlane32_swap_b32_e32 v37, v39
	v_permlane32_swap_b32_e32 v48, v50
	v_permlane32_swap_b32_e32 v49, v51
	v_permlane32_swap_b32_e32 v52, v54
	v_permlane32_swap_b32_e32 v53, v55
	ds_read_b64_tr_b16 v[40:41], v149 offset:0
	ds_read_b64_tr_b16 v[42:43], v149 offset:0x400
	ds_read_b64_tr_b16 v[44:45], v149 offset:0x800
	ds_read_b64_tr_b16 v[46:47], v149 offset:0xc00
	ds_read_b64_tr_b16 v[56:57], v149 offset:0x1000
	ds_read_b64_tr_b16 v[58:59], v149 offset:0x1400
	ds_read_b64_tr_b16 v[60:61], v149 offset:0x1800
	ds_read_b64_tr_b16 v[62:63], v149 offset:0x1c00
	s_nop 0
	s_waitcnt lgkmcnt(6)
	v_mfma_f32_32x32x16_bf16 v[0:15], v[32:35], v[40:43], v[0:15]
	ds_read_b64_tr_b16 v[40:41], v149 offset:0x200
	ds_read_b64_tr_b16 v[42:43], v149 offset:0x600
	s_waitcnt lgkmcnt(6)
	v_mfma_f32_32x32x16_bf16 v[0:15], v[36:39], v[44:47], v[0:15]
	ds_read_b64_tr_b16 v[44:45], v149 offset:0xa00
	ds_read_b64_tr_b16 v[46:47], v149 offset:0xe00
	s_waitcnt lgkmcnt(6)
	v_mfma_f32_32x32x16_bf16 v[0:15], v[48:51], v[56:59], v[0:15]
	ds_read_b64_tr_b16 v[56:57], v149 offset:0x1200
	ds_read_b64_tr_b16 v[58:59], v149 offset:0x1600
	s_waitcnt lgkmcnt(6)
	v_mfma_f32_32x32x16_bf16 v[0:15], v[52:55], v[60:63], v[0:15]
	ds_read_b64_tr_b16 v[60:61], v149 offset:0x1a00
	ds_read_b64_tr_b16 v[62:63], v149 offset:0x1e00
	s_waitcnt lgkmcnt(6)
	v_mfma_f32_32x32x16_bf16 v[16:31], v[32:35], v[40:43], v[16:31]
	s_nop 10
	v_mov_b32_e32 v43, v11
	v_mov_b32_e32 v42, v10
	v_mov_b32_e32 v41, v9
	v_mov_b32_e32 v40, v8
	v_mov_b32_e32 v35, v3
	v_mov_b32_e32 v34, v2
	v_mov_b32_e32 v33, v1
	s_waitcnt lgkmcnt(4)
	v_mfma_f32_32x32x16_bf16 v[16:31], v[36:39], v[44:47], v[16:31]
	v_mov_b32_e32 v47, v15
	v_mov_b32_e32 v46, v14
	v_mov_b32_e32 v45, v13
	v_mov_b32_e32 v44, v12
	v_mov_b32_e32 v39, v7
	v_mov_b32_e32 v38, v6
	v_mov_b32_e32 v37, v5
	s_waitcnt lgkmcnt(2)
	v_mfma_f32_32x32x16_bf16 v[16:31], v[48:51], v[56:59], v[16:31]
	v_mov_b32_e32 v36, v4
	v_mov_b32_e32 v32, v0
	s_waitcnt lgkmcnt(0)
	v_mfma_f32_32x32x16_bf16 v[16:31], v[52:55], v[60:63], v[16:31]
	s_nop 11
	v_mov_b32_e32 v63, v31
	v_mov_b32_e32 v62, v30
	v_mov_b32_e32 v61, v29
	v_mov_b32_e32 v60, v28
	v_mov_b32_e32 v59, v27
	v_mov_b32_e32 v58, v26
	v_mov_b32_e32 v57, v25
	v_mov_b32_e32 v56, v24
	v_mov_b32_e32 v55, v23
	v_mov_b32_e32 v54, v22
	v_mov_b32_e32 v53, v21
	v_mov_b32_e32 v52, v20
	v_mov_b32_e32 v51, v19
	v_mov_b32_e32 v50, v18
	v_mov_b32_e32 v49, v17
	v_mov_b32_e32 v48, v16
	s_and_saveexec_b64 s[4:5], s[0:1]
	s_cbranch_execnz .LBB0_1044
	s_branch .LBB0_1045
